# glu and ssm_out epilogues: side-input loads of two store iterations issued together with counted waits (were one load pair per store behind vmcnt 0)
# baseline (speedup 1.0000x reference)
; DI float bf_lo(unsigned u) { return __uint_as_float(u << 16); }
; DI float bf_hi(unsigned u) { return __uint_as_float(u & 0xffff0000u); }
; DI float fast_exp(float x) { return __builtin_amdgcn_exp2f(x * 1.44269504089f); }
; DI float gelu_tanh(float y) {
;   const float z = 0.7978845608028654f * (y + 0.044715f * y * y * y);
;   const float e = fast_exp(2.0f * z);
;   const float th = 1.0f - 2.0f / (e + 1.0f);
;   return 0.5f * y * (1.0f + th);
; }
; DI void phase_ssm_out(const Params& p, char* lds) {
;     ...
;     epi8_iter(acc, [&](int t, int n, float a, float b, float c, float d) {
;       const int nn = nt * 256 + n, tt = nn >> 4, pp = nn & 15;
;       const size_t tok = (size_t)(ct * 256 + t) * 32 + tt;
;       const uint2 uu = *(const uint2*)(u + tok * 512 + g * 16 + pp);
;       const float4 dd = *(const float4*)(p.ssm_d + g * 16 + pp);
;       store_bf4(yg + tok * 512 + g * 16 + pp, gelu_tanh(a + dd.x * bf_lo(uu.x)), gelu_tanh(b + dd.y * bf_hi(uu.x)),
;                 gelu_tanh(c + dd.z * bf_lo(uu.y)), gelu_tanh(d + dd.w * bf_hi(uu.y)));
;     });
.LBB0_241:
	v_mov_b32_e32 v128, v162
	v_mov_b32_e32 v129, v162
	s_lshl_b32 s24, s0, 8
	v_ashrrev_i32_e32 v137, 2, v129
	v_lshrrev_b32_e32 v131, 1, v129
	v_and_b32_e32 v129, 0xffffffc0, v137
	v_add_u32_e32 v136, s24, v129
	v_and_b32_e32 v130, 15, v128
	s_movk_i32 s29, 0x60
	v_ashrrev_i32_e32 v132, 4, v136
	s_lshl_b32 s1, s1, 22
	v_and_or_b32 v130, v131, s29, v130
	v_ashrrev_i32_e32 v133, 31, v132
	v_lshrrev_b32_e32 v128, 2, v128
	v_lshl_or_b32 v152, v130, 14, s1
	v_lshlrev_b64 v[130:131], 9, v[132:133]
	v_and_b32_e32 v140, 12, v128
	v_lshl_add_u64 v[128:129], v[130:131], 0, v[152:153]
	v_lshlrev_b64 v[134:135], 1, v[128:129]
	v_lshl_add_u64 v[128:129], s[36:37], 0, v[134:135]
	v_lshl_add_u64 v[138:139], v[128:129], 0, s[8:9]
	v_lshlrev_b32_e32 v128, 1, v140
	v_mov_b32_e32 v129, v153
	s_lshl_b64 s[0:1], s[80:81], 2
	v_readlane_b32 s12, v254, 63
	v_lshl_add_u64 v[138:139], v[138:139], 0, v[128:129]
	v_readlane_b32 s13, v255, 0
	s_add_u32 s80, s12, s0
	global_load_dwordx2 v[142:143], v[138:139], off
	v_lshlrev_b32_e32 v172, 2, v140
	v_or_b32_e32 v173, 0x40000, v152
	v_mov_b32_e32 v176, v153
	v_mov_b32_e32 v178, v173
	v_mov_b32_e32 v179, v176
	v_lshl_add_u64 v[182:183], v[130:131], 0, v[178:179]
	v_lshlrev_b64 v[184:185], 1, v[182:183]
	v_lshl_add_u64 v[186:187], s[36:37], 0, v[184:185]
	v_lshl_add_u64 v[188:189], v[186:187], 0, s[8:9]
	v_lshl_add_u64 v[190:191], v[188:189], 0, v[128:129]
	global_load_dwordx2 v[192:193], v[190:191], off
	s_addc_u32 s81, s13, s1
	global_load_dwordx4 v[138:141], v172, s[80:81]
	v_lshl_add_u64 v[134:135], s[26:27], 0, v[134:135]
	v_lshl_add_u64 v[134:135], v[134:135], 0, s[8:9]
	v_lshl_add_u64 v[134:135], v[134:135], 0, v[128:129]
	s_add_i32 s21, s21, s16
	v_readlane_b32 s84, v254, 14
	s_mov_b32 s58, s66
	s_mov_b64 s[14:15], s[64:65]
	s_mov_b64 s[74:75], s[18:19]
	s_mov_b64 s[90:91], s[44:45]
	v_readlane_b32 s85, v254, 15
	s_mov_b32 s20, s67
	s_mov_b32 s28, 0x1c000
	s_mov_b64 s[42:43], 0x1000
	s_mov_b64 s[68:69], 0x400000
	s_movk_i32 s96, 0x7fff
	s_waitcnt vmcnt(0)
	v_lshlrev_b32_e32 v144, 16, v142
	v_and_b32_e32 v145, 0xffff0000, v142
	v_pk_fma_f32 v[124:125], v[138:139], v[144:145], v[124:125]
	s_nop 0
	v_mul_f32_e32 v138, 0x3d372713, v124
	v_mul_f32_e32 v139, 0x3d372713, v125
	v_mul_f32_e32 v138, v124, v138
	v_mul_f32_e32 v139, v125, v139
	v_fma_f32 v138, v124, v138, v124
	v_fma_f32 v139, v125, v139, v125
	v_mul_f32_e32 v138, 0x3f4c422a, v138
	v_mul_f32_e32 v139, 0x3f4c422a, v139
	v_add_f32_e32 v138, v138, v138
	v_add_f32_e32 v139, v139, v139
	v_mul_f32_e32 v138, 0x3fb8aa3b, v138
	v_mul_f32_e32 v139, 0x3fb8aa3b, v139
	v_exp_f32_e32 v138, v138
	v_exp_f32_e32 v139, v139
	v_pk_mul_f32 v[124:125], v[124:125], 0.5 op_sel_hi:[1, 0]
	v_pk_add_f32 v[138:139], v[138:139], 1.0 op_sel_hi:[1, 0]
	s_nop 0
	v_div_scale_f32 v142, s[0:1], v139, v139, 2.0
	v_rcp_f32_e32 v144, v142
	s_nop 0
	v_fma_f32 v145, -v142, v144, 1.0
	v_fmac_f32_e32 v144, v145, v144
	v_div_scale_f32 v145, vcc, 2.0, v139, 2.0
	v_mul_f32_e32 v146, v145, v144
	v_fma_f32 v147, -v142, v146, v145
	v_fmac_f32_e32 v146, v147, v144
	v_fma_f32 v142, -v142, v146, v145
	v_div_fmas_f32 v142, v142, v144, v146
	v_div_fixup_f32 v139, v142, v139, 2.0
	v_div_scale_f32 v142, s[0:1], v138, v138, 2.0
	v_rcp_f32_e32 v144, v142
	s_nop 0
	v_fma_f32 v145, -v142, v144, 1.0
	v_fmac_f32_e32 v144, v145, v144
	v_div_scale_f32 v145, vcc, 2.0, v138, 2.0
	v_mul_f32_e32 v146, v145, v144
	v_fma_f32 v147, -v142, v146, v145
	v_fmac_f32_e32 v146, v147, v144
	v_fma_f32 v142, -v142, v146, v145
	v_div_fmas_f32 v142, v142, v144, v146
	v_div_fixup_f32 v138, v142, v138, 2.0
	v_pk_add_f32 v[138:139], v[138:139], 1.0 op_sel_hi:[1, 0] neg_lo:[1, 0] neg_hi:[1, 0]
	s_nop 0
	v_pk_add_f32 v[138:139], v[138:139], 1.0 op_sel_hi:[1, 0]
	s_nop 0
	v_pk_mul_f32 v[124:125], v[124:125], v[138:139]
	v_lshlrev_b32_e32 v138, 16, v143
	v_and_b32_e32 v139, 0xffff0000, v143
	v_pk_fma_f32 v[126:127], v[140:141], v[138:139], v[126:127]
	v_cvt_pk_bf16_f32 v124, v124, v125
	v_mul_f32_e32 v138, 0x3d372713, v126
	v_mul_f32_e32 v139, 0x3d372713, v127
	v_mul_f32_e32 v138, v126, v138
	v_mul_f32_e32 v139, v127, v139
	v_fma_f32 v138, v126, v138, v126
	v_fma_f32 v139, v127, v139, v127
	v_mul_f32_e32 v138, 0x3f4c422a, v138
	v_mul_f32_e32 v139, 0x3f4c422a, v139
	v_add_f32_e32 v138, v138, v138
	v_add_f32_e32 v139, v139, v139
	v_mul_f32_e32 v138, 0x3fb8aa3b, v138
	v_mul_f32_e32 v139, 0x3fb8aa3b, v139
	v_exp_f32_e32 v138, v138
	v_exp_f32_e32 v139, v139
	v_pk_mul_f32 v[126:127], v[126:127], 0.5 op_sel_hi:[1, 0]
	v_pk_add_f32 v[138:139], v[138:139], 1.0 op_sel_hi:[1, 0]
	s_nop 0
	v_div_scale_f32 v140, s[0:1], v139, v139, 2.0
	v_rcp_f32_e32 v141, v140
	s_nop 0
	v_fma_f32 v142, -v140, v141, 1.0
	v_fmac_f32_e32 v141, v142, v141
	v_div_scale_f32 v142, vcc, 2.0, v139, 2.0
	v_mul_f32_e32 v143, v142, v141
	v_fma_f32 v144, -v140, v143, v142
	v_fmac_f32_e32 v143, v144, v141
	v_fma_f32 v140, -v140, v143, v142
	v_div_fmas_f32 v140, v140, v141, v143
	v_div_fixup_f32 v139, v140, v139, 2.0
	v_div_scale_f32 v140, s[0:1], v138, v138, 2.0
	v_rcp_f32_e32 v141, v140
	s_nop 0
	v_fma_f32 v142, -v140, v141, 1.0
	v_fmac_f32_e32 v141, v142, v141
	v_div_scale_f32 v142, vcc, 2.0, v138, 2.0
	v_mul_f32_e32 v143, v142, v141
	v_fma_f32 v144, -v140, v143, v142
	v_fmac_f32_e32 v143, v144, v141
	v_fma_f32 v140, -v140, v143, v142
	v_div_fmas_f32 v140, v140, v141, v143
	v_div_fixup_f32 v138, v140, v138, 2.0
	v_pk_add_f32 v[138:139], v[138:139], 1.0 op_sel_hi:[1, 0] neg_lo:[1, 0] neg_hi:[1, 0]
	s_nop 0
	v_pk_add_f32 v[138:139], v[138:139], 1.0 op_sel_hi:[1, 0]
	s_nop 0
	v_pk_mul_f32 v[126:127], v[126:127], v[138:139]
	s_nop 0
	v_cvt_pk_bf16_f32 v125, v126, v127
	global_store_dwordx2 v[134:135], v[124:125], off
	v_lshl_add_u64 v[126:127], s[26:27], 0, v[184:185]
	global_load_dwordx4 v[138:141], v172, s[80:81]
	v_lshl_add_u64 v[126:127], v[126:127], 0, s[8:9]
	v_lshl_add_u64 v[126:127], v[126:127], 0, v[128:129]
	v_lshlrev_b32_e32 v142, 16, v192
	v_and_b32_e32 v143, 0xffff0000, v192
	s_waitcnt vmcnt(0)
; DI float bf_lo(unsigned u) { return __uint_as_float(u << 16); }
; DI float bf_hi(unsigned u) { return __uint_as_float(u & 0xffff0000u); }
; DI float fast_exp(float x) { return __builtin_amdgcn_exp2f(x * 1.44269504089f); }
; DI float gelu_tanh(float y) {
;   const float z = 0.7978845608028654f * (y + 0.044715f * y * y * y);
;   const float e = fast_exp(2.0f * z);
;   const float th = 1.0f - 2.0f / (e + 1.0f);
;   return 0.5f * y * (1.0f + th);
; }
; DI void phase_ssm_out(const Params& p, char* lds) {
;     ...
;     epi8_iter(acc, [&](int t, int n, float a, float b, float c, float d) {
;       const int nn = nt * 256 + n, tt = nn >> 4, pp = nn & 15;
;       const size_t tok = (size_t)(ct * 256 + t) * 32 + tt;
;       const uint2 uu = *(const uint2*)(u + tok * 512 + g * 16 + pp);
;       const float4 dd = *(const float4*)(p.ssm_d + g * 16 + pp);
;       store_bf4(yg + tok * 512 + g * 16 + pp, gelu_tanh(a + dd.x * bf_lo(uu.x)), gelu_tanh(b + dd.y * bf_hi(uu.x)),
;                 gelu_tanh(c + dd.z * bf_lo(uu.y)), gelu_tanh(d + dd.w * bf_hi(uu.y)));
;     });
	v_pk_fma_f32 v[120:121], v[138:139], v[142:143], v[120:121]
	s_nop 0
	v_mul_f32_e32 v134, 0x3d372713, v120
	v_mul_f32_e32 v134, v120, v134
	v_fma_f32 v134, v120, v134, v120
	v_mul_f32_e32 v134, 0x3f4c422a, v134
	v_add_f32_e32 v134, v134, v134
	v_mul_f32_e32 v134, 0x3fb8aa3b, v134
	v_exp_f32_e32 v138, v134
	v_mul_f32_e32 v134, 0x3d372713, v121
	v_mul_f32_e32 v134, v121, v134
	v_fma_f32 v134, v121, v134, v121
	v_mul_f32_e32 v134, 0x3f4c422a, v134
	v_add_f32_e32 v134, v134, v134
	v_mul_f32_e32 v134, 0x3fb8aa3b, v134
	v_exp_f32_e32 v139, v134
	v_pk_mul_f32 v[120:121], v[120:121], 0.5 op_sel_hi:[1, 0]
	v_pk_add_f32 v[138:139], v[138:139], 1.0 op_sel_hi:[1, 0]
	s_nop 0
	v_div_scale_f32 v134, s[0:1], v139, v139, 2.0
	v_rcp_f32_e32 v142, v134
	s_nop 0
	v_fma_f32 v143, -v134, v142, 1.0
	v_fmac_f32_e32 v142, v143, v142
	v_div_scale_f32 v143, vcc, 2.0, v139, 2.0
	v_mul_f32_e32 v144, v143, v142
	v_fma_f32 v145, -v134, v144, v143
	v_fmac_f32_e32 v144, v145, v142
	v_fma_f32 v134, -v134, v144, v143
	v_div_fmas_f32 v134, v134, v142, v144
	v_div_fixup_f32 v139, v134, v139, 2.0
	v_div_scale_f32 v134, s[0:1], v138, v138, 2.0
	v_rcp_f32_e32 v142, v134
	s_nop 0
	v_fma_f32 v143, -v134, v142, 1.0
	v_fmac_f32_e32 v142, v143, v142
	v_div_scale_f32 v143, vcc, 2.0, v138, 2.0
	v_mul_f32_e32 v144, v143, v142
	v_fma_f32 v145, -v134, v144, v143
	v_fmac_f32_e32 v144, v145, v142
	v_fma_f32 v134, -v134, v144, v143
	v_div_fmas_f32 v134, v134, v142, v144
	v_div_fixup_f32 v138, v134, v138, 2.0
	v_lshlrev_b32_e32 v134, 16, v193
	v_and_b32_e32 v135, 0xffff0000, v193
	v_pk_fma_f32 v[122:123], v[140:141], v[134:135], v[122:123]
	v_pk_add_f32 v[138:139], v[138:139], 1.0 op_sel_hi:[1, 0] neg_lo:[1, 0] neg_hi:[1, 0]
	v_mul_f32_e32 v134, 0x3d372713, v122
	v_mul_f32_e32 v135, 0x3d372713, v123
	v_mul_f32_e32 v134, v122, v134
	v_mul_f32_e32 v135, v123, v135
	v_fma_f32 v134, v122, v134, v122
	v_fma_f32 v135, v123, v135, v123
	v_mul_f32_e32 v134, 0x3f4c422a, v134
	v_mul_f32_e32 v135, 0x3f4c422a, v135
	v_add_f32_e32 v134, v134, v134
	v_add_f32_e32 v135, v135, v135
	v_mul_f32_e32 v134, 0x3fb8aa3b, v134
	v_mul_f32_e32 v135, 0x3fb8aa3b, v135
	v_exp_f32_e32 v134, v134
	v_exp_f32_e32 v135, v135
	v_pk_add_f32 v[138:139], v[138:139], 1.0 op_sel_hi:[1, 0]
	v_pk_mul_f32 v[122:123], v[122:123], 0.5 op_sel_hi:[1, 0]
	v_pk_mul_f32 v[120:121], v[120:121], v[138:139]
	v_pk_add_f32 v[134:135], v[134:135], 1.0 op_sel_hi:[1, 0]
	v_cvt_pk_bf16_f32 v120, v120, v121
	v_div_scale_f32 v138, s[0:1], v135, v135, 2.0
	v_rcp_f32_e32 v139, v138
	s_nop 0
	v_fma_f32 v140, -v138, v139, 1.0
	v_fmac_f32_e32 v139, v140, v139
	v_div_scale_f32 v140, vcc, 2.0, v135, 2.0
	v_mul_f32_e32 v141, v140, v139
	v_fma_f32 v142, -v138, v141, v140
	v_fmac_f32_e32 v141, v142, v139
	v_fma_f32 v138, -v138, v141, v140
	v_div_fmas_f32 v138, v138, v139, v141
	v_div_fixup_f32 v135, v138, v135, 2.0
	v_div_scale_f32 v138, s[0:1], v134, v134, 2.0
	v_rcp_f32_e32 v139, v138
	s_nop 0
	v_fma_f32 v140, -v138, v139, 1.0
	v_fmac_f32_e32 v139, v140, v139
	v_div_scale_f32 v140, vcc, 2.0, v134, 2.0
	v_mul_f32_e32 v141, v140, v139
	v_fma_f32 v142, -v138, v141, v140
	v_fmac_f32_e32 v141, v142, v139
	v_fma_f32 v138, -v138, v141, v140
	v_div_fmas_f32 v138, v138, v139, v141
	v_div_fixup_f32 v134, v138, v134, 2.0
	v_pk_add_f32 v[134:135], v[134:135], 1.0 op_sel_hi:[1, 0] neg_lo:[1, 0] neg_hi:[1, 0]
	s_nop 0
	v_pk_add_f32 v[134:135], v[134:135], 1.0 op_sel_hi:[1, 0]
	s_nop 0
	v_pk_mul_f32 v[122:123], v[122:123], v[134:135]
	s_nop 0
	v_cvt_pk_bf16_f32 v121, v122, v123
	global_store_dwordx2 v[126:127], v[120:121], off
	v_or_b32_e32 v120, 1, v132
	v_ashrrev_i32_e32 v121, 31, v120
	v_lshlrev_b64 v[120:121], 9, v[120:121]
	v_lshl_add_u64 v[122:123], v[120:121], 0, v[152:153]
	v_lshlrev_b64 v[122:123], 1, v[122:123]
	v_lshl_add_u64 v[126:127], s[36:37], 0, v[122:123]
	v_lshl_add_u64 v[126:127], v[126:127], 0, s[8:9]
	v_lshl_add_u64 v[126:127], v[126:127], 0, v[128:129]
	global_load_dwordx2 v[126:127], v[126:127], off
	global_load_dwordx4 v[212:215], v172, s[80:81]
	v_mov_b32_e32 v216, v173
	v_mov_b32_e32 v217, v176
	v_lshl_add_u64 v[218:219], v[120:121], 0, v[216:217]
	v_lshlrev_b64 v[220:221], 1, v[218:219]
	v_lshl_add_u64 v[224:225], s[36:37], 0, v[220:221]
	v_lshl_add_u64 v[226:227], v[224:225], 0, s[8:9]
	v_lshl_add_u64 v[228:229], v[226:227], 0, v[128:129]
	global_load_dwordx2 v[230:231], v[228:229], off
	global_load_dwordx4 v[232:235], v172, s[80:81]
	v_lshl_add_u64 v[122:123], s[26:27], 0, v[122:123]
	v_lshl_add_u64 v[122:123], v[122:123], 0, s[8:9]
	v_lshl_add_u64 v[122:123], v[122:123], 0, v[128:129]
	s_waitcnt vmcnt(3)
	v_lshlrev_b32_e32 v134, 16, v126
	v_and_b32_e32 v135, 0xffff0000, v126
	s_waitcnt vmcnt(2)
; DI float bf_lo(unsigned u) { return __uint_as_float(u << 16); }
; DI float bf_hi(unsigned u) { return __uint_as_float(u & 0xffff0000u); }
; DI float fast_exp(float x) { return __builtin_amdgcn_exp2f(x * 1.44269504089f); }
; DI float gelu_tanh(float y) {
;   const float z = 0.7978845608028654f * (y + 0.044715f * y * y * y);
;   const float e = fast_exp(2.0f * z);
;   const float th = 1.0f - 2.0f / (e + 1.0f);
;   return 0.5f * y * (1.0f + th);
; }
; DI void phase_ssm_out(const Params& p, char* lds) {
;     ...
;     epi8_iter(acc, [&](int t, int n, float a, float b, float c, float d) {
;       const int nn = nt * 256 + n, tt = nn >> 4, pp = nn & 15;
;       const size_t tok = (size_t)(ct * 256 + t) * 32 + tt;
;       const uint2 uu = *(const uint2*)(u + tok * 512 + g * 16 + pp);
;       const float4 dd = *(const float4*)(p.ssm_d + g * 16 + pp);
;       store_bf4(yg + tok * 512 + g * 16 + pp, gelu_tanh(a + dd.x * bf_lo(uu.x)), gelu_tanh(b + dd.y * bf_hi(uu.x)),
;                 gelu_tanh(c + dd.z * bf_lo(uu.y)), gelu_tanh(d + dd.w * bf_hi(uu.y)));
;     });
	v_pk_fma_f32 v[116:117], v[212:213], v[134:135], v[116:117]
	s_nop 0
	v_mul_f32_e32 v126, 0x3d372713, v116
	v_mul_f32_e32 v126, v116, v126
	v_fma_f32 v126, v116, v126, v116
	v_mul_f32_e32 v126, 0x3f4c422a, v126
	v_add_f32_e32 v126, v126, v126
	v_mul_f32_e32 v126, 0x3fb8aa3b, v126
	v_exp_f32_e32 v134, v126
	v_mul_f32_e32 v126, 0x3d372713, v117
	v_mul_f32_e32 v126, v117, v126
	v_fma_f32 v126, v117, v126, v117
	v_mul_f32_e32 v126, 0x3f4c422a, v126
	v_add_f32_e32 v126, v126, v126
	v_mul_f32_e32 v126, 0x3fb8aa3b, v126
	v_exp_f32_e32 v135, v126
	v_pk_mul_f32 v[116:117], v[116:117], 0.5 op_sel_hi:[1, 0]
	v_pk_add_f32 v[134:135], v[134:135], 1.0 op_sel_hi:[1, 0]
	s_nop 0
	v_div_scale_f32 v126, s[0:1], v135, v135, 2.0
	v_rcp_f32_e32 v138, v126
	s_nop 0
	v_fma_f32 v139, -v126, v138, 1.0
	v_fmac_f32_e32 v138, v139, v138
	v_div_scale_f32 v139, vcc, 2.0, v135, 2.0
	v_mul_f32_e32 v142, v139, v138
	v_fma_f32 v143, -v126, v142, v139
	v_fmac_f32_e32 v142, v143, v138
	v_fma_f32 v126, -v126, v142, v139
	v_div_fmas_f32 v126, v126, v138, v142
	v_div_fixup_f32 v135, v126, v135, 2.0
	v_div_scale_f32 v126, s[0:1], v134, v134, 2.0
	v_rcp_f32_e32 v138, v126
	s_nop 0
	v_fma_f32 v139, -v126, v138, 1.0
	v_fmac_f32_e32 v138, v139, v138
	v_div_scale_f32 v139, vcc, 2.0, v134, 2.0
	v_mul_f32_e32 v142, v139, v138
	v_fma_f32 v143, -v126, v142, v139
	v_fmac_f32_e32 v142, v143, v138
	v_fma_f32 v126, -v126, v142, v139
	v_div_fmas_f32 v126, v126, v138, v142
	v_div_fixup_f32 v134, v126, v134, 2.0
	v_lshlrev_b32_e32 v126, 16, v127
	v_and_b32_e32 v127, 0xffff0000, v127
	v_pk_fma_f32 v[118:119], v[214:215], v[126:127], v[118:119]
	v_pk_add_f32 v[134:135], v[134:135], 1.0 op_sel_hi:[1, 0] neg_lo:[1, 0] neg_hi:[1, 0]
	v_mul_f32_e32 v126, 0x3d372713, v118
	v_mul_f32_e32 v127, 0x3d372713, v119
	v_mul_f32_e32 v126, v118, v126
	v_mul_f32_e32 v127, v119, v127
	v_fma_f32 v126, v118, v126, v118
	v_fma_f32 v127, v119, v127, v119
	v_mul_f32_e32 v126, 0x3f4c422a, v126
	v_mul_f32_e32 v127, 0x3f4c422a, v127
	v_add_f32_e32 v126, v126, v126
	v_add_f32_e32 v127, v127, v127
	v_mul_f32_e32 v126, 0x3fb8aa3b, v126
	v_mul_f32_e32 v127, 0x3fb8aa3b, v127
	v_exp_f32_e32 v126, v126
	v_exp_f32_e32 v127, v127
	v_pk_add_f32 v[134:135], v[134:135], 1.0 op_sel_hi:[1, 0]
	v_pk_mul_f32 v[118:119], v[118:119], 0.5 op_sel_hi:[1, 0]
	v_pk_mul_f32 v[116:117], v[116:117], v[134:135]
	v_pk_add_f32 v[126:127], v[126:127], 1.0 op_sel_hi:[1, 0]
	v_cvt_pk_bf16_f32 v116, v116, v117
	v_div_scale_f32 v134, s[0:1], v127, v127, 2.0
	v_rcp_f32_e32 v135, v134
	s_nop 0
	v_fma_f32 v138, -v134, v135, 1.0
	v_fmac_f32_e32 v135, v138, v135
	v_div_scale_f32 v138, vcc, 2.0, v127, 2.0
	v_mul_f32_e32 v139, v138, v135
	v_fma_f32 v140, -v134, v139, v138
	v_fmac_f32_e32 v139, v140, v135
	v_fma_f32 v134, -v134, v139, v138
	v_div_fmas_f32 v134, v134, v135, v139
	v_div_fixup_f32 v127, v134, v127, 2.0
	v_div_scale_f32 v134, s[0:1], v126, v126, 2.0
	v_rcp_f32_e32 v135, v134
	s_nop 0
	v_fma_f32 v138, -v134, v135, 1.0
	v_fmac_f32_e32 v135, v138, v135
	v_div_scale_f32 v138, vcc, 2.0, v126, 2.0
	v_mul_f32_e32 v139, v138, v135
	v_fma_f32 v140, -v134, v139, v138
	v_fmac_f32_e32 v139, v140, v135
	v_fma_f32 v134, -v134, v139, v138
	v_div_fmas_f32 v134, v134, v135, v139
	v_div_fixup_f32 v126, v134, v126, 2.0
	v_pk_add_f32 v[126:127], v[126:127], 1.0 op_sel_hi:[1, 0] neg_lo:[1, 0] neg_hi:[1, 0]
	s_nop 0
	v_pk_add_f32 v[126:127], v[126:127], 1.0 op_sel_hi:[1, 0]
	s_nop 0
	v_pk_mul_f32 v[118:119], v[118:119], v[126:127]
	s_nop 0
	v_cvt_pk_bf16_f32 v117, v118, v119
	global_store_dwordx2 v[122:123], v[116:117], off
	v_lshl_add_u64 v[116:117], s[26:27], 0, v[220:221]
	v_lshl_add_u64 v[116:117], v[116:117], 0, s[8:9]
	v_lshl_add_u64 v[116:117], v[116:117], 0, v[128:129]
	s_waitcnt vmcnt(2)
	v_lshlrev_b32_e32 v122, 16, v230
	v_and_b32_e32 v123, 0xffff0000, v230
	s_waitcnt vmcnt(1)
	v_pk_fma_f32 v[112:113], v[232:233], v[122:123], v[112:113]
	s_nop 0
	v_mul_f32_e32 v118, 0x3d372713, v112
	v_mul_f32_e32 v118, v112, v118
	v_fma_f32 v118, v112, v118, v112
	v_mul_f32_e32 v118, 0x3f4c422a, v118
	v_add_f32_e32 v118, v118, v118
	v_mul_f32_e32 v118, 0x3fb8aa3b, v118
	v_exp_f32_e32 v122, v118
	v_mul_f32_e32 v118, 0x3d372713, v113
	v_mul_f32_e32 v118, v113, v118
	v_fma_f32 v118, v113, v118, v113
	v_mul_f32_e32 v118, 0x3f4c422a, v118
	v_add_f32_e32 v118, v118, v118
	v_mul_f32_e32 v118, 0x3fb8aa3b, v118
	v_exp_f32_e32 v123, v118
	v_pk_mul_f32 v[112:113], v[112:113], 0.5 op_sel_hi:[1, 0]
	v_pk_add_f32 v[122:123], v[122:123], 1.0 op_sel_hi:[1, 0]
	s_nop 0
	v_div_scale_f32 v118, s[0:1], v123, v123, 2.0
	v_rcp_f32_e32 v126, v118
	s_nop 0
	v_fma_f32 v127, -v118, v126, 1.0
	v_fmac_f32_e32 v126, v127, v126
	v_div_scale_f32 v127, vcc, 2.0, v123, 2.0
	v_mul_f32_e32 v134, v127, v126
	v_fma_f32 v135, -v118, v134, v127
	v_fmac_f32_e32 v134, v135, v126
	v_fma_f32 v118, -v118, v134, v127
	v_div_fmas_f32 v118, v118, v126, v134
	v_div_fixup_f32 v123, v118, v123, 2.0
	v_div_scale_f32 v118, s[0:1], v122, v122, 2.0
	v_rcp_f32_e32 v126, v118
	s_nop 0
	v_fma_f32 v127, -v118, v126, 1.0
	v_fmac_f32_e32 v126, v127, v126
	v_div_scale_f32 v127, vcc, 2.0, v122, 2.0
	v_mul_f32_e32 v134, v127, v126
	v_fma_f32 v135, -v118, v134, v127
	v_fmac_f32_e32 v134, v135, v126
	v_fma_f32 v118, -v118, v134, v127
	v_div_fmas_f32 v118, v118, v126, v134
	v_div_fixup_f32 v122, v118, v122, 2.0
	v_lshlrev_b32_e32 v118, 16, v231
	v_and_b32_e32 v119, 0xffff0000, v231
	v_pk_fma_f32 v[114:115], v[234:235], v[118:119], v[114:115]
	v_pk_add_f32 v[122:123], v[122:123], 1.0 op_sel_hi:[1, 0] neg_lo:[1, 0] neg_hi:[1, 0]
	v_mul_f32_e32 v118, 0x3d372713, v114
	v_mul_f32_e32 v119, 0x3d372713, v115
	v_mul_f32_e32 v118, v114, v118
; DI float bf_lo(unsigned u) { return __uint_as_float(u << 16); }
; DI float bf_hi(unsigned u) { return __uint_as_float(u & 0xffff0000u); }
; DI float fast_exp(float x) { return __builtin_amdgcn_exp2f(x * 1.44269504089f); }
; DI float gelu_tanh(float y) {
;   const float z = 0.7978845608028654f * (y + 0.044715f * y * y * y);
;   const float e = fast_exp(2.0f * z);
;   const float th = 1.0f - 2.0f / (e + 1.0f);
;   return 0.5f * y * (1.0f + th);
; }
; DI void phase_ssm_out(const Params& p, char* lds) {
;     ...
;     epi8_iter(acc, [&](int t, int n, float a, float b, float c, float d) {
;       const int nn = nt * 256 + n, tt = nn >> 4, pp = nn & 15;
;       const size_t tok = (size_t)(ct * 256 + t) * 32 + tt;
;       const uint2 uu = *(const uint2*)(u + tok * 512 + g * 16 + pp);
;       const float4 dd = *(const float4*)(p.ssm_d + g * 16 + pp);
;       store_bf4(yg + tok * 512 + g * 16 + pp, gelu_tanh(a + dd.x * bf_lo(uu.x)), gelu_tanh(b + dd.y * bf_hi(uu.x)),
;                 gelu_tanh(c + dd.z * bf_lo(uu.y)), gelu_tanh(d + dd.w * bf_hi(uu.y)));
;     });
	v_mul_f32_e32 v119, v115, v119
	v_fma_f32 v118, v114, v118, v114
	v_fma_f32 v119, v115, v119, v115
	v_mul_f32_e32 v118, 0x3f4c422a, v118
	v_mul_f32_e32 v119, 0x3f4c422a, v119
	v_add_f32_e32 v118, v118, v118
	v_add_f32_e32 v119, v119, v119
	v_mul_f32_e32 v118, 0x3fb8aa3b, v118
	v_mul_f32_e32 v119, 0x3fb8aa3b, v119
	v_exp_f32_e32 v118, v118
	v_exp_f32_e32 v119, v119
	v_pk_add_f32 v[122:123], v[122:123], 1.0 op_sel_hi:[1, 0]
	v_pk_mul_f32 v[114:115], v[114:115], 0.5 op_sel_hi:[1, 0]
	v_pk_mul_f32 v[112:113], v[112:113], v[122:123]
	v_pk_add_f32 v[118:119], v[118:119], 1.0 op_sel_hi:[1, 0]
	v_cvt_pk_bf16_f32 v112, v112, v113
	v_div_scale_f32 v122, s[0:1], v119, v119, 2.0
	v_rcp_f32_e32 v123, v122
	s_nop 0
	v_fma_f32 v126, -v122, v123, 1.0
	v_fmac_f32_e32 v123, v126, v123
	v_div_scale_f32 v126, vcc, 2.0, v119, 2.0
	v_mul_f32_e32 v127, v126, v123
	v_fma_f32 v134, -v122, v127, v126
	v_fmac_f32_e32 v127, v134, v123
	v_fma_f32 v122, -v122, v127, v126
	v_div_fmas_f32 v122, v122, v123, v127
	v_div_fixup_f32 v119, v122, v119, 2.0
	v_div_scale_f32 v122, s[0:1], v118, v118, 2.0
	v_rcp_f32_e32 v123, v122
	s_nop 0
	v_fma_f32 v126, -v122, v123, 1.0
	v_fmac_f32_e32 v123, v126, v123
	v_div_scale_f32 v126, vcc, 2.0, v118, 2.0
	v_mul_f32_e32 v127, v126, v123
	v_fma_f32 v134, -v122, v127, v126
	v_fmac_f32_e32 v127, v134, v123
	v_fma_f32 v122, -v122, v127, v126
	v_div_fmas_f32 v122, v122, v123, v127
	v_div_fixup_f32 v118, v122, v118, 2.0
	v_pk_add_f32 v[118:119], v[118:119], 1.0 op_sel_hi:[1, 0] neg_lo:[1, 0] neg_hi:[1, 0]
	s_nop 0
	v_pk_add_f32 v[118:119], v[118:119], 1.0 op_sel_hi:[1, 0]
	s_nop 0
	v_pk_mul_f32 v[114:115], v[114:115], v[118:119]
	s_nop 0
	v_cvt_pk_bf16_f32 v113, v114, v115
	global_store_dwordx2 v[116:117], v[112:113], off
	v_or_b32_e32 v112, 2, v132
	v_ashrrev_i32_e32 v113, 31, v112
	v_lshlrev_b64 v[112:113], 9, v[112:113]
	v_lshl_add_u64 v[114:115], v[112:113], 0, v[152:153]
	v_lshlrev_b64 v[114:115], 1, v[114:115]
	v_lshl_add_u64 v[116:117], s[36:37], 0, v[114:115]
	v_lshl_add_u64 v[116:117], v[116:117], 0, s[8:9]
	v_lshl_add_u64 v[116:117], v[116:117], 0, v[128:129]
	global_load_dwordx2 v[122:123], v[116:117], off
	global_load_dwordx4 v[184:187], v172, s[80:81]
	v_mov_b32_e32 v178, v173
	v_mov_b32_e32 v179, v176
	v_lshl_add_u64 v[182:183], v[112:113], 0, v[178:179]
	v_lshlrev_b64 v[188:189], 1, v[182:183]
	v_lshl_add_u64 v[190:191], s[36:37], 0, v[188:189]
	v_lshl_add_u64 v[192:193], v[190:191], 0, s[8:9]
	v_lshl_add_u64 v[194:195], v[192:193], 0, v[128:129]
	global_load_dwordx2 v[196:197], v[194:195], off
	global_load_dwordx4 v[200:203], v172, s[80:81]
	v_lshl_add_u64 v[114:115], s[26:27], 0, v[114:115]
	v_lshl_add_u64 v[114:115], v[114:115], 0, s[8:9]
	v_lshl_add_u64 v[114:115], v[114:115], 0, v[128:129]
	s_waitcnt vmcnt(3)
	v_lshlrev_b32_e32 v126, 16, v122
	v_and_b32_e32 v127, 0xffff0000, v122
	s_waitcnt vmcnt(2)
	v_pk_fma_f32 v[108:109], v[184:185], v[126:127], v[108:109]
	s_nop 0
	v_mul_f32_e32 v116, 0x3d372713, v108
	v_mul_f32_e32 v117, 0x3d372713, v109
	v_mul_f32_e32 v116, v108, v116
	v_mul_f32_e32 v117, v109, v117
	v_fma_f32 v116, v108, v116, v108
	v_fma_f32 v117, v109, v117, v109
	v_mul_f32_e32 v116, 0x3f4c422a, v116
	v_mul_f32_e32 v117, 0x3f4c422a, v117
	v_add_f32_e32 v116, v116, v116
	v_add_f32_e32 v117, v117, v117
	v_mul_f32_e32 v116, 0x3fb8aa3b, v116
	v_mul_f32_e32 v117, 0x3fb8aa3b, v117
	v_exp_f32_e32 v116, v116
	v_exp_f32_e32 v117, v117
	v_pk_mul_f32 v[108:109], v[108:109], 0.5 op_sel_hi:[1, 0]
	v_pk_add_f32 v[116:117], v[116:117], 1.0 op_sel_hi:[1, 0]
	s_nop 0
	v_div_scale_f32 v122, s[0:1], v117, v117, 2.0
	v_rcp_f32_e32 v126, v122
	s_nop 0
	v_fma_f32 v127, -v122, v126, 1.0
	v_fmac_f32_e32 v126, v127, v126
	v_div_scale_f32 v127, vcc, 2.0, v117, 2.0
	v_mul_f32_e32 v132, v127, v126
	v_fma_f32 v134, -v122, v132, v127
	v_fmac_f32_e32 v132, v134, v126
	v_fma_f32 v122, -v122, v132, v127
	v_div_fmas_f32 v122, v122, v126, v132
	v_div_fixup_f32 v117, v122, v117, 2.0
	v_div_scale_f32 v122, s[0:1], v116, v116, 2.0
	v_rcp_f32_e32 v126, v122
	s_nop 0
	v_fma_f32 v127, -v122, v126, 1.0
	v_fmac_f32_e32 v126, v127, v126
	v_div_scale_f32 v127, vcc, 2.0, v116, 2.0
	v_mul_f32_e32 v132, v127, v126
	v_fma_f32 v134, -v122, v132, v127
	v_fmac_f32_e32 v132, v134, v126
	v_fma_f32 v122, -v122, v132, v127
	v_div_fmas_f32 v122, v122, v126, v132
	v_div_fixup_f32 v116, v122, v116, 2.0
	v_pk_add_f32 v[116:117], v[116:117], 1.0 op_sel_hi:[1, 0] neg_lo:[1, 0] neg_hi:[1, 0]
	s_nop 0
	v_pk_add_f32 v[116:117], v[116:117], 1.0 op_sel_hi:[1, 0]
	s_nop 0
	v_pk_mul_f32 v[108:109], v[108:109], v[116:117]
	v_lshlrev_b32_e32 v116, 16, v123
	v_and_b32_e32 v117, 0xffff0000, v123
	v_pk_fma_f32 v[110:111], v[186:187], v[116:117], v[110:111]
	v_cvt_pk_bf16_f32 v108, v108, v109
	v_mul_f32_e32 v116, 0x3d372713, v110
	v_mul_f32_e32 v117, 0x3d372713, v111
	v_mul_f32_e32 v116, v110, v116
	v_mul_f32_e32 v117, v111, v117
	v_fma_f32 v116, v110, v116, v110
	v_fma_f32 v117, v111, v117, v111
	v_mul_f32_e32 v116, 0x3f4c422a, v116
	v_mul_f32_e32 v117, 0x3f4c422a, v117
	v_add_f32_e32 v116, v116, v116
	v_add_f32_e32 v117, v117, v117
	v_mul_f32_e32 v116, 0x3fb8aa3b, v116
	v_mul_f32_e32 v117, 0x3fb8aa3b, v117
	v_exp_f32_e32 v116, v116
	v_exp_f32_e32 v117, v117
	v_pk_mul_f32 v[110:111], v[110:111], 0.5 op_sel_hi:[1, 0]
	v_pk_add_f32 v[116:117], v[116:117], 1.0 op_sel_hi:[1, 0]
	s_nop 0
	v_div_scale_f32 v118, s[0:1], v117, v117, 2.0
	v_rcp_f32_e32 v119, v118
	s_nop 0
	v_fma_f32 v122, -v118, v119, 1.0
	v_fmac_f32_e32 v119, v122, v119
	v_div_scale_f32 v122, vcc, 2.0, v117, 2.0
	v_mul_f32_e32 v123, v122, v119
	v_fma_f32 v126, -v118, v123, v122
	v_fmac_f32_e32 v123, v126, v119
	v_fma_f32 v118, -v118, v123, v122
	v_div_fmas_f32 v118, v118, v119, v123
	v_div_fixup_f32 v117, v118, v117, 2.0
	v_div_scale_f32 v118, s[0:1], v116, v116, 2.0
	v_rcp_f32_e32 v119, v118
	s_nop 0
	v_fma_f32 v122, -v118, v119, 1.0
	v_fmac_f32_e32 v119, v122, v119
	v_div_scale_f32 v122, vcc, 2.0, v116, 2.0
	v_mul_f32_e32 v123, v122, v119
	v_fma_f32 v126, -v118, v123, v122
	v_fmac_f32_e32 v123, v126, v119
	v_fma_f32 v118, -v118, v123, v122
	v_div_fmas_f32 v118, v118, v119, v123
	v_div_fixup_f32 v116, v118, v116, 2.0
	v_pk_add_f32 v[116:117], v[116:117], 1.0 op_sel_hi:[1, 0] neg_lo:[1, 0] neg_hi:[1, 0]
	s_nop 0
	v_pk_add_f32 v[116:117], v[116:117], 1.0 op_sel_hi:[1, 0]
	s_nop 0
	v_pk_mul_f32 v[110:111], v[110:111], v[116:117]
	s_nop 0
	v_cvt_pk_bf16_f32 v109, v110, v111
	global_store_dwordx2 v[114:115], v[108:109], off
	v_lshl_add_u64 v[108:109], s[26:27], 0, v[188:189]
	v_lshl_add_u64 v[108:109], v[108:109], 0, s[8:9]
	v_lshl_add_u64 v[108:109], v[108:109], 0, v[128:129]
	s_waitcnt vmcnt(2)
; DI float bf_lo(unsigned u) { return __uint_as_float(u << 16); }
; DI float bf_hi(unsigned u) { return __uint_as_float(u & 0xffff0000u); }
; DI float fast_exp(float x) { return __builtin_amdgcn_exp2f(x * 1.44269504089f); }
; DI float gelu_tanh(float y) {
;   const float z = 0.7978845608028654f * (y + 0.044715f * y * y * y);
;   const float e = fast_exp(2.0f * z);
;   const float th = 1.0f - 2.0f / (e + 1.0f);
;   return 0.5f * y * (1.0f + th);
; }
; DI void phase_ssm_out(const Params& p, char* lds) {
;     ...
;     epi8_iter(acc, [&](int t, int n, float a, float b, float c, float d) {
;       const int nn = nt * 256 + n, tt = nn >> 4, pp = nn & 15;
;       const size_t tok = (size_t)(ct * 256 + t) * 32 + tt;
;       const uint2 uu = *(const uint2*)(u + tok * 512 + g * 16 + pp);
;       const float4 dd = *(const float4*)(p.ssm_d + g * 16 + pp);
;       store_bf4(yg + tok * 512 + g * 16 + pp, gelu_tanh(a + dd.x * bf_lo(uu.x)), gelu_tanh(b + dd.y * bf_hi(uu.x)),
;                 gelu_tanh(c + dd.z * bf_lo(uu.y)), gelu_tanh(d + dd.w * bf_hi(uu.y)));
;     });
	v_lshlrev_b32_e32 v118, 16, v196
	v_and_b32_e32 v119, 0xffff0000, v196
	s_waitcnt vmcnt(1)
	v_pk_fma_f32 v[104:105], v[200:201], v[118:119], v[104:105]
	s_nop 0
	v_mul_f32_e32 v110, 0x3d372713, v104
	v_mul_f32_e32 v110, v104, v110
	v_fma_f32 v110, v104, v110, v104
	v_mul_f32_e32 v110, 0x3f4c422a, v110
	v_add_f32_e32 v110, v110, v110
	v_mul_f32_e32 v110, 0x3fb8aa3b, v110
	v_exp_f32_e32 v114, v110
	v_mul_f32_e32 v110, 0x3d372713, v105
	v_mul_f32_e32 v110, v105, v110
	v_fma_f32 v110, v105, v110, v105
	v_mul_f32_e32 v110, 0x3f4c422a, v110
	v_add_f32_e32 v110, v110, v110
	v_mul_f32_e32 v110, 0x3fb8aa3b, v110
	v_exp_f32_e32 v115, v110
	v_pk_mul_f32 v[104:105], v[104:105], 0.5 op_sel_hi:[1, 0]
	v_pk_add_f32 v[114:115], v[114:115], 1.0 op_sel_hi:[1, 0]
	s_nop 0
	v_div_scale_f32 v110, s[0:1], v115, v115, 2.0
	v_rcp_f32_e32 v118, v110
	s_nop 0
	v_fma_f32 v119, -v110, v118, 1.0
	v_fmac_f32_e32 v118, v119, v118
	v_div_scale_f32 v119, vcc, 2.0, v115, 2.0
	v_mul_f32_e32 v122, v119, v118
	v_fma_f32 v123, -v110, v122, v119
	v_fmac_f32_e32 v122, v123, v118
	v_fma_f32 v110, -v110, v122, v119
	v_div_fmas_f32 v110, v110, v118, v122
	v_div_fixup_f32 v115, v110, v115, 2.0
	v_div_scale_f32 v110, s[0:1], v114, v114, 2.0
	v_rcp_f32_e32 v118, v110
	s_nop 0
	v_fma_f32 v119, -v110, v118, 1.0
	v_fmac_f32_e32 v118, v119, v118
	v_div_scale_f32 v119, vcc, 2.0, v114, 2.0
	v_mul_f32_e32 v122, v119, v118
	v_fma_f32 v123, -v110, v122, v119
	v_fmac_f32_e32 v122, v123, v118
	v_fma_f32 v110, -v110, v122, v119
	v_div_fmas_f32 v110, v110, v118, v122
	v_div_fixup_f32 v114, v110, v114, 2.0
	v_lshlrev_b32_e32 v110, 16, v197
	v_and_b32_e32 v111, 0xffff0000, v197
	v_pk_fma_f32 v[106:107], v[202:203], v[110:111], v[106:107]
	v_pk_add_f32 v[114:115], v[114:115], 1.0 op_sel_hi:[1, 0] neg_lo:[1, 0] neg_hi:[1, 0]
	v_mul_f32_e32 v110, 0x3d372713, v106
	v_mul_f32_e32 v111, 0x3d372713, v107
	v_mul_f32_e32 v110, v106, v110
	v_mul_f32_e32 v111, v107, v111
	v_fma_f32 v110, v106, v110, v106
	v_fma_f32 v111, v107, v111, v107
	v_mul_f32_e32 v110, 0x3f4c422a, v110
	v_mul_f32_e32 v111, 0x3f4c422a, v111
	v_add_f32_e32 v110, v110, v110
	v_add_f32_e32 v111, v111, v111
	v_mul_f32_e32 v110, 0x3fb8aa3b, v110
	v_mul_f32_e32 v111, 0x3fb8aa3b, v111
	v_exp_f32_e32 v110, v110
	v_exp_f32_e32 v111, v111
	v_pk_add_f32 v[114:115], v[114:115], 1.0 op_sel_hi:[1, 0]
	v_pk_mul_f32 v[106:107], v[106:107], 0.5 op_sel_hi:[1, 0]
	v_pk_mul_f32 v[104:105], v[104:105], v[114:115]
	v_pk_add_f32 v[110:111], v[110:111], 1.0 op_sel_hi:[1, 0]
	v_cvt_pk_bf16_f32 v104, v104, v105
	v_div_scale_f32 v114, s[0:1], v111, v111, 2.0
	v_rcp_f32_e32 v115, v114
	s_nop 0
	v_fma_f32 v116, -v114, v115, 1.0
	v_fmac_f32_e32 v115, v116, v115
	v_div_scale_f32 v116, vcc, 2.0, v111, 2.0
	v_mul_f32_e32 v117, v116, v115
	v_fma_f32 v118, -v114, v117, v116
	v_fmac_f32_e32 v117, v118, v115
	v_fma_f32 v114, -v114, v117, v116
	v_div_fmas_f32 v114, v114, v115, v117
	v_div_fixup_f32 v111, v114, v111, 2.0
	v_div_scale_f32 v114, s[0:1], v110, v110, 2.0
	v_rcp_f32_e32 v115, v114
	s_nop 0
	v_fma_f32 v116, -v114, v115, 1.0
	v_fmac_f32_e32 v115, v116, v115
	v_div_scale_f32 v116, vcc, 2.0, v110, 2.0
	v_mul_f32_e32 v117, v116, v115
	v_fma_f32 v118, -v114, v117, v116
	v_fmac_f32_e32 v117, v118, v115
	v_fma_f32 v114, -v114, v117, v116
	v_div_fmas_f32 v114, v114, v115, v117
	v_div_fixup_f32 v110, v114, v110, 2.0
	v_pk_add_f32 v[110:111], v[110:111], 1.0 op_sel_hi:[1, 0] neg_lo:[1, 0] neg_hi:[1, 0]
	s_nop 0
	v_pk_add_f32 v[110:111], v[110:111], 1.0 op_sel_hi:[1, 0]
	s_nop 0
	v_pk_mul_f32 v[106:107], v[106:107], v[110:111]
	s_nop 0
	v_cvt_pk_bf16_f32 v105, v106, v107
	global_store_dwordx2 v[108:109], v[104:105], off
	v_or_b32_e32 v104, 48, v137
	v_add_u32_e32 v104, s24, v104
	v_ashrrev_i32_e32 v104, 4, v104
	v_ashrrev_i32_e32 v105, 31, v104
	v_lshlrev_b64 v[104:105], 9, v[104:105]
	v_lshl_add_u64 v[106:107], v[104:105], 0, v[152:153]
	v_lshlrev_b64 v[106:107], 1, v[106:107]
	v_lshl_add_u64 v[108:109], s[36:37], 0, v[106:107]
	v_lshl_add_u64 v[108:109], v[108:109], 0, s[8:9]
	v_lshl_add_u64 v[108:109], v[108:109], 0, v[128:129]
	global_load_dwordx2 v[114:115], v[108:109], off
	global_load_dwordx4 v[212:215], v172, s[80:81]
	v_mov_b32_e32 v216, v173
	v_mov_b32_e32 v217, v176
	v_lshl_add_u64 v[218:219], v[104:105], 0, v[216:217]
	v_lshlrev_b64 v[220:221], 1, v[218:219]
	v_lshl_add_u64 v[224:225], s[36:37], 0, v[220:221]
	v_lshl_add_u64 v[226:227], v[224:225], 0, s[8:9]
	v_lshl_add_u64 v[228:229], v[226:227], 0, v[128:129]
	global_load_dwordx2 v[230:231], v[228:229], off
	global_load_dwordx4 v[244:247], v172, s[80:81]
	v_lshl_add_u64 v[106:107], s[26:27], 0, v[106:107]
	v_lshl_add_u64 v[106:107], v[106:107], 0, s[8:9]
	v_lshl_add_u64 v[106:107], v[106:107], 0, v[128:129]
	s_waitcnt vmcnt(3)
	v_lshlrev_b32_e32 v116, 16, v114
	v_and_b32_e32 v117, 0xffff0000, v114
	s_waitcnt vmcnt(2)
; DI float bf_lo(unsigned u) { return __uint_as_float(u << 16); }
; DI float bf_hi(unsigned u) { return __uint_as_float(u & 0xffff0000u); }
; DI float fast_exp(float x) { return __builtin_amdgcn_exp2f(x * 1.44269504089f); }
; DI float gelu_tanh(float y) {
;   const float z = 0.7978845608028654f * (y + 0.044715f * y * y * y);
;   const float e = fast_exp(2.0f * z);
;   const float th = 1.0f - 2.0f / (e + 1.0f);
;   return 0.5f * y * (1.0f + th);
; }
; DI void phase_ssm_out(const Params& p, char* lds) {
;     ...
;     epi8_iter(acc, [&](int t, int n, float a, float b, float c, float d) {
;       const int nn = nt * 256 + n, tt = nn >> 4, pp = nn & 15;
;       const size_t tok = (size_t)(ct * 256 + t) * 32 + tt;
;       const uint2 uu = *(const uint2*)(u + tok * 512 + g * 16 + pp);
;       const float4 dd = *(const float4*)(p.ssm_d + g * 16 + pp);
;       store_bf4(yg + tok * 512 + g * 16 + pp, gelu_tanh(a + dd.x * bf_lo(uu.x)), gelu_tanh(b + dd.y * bf_hi(uu.x)),
;                 gelu_tanh(c + dd.z * bf_lo(uu.y)), gelu_tanh(d + dd.w * bf_hi(uu.y)));
;     });
	v_pk_fma_f32 v[100:101], v[212:213], v[116:117], v[100:101]
	s_nop 0
	v_mul_f32_e32 v108, 0x3d372713, v100
	v_mul_f32_e32 v109, 0x3d372713, v101
	v_mul_f32_e32 v108, v100, v108
	v_mul_f32_e32 v109, v101, v109
	v_fma_f32 v108, v100, v108, v100
	v_fma_f32 v109, v101, v109, v101
	v_mul_f32_e32 v108, 0x3f4c422a, v108
	v_mul_f32_e32 v109, 0x3f4c422a, v109
	v_add_f32_e32 v108, v108, v108
	v_add_f32_e32 v109, v109, v109
	v_mul_f32_e32 v108, 0x3fb8aa3b, v108
	v_mul_f32_e32 v109, 0x3fb8aa3b, v109
	v_exp_f32_e32 v108, v108
	v_exp_f32_e32 v109, v109
	v_pk_mul_f32 v[100:101], v[100:101], 0.5 op_sel_hi:[1, 0]
	v_pk_add_f32 v[108:109], v[108:109], 1.0 op_sel_hi:[1, 0]
	s_nop 0
	v_div_scale_f32 v114, s[0:1], v109, v109, 2.0
	v_rcp_f32_e32 v116, v114
	s_nop 0
	v_fma_f32 v117, -v114, v116, 1.0
	v_fmac_f32_e32 v116, v117, v116
	v_div_scale_f32 v117, vcc, 2.0, v109, 2.0
	v_mul_f32_e32 v118, v117, v116
	v_fma_f32 v119, -v114, v118, v117
	v_fmac_f32_e32 v118, v119, v116
	v_fma_f32 v114, -v114, v118, v117
	v_div_fmas_f32 v114, v114, v116, v118
	v_div_fixup_f32 v109, v114, v109, 2.0
	v_div_scale_f32 v114, s[0:1], v108, v108, 2.0
	v_rcp_f32_e32 v116, v114
	s_nop 0
	v_fma_f32 v117, -v114, v116, 1.0
	v_fmac_f32_e32 v116, v117, v116
	v_div_scale_f32 v117, vcc, 2.0, v108, 2.0
	v_mul_f32_e32 v118, v117, v116
	v_fma_f32 v119, -v114, v118, v117
	v_fmac_f32_e32 v118, v119, v116
	v_fma_f32 v114, -v114, v118, v117
	v_div_fmas_f32 v114, v114, v116, v118
	v_div_fixup_f32 v108, v114, v108, 2.0
	v_pk_add_f32 v[108:109], v[108:109], 1.0 op_sel_hi:[1, 0] neg_lo:[1, 0] neg_hi:[1, 0]
	s_nop 0
	v_pk_add_f32 v[108:109], v[108:109], 1.0 op_sel_hi:[1, 0]
	s_nop 0
	v_pk_mul_f32 v[100:101], v[100:101], v[108:109]
	v_lshlrev_b32_e32 v108, 16, v115
	v_and_b32_e32 v109, 0xffff0000, v115
	v_pk_fma_f32 v[102:103], v[214:215], v[108:109], v[102:103]
	v_cvt_pk_bf16_f32 v100, v100, v101
	v_mul_f32_e32 v108, 0x3d372713, v102
	v_mul_f32_e32 v109, 0x3d372713, v103
	v_mul_f32_e32 v108, v102, v108
	v_mul_f32_e32 v109, v103, v109
	v_fma_f32 v108, v102, v108, v102
	v_fma_f32 v109, v103, v109, v103
	v_mul_f32_e32 v108, 0x3f4c422a, v108
	v_mul_f32_e32 v109, 0x3f4c422a, v109
	v_add_f32_e32 v108, v108, v108
	v_add_f32_e32 v109, v109, v109
	v_mul_f32_e32 v108, 0x3fb8aa3b, v108
	v_mul_f32_e32 v109, 0x3fb8aa3b, v109
	v_exp_f32_e32 v108, v108
	v_exp_f32_e32 v109, v109
	v_pk_mul_f32 v[102:103], v[102:103], 0.5 op_sel_hi:[1, 0]
	v_pk_add_f32 v[108:109], v[108:109], 1.0 op_sel_hi:[1, 0]
	s_nop 0
	v_div_scale_f32 v110, s[0:1], v109, v109, 2.0
	v_rcp_f32_e32 v111, v110
	s_nop 0
	v_fma_f32 v114, -v110, v111, 1.0
	v_fmac_f32_e32 v111, v114, v111
	v_div_scale_f32 v114, vcc, 2.0, v109, 2.0
	v_mul_f32_e32 v115, v114, v111
	v_fma_f32 v116, -v110, v115, v114
	v_fmac_f32_e32 v115, v116, v111
	v_fma_f32 v110, -v110, v115, v114
	v_div_fmas_f32 v110, v110, v111, v115
	v_div_fixup_f32 v109, v110, v109, 2.0
	v_div_scale_f32 v110, s[0:1], v108, v108, 2.0
	v_rcp_f32_e32 v111, v110
	s_nop 0
	v_fma_f32 v114, -v110, v111, 1.0
	v_fmac_f32_e32 v111, v114, v111
	v_div_scale_f32 v114, vcc, 2.0, v108, 2.0
	v_mul_f32_e32 v115, v114, v111
	v_fma_f32 v116, -v110, v115, v114
	v_fmac_f32_e32 v115, v116, v111
	v_fma_f32 v110, -v110, v115, v114
	v_div_fmas_f32 v110, v110, v111, v115
	v_div_fixup_f32 v108, v110, v108, 2.0
	v_pk_add_f32 v[108:109], v[108:109], 1.0 op_sel_hi:[1, 0] neg_lo:[1, 0] neg_hi:[1, 0]
	s_nop 0
	v_pk_add_f32 v[108:109], v[108:109], 1.0 op_sel_hi:[1, 0]
	s_nop 0
	v_pk_mul_f32 v[102:103], v[102:103], v[108:109]
	s_nop 0
	v_cvt_pk_bf16_f32 v101, v102, v103
	global_store_dwordx2 v[106:107], v[100:101], off
	v_lshl_add_u64 v[100:101], s[26:27], 0, v[220:221]
	v_lshl_add_u64 v[100:101], v[100:101], 0, s[8:9]
	v_lshl_add_u64 v[100:101], v[100:101], 0, v[128:129]
	s_waitcnt vmcnt(2)
	v_lshlrev_b32_e32 v110, 16, v230
	v_and_b32_e32 v111, 0xffff0000, v230
	s_waitcnt vmcnt(1)
	v_pk_fma_f32 v[96:97], v[244:245], v[110:111], v[96:97]
	s_nop 0
	v_mul_f32_e32 v102, 0x3d372713, v96
	v_mul_f32_e32 v102, v96, v102
	v_fma_f32 v102, v96, v102, v96
	v_mul_f32_e32 v102, 0x3f4c422a, v102
	v_add_f32_e32 v102, v102, v102
	v_mul_f32_e32 v102, 0x3fb8aa3b, v102
	v_exp_f32_e32 v106, v102
	v_mul_f32_e32 v102, 0x3d372713, v97
	v_mul_f32_e32 v102, v97, v102
	v_fma_f32 v102, v97, v102, v97
	v_mul_f32_e32 v102, 0x3f4c422a, v102
	v_add_f32_e32 v102, v102, v102
	v_mul_f32_e32 v102, 0x3fb8aa3b, v102
	v_exp_f32_e32 v107, v102
	v_pk_mul_f32 v[96:97], v[96:97], 0.5 op_sel_hi:[1, 0]
	v_pk_add_f32 v[106:107], v[106:107], 1.0 op_sel_hi:[1, 0]
	s_nop 0
	v_div_scale_f32 v102, s[0:1], v107, v107, 2.0
	v_rcp_f32_e32 v110, v102
	s_nop 0
	v_fma_f32 v111, -v102, v110, 1.0
	v_fmac_f32_e32 v110, v111, v110
	v_div_scale_f32 v111, vcc, 2.0, v107, 2.0
	v_mul_f32_e32 v114, v111, v110
	v_fma_f32 v115, -v102, v114, v111
	v_fmac_f32_e32 v114, v115, v110
	v_fma_f32 v102, -v102, v114, v111
	v_div_fmas_f32 v102, v102, v110, v114
	v_div_fixup_f32 v107, v102, v107, 2.0
	v_div_scale_f32 v102, s[0:1], v106, v106, 2.0
	v_rcp_f32_e32 v110, v102
	s_nop 0
	v_fma_f32 v111, -v102, v110, 1.0
	v_fmac_f32_e32 v110, v111, v110
	v_div_scale_f32 v111, vcc, 2.0, v106, 2.0
	v_mul_f32_e32 v114, v111, v110
	v_fma_f32 v115, -v102, v114, v111
	v_fmac_f32_e32 v114, v115, v110
	v_fma_f32 v102, -v102, v114, v111
	v_div_fmas_f32 v102, v102, v110, v114
	v_div_fixup_f32 v106, v102, v106, 2.0
	v_lshlrev_b32_e32 v102, 16, v231
	v_and_b32_e32 v103, 0xffff0000, v231
	v_pk_fma_f32 v[98:99], v[246:247], v[102:103], v[98:99]
	v_pk_add_f32 v[106:107], v[106:107], 1.0 op_sel_hi:[1, 0] neg_lo:[1, 0] neg_hi:[1, 0]
	v_mul_f32_e32 v102, 0x3d372713, v98
	v_mul_f32_e32 v103, 0x3d372713, v99
	v_mul_f32_e32 v102, v98, v102
; DI float bf_lo(unsigned u) { return __uint_as_float(u << 16); }
; DI float bf_hi(unsigned u) { return __uint_as_float(u & 0xffff0000u); }
; DI float fast_exp(float x) { return __builtin_amdgcn_exp2f(x * 1.44269504089f); }
; DI float gelu_tanh(float y) {
;   const float z = 0.7978845608028654f * (y + 0.044715f * y * y * y);
;   const float e = fast_exp(2.0f * z);
;   const float th = 1.0f - 2.0f / (e + 1.0f);
;   return 0.5f * y * (1.0f + th);
; }
; DI void phase_ssm_out(const Params& p, char* lds) {
;     ...
;     epi8_iter(acc, [&](int t, int n, float a, float b, float c, float d) {
;       const int nn = nt * 256 + n, tt = nn >> 4, pp = nn & 15;
;       const size_t tok = (size_t)(ct * 256 + t) * 32 + tt;
;       const uint2 uu = *(const uint2*)(u + tok * 512 + g * 16 + pp);
;       const float4 dd = *(const float4*)(p.ssm_d + g * 16 + pp);
;       store_bf4(yg + tok * 512 + g * 16 + pp, gelu_tanh(a + dd.x * bf_lo(uu.x)), gelu_tanh(b + dd.y * bf_hi(uu.x)),
;                 gelu_tanh(c + dd.z * bf_lo(uu.y)), gelu_tanh(d + dd.w * bf_hi(uu.y)));
;     });
	v_mul_f32_e32 v103, v99, v103
	v_fma_f32 v102, v98, v102, v98
	v_fma_f32 v103, v99, v103, v99
	v_mul_f32_e32 v102, 0x3f4c422a, v102
	v_mul_f32_e32 v103, 0x3f4c422a, v103
	v_add_f32_e32 v102, v102, v102
	v_add_f32_e32 v103, v103, v103
	v_mul_f32_e32 v102, 0x3fb8aa3b, v102
	v_mul_f32_e32 v103, 0x3fb8aa3b, v103
	v_exp_f32_e32 v102, v102
	v_exp_f32_e32 v103, v103
	v_pk_add_f32 v[106:107], v[106:107], 1.0 op_sel_hi:[1, 0]
	v_pk_mul_f32 v[98:99], v[98:99], 0.5 op_sel_hi:[1, 0]
	v_pk_mul_f32 v[96:97], v[96:97], v[106:107]
	v_pk_add_f32 v[102:103], v[102:103], 1.0 op_sel_hi:[1, 0]
	v_cvt_pk_bf16_f32 v96, v96, v97
	v_div_scale_f32 v106, s[0:1], v103, v103, 2.0
	v_rcp_f32_e32 v107, v106
	s_nop 0
	v_fma_f32 v108, -v106, v107, 1.0
	v_fmac_f32_e32 v107, v108, v107
	v_div_scale_f32 v108, vcc, 2.0, v103, 2.0
	v_mul_f32_e32 v109, v108, v107
	v_fma_f32 v110, -v106, v109, v108
	v_fmac_f32_e32 v109, v110, v107
	v_fma_f32 v106, -v106, v109, v108
	v_div_fmas_f32 v106, v106, v107, v109
	v_div_fixup_f32 v103, v106, v103, 2.0
	v_div_scale_f32 v106, s[0:1], v102, v102, 2.0
	v_rcp_f32_e32 v107, v106
	s_nop 0
	v_fma_f32 v108, -v106, v107, 1.0
	v_fmac_f32_e32 v107, v108, v107
	v_div_scale_f32 v108, vcc, 2.0, v102, 2.0
	v_mul_f32_e32 v109, v108, v107
	v_fma_f32 v110, -v106, v109, v108
	v_fmac_f32_e32 v109, v110, v107
	v_fma_f32 v106, -v106, v109, v108
	v_div_fmas_f32 v106, v106, v107, v109
	v_div_fixup_f32 v102, v106, v102, 2.0
	v_pk_add_f32 v[102:103], v[102:103], 1.0 op_sel_hi:[1, 0] neg_lo:[1, 0] neg_hi:[1, 0]
	s_nop 0
	v_pk_add_f32 v[102:103], v[102:103], 1.0 op_sel_hi:[1, 0]
	s_nop 0
	v_pk_mul_f32 v[98:99], v[98:99], v[102:103]
	s_nop 0
	v_cvt_pk_bf16_f32 v97, v98, v99
	global_store_dwordx2 v[100:101], v[96:97], off
	v_or_b32_e32 v96, 0x200000, v152
	v_mov_b32_e32 v97, v153
	v_lshl_add_u64 v[98:99], v[130:131], 0, v[96:97]
	v_lshlrev_b64 v[98:99], 1, v[98:99]
	v_lshl_add_u64 v[100:101], s[36:37], 0, v[98:99]
	v_lshl_add_u64 v[100:101], v[100:101], 0, s[8:9]
	v_lshl_add_u64 v[100:101], v[100:101], 0, v[128:129]
	global_load_dwordx2 v[106:107], v[100:101], off
	global_load_dwordx4 v[184:187], v172, s[80:81]
	v_or_b32_e32 v177, 0x240000, v152
	v_mov_b32_e32 v178, v153
	v_mov_b32_e32 v182, v177
	v_mov_b32_e32 v183, v178
	v_lshl_add_u64 v[188:189], v[130:131], 0, v[182:183]
	v_lshlrev_b64 v[190:191], 1, v[188:189]
	v_lshl_add_u64 v[192:193], s[36:37], 0, v[190:191]
	v_lshl_add_u64 v[194:195], v[192:193], 0, s[8:9]
	v_lshl_add_u64 v[196:197], v[194:195], 0, v[128:129]
	global_load_dwordx2 v[198:199], v[196:197], off
	global_load_dwordx4 v[200:203], v172, s[80:81]
	v_lshl_add_u64 v[98:99], s[26:27], 0, v[98:99]
	v_lshl_add_u64 v[98:99], v[98:99], 0, s[8:9]
	v_lshl_add_u64 v[98:99], v[98:99], 0, v[128:129]
	s_waitcnt vmcnt(3)
	v_lshlrev_b32_e32 v108, 16, v106
	v_and_b32_e32 v109, 0xffff0000, v106
	s_waitcnt vmcnt(2)
	v_pk_fma_f32 v[92:93], v[184:185], v[108:109], v[92:93]
	s_nop 0
	v_mul_f32_e32 v100, 0x3d372713, v92
	v_mul_f32_e32 v101, 0x3d372713, v93
	v_mul_f32_e32 v100, v92, v100
	v_mul_f32_e32 v101, v93, v101
	v_fma_f32 v100, v92, v100, v92
	v_fma_f32 v101, v93, v101, v93
	v_mul_f32_e32 v100, 0x3f4c422a, v100
	v_mul_f32_e32 v101, 0x3f4c422a, v101
	v_add_f32_e32 v100, v100, v100
	v_add_f32_e32 v101, v101, v101
	v_mul_f32_e32 v100, 0x3fb8aa3b, v100
	v_mul_f32_e32 v101, 0x3fb8aa3b, v101
	v_exp_f32_e32 v100, v100
	v_exp_f32_e32 v101, v101
	v_pk_mul_f32 v[92:93], v[92:93], 0.5 op_sel_hi:[1, 0]
	v_pk_add_f32 v[100:101], v[100:101], 1.0 op_sel_hi:[1, 0]
	s_nop 0
	v_div_scale_f32 v106, s[0:1], v101, v101, 2.0
	v_rcp_f32_e32 v108, v106
	s_nop 0
	v_fma_f32 v109, -v106, v108, 1.0
	v_fmac_f32_e32 v108, v109, v108
	v_div_scale_f32 v109, vcc, 2.0, v101, 2.0
	v_mul_f32_e32 v110, v109, v108
	v_fma_f32 v111, -v106, v110, v109
	v_fmac_f32_e32 v110, v111, v108
	v_fma_f32 v106, -v106, v110, v109
	v_div_fmas_f32 v106, v106, v108, v110
	v_div_fixup_f32 v101, v106, v101, 2.0
	v_div_scale_f32 v106, s[0:1], v100, v100, 2.0
	v_rcp_f32_e32 v108, v106
	s_nop 0
	v_fma_f32 v109, -v106, v108, 1.0
	v_fmac_f32_e32 v108, v109, v108
	v_div_scale_f32 v109, vcc, 2.0, v100, 2.0
	v_mul_f32_e32 v110, v109, v108
	v_fma_f32 v111, -v106, v110, v109
	v_fmac_f32_e32 v110, v111, v108
	v_fma_f32 v106, -v106, v110, v109
	v_div_fmas_f32 v106, v106, v108, v110
	v_div_fixup_f32 v100, v106, v100, 2.0
	v_pk_add_f32 v[100:101], v[100:101], 1.0 op_sel_hi:[1, 0] neg_lo:[1, 0] neg_hi:[1, 0]
	s_nop 0
	v_pk_add_f32 v[100:101], v[100:101], 1.0 op_sel_hi:[1, 0]
	s_nop 0
	v_pk_mul_f32 v[92:93], v[92:93], v[100:101]
	v_lshlrev_b32_e32 v100, 16, v107
	v_and_b32_e32 v101, 0xffff0000, v107
	v_pk_fma_f32 v[94:95], v[186:187], v[100:101], v[94:95]
	v_cvt_pk_bf16_f32 v92, v92, v93
	v_mul_f32_e32 v100, 0x3d372713, v94
	v_mul_f32_e32 v101, 0x3d372713, v95
	v_mul_f32_e32 v100, v94, v100
	v_mul_f32_e32 v101, v95, v101
	v_fma_f32 v100, v94, v100, v94
	v_fma_f32 v101, v95, v101, v95
	v_mul_f32_e32 v100, 0x3f4c422a, v100
	v_mul_f32_e32 v101, 0x3f4c422a, v101
	v_add_f32_e32 v100, v100, v100
	v_add_f32_e32 v101, v101, v101
	v_mul_f32_e32 v100, 0x3fb8aa3b, v100
	v_mul_f32_e32 v101, 0x3fb8aa3b, v101
	v_exp_f32_e32 v100, v100
	v_exp_f32_e32 v101, v101
	v_pk_mul_f32 v[94:95], v[94:95], 0.5 op_sel_hi:[1, 0]
	v_pk_add_f32 v[100:101], v[100:101], 1.0 op_sel_hi:[1, 0]
	s_nop 0
	v_div_scale_f32 v102, s[0:1], v101, v101, 2.0
	v_rcp_f32_e32 v103, v102
	s_nop 0
	v_fma_f32 v106, -v102, v103, 1.0
	v_fmac_f32_e32 v103, v106, v103
	v_div_scale_f32 v106, vcc, 2.0, v101, 2.0
	v_mul_f32_e32 v107, v106, v103
	v_fma_f32 v108, -v102, v107, v106
	v_fmac_f32_e32 v107, v108, v103
	v_fma_f32 v102, -v102, v107, v106
	v_div_fmas_f32 v102, v102, v103, v107
	v_div_fixup_f32 v101, v102, v101, 2.0
	v_div_scale_f32 v102, s[0:1], v100, v100, 2.0
	v_rcp_f32_e32 v103, v102
	s_nop 0
	v_fma_f32 v106, -v102, v103, 1.0
	v_fmac_f32_e32 v103, v106, v103
	v_div_scale_f32 v106, vcc, 2.0, v100, 2.0
	v_mul_f32_e32 v107, v106, v103
	v_fma_f32 v108, -v102, v107, v106
	v_fmac_f32_e32 v107, v108, v103
	v_fma_f32 v102, -v102, v107, v106
	v_div_fmas_f32 v102, v102, v103, v107
	v_div_fixup_f32 v100, v102, v100, 2.0
	v_pk_add_f32 v[100:101], v[100:101], 1.0 op_sel_hi:[1, 0] neg_lo:[1, 0] neg_hi:[1, 0]
	s_nop 0
	v_pk_add_f32 v[100:101], v[100:101], 1.0 op_sel_hi:[1, 0]
	s_nop 0
	v_pk_mul_f32 v[94:95], v[94:95], v[100:101]
	s_nop 0
	v_cvt_pk_bf16_f32 v93, v94, v95
	global_store_dwordx2 v[98:99], v[92:93], off
	v_lshl_add_u64 v[94:95], s[26:27], 0, v[190:191]
	v_lshl_add_u64 v[94:95], v[94:95], 0, s[8:9]
	v_lshl_add_u64 v[94:95], v[94:95], 0, v[128:129]
	s_waitcnt vmcnt(2)
; DI float bf_lo(unsigned u) { return __uint_as_float(u << 16); }
; DI float bf_hi(unsigned u) { return __uint_as_float(u & 0xffff0000u); }
; DI float fast_exp(float x) { return __builtin_amdgcn_exp2f(x * 1.44269504089f); }
; DI float gelu_tanh(float y) {
;   const float z = 0.7978845608028654f * (y + 0.044715f * y * y * y);
;   const float e = fast_exp(2.0f * z);
;   const float th = 1.0f - 2.0f / (e + 1.0f);
;   return 0.5f * y * (1.0f + th);
; }
; DI void phase_ssm_out(const Params& p, char* lds) {
;     ...
;     epi8_iter(acc, [&](int t, int n, float a, float b, float c, float d) {
;       const int nn = nt * 256 + n, tt = nn >> 4, pp = nn & 15;
;       const size_t tok = (size_t)(ct * 256 + t) * 32 + tt;
;       const uint2 uu = *(const uint2*)(u + tok * 512 + g * 16 + pp);
;       const float4 dd = *(const float4*)(p.ssm_d + g * 16 + pp);
;       store_bf4(yg + tok * 512 + g * 16 + pp, gelu_tanh(a + dd.x * bf_lo(uu.x)), gelu_tanh(b + dd.y * bf_hi(uu.x)),
;                 gelu_tanh(c + dd.z * bf_lo(uu.y)), gelu_tanh(d + dd.w * bf_hi(uu.y)));
;     });
	v_lshlrev_b32_e32 v106, 16, v198
	v_and_b32_e32 v107, 0xffff0000, v198
	s_waitcnt vmcnt(1)
	v_pk_fma_f32 v[88:89], v[200:201], v[106:107], v[88:89]
	s_nop 0
	v_mul_f32_e32 v98, 0x3d372713, v88
	v_mul_f32_e32 v99, 0x3d372713, v89
	v_mul_f32_e32 v98, v88, v98
	v_mul_f32_e32 v99, v89, v99
	v_fma_f32 v98, v88, v98, v88
	v_fma_f32 v99, v89, v99, v89
	v_mul_f32_e32 v98, 0x3f4c422a, v98
	v_mul_f32_e32 v99, 0x3f4c422a, v99
	v_add_f32_e32 v98, v98, v98
	v_add_f32_e32 v99, v99, v99
	v_mul_f32_e32 v98, 0x3fb8aa3b, v98
	v_mul_f32_e32 v99, 0x3fb8aa3b, v99
	v_exp_f32_e32 v98, v98
	v_exp_f32_e32 v99, v99
	v_pk_mul_f32 v[88:89], v[88:89], 0.5 op_sel_hi:[1, 0]
	v_pk_add_f32 v[98:99], v[98:99], 1.0 op_sel_hi:[1, 0]
	s_nop 0
	v_div_scale_f32 v102, s[0:1], v99, v99, 2.0
	v_rcp_f32_e32 v106, v102
	s_nop 0
	v_fma_f32 v107, -v102, v106, 1.0
	v_fmac_f32_e32 v106, v107, v106
	v_div_scale_f32 v107, vcc, 2.0, v99, 2.0
	v_mul_f32_e32 v108, v107, v106
	v_fma_f32 v109, -v102, v108, v107
	v_fmac_f32_e32 v108, v109, v106
	v_fma_f32 v102, -v102, v108, v107
	v_div_fmas_f32 v102, v102, v106, v108
	v_div_fixup_f32 v99, v102, v99, 2.0
	v_div_scale_f32 v102, s[0:1], v98, v98, 2.0
	v_rcp_f32_e32 v106, v102
	s_nop 0
	v_fma_f32 v107, -v102, v106, 1.0
	v_fmac_f32_e32 v106, v107, v106
	v_div_scale_f32 v107, vcc, 2.0, v98, 2.0
	v_mul_f32_e32 v108, v107, v106
	v_fma_f32 v109, -v102, v108, v107
	v_fmac_f32_e32 v108, v109, v106
	v_fma_f32 v102, -v102, v108, v107
	v_div_fmas_f32 v102, v102, v106, v108
	v_div_fixup_f32 v98, v102, v98, 2.0
	v_pk_add_f32 v[98:99], v[98:99], 1.0 op_sel_hi:[1, 0] neg_lo:[1, 0] neg_hi:[1, 0]
	s_nop 0
	v_pk_add_f32 v[98:99], v[98:99], 1.0 op_sel_hi:[1, 0]
	s_nop 0
	v_pk_mul_f32 v[88:89], v[88:89], v[98:99]
	v_lshlrev_b32_e32 v98, 16, v199
	v_and_b32_e32 v99, 0xffff0000, v199
	v_pk_fma_f32 v[90:91], v[202:203], v[98:99], v[90:91]
	v_cvt_pk_bf16_f32 v88, v88, v89
	v_mul_f32_e32 v98, 0x3d372713, v90
	v_mul_f32_e32 v99, 0x3d372713, v91
	v_mul_f32_e32 v98, v90, v98
	v_mul_f32_e32 v99, v91, v99
	v_fma_f32 v98, v90, v98, v90
	v_fma_f32 v99, v91, v99, v91
	v_mul_f32_e32 v98, 0x3f4c422a, v98
	v_mul_f32_e32 v99, 0x3f4c422a, v99
	v_add_f32_e32 v98, v98, v98
	v_add_f32_e32 v99, v99, v99
	v_mul_f32_e32 v98, 0x3fb8aa3b, v98
	v_mul_f32_e32 v99, 0x3fb8aa3b, v99
	v_exp_f32_e32 v98, v98
	v_exp_f32_e32 v99, v99
	v_pk_mul_f32 v[90:91], v[90:91], 0.5 op_sel_hi:[1, 0]
	v_pk_add_f32 v[98:99], v[98:99], 1.0 op_sel_hi:[1, 0]
	s_nop 0
	v_div_scale_f32 v100, s[0:1], v99, v99, 2.0
	v_rcp_f32_e32 v101, v100
	s_nop 0
	v_fma_f32 v102, -v100, v101, 1.0
	v_fmac_f32_e32 v101, v102, v101
	v_div_scale_f32 v102, vcc, 2.0, v99, 2.0
	v_mul_f32_e32 v103, v102, v101
	v_fma_f32 v106, -v100, v103, v102
	v_fmac_f32_e32 v103, v106, v101
	v_fma_f32 v100, -v100, v103, v102
	v_div_fmas_f32 v100, v100, v101, v103
	v_div_fixup_f32 v99, v100, v99, 2.0
	v_div_scale_f32 v100, s[0:1], v98, v98, 2.0
	v_rcp_f32_e32 v101, v100
	s_nop 0
	v_fma_f32 v102, -v100, v101, 1.0
	v_fmac_f32_e32 v101, v102, v101
	v_div_scale_f32 v102, vcc, 2.0, v98, 2.0
	v_mul_f32_e32 v103, v102, v101
	v_fma_f32 v106, -v100, v103, v102
	v_fmac_f32_e32 v103, v106, v101
	v_fma_f32 v100, -v100, v103, v102
	v_div_fmas_f32 v100, v100, v101, v103
	v_div_fixup_f32 v98, v100, v98, 2.0
	v_pk_add_f32 v[98:99], v[98:99], 1.0 op_sel_hi:[1, 0] neg_lo:[1, 0] neg_hi:[1, 0]
	s_nop 0
	v_pk_add_f32 v[98:99], v[98:99], 1.0 op_sel_hi:[1, 0]
	s_nop 0
	v_pk_mul_f32 v[90:91], v[90:91], v[98:99]
	s_nop 0
	v_cvt_pk_bf16_f32 v89, v90, v91
	global_store_dwordx2 v[94:95], v[88:89], off
	v_lshl_add_u64 v[88:89], v[120:121], 0, v[96:97]
	v_lshlrev_b64 v[88:89], 1, v[88:89]
	v_lshl_add_u64 v[90:91], s[36:37], 0, v[88:89]
	v_lshl_add_u64 v[90:91], v[90:91], 0, s[8:9]
	v_lshl_add_u64 v[90:91], v[90:91], 0, v[128:129]
	global_load_dwordx2 v[90:91], v[90:91], off
	global_load_dwordx4 v[212:215], v172, s[80:81]
	v_mov_b32_e32 v216, v177
	v_mov_b32_e32 v217, v178
	v_lshl_add_u64 v[218:219], v[120:121], 0, v[216:217]
	v_lshlrev_b64 v[220:221], 1, v[218:219]
	v_lshl_add_u64 v[224:225], s[36:37], 0, v[220:221]
	v_lshl_add_u64 v[226:227], v[224:225], 0, s[8:9]
	v_lshl_add_u64 v[228:229], v[226:227], 0, v[128:129]
	global_load_dwordx2 v[230:231], v[228:229], off
	global_load_dwordx4 v[244:247], v172, s[80:81]
	v_lshl_add_u64 v[88:89], s[26:27], 0, v[88:89]
	v_lshl_add_u64 v[88:89], v[88:89], 0, s[8:9]
	v_lshl_add_u64 v[88:89], v[88:89], 0, v[128:129]
	s_waitcnt vmcnt(3)
	v_lshlrev_b32_e32 v94, 16, v90
	v_and_b32_e32 v95, 0xffff0000, v90
	s_waitcnt vmcnt(2)
; DI float bf_lo(unsigned u) { return __uint_as_float(u << 16); }
; DI float bf_hi(unsigned u) { return __uint_as_float(u & 0xffff0000u); }
; DI float fast_exp(float x) { return __builtin_amdgcn_exp2f(x * 1.44269504089f); }
; DI float gelu_tanh(float y) {
;   const float z = 0.7978845608028654f * (y + 0.044715f * y * y * y);
;   const float e = fast_exp(2.0f * z);
;   const float th = 1.0f - 2.0f / (e + 1.0f);
;   return 0.5f * y * (1.0f + th);
; }
; DI void phase_ssm_out(const Params& p, char* lds) {
;     ...
;     epi8_iter(acc, [&](int t, int n, float a, float b, float c, float d) {
;       const int nn = nt * 256 + n, tt = nn >> 4, pp = nn & 15;
;       const size_t tok = (size_t)(ct * 256 + t) * 32 + tt;
;       const uint2 uu = *(const uint2*)(u + tok * 512 + g * 16 + pp);
;       const float4 dd = *(const float4*)(p.ssm_d + g * 16 + pp);
;       store_bf4(yg + tok * 512 + g * 16 + pp, gelu_tanh(a + dd.x * bf_lo(uu.x)), gelu_tanh(b + dd.y * bf_hi(uu.x)),
;                 gelu_tanh(c + dd.z * bf_lo(uu.y)), gelu_tanh(d + dd.w * bf_hi(uu.y)));
	v_pk_fma_f32 v[84:85], v[212:213], v[94:95], v[84:85]
	s_nop 0
	v_mul_f32_e32 v90, 0x3d372713, v84
	v_mul_f32_e32 v90, v84, v90
	v_fma_f32 v90, v84, v90, v84
	v_mul_f32_e32 v90, 0x3f4c422a, v90
	v_add_f32_e32 v90, v90, v90
	v_mul_f32_e32 v90, 0x3fb8aa3b, v90
	v_exp_f32_e32 v94, v90
	v_mul_f32_e32 v90, 0x3d372713, v85
	v_mul_f32_e32 v90, v85, v90
	v_fma_f32 v90, v85, v90, v85
	v_mul_f32_e32 v90, 0x3f4c422a, v90
	v_add_f32_e32 v90, v90, v90
	v_mul_f32_e32 v90, 0x3fb8aa3b, v90
	v_exp_f32_e32 v95, v90
	v_pk_mul_f32 v[84:85], v[84:85], 0.5 op_sel_hi:[1, 0]
	v_pk_add_f32 v[94:95], v[94:95], 1.0 op_sel_hi:[1, 0]
	s_nop 0
	v_div_scale_f32 v90, s[0:1], v95, v95, 2.0
	v_rcp_f32_e32 v98, v90
	s_nop 0
	v_fma_f32 v99, -v90, v98, 1.0
	v_fmac_f32_e32 v98, v99, v98
	v_div_scale_f32 v99, vcc, 2.0, v95, 2.0
	v_mul_f32_e32 v102, v99, v98
	v_fma_f32 v103, -v90, v102, v99
	v_fmac_f32_e32 v102, v103, v98
	v_fma_f32 v90, -v90, v102, v99
	v_div_fmas_f32 v90, v90, v98, v102
	v_div_fixup_f32 v95, v90, v95, 2.0
	v_div_scale_f32 v90, s[0:1], v94, v94, 2.0
	v_rcp_f32_e32 v98, v90
	s_nop 0
	v_fma_f32 v99, -v90, v98, 1.0
	v_fmac_f32_e32 v98, v99, v98
	v_div_scale_f32 v99, vcc, 2.0, v94, 2.0
	v_mul_f32_e32 v102, v99, v98
	v_fma_f32 v103, -v90, v102, v99
	v_fmac_f32_e32 v102, v103, v98
	v_fma_f32 v90, -v90, v102, v99
	v_div_fmas_f32 v90, v90, v98, v102
	v_div_fixup_f32 v94, v90, v94, 2.0
	v_lshlrev_b32_e32 v90, 16, v91
	v_and_b32_e32 v91, 0xffff0000, v91
	v_pk_fma_f32 v[86:87], v[214:215], v[90:91], v[86:87]
	v_pk_add_f32 v[94:95], v[94:95], 1.0 op_sel_hi:[1, 0] neg_lo:[1, 0] neg_hi:[1, 0]
	v_mul_f32_e32 v90, 0x3d372713, v86
	v_mul_f32_e32 v91, 0x3d372713, v87
	v_mul_f32_e32 v90, v86, v90
	v_mul_f32_e32 v91, v87, v91
	v_fma_f32 v90, v86, v90, v86
	v_fma_f32 v91, v87, v91, v87
	v_mul_f32_e32 v90, 0x3f4c422a, v90
	v_mul_f32_e32 v91, 0x3f4c422a, v91
	v_add_f32_e32 v90, v90, v90
	v_add_f32_e32 v91, v91, v91
	v_mul_f32_e32 v90, 0x3fb8aa3b, v90
	v_mul_f32_e32 v91, 0x3fb8aa3b, v91
	v_exp_f32_e32 v90, v90
	v_exp_f32_e32 v91, v91
	v_pk_add_f32 v[94:95], v[94:95], 1.0 op_sel_hi:[1, 0]
	v_pk_mul_f32 v[86:87], v[86:87], 0.5 op_sel_hi:[1, 0]
	v_pk_mul_f32 v[84:85], v[84:85], v[94:95]
	v_pk_add_f32 v[90:91], v[90:91], 1.0 op_sel_hi:[1, 0]
	v_cvt_pk_bf16_f32 v84, v84, v85
	v_div_scale_f32 v94, s[0:1], v91, v91, 2.0
	v_rcp_f32_e32 v95, v94
	s_nop 0
	v_fma_f32 v98, -v94, v95, 1.0
	v_fmac_f32_e32 v95, v98, v95
	v_div_scale_f32 v98, vcc, 2.0, v91, 2.0
	v_mul_f32_e32 v99, v98, v95
	v_fma_f32 v100, -v94, v99, v98
	v_fmac_f32_e32 v99, v100, v95
	v_fma_f32 v94, -v94, v99, v98
	v_div_fmas_f32 v94, v94, v95, v99
	v_div_fixup_f32 v91, v94, v91, 2.0
	v_div_scale_f32 v94, s[0:1], v90, v90, 2.0
	v_rcp_f32_e32 v95, v94
	s_nop 0
	v_fma_f32 v98, -v94, v95, 1.0
	v_fmac_f32_e32 v95, v98, v95
	v_div_scale_f32 v98, vcc, 2.0, v90, 2.0
	v_mul_f32_e32 v99, v98, v95
	v_fma_f32 v100, -v94, v99, v98
	v_fmac_f32_e32 v99, v100, v95
	v_fma_f32 v94, -v94, v99, v98
	v_div_fmas_f32 v94, v94, v95, v99
	v_div_fixup_f32 v90, v94, v90, 2.0
	v_pk_add_f32 v[90:91], v[90:91], 1.0 op_sel_hi:[1, 0] neg_lo:[1, 0] neg_hi:[1, 0]
	s_nop 0
	v_pk_add_f32 v[90:91], v[90:91], 1.0 op_sel_hi:[1, 0]
	s_nop 0
	v_pk_mul_f32 v[86:87], v[86:87], v[90:91]
	s_nop 0
	v_cvt_pk_bf16_f32 v85, v86, v87
	global_store_dwordx2 v[88:89], v[84:85], off
	v_lshl_add_u64 v[84:85], s[26:27], 0, v[220:221]
	v_lshl_add_u64 v[84:85], v[84:85], 0, s[8:9]
	v_lshl_add_u64 v[84:85], v[84:85], 0, v[128:129]
	s_waitcnt vmcnt(2)
	v_lshlrev_b32_e32 v94, 16, v230
	v_and_b32_e32 v95, 0xffff0000, v230
	s_waitcnt vmcnt(1)
	v_pk_fma_f32 v[80:81], v[244:245], v[94:95], v[80:81]
	s_nop 0
	v_mul_f32_e32 v86, 0x3d372713, v80
	v_mul_f32_e32 v87, 0x3d372713, v81
	v_mul_f32_e32 v86, v80, v86
	v_mul_f32_e32 v87, v81, v87
	v_fma_f32 v86, v80, v86, v80
	v_fma_f32 v87, v81, v87, v81
	v_mul_f32_e32 v86, 0x3f4c422a, v86
	v_mul_f32_e32 v87, 0x3f4c422a, v87
	v_add_f32_e32 v86, v86, v86
	v_add_f32_e32 v87, v87, v87
	v_mul_f32_e32 v86, 0x3fb8aa3b, v86
	v_mul_f32_e32 v87, 0x3fb8aa3b, v87
	v_exp_f32_e32 v86, v86
	v_exp_f32_e32 v87, v87
	v_pk_mul_f32 v[80:81], v[80:81], 0.5 op_sel_hi:[1, 0]
	v_pk_add_f32 v[86:87], v[86:87], 1.0 op_sel_hi:[1, 0]
	s_nop 0
	v_div_scale_f32 v90, s[0:1], v87, v87, 2.0
	v_rcp_f32_e32 v94, v90
	s_nop 0
	v_fma_f32 v95, -v90, v94, 1.0
	v_fmac_f32_e32 v94, v95, v94
	v_div_scale_f32 v95, vcc, 2.0, v87, 2.0
	v_mul_f32_e32 v98, v95, v94
	v_fma_f32 v99, -v90, v98, v95
	v_fmac_f32_e32 v98, v99, v94
	v_fma_f32 v90, -v90, v98, v95
	v_div_fmas_f32 v90, v90, v94, v98
	v_div_fixup_f32 v87, v90, v87, 2.0
	v_div_scale_f32 v90, s[0:1], v86, v86, 2.0
	v_rcp_f32_e32 v94, v90
	s_nop 0
	v_fma_f32 v95, -v90, v94, 1.0
	v_fmac_f32_e32 v94, v95, v94
	v_div_scale_f32 v95, vcc, 2.0, v86, 2.0
	v_mul_f32_e32 v98, v95, v94
	v_fma_f32 v99, -v90, v98, v95
	v_fmac_f32_e32 v98, v99, v94
	v_fma_f32 v90, -v90, v98, v95
	v_div_fmas_f32 v90, v90, v94, v98
	v_div_fixup_f32 v86, v90, v86, 2.0
	v_pk_add_f32 v[86:87], v[86:87], 1.0 op_sel_hi:[1, 0] neg_lo:[1, 0] neg_hi:[1, 0]
	s_nop 0
	v_pk_add_f32 v[86:87], v[86:87], 1.0 op_sel_hi:[1, 0]
	s_nop 0
	v_pk_mul_f32 v[80:81], v[80:81], v[86:87]
	v_lshlrev_b32_e32 v86, 16, v231
	v_and_b32_e32 v87, 0xffff0000, v231
	v_pk_fma_f32 v[82:83], v[246:247], v[86:87], v[82:83]
	v_cvt_pk_bf16_f32 v80, v80, v81
	v_mul_f32_e32 v86, 0x3d372713, v82
	v_mul_f32_e32 v87, 0x3d372713, v83
	v_mul_f32_e32 v86, v82, v86
	v_mul_f32_e32 v87, v83, v87
	v_fma_f32 v86, v82, v86, v82
	v_fma_f32 v87, v83, v87, v83
	v_mul_f32_e32 v86, 0x3f4c422a, v86
	v_mul_f32_e32 v87, 0x3f4c422a, v87
	v_add_f32_e32 v86, v86, v86
	v_add_f32_e32 v87, v87, v87
	v_mul_f32_e32 v86, 0x3fb8aa3b, v86
; DI float bf_lo(unsigned u) { return __uint_as_float(u << 16); }
; DI float bf_hi(unsigned u) { return __uint_as_float(u & 0xffff0000u); }
; DI float fast_exp(float x) { return __builtin_amdgcn_exp2f(x * 1.44269504089f); }
; DI float gelu_tanh(float y) {
;   const float z = 0.7978845608028654f * (y + 0.044715f * y * y * y);
;   const float e = fast_exp(2.0f * z);
;   const float th = 1.0f - 2.0f / (e + 1.0f);
;   return 0.5f * y * (1.0f + th);
; }
; DI void phase_ssm_out(const Params& p, char* lds) {
;     ...
;     epi8_iter(acc, [&](int t, int n, float a, float b, float c, float d) {
;       const int nn = nt * 256 + n, tt = nn >> 4, pp = nn & 15;
;       const size_t tok = (size_t)(ct * 256 + t) * 32 + tt;
;       const uint2 uu = *(const uint2*)(u + tok * 512 + g * 16 + pp);
;       const float4 dd = *(const float4*)(p.ssm_d + g * 16 + pp);
;       store_bf4(yg + tok * 512 + g * 16 + pp, gelu_tanh(a + dd.x * bf_lo(uu.x)), gelu_tanh(b + dd.y * bf_hi(uu.x)),
;                 gelu_tanh(c + dd.z * bf_lo(uu.y)), gelu_tanh(d + dd.w * bf_hi(uu.y)));
	v_mul_f32_e32 v87, 0x3fb8aa3b, v87
	v_exp_f32_e32 v86, v86
	v_exp_f32_e32 v87, v87
	v_pk_mul_f32 v[82:83], v[82:83], 0.5 op_sel_hi:[1, 0]
	v_pk_add_f32 v[86:87], v[86:87], 1.0 op_sel_hi:[1, 0]
	s_nop 0
	v_div_scale_f32 v88, s[0:1], v87, v87, 2.0
	v_rcp_f32_e32 v89, v88
	s_nop 0
	v_fma_f32 v90, -v88, v89, 1.0
	v_fmac_f32_e32 v89, v90, v89
	v_div_scale_f32 v90, vcc, 2.0, v87, 2.0
	v_mul_f32_e32 v91, v90, v89
	v_fma_f32 v94, -v88, v91, v90
	v_fmac_f32_e32 v91, v94, v89
	v_fma_f32 v88, -v88, v91, v90
	v_div_fmas_f32 v88, v88, v89, v91
	v_div_fixup_f32 v87, v88, v87, 2.0
	v_div_scale_f32 v88, s[0:1], v86, v86, 2.0
	v_rcp_f32_e32 v89, v88
	s_nop 0
	v_fma_f32 v90, -v88, v89, 1.0
	v_fmac_f32_e32 v89, v90, v89
	v_div_scale_f32 v90, vcc, 2.0, v86, 2.0
	v_mul_f32_e32 v91, v90, v89
	v_fma_f32 v94, -v88, v91, v90
	v_fmac_f32_e32 v91, v94, v89
	v_fma_f32 v88, -v88, v91, v90
	v_div_fmas_f32 v88, v88, v89, v91
	v_div_fixup_f32 v86, v88, v86, 2.0
	v_pk_add_f32 v[86:87], v[86:87], 1.0 op_sel_hi:[1, 0] neg_lo:[1, 0] neg_hi:[1, 0]
	s_nop 0
	v_pk_add_f32 v[86:87], v[86:87], 1.0 op_sel_hi:[1, 0]
	s_nop 0
	v_pk_mul_f32 v[82:83], v[82:83], v[86:87]
	s_nop 0
	v_cvt_pk_bf16_f32 v81, v82, v83
	global_store_dwordx2 v[84:85], v[80:81], off
	v_lshl_add_u64 v[80:81], v[112:113], 0, v[96:97]
	v_lshlrev_b64 v[80:81], 1, v[80:81]
	v_lshl_add_u64 v[82:83], s[36:37], 0, v[80:81]
	v_lshl_add_u64 v[82:83], v[82:83], 0, s[8:9]
	v_lshl_add_u64 v[82:83], v[82:83], 0, v[128:129]
	global_load_dwordx2 v[86:87], v[82:83], off
	global_load_dwordx4 v[184:187], v172, s[80:81]
	v_mov_b32_e32 v182, v177
	v_mov_b32_e32 v183, v178
	v_lshl_add_u64 v[188:189], v[112:113], 0, v[182:183]
	v_lshlrev_b64 v[190:191], 1, v[188:189]
	v_lshl_add_u64 v[192:193], s[36:37], 0, v[190:191]
	v_lshl_add_u64 v[194:195], v[192:193], 0, s[8:9]
	v_lshl_add_u64 v[196:197], v[194:195], 0, v[128:129]
	global_load_dwordx2 v[198:199], v[196:197], off
	global_load_dwordx4 v[200:203], v172, s[80:81]
	v_lshl_add_u64 v[80:81], s[26:27], 0, v[80:81]
	v_lshl_add_u64 v[80:81], v[80:81], 0, s[8:9]
	v_lshl_add_u64 v[80:81], v[80:81], 0, v[128:129]
	s_waitcnt vmcnt(3)
	v_lshlrev_b32_e32 v88, 16, v86
	v_and_b32_e32 v89, 0xffff0000, v86
	s_waitcnt vmcnt(2)
	v_pk_fma_f32 v[76:77], v[184:185], v[88:89], v[76:77]
	s_nop 0
	v_mul_f32_e32 v82, 0x3d372713, v76
	v_mul_f32_e32 v83, 0x3d372713, v77
	v_mul_f32_e32 v82, v76, v82
	v_mul_f32_e32 v83, v77, v83
	v_fma_f32 v82, v76, v82, v76
	v_fma_f32 v83, v77, v83, v77
	v_mul_f32_e32 v82, 0x3f4c422a, v82
	v_mul_f32_e32 v83, 0x3f4c422a, v83
	v_add_f32_e32 v82, v82, v82
	v_add_f32_e32 v83, v83, v83
	v_mul_f32_e32 v82, 0x3fb8aa3b, v82
	v_mul_f32_e32 v83, 0x3fb8aa3b, v83
	v_exp_f32_e32 v82, v82
	v_exp_f32_e32 v83, v83
	v_pk_mul_f32 v[76:77], v[76:77], 0.5 op_sel_hi:[1, 0]
	v_pk_add_f32 v[82:83], v[82:83], 1.0 op_sel_hi:[1, 0]
	s_nop 0
	v_div_scale_f32 v86, s[0:1], v83, v83, 2.0
	v_rcp_f32_e32 v88, v86
	s_nop 0
	v_fma_f32 v89, -v86, v88, 1.0
	v_fmac_f32_e32 v88, v89, v88
	v_div_scale_f32 v89, vcc, 2.0, v83, 2.0
	v_mul_f32_e32 v90, v89, v88
	v_fma_f32 v91, -v86, v90, v89
	v_fmac_f32_e32 v90, v91, v88
	v_fma_f32 v86, -v86, v90, v89
	v_div_fmas_f32 v86, v86, v88, v90
	v_div_fixup_f32 v83, v86, v83, 2.0
	v_div_scale_f32 v86, s[0:1], v82, v82, 2.0
	v_rcp_f32_e32 v88, v86
	s_nop 0
	v_fma_f32 v89, -v86, v88, 1.0
	v_fmac_f32_e32 v88, v89, v88
	v_div_scale_f32 v89, vcc, 2.0, v82, 2.0
	v_mul_f32_e32 v90, v89, v88
	v_fma_f32 v91, -v86, v90, v89
	v_fmac_f32_e32 v90, v91, v88
	v_fma_f32 v86, -v86, v90, v89
	v_div_fmas_f32 v86, v86, v88, v90
	v_div_fixup_f32 v82, v86, v82, 2.0
	v_pk_add_f32 v[82:83], v[82:83], 1.0 op_sel_hi:[1, 0] neg_lo:[1, 0] neg_hi:[1, 0]
	s_nop 0
	v_pk_add_f32 v[82:83], v[82:83], 1.0 op_sel_hi:[1, 0]
	s_nop 0
	v_pk_mul_f32 v[76:77], v[76:77], v[82:83]
	v_lshlrev_b32_e32 v82, 16, v87
	v_and_b32_e32 v83, 0xffff0000, v87
	v_pk_fma_f32 v[78:79], v[186:187], v[82:83], v[78:79]
	v_cvt_pk_bf16_f32 v76, v76, v77
	v_mul_f32_e32 v82, 0x3d372713, v78
	v_mul_f32_e32 v83, 0x3d372713, v79
	v_mul_f32_e32 v82, v78, v82
	v_mul_f32_e32 v83, v79, v83
	v_fma_f32 v82, v78, v82, v78
	v_fma_f32 v83, v79, v83, v79
	v_mul_f32_e32 v82, 0x3f4c422a, v82
	v_mul_f32_e32 v83, 0x3f4c422a, v83
	v_add_f32_e32 v82, v82, v82
	v_add_f32_e32 v83, v83, v83
	v_mul_f32_e32 v82, 0x3fb8aa3b, v82
	v_mul_f32_e32 v83, 0x3fb8aa3b, v83
	v_exp_f32_e32 v82, v82
	v_exp_f32_e32 v83, v83
	v_pk_mul_f32 v[78:79], v[78:79], 0.5 op_sel_hi:[1, 0]
	v_pk_add_f32 v[82:83], v[82:83], 1.0 op_sel_hi:[1, 0]
	s_nop 0
	v_div_scale_f32 v84, s[0:1], v83, v83, 2.0
	v_rcp_f32_e32 v85, v84
	s_nop 0
	v_fma_f32 v86, -v84, v85, 1.0
	v_fmac_f32_e32 v85, v86, v85
	v_div_scale_f32 v86, vcc, 2.0, v83, 2.0
	v_mul_f32_e32 v87, v86, v85
	v_fma_f32 v88, -v84, v87, v86
	v_fmac_f32_e32 v87, v88, v85
	v_fma_f32 v84, -v84, v87, v86
	v_div_fmas_f32 v84, v84, v85, v87
	v_div_fixup_f32 v83, v84, v83, 2.0
	v_div_scale_f32 v84, s[0:1], v82, v82, 2.0
	v_rcp_f32_e32 v85, v84
	s_nop 0
	v_fma_f32 v86, -v84, v85, 1.0
	v_fmac_f32_e32 v85, v86, v85
	v_div_scale_f32 v86, vcc, 2.0, v82, 2.0
	v_mul_f32_e32 v87, v86, v85
	v_fma_f32 v88, -v84, v87, v86
	v_fmac_f32_e32 v87, v88, v85
	v_fma_f32 v84, -v84, v87, v86
	v_div_fmas_f32 v84, v84, v85, v87
	v_div_fixup_f32 v82, v84, v82, 2.0
	v_pk_add_f32 v[82:83], v[82:83], 1.0 op_sel_hi:[1, 0] neg_lo:[1, 0] neg_hi:[1, 0]
	s_nop 0
	v_pk_add_f32 v[82:83], v[82:83], 1.0 op_sel_hi:[1, 0]
	s_nop 0
	v_pk_mul_f32 v[78:79], v[78:79], v[82:83]
	s_nop 0
	v_cvt_pk_bf16_f32 v77, v78, v79
	global_store_dwordx2 v[80:81], v[76:77], off
	v_lshl_add_u64 v[76:77], s[26:27], 0, v[190:191]
	v_lshl_add_u64 v[76:77], v[76:77], 0, s[8:9]
	v_lshl_add_u64 v[76:77], v[76:77], 0, v[128:129]
	s_waitcnt vmcnt(2)
; DI float bf_lo(unsigned u) { return __uint_as_float(u << 16); }
; DI float bf_hi(unsigned u) { return __uint_as_float(u & 0xffff0000u); }
; DI float fast_exp(float x) { return __builtin_amdgcn_exp2f(x * 1.44269504089f); }
; DI float gelu_tanh(float y) {
;   const float z = 0.7978845608028654f * (y + 0.044715f * y * y * y);
;   const float e = fast_exp(2.0f * z);
;   const float th = 1.0f - 2.0f / (e + 1.0f);
;   return 0.5f * y * (1.0f + th);
; }
; DI void phase_ssm_out(const Params& p, char* lds) {
;     ...
;     epi8_iter(acc, [&](int t, int n, float a, float b, float c, float d) {
;       const int nn = nt * 256 + n, tt = nn >> 4, pp = nn & 15;
;       const size_t tok = (size_t)(ct * 256 + t) * 32 + tt;
;       const uint2 uu = *(const uint2*)(u + tok * 512 + g * 16 + pp);
;       const float4 dd = *(const float4*)(p.ssm_d + g * 16 + pp);
;       store_bf4(yg + tok * 512 + g * 16 + pp, gelu_tanh(a + dd.x * bf_lo(uu.x)), gelu_tanh(b + dd.y * bf_hi(uu.x)),
;                 gelu_tanh(c + dd.z * bf_lo(uu.y)), gelu_tanh(d + dd.w * bf_hi(uu.y)));
	v_lshlrev_b32_e32 v84, 16, v198
	v_and_b32_e32 v85, 0xffff0000, v198
	s_waitcnt vmcnt(1)
	v_pk_fma_f32 v[72:73], v[200:201], v[84:85], v[72:73]
	s_nop 0
	v_mul_f32_e32 v78, 0x3d372713, v72
	v_mul_f32_e32 v79, 0x3d372713, v73
	v_mul_f32_e32 v78, v72, v78
	v_mul_f32_e32 v79, v73, v79
	v_fma_f32 v78, v72, v78, v72
	v_fma_f32 v79, v73, v79, v73
	v_mul_f32_e32 v78, 0x3f4c422a, v78
	v_mul_f32_e32 v79, 0x3f4c422a, v79
	v_add_f32_e32 v78, v78, v78
	v_add_f32_e32 v79, v79, v79
	v_mul_f32_e32 v78, 0x3fb8aa3b, v78
	v_mul_f32_e32 v79, 0x3fb8aa3b, v79
	v_exp_f32_e32 v78, v78
	v_exp_f32_e32 v79, v79
	v_pk_mul_f32 v[72:73], v[72:73], 0.5 op_sel_hi:[1, 0]
	v_pk_add_f32 v[78:79], v[78:79], 1.0 op_sel_hi:[1, 0]
	s_nop 0
	v_div_scale_f32 v82, s[0:1], v79, v79, 2.0
	v_rcp_f32_e32 v84, v82
	s_nop 0
	v_fma_f32 v85, -v82, v84, 1.0
	v_fmac_f32_e32 v84, v85, v84
	v_div_scale_f32 v85, vcc, 2.0, v79, 2.0
	v_mul_f32_e32 v86, v85, v84
	v_fma_f32 v87, -v82, v86, v85
	v_fmac_f32_e32 v86, v87, v84
	v_fma_f32 v82, -v82, v86, v85
	v_div_fmas_f32 v82, v82, v84, v86
	v_div_fixup_f32 v79, v82, v79, 2.0
	v_div_scale_f32 v82, s[0:1], v78, v78, 2.0
	v_rcp_f32_e32 v84, v82
	s_nop 0
	v_fma_f32 v85, -v82, v84, 1.0
	v_fmac_f32_e32 v84, v85, v84
	v_div_scale_f32 v85, vcc, 2.0, v78, 2.0
	v_mul_f32_e32 v86, v85, v84
	v_fma_f32 v87, -v82, v86, v85
	v_fmac_f32_e32 v86, v87, v84
	v_fma_f32 v82, -v82, v86, v85
	v_div_fmas_f32 v82, v82, v84, v86
	v_div_fixup_f32 v78, v82, v78, 2.0
	v_pk_add_f32 v[78:79], v[78:79], 1.0 op_sel_hi:[1, 0] neg_lo:[1, 0] neg_hi:[1, 0]
	s_nop 0
	v_pk_add_f32 v[78:79], v[78:79], 1.0 op_sel_hi:[1, 0]
	s_nop 0
	v_pk_mul_f32 v[72:73], v[72:73], v[78:79]
	v_lshlrev_b32_e32 v78, 16, v199
	v_and_b32_e32 v79, 0xffff0000, v199
	v_pk_fma_f32 v[74:75], v[202:203], v[78:79], v[74:75]
	v_cvt_pk_bf16_f32 v72, v72, v73
	v_mul_f32_e32 v78, 0x3d372713, v74
	v_mul_f32_e32 v79, 0x3d372713, v75
	v_mul_f32_e32 v78, v74, v78
	v_mul_f32_e32 v79, v75, v79
	v_fma_f32 v78, v74, v78, v74
	v_fma_f32 v79, v75, v79, v75
	v_mul_f32_e32 v78, 0x3f4c422a, v78
	v_mul_f32_e32 v79, 0x3f4c422a, v79
	v_add_f32_e32 v78, v78, v78
	v_add_f32_e32 v79, v79, v79
	v_mul_f32_e32 v78, 0x3fb8aa3b, v78
	v_mul_f32_e32 v79, 0x3fb8aa3b, v79
	v_exp_f32_e32 v78, v78
	v_exp_f32_e32 v79, v79
	v_pk_mul_f32 v[74:75], v[74:75], 0.5 op_sel_hi:[1, 0]
	v_pk_add_f32 v[78:79], v[78:79], 1.0 op_sel_hi:[1, 0]
	s_nop 0
	v_div_scale_f32 v80, s[0:1], v79, v79, 2.0
	v_rcp_f32_e32 v81, v80
	s_nop 0
	v_fma_f32 v82, -v80, v81, 1.0
	v_fmac_f32_e32 v81, v82, v81
	v_div_scale_f32 v82, vcc, 2.0, v79, 2.0
	v_mul_f32_e32 v83, v82, v81
	v_fma_f32 v84, -v80, v83, v82
	v_fmac_f32_e32 v83, v84, v81
	v_fma_f32 v80, -v80, v83, v82
	v_div_fmas_f32 v80, v80, v81, v83
	v_div_fixup_f32 v79, v80, v79, 2.0
	v_div_scale_f32 v80, s[0:1], v78, v78, 2.0
	v_rcp_f32_e32 v81, v80
	s_nop 0
	v_fma_f32 v82, -v80, v81, 1.0
	v_fmac_f32_e32 v81, v82, v81
	v_div_scale_f32 v82, vcc, 2.0, v78, 2.0
	v_mul_f32_e32 v83, v82, v81
	v_fma_f32 v84, -v80, v83, v82
	v_fmac_f32_e32 v83, v84, v81
	v_fma_f32 v80, -v80, v83, v82
	v_div_fmas_f32 v80, v80, v81, v83
	v_div_fixup_f32 v78, v80, v78, 2.0
	v_pk_add_f32 v[78:79], v[78:79], 1.0 op_sel_hi:[1, 0] neg_lo:[1, 0] neg_hi:[1, 0]
	s_nop 0
	v_pk_add_f32 v[78:79], v[78:79], 1.0 op_sel_hi:[1, 0]
	s_nop 0
	v_pk_mul_f32 v[74:75], v[74:75], v[78:79]
	s_nop 0
	v_cvt_pk_bf16_f32 v73, v74, v75
	global_store_dwordx2 v[76:77], v[72:73], off
	v_lshl_add_u64 v[72:73], v[104:105], 0, v[96:97]
	v_lshlrev_b64 v[72:73], 1, v[72:73]
	v_lshl_add_u64 v[74:75], s[36:37], 0, v[72:73]
	v_lshl_add_u64 v[74:75], v[74:75], 0, s[8:9]
	v_lshl_add_u64 v[74:75], v[74:75], 0, v[128:129]
	global_load_dwordx2 v[78:79], v[74:75], off
	global_load_dwordx4 v[216:219], v172, s[80:81]
	v_mov_b32_e32 v212, v177
	v_mov_b32_e32 v213, v178
	v_lshl_add_u64 v[220:221], v[104:105], 0, v[212:213]
	v_lshlrev_b64 v[224:225], 1, v[220:221]
	v_lshl_add_u64 v[226:227], s[36:37], 0, v[224:225]
	v_lshl_add_u64 v[228:229], v[226:227], 0, s[8:9]
	v_lshl_add_u64 v[230:231], v[228:229], 0, v[128:129]
	global_load_dwordx2 v[236:237], v[230:231], off
	global_load_dwordx4 v[244:247], v172, s[80:81]
	v_lshl_add_u64 v[72:73], s[26:27], 0, v[72:73]
	v_lshl_add_u64 v[72:73], v[72:73], 0, s[8:9]
	v_lshl_add_u64 v[72:73], v[72:73], 0, v[128:129]
	s_waitcnt vmcnt(3)
	v_lshlrev_b32_e32 v80, 16, v78
	v_and_b32_e32 v81, 0xffff0000, v78
	s_waitcnt vmcnt(2)
; DI float bf_lo(unsigned u) { return __uint_as_float(u << 16); }
; DI float bf_hi(unsigned u) { return __uint_as_float(u & 0xffff0000u); }
; DI float fast_exp(float x) { return __builtin_amdgcn_exp2f(x * 1.44269504089f); }
; DI float gelu_tanh(float y) {
;   const float z = 0.7978845608028654f * (y + 0.044715f * y * y * y);
;   const float e = fast_exp(2.0f * z);
;   const float th = 1.0f - 2.0f / (e + 1.0f);
;   return 0.5f * y * (1.0f + th);
; }
; DI void phase_ssm_out(const Params& p, char* lds) {
;     ...
;     epi8_iter(acc, [&](int t, int n, float a, float b, float c, float d) {
;       const int nn = nt * 256 + n, tt = nn >> 4, pp = nn & 15;
;       const size_t tok = (size_t)(ct * 256 + t) * 32 + tt;
;       const uint2 uu = *(const uint2*)(u + tok * 512 + g * 16 + pp);
;       const float4 dd = *(const float4*)(p.ssm_d + g * 16 + pp);
;       store_bf4(yg + tok * 512 + g * 16 + pp, gelu_tanh(a + dd.x * bf_lo(uu.x)), gelu_tanh(b + dd.y * bf_hi(uu.x)),
;                 gelu_tanh(c + dd.z * bf_lo(uu.y)), gelu_tanh(d + dd.w * bf_hi(uu.y)));
	v_pk_fma_f32 v[68:69], v[216:217], v[80:81], v[68:69]
	s_nop 0
	v_mul_f32_e32 v74, 0x3d372713, v68
	v_mul_f32_e32 v75, 0x3d372713, v69
	v_mul_f32_e32 v74, v68, v74
	v_mul_f32_e32 v75, v69, v75
	v_fma_f32 v74, v68, v74, v68
	v_fma_f32 v75, v69, v75, v69
	v_mul_f32_e32 v74, 0x3f4c422a, v74
	v_mul_f32_e32 v75, 0x3f4c422a, v75
	v_add_f32_e32 v74, v74, v74
	v_add_f32_e32 v75, v75, v75
	v_mul_f32_e32 v74, 0x3fb8aa3b, v74
	v_mul_f32_e32 v75, 0x3fb8aa3b, v75
	v_exp_f32_e32 v74, v74
	v_exp_f32_e32 v75, v75
	v_pk_mul_f32 v[68:69], v[68:69], 0.5 op_sel_hi:[1, 0]
	v_pk_add_f32 v[74:75], v[74:75], 1.0 op_sel_hi:[1, 0]
	s_nop 0
	v_div_scale_f32 v78, s[0:1], v75, v75, 2.0
	v_rcp_f32_e32 v80, v78
	s_nop 0
	v_fma_f32 v81, -v78, v80, 1.0
	v_fmac_f32_e32 v80, v81, v80
	v_div_scale_f32 v81, vcc, 2.0, v75, 2.0
	v_mul_f32_e32 v82, v81, v80
	v_fma_f32 v83, -v78, v82, v81
	v_fmac_f32_e32 v82, v83, v80
	v_fma_f32 v78, -v78, v82, v81
	v_div_fmas_f32 v78, v78, v80, v82
	v_div_fixup_f32 v75, v78, v75, 2.0
	v_div_scale_f32 v78, s[0:1], v74, v74, 2.0
	v_rcp_f32_e32 v80, v78
	s_nop 0
	v_fma_f32 v81, -v78, v80, 1.0
	v_fmac_f32_e32 v80, v81, v80
	v_div_scale_f32 v81, vcc, 2.0, v74, 2.0
	v_mul_f32_e32 v82, v81, v80
	v_fma_f32 v83, -v78, v82, v81
	v_fmac_f32_e32 v82, v83, v80
	v_fma_f32 v78, -v78, v82, v81
	v_div_fmas_f32 v78, v78, v80, v82
	v_div_fixup_f32 v74, v78, v74, 2.0
	v_pk_add_f32 v[74:75], v[74:75], 1.0 op_sel_hi:[1, 0] neg_lo:[1, 0] neg_hi:[1, 0]
	s_nop 0
	v_pk_add_f32 v[74:75], v[74:75], 1.0 op_sel_hi:[1, 0]
	s_nop 0
	v_pk_mul_f32 v[68:69], v[68:69], v[74:75]
	v_lshlrev_b32_e32 v74, 16, v79
	v_and_b32_e32 v75, 0xffff0000, v79
	v_pk_fma_f32 v[70:71], v[218:219], v[74:75], v[70:71]
	v_cvt_pk_bf16_f32 v68, v68, v69
	v_mul_f32_e32 v74, 0x3d372713, v70
	v_mul_f32_e32 v75, 0x3d372713, v71
	v_mul_f32_e32 v74, v70, v74
	v_mul_f32_e32 v75, v71, v75
	v_fma_f32 v74, v70, v74, v70
	v_fma_f32 v75, v71, v75, v71
	v_mul_f32_e32 v74, 0x3f4c422a, v74
	v_mul_f32_e32 v75, 0x3f4c422a, v75
	v_add_f32_e32 v74, v74, v74
	v_add_f32_e32 v75, v75, v75
	v_mul_f32_e32 v74, 0x3fb8aa3b, v74
	v_mul_f32_e32 v75, 0x3fb8aa3b, v75
	v_exp_f32_e32 v74, v74
	v_exp_f32_e32 v75, v75
	v_pk_mul_f32 v[70:71], v[70:71], 0.5 op_sel_hi:[1, 0]
	v_pk_add_f32 v[74:75], v[74:75], 1.0 op_sel_hi:[1, 0]
	s_nop 0
	v_div_scale_f32 v76, s[0:1], v75, v75, 2.0
	v_rcp_f32_e32 v77, v76
	s_nop 0
	v_fma_f32 v78, -v76, v77, 1.0
	v_fmac_f32_e32 v77, v78, v77
	v_div_scale_f32 v78, vcc, 2.0, v75, 2.0
	v_mul_f32_e32 v79, v78, v77
	v_fma_f32 v80, -v76, v79, v78
	v_fmac_f32_e32 v79, v80, v77
	v_fma_f32 v76, -v76, v79, v78
	v_div_fmas_f32 v76, v76, v77, v79
	v_div_fixup_f32 v75, v76, v75, 2.0
	v_div_scale_f32 v76, s[0:1], v74, v74, 2.0
	v_rcp_f32_e32 v77, v76
	s_nop 0
	v_fma_f32 v78, -v76, v77, 1.0
	v_fmac_f32_e32 v77, v78, v77
	v_div_scale_f32 v78, vcc, 2.0, v74, 2.0
	v_mul_f32_e32 v79, v78, v77
	v_fma_f32 v80, -v76, v79, v78
	v_fmac_f32_e32 v79, v80, v77
	v_fma_f32 v76, -v76, v79, v78
	v_div_fmas_f32 v76, v76, v77, v79
	v_div_fixup_f32 v74, v76, v74, 2.0
	v_pk_add_f32 v[74:75], v[74:75], 1.0 op_sel_hi:[1, 0] neg_lo:[1, 0] neg_hi:[1, 0]
	s_nop 0
	v_pk_add_f32 v[74:75], v[74:75], 1.0 op_sel_hi:[1, 0]
	s_nop 0
	v_pk_mul_f32 v[70:71], v[70:71], v[74:75]
	s_nop 0
	v_cvt_pk_bf16_f32 v69, v70, v71
	global_store_dwordx2 v[72:73], v[68:69], off
	v_lshl_add_u64 v[68:69], s[26:27], 0, v[224:225]
	v_lshl_add_u64 v[68:69], v[68:69], 0, s[8:9]
	v_lshl_add_u64 v[68:69], v[68:69], 0, v[128:129]
	s_waitcnt vmcnt(2)
	v_lshlrev_b32_e32 v76, 16, v236
	v_and_b32_e32 v77, 0xffff0000, v236
	s_waitcnt vmcnt(1)
	v_pk_fma_f32 v[64:65], v[244:245], v[76:77], v[64:65]
	s_nop 0
	v_mul_f32_e32 v70, 0x3d372713, v64
	v_mul_f32_e32 v71, 0x3d372713, v65
	v_mul_f32_e32 v70, v64, v70
	v_mul_f32_e32 v71, v65, v71
	v_fma_f32 v70, v64, v70, v64
	v_fma_f32 v71, v65, v71, v65
	v_mul_f32_e32 v70, 0x3f4c422a, v70
	v_mul_f32_e32 v71, 0x3f4c422a, v71
	v_add_f32_e32 v70, v70, v70
	v_add_f32_e32 v71, v71, v71
	v_mul_f32_e32 v70, 0x3fb8aa3b, v70
	v_mul_f32_e32 v71, 0x3fb8aa3b, v71
	v_exp_f32_e32 v70, v70
	v_exp_f32_e32 v71, v71
	v_pk_mul_f32 v[64:65], v[64:65], 0.5 op_sel_hi:[1, 0]
	v_pk_add_f32 v[70:71], v[70:71], 1.0 op_sel_hi:[1, 0]
	s_nop 0
	v_div_scale_f32 v74, s[0:1], v71, v71, 2.0
	v_rcp_f32_e32 v76, v74
	s_nop 0
	v_fma_f32 v77, -v74, v76, 1.0
	v_fmac_f32_e32 v76, v77, v76
	v_div_scale_f32 v77, vcc, 2.0, v71, 2.0
	v_mul_f32_e32 v78, v77, v76
	v_fma_f32 v79, -v74, v78, v77
	v_fmac_f32_e32 v78, v79, v76
	v_fma_f32 v74, -v74, v78, v77
	v_div_fmas_f32 v74, v74, v76, v78
	v_div_fixup_f32 v71, v74, v71, 2.0
	v_div_scale_f32 v74, s[0:1], v70, v70, 2.0
	v_rcp_f32_e32 v76, v74
	s_nop 0
	v_fma_f32 v77, -v74, v76, 1.0
	v_fmac_f32_e32 v76, v77, v76
	v_div_scale_f32 v77, vcc, 2.0, v70, 2.0
	v_mul_f32_e32 v78, v77, v76
	v_fma_f32 v79, -v74, v78, v77
	v_fmac_f32_e32 v78, v79, v76
	v_fma_f32 v74, -v74, v78, v77
	v_div_fmas_f32 v74, v74, v76, v78
	v_div_fixup_f32 v70, v74, v70, 2.0
	v_pk_add_f32 v[70:71], v[70:71], 1.0 op_sel_hi:[1, 0] neg_lo:[1, 0] neg_hi:[1, 0]
	s_nop 0
	v_pk_add_f32 v[70:71], v[70:71], 1.0 op_sel_hi:[1, 0]
	s_nop 0
	v_pk_mul_f32 v[64:65], v[64:65], v[70:71]
	v_lshlrev_b32_e32 v70, 16, v237
	v_and_b32_e32 v71, 0xffff0000, v237
	v_pk_fma_f32 v[66:67], v[246:247], v[70:71], v[66:67]
	v_cvt_pk_bf16_f32 v64, v64, v65
	v_mul_f32_e32 v70, 0x3d372713, v66
	v_mul_f32_e32 v71, 0x3d372713, v67
	v_mul_f32_e32 v70, v66, v70
	v_mul_f32_e32 v71, v67, v71
	v_fma_f32 v70, v66, v70, v66
	v_fma_f32 v71, v67, v71, v67
	v_mul_f32_e32 v70, 0x3f4c422a, v70
	v_mul_f32_e32 v71, 0x3f4c422a, v71
	v_add_f32_e32 v70, v70, v70
	v_add_f32_e32 v71, v71, v71
	v_mul_f32_e32 v70, 0x3fb8aa3b, v70
; DI int tidx() { int t = threadIdx.x; asm volatile("" : "+v"(t)); return t; }
; DI float bf_lo(unsigned u) { return __uint_as_float(u << 16); }
; DI float bf_hi(unsigned u) { return __uint_as_float(u & 0xffff0000u); }
; template <class F>
; DI void epi8_iter(const acc8_t& acc, F f) {
;   const int lane = tidx() & 63, wid = tidx() >> 6, wr = wid >> 2, wc = wid & 3, fr = lane & 15, fq = lane >> 4;
; #pragma unroll
;   for (int ai = 0; ai < 2; ++ai)
; #pragma unroll
;     for (int bj = 0; bj < 2; ++bj)
; #pragma unroll
;       for (int m = 0; m < 4; ++m)
; #pragma unroll
;         for (int q = 0; q < 2; ++q)
;           f(bj * 128 + wc * 32 + q * 16 + fr, ai * 128 + wr * 64 + m * 16 + fq * 4, acc[ai][bj][m][q][0], acc[ai][bj][m][q][1],
;             acc[ai][bj][m][q][2], acc[ai][bj][m][q][3]);
; DI void phase_ssm_out(const Params& p, char* lds) {
;     ...
;     epi8_iter(acc, [&](int t, int n, float a, float b, float c, float d) {
;       const int nn = nt * 256 + n, tt = nn >> 4, pp = nn & 15;
;       const size_t tok = (size_t)(ct * 256 + t) * 32 + tt;
;       const uint2 uu = *(const uint2*)(u + tok * 512 + g * 16 + pp);
;       const float4 dd = *(const float4*)(p.ssm_d + g * 16 + pp);
;       store_bf4(yg + tok * 512 + g * 16 + pp, gelu_tanh(a + dd.x * bf_lo(uu.x)), gelu_tanh(b + dd.y * bf_hi(uu.x)),
;                 gelu_tanh(c + dd.z * bf_lo(uu.y)), gelu_tanh(d + dd.w * bf_hi(uu.y)));
	v_mul_f32_e32 v71, 0x3fb8aa3b, v71
	v_exp_f32_e32 v70, v70
	v_exp_f32_e32 v71, v71
	v_pk_mul_f32 v[66:67], v[66:67], 0.5 op_sel_hi:[1, 0]
	v_pk_add_f32 v[70:71], v[70:71], 1.0 op_sel_hi:[1, 0]
	s_nop 0
	v_div_scale_f32 v72, s[0:1], v71, v71, 2.0
	v_rcp_f32_e32 v73, v72
	s_nop 0
	v_fma_f32 v74, -v72, v73, 1.0
	v_fmac_f32_e32 v73, v74, v73
	v_div_scale_f32 v74, vcc, 2.0, v71, 2.0
	v_mul_f32_e32 v75, v74, v73
	v_fma_f32 v76, -v72, v75, v74
	v_fmac_f32_e32 v75, v76, v73
	v_fma_f32 v72, -v72, v75, v74
	v_div_fmas_f32 v72, v72, v73, v75
	v_div_fixup_f32 v71, v72, v71, 2.0
	v_div_scale_f32 v72, s[0:1], v70, v70, 2.0
	v_rcp_f32_e32 v73, v72
	s_nop 0
	v_fma_f32 v74, -v72, v73, 1.0
	v_fmac_f32_e32 v73, v74, v73
	v_div_scale_f32 v74, vcc, 2.0, v70, 2.0
	v_mul_f32_e32 v75, v74, v73
	v_fma_f32 v76, -v72, v75, v74
	v_fmac_f32_e32 v75, v76, v73
	v_fma_f32 v72, -v72, v75, v74
	v_div_fmas_f32 v72, v72, v73, v75
	v_div_fixup_f32 v70, v72, v70, 2.0
	v_pk_add_f32 v[70:71], v[70:71], 1.0 op_sel_hi:[1, 0] neg_lo:[1, 0] neg_hi:[1, 0]
	s_nop 0
	v_pk_add_f32 v[70:71], v[70:71], 1.0 op_sel_hi:[1, 0]
	s_nop 0
	v_pk_mul_f32 v[66:67], v[66:67], v[70:71]
	s_nop 0
	v_cvt_pk_bf16_f32 v65, v66, v67
	global_store_dwordx2 v[68:69], v[64:65], off
	v_add_u32_e32 v64, 0x80, v136
	v_ashrrev_i32_e32 v64, 4, v64
	v_ashrrev_i32_e32 v65, 31, v64
	v_lshlrev_b64 v[64:65], 9, v[64:65]
	v_lshl_add_u64 v[66:67], v[64:65], 0, v[152:153]
	v_lshlrev_b64 v[66:67], 1, v[66:67]
	v_lshl_add_u64 v[68:69], s[36:37], 0, v[66:67]
	v_lshl_add_u64 v[68:69], v[68:69], 0, s[8:9]
	v_lshl_add_u64 v[68:69], v[68:69], 0, v[128:129]
	global_load_dwordx2 v[72:73], v[68:69], off
	global_load_dwordx4 v[184:187], v172, s[80:81]
	v_mov_b32_e32 v182, v173
	v_mov_b32_e32 v183, v176
	v_lshl_add_u64 v[188:189], v[64:65], 0, v[182:183]
	v_lshlrev_b64 v[190:191], 1, v[188:189]
	v_lshl_add_u64 v[192:193], s[36:37], 0, v[190:191]
	v_lshl_add_u64 v[194:195], v[192:193], 0, s[8:9]
	v_lshl_add_u64 v[196:197], v[194:195], 0, v[128:129]
	global_load_dwordx2 v[198:199], v[196:197], off
	global_load_dwordx4 v[200:203], v172, s[80:81]
	v_lshl_add_u64 v[66:67], s[26:27], 0, v[66:67]
	v_lshl_add_u64 v[66:67], v[66:67], 0, s[8:9]
	v_lshl_add_u64 v[66:67], v[66:67], 0, v[128:129]
	s_waitcnt vmcnt(3)
	v_lshlrev_b32_e32 v74, 16, v72
	v_and_b32_e32 v75, 0xffff0000, v72
	s_waitcnt vmcnt(2)
	v_pk_fma_f32 v[60:61], v[184:185], v[74:75], v[60:61]
	s_nop 0
	v_mul_f32_e32 v68, 0x3d372713, v60
	v_mul_f32_e32 v69, 0x3d372713, v61
	v_mul_f32_e32 v68, v60, v68
	v_mul_f32_e32 v69, v61, v69
	v_fma_f32 v68, v60, v68, v60
	v_fma_f32 v69, v61, v69, v61
	v_mul_f32_e32 v68, 0x3f4c422a, v68
	v_mul_f32_e32 v69, 0x3f4c422a, v69
	v_add_f32_e32 v68, v68, v68
	v_add_f32_e32 v69, v69, v69
	v_mul_f32_e32 v68, 0x3fb8aa3b, v68
	v_mul_f32_e32 v69, 0x3fb8aa3b, v69
	v_exp_f32_e32 v68, v68
	v_exp_f32_e32 v69, v69
	v_pk_mul_f32 v[60:61], v[60:61], 0.5 op_sel_hi:[1, 0]
	v_pk_add_f32 v[68:69], v[68:69], 1.0 op_sel_hi:[1, 0]
	s_nop 0
	v_div_scale_f32 v72, s[0:1], v69, v69, 2.0
	v_rcp_f32_e32 v74, v72
	s_nop 0
	v_fma_f32 v75, -v72, v74, 1.0
	v_fmac_f32_e32 v74, v75, v74
	v_div_scale_f32 v75, vcc, 2.0, v69, 2.0
	v_mul_f32_e32 v76, v75, v74
	v_fma_f32 v77, -v72, v76, v75
	v_fmac_f32_e32 v76, v77, v74
	v_fma_f32 v72, -v72, v76, v75
	v_div_fmas_f32 v72, v72, v74, v76
	v_div_fixup_f32 v69, v72, v69, 2.0
	v_div_scale_f32 v72, s[0:1], v68, v68, 2.0
	v_rcp_f32_e32 v74, v72
	s_nop 0
	v_fma_f32 v75, -v72, v74, 1.0
	v_fmac_f32_e32 v74, v75, v74
	v_div_scale_f32 v75, vcc, 2.0, v68, 2.0
	v_mul_f32_e32 v76, v75, v74
	v_fma_f32 v77, -v72, v76, v75
	v_fmac_f32_e32 v76, v77, v74
	v_fma_f32 v72, -v72, v76, v75
	v_div_fmas_f32 v72, v72, v74, v76
	v_div_fixup_f32 v68, v72, v68, 2.0
	v_pk_add_f32 v[68:69], v[68:69], 1.0 op_sel_hi:[1, 0] neg_lo:[1, 0] neg_hi:[1, 0]
	s_nop 0
	v_pk_add_f32 v[68:69], v[68:69], 1.0 op_sel_hi:[1, 0]
	s_nop 0
	v_pk_mul_f32 v[60:61], v[60:61], v[68:69]
	v_lshlrev_b32_e32 v68, 16, v73
	v_and_b32_e32 v69, 0xffff0000, v73
	v_pk_fma_f32 v[62:63], v[186:187], v[68:69], v[62:63]
	v_cvt_pk_bf16_f32 v60, v60, v61
	v_mul_f32_e32 v68, 0x3d372713, v62
	v_mul_f32_e32 v69, 0x3d372713, v63
	v_mul_f32_e32 v68, v62, v68
	v_mul_f32_e32 v69, v63, v69
	v_fma_f32 v68, v62, v68, v62
	v_fma_f32 v69, v63, v69, v63
	v_mul_f32_e32 v68, 0x3f4c422a, v68
	v_mul_f32_e32 v69, 0x3f4c422a, v69
	v_add_f32_e32 v68, v68, v68
	v_add_f32_e32 v69, v69, v69
	v_mul_f32_e32 v68, 0x3fb8aa3b, v68
	v_mul_f32_e32 v69, 0x3fb8aa3b, v69
	v_exp_f32_e32 v68, v68
	v_exp_f32_e32 v69, v69
	v_pk_mul_f32 v[62:63], v[62:63], 0.5 op_sel_hi:[1, 0]
	v_pk_add_f32 v[68:69], v[68:69], 1.0 op_sel_hi:[1, 0]
	s_nop 0
	v_div_scale_f32 v70, s[0:1], v69, v69, 2.0
	v_rcp_f32_e32 v71, v70
	s_nop 0
	v_fma_f32 v72, -v70, v71, 1.0
	v_fmac_f32_e32 v71, v72, v71
	v_div_scale_f32 v72, vcc, 2.0, v69, 2.0
	v_mul_f32_e32 v73, v72, v71
	v_fma_f32 v74, -v70, v73, v72
	v_fmac_f32_e32 v73, v74, v71
	v_fma_f32 v70, -v70, v73, v72
	v_div_fmas_f32 v70, v70, v71, v73
	v_div_fixup_f32 v69, v70, v69, 2.0
	v_div_scale_f32 v70, s[0:1], v68, v68, 2.0
	v_rcp_f32_e32 v71, v70
	s_nop 0
	v_fma_f32 v72, -v70, v71, 1.0
	v_fmac_f32_e32 v71, v72, v71
	v_div_scale_f32 v72, vcc, 2.0, v68, 2.0
	v_mul_f32_e32 v73, v72, v71
	v_fma_f32 v74, -v70, v73, v72
	v_fmac_f32_e32 v73, v74, v71
	v_fma_f32 v70, -v70, v73, v72
	v_div_fmas_f32 v70, v70, v71, v73
	v_div_fixup_f32 v68, v70, v68, 2.0
	v_pk_add_f32 v[68:69], v[68:69], 1.0 op_sel_hi:[1, 0] neg_lo:[1, 0] neg_hi:[1, 0]
	s_nop 0
	v_pk_add_f32 v[68:69], v[68:69], 1.0 op_sel_hi:[1, 0]
	s_nop 0
	v_pk_mul_f32 v[62:63], v[62:63], v[68:69]
	s_nop 0
	v_cvt_pk_bf16_f32 v61, v62, v63
	global_store_dwordx2 v[66:67], v[60:61], off
	v_lshl_add_u64 v[60:61], s[26:27], 0, v[190:191]
	v_lshl_add_u64 v[60:61], v[60:61], 0, s[8:9]
	v_lshl_add_u64 v[60:61], v[60:61], 0, v[128:129]
	s_waitcnt vmcnt(2)
; DI float bf_lo(unsigned u) { return __uint_as_float(u << 16); }
; DI float bf_hi(unsigned u) { return __uint_as_float(u & 0xffff0000u); }
; DI float fast_exp(float x) { return __builtin_amdgcn_exp2f(x * 1.44269504089f); }
; DI float gelu_tanh(float y) {
;   const float z = 0.7978845608028654f * (y + 0.044715f * y * y * y);
;   const float e = fast_exp(2.0f * z);
;   const float th = 1.0f - 2.0f / (e + 1.0f);
;   return 0.5f * y * (1.0f + th);
; }
; DI void phase_ssm_out(const Params& p, char* lds) {
;     ...
;     epi8_iter(acc, [&](int t, int n, float a, float b, float c, float d) {
;       const int nn = nt * 256 + n, tt = nn >> 4, pp = nn & 15;
;       const size_t tok = (size_t)(ct * 256 + t) * 32 + tt;
;       const uint2 uu = *(const uint2*)(u + tok * 512 + g * 16 + pp);
;       const float4 dd = *(const float4*)(p.ssm_d + g * 16 + pp);
;       store_bf4(yg + tok * 512 + g * 16 + pp, gelu_tanh(a + dd.x * bf_lo(uu.x)), gelu_tanh(b + dd.y * bf_hi(uu.x)),
;                 gelu_tanh(c + dd.z * bf_lo(uu.y)), gelu_tanh(d + dd.w * bf_hi(uu.y)));
	v_lshlrev_b32_e32 v70, 16, v198
	v_and_b32_e32 v71, 0xffff0000, v198
	s_waitcnt vmcnt(1)
	v_pk_fma_f32 v[56:57], v[200:201], v[70:71], v[56:57]
	s_nop 0
	v_mul_f32_e32 v62, 0x3d372713, v56
	v_mul_f32_e32 v62, v56, v62
	v_fma_f32 v62, v56, v62, v56
	v_mul_f32_e32 v62, 0x3f4c422a, v62
	v_add_f32_e32 v62, v62, v62
	v_mul_f32_e32 v62, 0x3fb8aa3b, v62
	v_exp_f32_e32 v66, v62
	v_mul_f32_e32 v62, 0x3d372713, v57
	v_mul_f32_e32 v62, v57, v62
	v_fma_f32 v62, v57, v62, v57
	v_mul_f32_e32 v62, 0x3f4c422a, v62
	v_add_f32_e32 v62, v62, v62
	v_mul_f32_e32 v62, 0x3fb8aa3b, v62
	v_exp_f32_e32 v67, v62
	v_pk_mul_f32 v[56:57], v[56:57], 0.5 op_sel_hi:[1, 0]
	v_pk_add_f32 v[66:67], v[66:67], 1.0 op_sel_hi:[1, 0]
	s_nop 0
	v_div_scale_f32 v62, s[0:1], v67, v67, 2.0
	v_rcp_f32_e32 v70, v62
	s_nop 0
	v_fma_f32 v71, -v62, v70, 1.0
	v_fmac_f32_e32 v70, v71, v70
	v_div_scale_f32 v71, vcc, 2.0, v67, 2.0
	v_mul_f32_e32 v72, v71, v70
	v_fma_f32 v73, -v62, v72, v71
	v_fmac_f32_e32 v72, v73, v70
	v_fma_f32 v62, -v62, v72, v71
	v_div_fmas_f32 v62, v62, v70, v72
	v_div_fixup_f32 v67, v62, v67, 2.0
	v_div_scale_f32 v62, s[0:1], v66, v66, 2.0
	v_rcp_f32_e32 v70, v62
	s_nop 0
	v_fma_f32 v71, -v62, v70, 1.0
	v_fmac_f32_e32 v70, v71, v70
	v_div_scale_f32 v71, vcc, 2.0, v66, 2.0
	v_mul_f32_e32 v72, v71, v70
	v_fma_f32 v73, -v62, v72, v71
	v_fmac_f32_e32 v72, v73, v70
	v_fma_f32 v62, -v62, v72, v71
	v_div_fmas_f32 v62, v62, v70, v72
	v_div_fixup_f32 v66, v62, v66, 2.0
	v_lshlrev_b32_e32 v62, 16, v199
	v_and_b32_e32 v63, 0xffff0000, v199
	v_pk_fma_f32 v[58:59], v[202:203], v[62:63], v[58:59]
	v_pk_add_f32 v[66:67], v[66:67], 1.0 op_sel_hi:[1, 0] neg_lo:[1, 0] neg_hi:[1, 0]
	v_mul_f32_e32 v62, 0x3d372713, v58
	v_mul_f32_e32 v63, 0x3d372713, v59
	v_mul_f32_e32 v62, v58, v62
	v_mul_f32_e32 v63, v59, v63
	v_fma_f32 v62, v58, v62, v58
	v_fma_f32 v63, v59, v63, v59
	v_mul_f32_e32 v62, 0x3f4c422a, v62
	v_mul_f32_e32 v63, 0x3f4c422a, v63
	v_add_f32_e32 v62, v62, v62
	v_add_f32_e32 v63, v63, v63
	v_mul_f32_e32 v62, 0x3fb8aa3b, v62
	v_mul_f32_e32 v63, 0x3fb8aa3b, v63
	v_exp_f32_e32 v62, v62
	v_exp_f32_e32 v63, v63
	v_pk_add_f32 v[66:67], v[66:67], 1.0 op_sel_hi:[1, 0]
	v_pk_mul_f32 v[58:59], v[58:59], 0.5 op_sel_hi:[1, 0]
	v_pk_mul_f32 v[56:57], v[56:57], v[66:67]
	v_pk_add_f32 v[62:63], v[62:63], 1.0 op_sel_hi:[1, 0]
	v_cvt_pk_bf16_f32 v56, v56, v57
	v_div_scale_f32 v66, s[0:1], v63, v63, 2.0
	v_rcp_f32_e32 v67, v66
	s_nop 0
	v_fma_f32 v68, -v66, v67, 1.0
	v_fmac_f32_e32 v67, v68, v67
	v_div_scale_f32 v68, vcc, 2.0, v63, 2.0
	v_mul_f32_e32 v69, v68, v67
	v_fma_f32 v70, -v66, v69, v68
	v_fmac_f32_e32 v69, v70, v67
	v_fma_f32 v66, -v66, v69, v68
	v_div_fmas_f32 v66, v66, v67, v69
	v_div_fixup_f32 v63, v66, v63, 2.0
	v_div_scale_f32 v66, s[0:1], v62, v62, 2.0
	v_rcp_f32_e32 v67, v66
	s_nop 0
	v_fma_f32 v68, -v66, v67, 1.0
	v_fmac_f32_e32 v67, v68, v67
	v_div_scale_f32 v68, vcc, 2.0, v62, 2.0
	v_mul_f32_e32 v69, v68, v67
	v_fma_f32 v70, -v66, v69, v68
	v_fmac_f32_e32 v69, v70, v67
	v_fma_f32 v66, -v66, v69, v68
	v_div_fmas_f32 v66, v66, v67, v69
	v_div_fixup_f32 v62, v66, v62, 2.0
	v_pk_add_f32 v[62:63], v[62:63], 1.0 op_sel_hi:[1, 0] neg_lo:[1, 0] neg_hi:[1, 0]
	s_nop 0
	v_pk_add_f32 v[62:63], v[62:63], 1.0 op_sel_hi:[1, 0]
	s_nop 0
	v_pk_mul_f32 v[58:59], v[58:59], v[62:63]
	s_nop 0
	v_cvt_pk_bf16_f32 v57, v58, v59
	global_store_dwordx2 v[60:61], v[56:57], off
	v_add_u32_e32 v56, 0x90, v136
	v_ashrrev_i32_e32 v56, 4, v56
	v_ashrrev_i32_e32 v57, 31, v56
	v_lshlrev_b64 v[56:57], 9, v[56:57]
	v_lshl_add_u64 v[58:59], v[56:57], 0, v[152:153]
	v_lshlrev_b64 v[58:59], 1, v[58:59]
	v_lshl_add_u64 v[60:61], s[36:37], 0, v[58:59]
	v_lshl_add_u64 v[60:61], v[60:61], 0, s[8:9]
	v_lshl_add_u64 v[60:61], v[60:61], 0, v[128:129]
	global_load_dwordx2 v[66:67], v[60:61], off
	global_load_dwordx4 v[216:219], v172, s[80:81]
	v_mov_b32_e32 v212, v173
	v_mov_b32_e32 v213, v176
	v_lshl_add_u64 v[220:221], v[56:57], 0, v[212:213]
	v_lshlrev_b64 v[224:225], 1, v[220:221]
	v_lshl_add_u64 v[226:227], s[36:37], 0, v[224:225]
	v_lshl_add_u64 v[228:229], v[226:227], 0, s[8:9]
	v_lshl_add_u64 v[230:231], v[228:229], 0, v[128:129]
	global_load_dwordx2 v[236:237], v[230:231], off
	global_load_dwordx4 v[244:247], v172, s[80:81]
	v_lshl_add_u64 v[58:59], s[26:27], 0, v[58:59]
	v_lshl_add_u64 v[58:59], v[58:59], 0, s[8:9]
	v_lshl_add_u64 v[58:59], v[58:59], 0, v[128:129]
	s_waitcnt vmcnt(3)
	v_lshlrev_b32_e32 v68, 16, v66
	v_and_b32_e32 v69, 0xffff0000, v66
	s_waitcnt vmcnt(2)
; DI float bf_lo(unsigned u) { return __uint_as_float(u << 16); }
; DI float bf_hi(unsigned u) { return __uint_as_float(u & 0xffff0000u); }
; DI float fast_exp(float x) { return __builtin_amdgcn_exp2f(x * 1.44269504089f); }
; DI float gelu_tanh(float y) {
;   const float z = 0.7978845608028654f * (y + 0.044715f * y * y * y);
;   const float e = fast_exp(2.0f * z);
;   const float th = 1.0f - 2.0f / (e + 1.0f);
;   return 0.5f * y * (1.0f + th);
; }
; DI void phase_ssm_out(const Params& p, char* lds) {
;     ...
;     epi8_iter(acc, [&](int t, int n, float a, float b, float c, float d) {
;       const int nn = nt * 256 + n, tt = nn >> 4, pp = nn & 15;
;       const size_t tok = (size_t)(ct * 256 + t) * 32 + tt;
;       const uint2 uu = *(const uint2*)(u + tok * 512 + g * 16 + pp);
;       const float4 dd = *(const float4*)(p.ssm_d + g * 16 + pp);
;       store_bf4(yg + tok * 512 + g * 16 + pp, gelu_tanh(a + dd.x * bf_lo(uu.x)), gelu_tanh(b + dd.y * bf_hi(uu.x)),
;                 gelu_tanh(c + dd.z * bf_lo(uu.y)), gelu_tanh(d + dd.w * bf_hi(uu.y)));
	v_pk_fma_f32 v[52:53], v[216:217], v[68:69], v[52:53]
	s_nop 0
	v_mul_f32_e32 v60, 0x3d372713, v52
	v_mul_f32_e32 v61, 0x3d372713, v53
	v_mul_f32_e32 v60, v52, v60
	v_mul_f32_e32 v61, v53, v61
	v_fma_f32 v60, v52, v60, v52
	v_fma_f32 v61, v53, v61, v53
	v_mul_f32_e32 v60, 0x3f4c422a, v60
	v_mul_f32_e32 v61, 0x3f4c422a, v61
	v_add_f32_e32 v60, v60, v60
	v_add_f32_e32 v61, v61, v61
	v_mul_f32_e32 v60, 0x3fb8aa3b, v60
	v_mul_f32_e32 v61, 0x3fb8aa3b, v61
	v_exp_f32_e32 v60, v60
	v_exp_f32_e32 v61, v61
	v_pk_mul_f32 v[52:53], v[52:53], 0.5 op_sel_hi:[1, 0]
	v_pk_add_f32 v[60:61], v[60:61], 1.0 op_sel_hi:[1, 0]
	s_nop 0
	v_div_scale_f32 v66, s[0:1], v61, v61, 2.0
	v_rcp_f32_e32 v68, v66
	s_nop 0
	v_fma_f32 v69, -v66, v68, 1.0
	v_fmac_f32_e32 v68, v69, v68
	v_div_scale_f32 v69, vcc, 2.0, v61, 2.0
	v_mul_f32_e32 v70, v69, v68
	v_fma_f32 v71, -v66, v70, v69
	v_fmac_f32_e32 v70, v71, v68
	v_fma_f32 v66, -v66, v70, v69
	v_div_fmas_f32 v66, v66, v68, v70
	v_div_fixup_f32 v61, v66, v61, 2.0
	v_div_scale_f32 v66, s[0:1], v60, v60, 2.0
	v_rcp_f32_e32 v68, v66
	s_nop 0
	v_fma_f32 v69, -v66, v68, 1.0
	v_fmac_f32_e32 v68, v69, v68
	v_div_scale_f32 v69, vcc, 2.0, v60, 2.0
	v_mul_f32_e32 v70, v69, v68
	v_fma_f32 v71, -v66, v70, v69
	v_fmac_f32_e32 v70, v71, v68
	v_fma_f32 v66, -v66, v70, v69
	v_div_fmas_f32 v66, v66, v68, v70
	v_div_fixup_f32 v60, v66, v60, 2.0
	v_pk_add_f32 v[60:61], v[60:61], 1.0 op_sel_hi:[1, 0] neg_lo:[1, 0] neg_hi:[1, 0]
	s_nop 0
	v_pk_add_f32 v[60:61], v[60:61], 1.0 op_sel_hi:[1, 0]
	s_nop 0
	v_pk_mul_f32 v[52:53], v[52:53], v[60:61]
	v_lshlrev_b32_e32 v60, 16, v67
	v_and_b32_e32 v61, 0xffff0000, v67
	v_pk_fma_f32 v[54:55], v[218:219], v[60:61], v[54:55]
	v_cvt_pk_bf16_f32 v52, v52, v53
	v_mul_f32_e32 v60, 0x3d372713, v54
	v_mul_f32_e32 v61, 0x3d372713, v55
	v_mul_f32_e32 v60, v54, v60
	v_mul_f32_e32 v61, v55, v61
	v_fma_f32 v60, v54, v60, v54
	v_fma_f32 v61, v55, v61, v55
	v_mul_f32_e32 v60, 0x3f4c422a, v60
	v_mul_f32_e32 v61, 0x3f4c422a, v61
	v_add_f32_e32 v60, v60, v60
	v_add_f32_e32 v61, v61, v61
	v_mul_f32_e32 v60, 0x3fb8aa3b, v60
	v_mul_f32_e32 v61, 0x3fb8aa3b, v61
	v_exp_f32_e32 v60, v60
	v_exp_f32_e32 v61, v61
	v_pk_mul_f32 v[54:55], v[54:55], 0.5 op_sel_hi:[1, 0]
	v_pk_add_f32 v[60:61], v[60:61], 1.0 op_sel_hi:[1, 0]
	s_nop 0
	v_div_scale_f32 v62, s[0:1], v61, v61, 2.0
	v_rcp_f32_e32 v63, v62
	s_nop 0
	v_fma_f32 v66, -v62, v63, 1.0
	v_fmac_f32_e32 v63, v66, v63
	v_div_scale_f32 v66, vcc, 2.0, v61, 2.0
	v_mul_f32_e32 v67, v66, v63
	v_fma_f32 v68, -v62, v67, v66
	v_fmac_f32_e32 v67, v68, v63
	v_fma_f32 v62, -v62, v67, v66
	v_div_fmas_f32 v62, v62, v63, v67
	v_div_fixup_f32 v61, v62, v61, 2.0
	v_div_scale_f32 v62, s[0:1], v60, v60, 2.0
	v_rcp_f32_e32 v63, v62
	s_nop 0
	v_fma_f32 v66, -v62, v63, 1.0
	v_fmac_f32_e32 v63, v66, v63
	v_div_scale_f32 v66, vcc, 2.0, v60, 2.0
	v_mul_f32_e32 v67, v66, v63
	v_fma_f32 v68, -v62, v67, v66
	v_fmac_f32_e32 v67, v68, v63
	v_fma_f32 v62, -v62, v67, v66
	v_div_fmas_f32 v62, v62, v63, v67
	v_div_fixup_f32 v60, v62, v60, 2.0
	v_pk_add_f32 v[60:61], v[60:61], 1.0 op_sel_hi:[1, 0] neg_lo:[1, 0] neg_hi:[1, 0]
	s_nop 0
	v_pk_add_f32 v[60:61], v[60:61], 1.0 op_sel_hi:[1, 0]
	s_nop 0
	v_pk_mul_f32 v[54:55], v[54:55], v[60:61]
	s_nop 0
	v_cvt_pk_bf16_f32 v53, v54, v55
	global_store_dwordx2 v[58:59], v[52:53], off
	v_lshl_add_u64 v[52:53], s[26:27], 0, v[224:225]
	v_lshl_add_u64 v[52:53], v[52:53], 0, s[8:9]
	v_lshl_add_u64 v[52:53], v[52:53], 0, v[128:129]
	s_waitcnt vmcnt(2)
	v_lshlrev_b32_e32 v62, 16, v236
	v_and_b32_e32 v63, 0xffff0000, v236
	s_waitcnt vmcnt(1)
	v_pk_fma_f32 v[48:49], v[244:245], v[62:63], v[48:49]
	s_nop 0
	v_mul_f32_e32 v54, 0x3d372713, v48
	v_mul_f32_e32 v54, v48, v54
	v_fma_f32 v54, v48, v54, v48
	v_mul_f32_e32 v54, 0x3f4c422a, v54
	v_add_f32_e32 v54, v54, v54
	v_mul_f32_e32 v54, 0x3fb8aa3b, v54
	v_exp_f32_e32 v58, v54
	v_mul_f32_e32 v54, 0x3d372713, v49
	v_mul_f32_e32 v54, v49, v54
	v_fma_f32 v54, v49, v54, v49
	v_mul_f32_e32 v54, 0x3f4c422a, v54
	v_add_f32_e32 v54, v54, v54
	v_mul_f32_e32 v54, 0x3fb8aa3b, v54
	v_exp_f32_e32 v59, v54
	v_pk_mul_f32 v[48:49], v[48:49], 0.5 op_sel_hi:[1, 0]
	v_pk_add_f32 v[58:59], v[58:59], 1.0 op_sel_hi:[1, 0]
	s_nop 0
	v_div_scale_f32 v54, s[0:1], v59, v59, 2.0
	v_rcp_f32_e32 v62, v54
	s_nop 0
	v_fma_f32 v63, -v54, v62, 1.0
	v_fmac_f32_e32 v62, v63, v62
	v_div_scale_f32 v63, vcc, 2.0, v59, 2.0
	v_mul_f32_e32 v66, v63, v62
	v_fma_f32 v67, -v54, v66, v63
	v_fmac_f32_e32 v66, v67, v62
	v_fma_f32 v54, -v54, v66, v63
	v_div_fmas_f32 v54, v54, v62, v66
	v_div_fixup_f32 v59, v54, v59, 2.0
	v_div_scale_f32 v54, s[0:1], v58, v58, 2.0
	v_rcp_f32_e32 v62, v54
	s_nop 0
	v_fma_f32 v63, -v54, v62, 1.0
	v_fmac_f32_e32 v62, v63, v62
	v_div_scale_f32 v63, vcc, 2.0, v58, 2.0
	v_mul_f32_e32 v66, v63, v62
	v_fma_f32 v67, -v54, v66, v63
	v_fmac_f32_e32 v66, v67, v62
	v_fma_f32 v54, -v54, v66, v63
	v_div_fmas_f32 v54, v54, v62, v66
	v_div_fixup_f32 v58, v54, v58, 2.0
	v_lshlrev_b32_e32 v54, 16, v237
	v_and_b32_e32 v55, 0xffff0000, v237
	v_pk_fma_f32 v[50:51], v[246:247], v[54:55], v[50:51]
	v_pk_add_f32 v[58:59], v[58:59], 1.0 op_sel_hi:[1, 0] neg_lo:[1, 0] neg_hi:[1, 0]
	v_mul_f32_e32 v54, 0x3d372713, v50
	v_mul_f32_e32 v55, 0x3d372713, v51
	v_mul_f32_e32 v54, v50, v54
	v_mul_f32_e32 v55, v51, v55
	v_fma_f32 v54, v50, v54, v50
	v_fma_f32 v55, v51, v55, v51
	v_mul_f32_e32 v54, 0x3f4c422a, v54
	v_mul_f32_e32 v55, 0x3f4c422a, v55
	v_add_f32_e32 v54, v54, v54
	v_add_f32_e32 v55, v55, v55
	v_mul_f32_e32 v54, 0x3fb8aa3b, v54
	v_mul_f32_e32 v55, 0x3fb8aa3b, v55
	v_exp_f32_e32 v54, v54
	v_exp_f32_e32 v55, v55
	v_pk_add_f32 v[58:59], v[58:59], 1.0 op_sel_hi:[1, 0]
; DI int tidx() { int t = threadIdx.x; asm volatile("" : "+v"(t)); return t; }
; DI float bf_lo(unsigned u) { return __uint_as_float(u << 16); }
; DI float bf_hi(unsigned u) { return __uint_as_float(u & 0xffff0000u); }
; template <class F>
; DI void epi8_iter(const acc8_t& acc, F f) {
;   const int lane = tidx() & 63, wid = tidx() >> 6, wr = wid >> 2, wc = wid & 3, fr = lane & 15, fq = lane >> 4;
; #pragma unroll
;   for (int ai = 0; ai < 2; ++ai)
; #pragma unroll
;     for (int bj = 0; bj < 2; ++bj)
; #pragma unroll
;       for (int m = 0; m < 4; ++m)
; #pragma unroll
;         for (int q = 0; q < 2; ++q)
;           f(bj * 128 + wc * 32 + q * 16 + fr, ai * 128 + wr * 64 + m * 16 + fq * 4, acc[ai][bj][m][q][0], acc[ai][bj][m][q][1],
;             acc[ai][bj][m][q][2], acc[ai][bj][m][q][3]);
; DI void phase_ssm_out(const Params& p, char* lds) {
;     ...
;     epi8_iter(acc, [&](int t, int n, float a, float b, float c, float d) {
;       const int nn = nt * 256 + n, tt = nn >> 4, pp = nn & 15;
;       const size_t tok = (size_t)(ct * 256 + t) * 32 + tt;
;       const uint2 uu = *(const uint2*)(u + tok * 512 + g * 16 + pp);
;       const float4 dd = *(const float4*)(p.ssm_d + g * 16 + pp);
;       store_bf4(yg + tok * 512 + g * 16 + pp, gelu_tanh(a + dd.x * bf_lo(uu.x)), gelu_tanh(b + dd.y * bf_hi(uu.x)),
;                 gelu_tanh(c + dd.z * bf_lo(uu.y)), gelu_tanh(d + dd.w * bf_hi(uu.y)));
	v_pk_mul_f32 v[50:51], v[50:51], 0.5 op_sel_hi:[1, 0]
	v_pk_mul_f32 v[48:49], v[48:49], v[58:59]
	v_pk_add_f32 v[54:55], v[54:55], 1.0 op_sel_hi:[1, 0]
	v_cvt_pk_bf16_f32 v48, v48, v49
	v_div_scale_f32 v58, s[0:1], v55, v55, 2.0
	v_rcp_f32_e32 v59, v58
	s_nop 0
	v_fma_f32 v60, -v58, v59, 1.0
	v_fmac_f32_e32 v59, v60, v59
	v_div_scale_f32 v60, vcc, 2.0, v55, 2.0
	v_mul_f32_e32 v61, v60, v59
	v_fma_f32 v62, -v58, v61, v60
	v_fmac_f32_e32 v61, v62, v59
	v_fma_f32 v58, -v58, v61, v60
	v_div_fmas_f32 v58, v58, v59, v61
	v_div_fixup_f32 v55, v58, v55, 2.0
	v_div_scale_f32 v58, s[0:1], v54, v54, 2.0
	v_rcp_f32_e32 v59, v58
	s_nop 0
	v_fma_f32 v60, -v58, v59, 1.0
	v_fmac_f32_e32 v59, v60, v59
	v_div_scale_f32 v60, vcc, 2.0, v54, 2.0
	v_mul_f32_e32 v61, v60, v59
	v_fma_f32 v62, -v58, v61, v60
	v_fmac_f32_e32 v61, v62, v59
	v_fma_f32 v58, -v58, v61, v60
	v_div_fmas_f32 v58, v58, v59, v61
	v_div_fixup_f32 v54, v58, v54, 2.0
	v_pk_add_f32 v[54:55], v[54:55], 1.0 op_sel_hi:[1, 0] neg_lo:[1, 0] neg_hi:[1, 0]
	s_nop 0
	v_pk_add_f32 v[54:55], v[54:55], 1.0 op_sel_hi:[1, 0]
	s_nop 0
	v_pk_mul_f32 v[50:51], v[50:51], v[54:55]
	s_nop 0
	v_cvt_pk_bf16_f32 v49, v50, v51
	global_store_dwordx2 v[52:53], v[48:49], off
	v_add_u32_e32 v48, 0xa0, v136
	v_ashrrev_i32_e32 v48, 4, v48
	v_ashrrev_i32_e32 v49, 31, v48
	v_lshlrev_b64 v[48:49], 9, v[48:49]
	v_lshl_add_u64 v[50:51], v[48:49], 0, v[152:153]
	v_lshlrev_b64 v[50:51], 1, v[50:51]
	v_lshl_add_u64 v[52:53], s[36:37], 0, v[50:51]
	v_lshl_add_u64 v[52:53], v[52:53], 0, s[8:9]
	v_lshl_add_u64 v[52:53], v[52:53], 0, v[128:129]
	global_load_dwordx2 v[58:59], v[52:53], off
	global_load_dwordx4 v[184:187], v172, s[80:81]
	v_mov_b32_e32 v182, v173
	v_mov_b32_e32 v183, v176
	v_lshl_add_u64 v[188:189], v[48:49], 0, v[182:183]
	v_lshlrev_b64 v[190:191], 1, v[188:189]
	v_lshl_add_u64 v[192:193], s[36:37], 0, v[190:191]
	v_lshl_add_u64 v[194:195], v[192:193], 0, s[8:9]
	v_lshl_add_u64 v[196:197], v[194:195], 0, v[128:129]
	global_load_dwordx2 v[198:199], v[196:197], off
	global_load_dwordx4 v[200:203], v172, s[80:81]
	v_lshl_add_u64 v[50:51], s[26:27], 0, v[50:51]
	v_lshl_add_u64 v[50:51], v[50:51], 0, s[8:9]
	v_lshl_add_u64 v[50:51], v[50:51], 0, v[128:129]
	s_waitcnt vmcnt(3)
	v_lshlrev_b32_e32 v60, 16, v58
	v_and_b32_e32 v61, 0xffff0000, v58
	s_waitcnt vmcnt(2)
	v_pk_fma_f32 v[44:45], v[184:185], v[60:61], v[44:45]
	s_nop 0
	v_mul_f32_e32 v52, 0x3d372713, v44
	v_mul_f32_e32 v53, 0x3d372713, v45
	v_mul_f32_e32 v52, v44, v52
	v_mul_f32_e32 v53, v45, v53
	v_fma_f32 v52, v44, v52, v44
	v_fma_f32 v53, v45, v53, v45
	v_mul_f32_e32 v52, 0x3f4c422a, v52
	v_mul_f32_e32 v53, 0x3f4c422a, v53
	v_add_f32_e32 v52, v52, v52
	v_add_f32_e32 v53, v53, v53
	v_mul_f32_e32 v52, 0x3fb8aa3b, v52
	v_mul_f32_e32 v53, 0x3fb8aa3b, v53
	v_exp_f32_e32 v52, v52
	v_exp_f32_e32 v53, v53
	v_pk_mul_f32 v[44:45], v[44:45], 0.5 op_sel_hi:[1, 0]
	v_pk_add_f32 v[52:53], v[52:53], 1.0 op_sel_hi:[1, 0]
	s_nop 0
	v_div_scale_f32 v58, s[0:1], v53, v53, 2.0
	v_rcp_f32_e32 v60, v58
	s_nop 0
	v_fma_f32 v61, -v58, v60, 1.0
	v_fmac_f32_e32 v60, v61, v60
	v_div_scale_f32 v61, vcc, 2.0, v53, 2.0
	v_mul_f32_e32 v62, v61, v60
	v_fma_f32 v63, -v58, v62, v61
	v_fmac_f32_e32 v62, v63, v60
	v_fma_f32 v58, -v58, v62, v61
	v_div_fmas_f32 v58, v58, v60, v62
	v_div_fixup_f32 v53, v58, v53, 2.0
	v_div_scale_f32 v58, s[0:1], v52, v52, 2.0
	v_rcp_f32_e32 v60, v58
	s_nop 0
	v_fma_f32 v61, -v58, v60, 1.0
	v_fmac_f32_e32 v60, v61, v60
	v_div_scale_f32 v61, vcc, 2.0, v52, 2.0
	v_mul_f32_e32 v62, v61, v60
	v_fma_f32 v63, -v58, v62, v61
	v_fmac_f32_e32 v62, v63, v60
	v_fma_f32 v58, -v58, v62, v61
	v_div_fmas_f32 v58, v58, v60, v62
	v_div_fixup_f32 v52, v58, v52, 2.0
	v_pk_add_f32 v[52:53], v[52:53], 1.0 op_sel_hi:[1, 0] neg_lo:[1, 0] neg_hi:[1, 0]
	s_nop 0
	v_pk_add_f32 v[52:53], v[52:53], 1.0 op_sel_hi:[1, 0]
	s_nop 0
	v_pk_mul_f32 v[44:45], v[44:45], v[52:53]
	v_lshlrev_b32_e32 v52, 16, v59
	v_and_b32_e32 v53, 0xffff0000, v59
	v_pk_fma_f32 v[46:47], v[186:187], v[52:53], v[46:47]
	v_cvt_pk_bf16_f32 v44, v44, v45
	v_mul_f32_e32 v52, 0x3d372713, v46
	v_mul_f32_e32 v53, 0x3d372713, v47
	v_mul_f32_e32 v52, v46, v52
	v_mul_f32_e32 v53, v47, v53
	v_fma_f32 v52, v46, v52, v46
	v_fma_f32 v53, v47, v53, v47
	v_mul_f32_e32 v52, 0x3f4c422a, v52
	v_mul_f32_e32 v53, 0x3f4c422a, v53
	v_add_f32_e32 v52, v52, v52
	v_add_f32_e32 v53, v53, v53
	v_mul_f32_e32 v52, 0x3fb8aa3b, v52
	v_mul_f32_e32 v53, 0x3fb8aa3b, v53
	v_exp_f32_e32 v52, v52
	v_exp_f32_e32 v53, v53
	v_pk_mul_f32 v[46:47], v[46:47], 0.5 op_sel_hi:[1, 0]
	v_pk_add_f32 v[52:53], v[52:53], 1.0 op_sel_hi:[1, 0]
	s_nop 0
	v_div_scale_f32 v54, s[0:1], v53, v53, 2.0
	v_rcp_f32_e32 v55, v54
	s_nop 0
	v_fma_f32 v58, -v54, v55, 1.0
	v_fmac_f32_e32 v55, v58, v55
	v_div_scale_f32 v58, vcc, 2.0, v53, 2.0
	v_mul_f32_e32 v59, v58, v55
	v_fma_f32 v60, -v54, v59, v58
	v_fmac_f32_e32 v59, v60, v55
	v_fma_f32 v54, -v54, v59, v58
	v_div_fmas_f32 v54, v54, v55, v59
	v_div_fixup_f32 v53, v54, v53, 2.0
	v_div_scale_f32 v54, s[0:1], v52, v52, 2.0
	v_rcp_f32_e32 v55, v54
	s_nop 0
	v_fma_f32 v58, -v54, v55, 1.0
	v_fmac_f32_e32 v55, v58, v55
	v_div_scale_f32 v58, vcc, 2.0, v52, 2.0
	v_mul_f32_e32 v59, v58, v55
	v_fma_f32 v60, -v54, v59, v58
	v_fmac_f32_e32 v59, v60, v55
	v_fma_f32 v54, -v54, v59, v58
	v_div_fmas_f32 v54, v54, v55, v59
	v_div_fixup_f32 v52, v54, v52, 2.0
	v_pk_add_f32 v[52:53], v[52:53], 1.0 op_sel_hi:[1, 0] neg_lo:[1, 0] neg_hi:[1, 0]
	s_nop 0
	v_pk_add_f32 v[52:53], v[52:53], 1.0 op_sel_hi:[1, 0]
	s_nop 0
	v_pk_mul_f32 v[46:47], v[46:47], v[52:53]
	s_nop 0
	v_cvt_pk_bf16_f32 v45, v46, v47
	global_store_dwordx2 v[50:51], v[44:45], off
	v_lshl_add_u64 v[44:45], s[26:27], 0, v[190:191]
	v_lshl_add_u64 v[44:45], v[44:45], 0, s[8:9]
	v_lshl_add_u64 v[44:45], v[44:45], 0, v[128:129]
	s_waitcnt vmcnt(2)
; DI float bf_lo(unsigned u) { return __uint_as_float(u << 16); }
; DI float bf_hi(unsigned u) { return __uint_as_float(u & 0xffff0000u); }
; DI float fast_exp(float x) { return __builtin_amdgcn_exp2f(x * 1.44269504089f); }
; DI float gelu_tanh(float y) {
;   const float z = 0.7978845608028654f * (y + 0.044715f * y * y * y);
;   const float e = fast_exp(2.0f * z);
;   const float th = 1.0f - 2.0f / (e + 1.0f);
;   return 0.5f * y * (1.0f + th);
; }
; DI void phase_ssm_out(const Params& p, char* lds) {
;     ...
;     epi8_iter(acc, [&](int t, int n, float a, float b, float c, float d) {
;       const int nn = nt * 256 + n, tt = nn >> 4, pp = nn & 15;
;       const size_t tok = (size_t)(ct * 256 + t) * 32 + tt;
;       const uint2 uu = *(const uint2*)(u + tok * 512 + g * 16 + pp);
;       const float4 dd = *(const float4*)(p.ssm_d + g * 16 + pp);
;       store_bf4(yg + tok * 512 + g * 16 + pp, gelu_tanh(a + dd.x * bf_lo(uu.x)), gelu_tanh(b + dd.y * bf_hi(uu.x)),
;                 gelu_tanh(c + dd.z * bf_lo(uu.y)), gelu_tanh(d + dd.w * bf_hi(uu.y)));
	v_lshlrev_b32_e32 v54, 16, v198
	v_and_b32_e32 v55, 0xffff0000, v198
	s_waitcnt vmcnt(1)
	v_pk_fma_f32 v[40:41], v[200:201], v[54:55], v[40:41]
	s_nop 0
	v_mul_f32_e32 v46, 0x3d372713, v40
	v_mul_f32_e32 v46, v40, v46
	v_fma_f32 v46, v40, v46, v40
	v_mul_f32_e32 v46, 0x3f4c422a, v46
	v_add_f32_e32 v46, v46, v46
	v_mul_f32_e32 v46, 0x3fb8aa3b, v46
	v_exp_f32_e32 v50, v46
	v_mul_f32_e32 v46, 0x3d372713, v41
	v_mul_f32_e32 v46, v41, v46
	v_fma_f32 v46, v41, v46, v41
	v_mul_f32_e32 v46, 0x3f4c422a, v46
	v_add_f32_e32 v46, v46, v46
	v_mul_f32_e32 v46, 0x3fb8aa3b, v46
	v_exp_f32_e32 v51, v46
	v_pk_mul_f32 v[40:41], v[40:41], 0.5 op_sel_hi:[1, 0]
	v_pk_add_f32 v[50:51], v[50:51], 1.0 op_sel_hi:[1, 0]
	s_nop 0
	v_div_scale_f32 v46, s[0:1], v51, v51, 2.0
	v_rcp_f32_e32 v54, v46
	s_nop 0
	v_fma_f32 v55, -v46, v54, 1.0
	v_fmac_f32_e32 v54, v55, v54
	v_div_scale_f32 v55, vcc, 2.0, v51, 2.0
	v_mul_f32_e32 v58, v55, v54
	v_fma_f32 v59, -v46, v58, v55
	v_fmac_f32_e32 v58, v59, v54
	v_fma_f32 v46, -v46, v58, v55
	v_div_fmas_f32 v46, v46, v54, v58
	v_div_fixup_f32 v51, v46, v51, 2.0
	v_div_scale_f32 v46, s[0:1], v50, v50, 2.0
	v_rcp_f32_e32 v54, v46
	s_nop 0
	v_fma_f32 v55, -v46, v54, 1.0
	v_fmac_f32_e32 v54, v55, v54
	v_div_scale_f32 v55, vcc, 2.0, v50, 2.0
	v_mul_f32_e32 v58, v55, v54
	v_fma_f32 v59, -v46, v58, v55
	v_fmac_f32_e32 v58, v59, v54
	v_fma_f32 v46, -v46, v58, v55
	v_div_fmas_f32 v46, v46, v54, v58
	v_div_fixup_f32 v50, v46, v50, 2.0
	v_lshlrev_b32_e32 v46, 16, v199
	v_and_b32_e32 v47, 0xffff0000, v199
	v_pk_fma_f32 v[42:43], v[202:203], v[46:47], v[42:43]
	v_pk_add_f32 v[50:51], v[50:51], 1.0 op_sel_hi:[1, 0] neg_lo:[1, 0] neg_hi:[1, 0]
	v_mul_f32_e32 v46, 0x3d372713, v42
	v_mul_f32_e32 v47, 0x3d372713, v43
	v_mul_f32_e32 v46, v42, v46
	v_mul_f32_e32 v47, v43, v47
	v_fma_f32 v46, v42, v46, v42
	v_fma_f32 v47, v43, v47, v43
	v_mul_f32_e32 v46, 0x3f4c422a, v46
	v_mul_f32_e32 v47, 0x3f4c422a, v47
	v_add_f32_e32 v46, v46, v46
	v_add_f32_e32 v47, v47, v47
	v_mul_f32_e32 v46, 0x3fb8aa3b, v46
	v_mul_f32_e32 v47, 0x3fb8aa3b, v47
	v_exp_f32_e32 v46, v46
	v_exp_f32_e32 v47, v47
	v_pk_add_f32 v[50:51], v[50:51], 1.0 op_sel_hi:[1, 0]
	v_pk_mul_f32 v[42:43], v[42:43], 0.5 op_sel_hi:[1, 0]
	v_pk_mul_f32 v[40:41], v[40:41], v[50:51]
	v_pk_add_f32 v[46:47], v[46:47], 1.0 op_sel_hi:[1, 0]
	v_cvt_pk_bf16_f32 v40, v40, v41
	v_div_scale_f32 v50, s[0:1], v47, v47, 2.0
	v_rcp_f32_e32 v51, v50
	s_nop 0
	v_fma_f32 v52, -v50, v51, 1.0
	v_fmac_f32_e32 v51, v52, v51
	v_div_scale_f32 v52, vcc, 2.0, v47, 2.0
	v_mul_f32_e32 v53, v52, v51
	v_fma_f32 v54, -v50, v53, v52
	v_fmac_f32_e32 v53, v54, v51
	v_fma_f32 v50, -v50, v53, v52
	v_div_fmas_f32 v50, v50, v51, v53
	v_div_fixup_f32 v47, v50, v47, 2.0
	v_div_scale_f32 v50, s[0:1], v46, v46, 2.0
	v_rcp_f32_e32 v51, v50
	s_nop 0
	v_fma_f32 v52, -v50, v51, 1.0
	v_fmac_f32_e32 v51, v52, v51
	v_div_scale_f32 v52, vcc, 2.0, v46, 2.0
	v_mul_f32_e32 v53, v52, v51
	v_fma_f32 v54, -v50, v53, v52
	v_fmac_f32_e32 v53, v54, v51
	v_fma_f32 v50, -v50, v53, v52
	v_div_fmas_f32 v50, v50, v51, v53
	v_div_fixup_f32 v46, v50, v46, 2.0
	v_pk_add_f32 v[46:47], v[46:47], 1.0 op_sel_hi:[1, 0] neg_lo:[1, 0] neg_hi:[1, 0]
	s_nop 0
	v_pk_add_f32 v[46:47], v[46:47], 1.0 op_sel_hi:[1, 0]
	s_nop 0
	v_pk_mul_f32 v[42:43], v[42:43], v[46:47]
	s_nop 0
	v_cvt_pk_bf16_f32 v41, v42, v43
	global_store_dwordx2 v[44:45], v[40:41], off
	v_add_u32_e32 v40, 0xb0, v136
	v_ashrrev_i32_e32 v40, 4, v40
	v_ashrrev_i32_e32 v41, 31, v40
	v_lshlrev_b64 v[40:41], 9, v[40:41]
	v_lshl_add_u64 v[42:43], v[40:41], 0, v[152:153]
	v_lshlrev_b64 v[42:43], 1, v[42:43]
	v_lshl_add_u64 v[44:45], s[36:37], 0, v[42:43]
	v_lshl_add_u64 v[44:45], v[44:45], 0, s[8:9]
	v_lshl_add_u64 v[44:45], v[44:45], 0, v[128:129]
	global_load_dwordx2 v[50:51], v[44:45], off
	global_load_dwordx4 v[216:219], v172, s[80:81]
	v_mov_b32_e32 v212, v173
	v_mov_b32_e32 v213, v176
	v_lshl_add_u64 v[220:221], v[40:41], 0, v[212:213]
	v_lshlrev_b64 v[224:225], 1, v[220:221]
	v_lshl_add_u64 v[226:227], s[36:37], 0, v[224:225]
	v_lshl_add_u64 v[228:229], v[226:227], 0, s[8:9]
	v_lshl_add_u64 v[230:231], v[228:229], 0, v[128:129]
	global_load_dwordx2 v[236:237], v[230:231], off
	global_load_dwordx4 v[244:247], v172, s[80:81]
	v_lshl_add_u64 v[42:43], s[26:27], 0, v[42:43]
	v_lshl_add_u64 v[42:43], v[42:43], 0, s[8:9]
	v_lshl_add_u64 v[42:43], v[42:43], 0, v[128:129]
	s_waitcnt vmcnt(3)
	v_lshlrev_b32_e32 v52, 16, v50
	v_and_b32_e32 v53, 0xffff0000, v50
	s_waitcnt vmcnt(2)
; DI float bf_lo(unsigned u) { return __uint_as_float(u << 16); }
; DI float bf_hi(unsigned u) { return __uint_as_float(u & 0xffff0000u); }
; DI float fast_exp(float x) { return __builtin_amdgcn_exp2f(x * 1.44269504089f); }
; DI float gelu_tanh(float y) {
;   const float z = 0.7978845608028654f * (y + 0.044715f * y * y * y);
;   const float e = fast_exp(2.0f * z);
;   const float th = 1.0f - 2.0f / (e + 1.0f);
;   return 0.5f * y * (1.0f + th);
; }
; DI void phase_ssm_out(const Params& p, char* lds) {
;     ...
;     epi8_iter(acc, [&](int t, int n, float a, float b, float c, float d) {
;       const int nn = nt * 256 + n, tt = nn >> 4, pp = nn & 15;
;       const size_t tok = (size_t)(ct * 256 + t) * 32 + tt;
;       const uint2 uu = *(const uint2*)(u + tok * 512 + g * 16 + pp);
;       const float4 dd = *(const float4*)(p.ssm_d + g * 16 + pp);
;       store_bf4(yg + tok * 512 + g * 16 + pp, gelu_tanh(a + dd.x * bf_lo(uu.x)), gelu_tanh(b + dd.y * bf_hi(uu.x)),
;                 gelu_tanh(c + dd.z * bf_lo(uu.y)), gelu_tanh(d + dd.w * bf_hi(uu.y)));
	v_pk_fma_f32 v[36:37], v[216:217], v[52:53], v[36:37]
	s_nop 0
	v_mul_f32_e32 v44, 0x3d372713, v36
	v_mul_f32_e32 v45, 0x3d372713, v37
	v_mul_f32_e32 v44, v36, v44
	v_mul_f32_e32 v45, v37, v45
	v_fma_f32 v44, v36, v44, v36
	v_fma_f32 v45, v37, v45, v37
	v_mul_f32_e32 v44, 0x3f4c422a, v44
	v_mul_f32_e32 v45, 0x3f4c422a, v45
	v_add_f32_e32 v44, v44, v44
	v_add_f32_e32 v45, v45, v45
	v_mul_f32_e32 v44, 0x3fb8aa3b, v44
	v_mul_f32_e32 v45, 0x3fb8aa3b, v45
	v_exp_f32_e32 v44, v44
	v_exp_f32_e32 v45, v45
	v_pk_mul_f32 v[36:37], v[36:37], 0.5 op_sel_hi:[1, 0]
	v_pk_add_f32 v[44:45], v[44:45], 1.0 op_sel_hi:[1, 0]
	s_nop 0
	v_div_scale_f32 v50, s[0:1], v45, v45, 2.0
	v_rcp_f32_e32 v52, v50
	s_nop 0
	v_fma_f32 v53, -v50, v52, 1.0
	v_fmac_f32_e32 v52, v53, v52
	v_div_scale_f32 v53, vcc, 2.0, v45, 2.0
	v_mul_f32_e32 v54, v53, v52
	v_fma_f32 v55, -v50, v54, v53
	v_fmac_f32_e32 v54, v55, v52
	v_fma_f32 v50, -v50, v54, v53
	v_div_fmas_f32 v50, v50, v52, v54
	v_div_fixup_f32 v45, v50, v45, 2.0
	v_div_scale_f32 v50, s[0:1], v44, v44, 2.0
	v_rcp_f32_e32 v52, v50
	s_nop 0
	v_fma_f32 v53, -v50, v52, 1.0
	v_fmac_f32_e32 v52, v53, v52
	v_div_scale_f32 v53, vcc, 2.0, v44, 2.0
	v_mul_f32_e32 v54, v53, v52
	v_fma_f32 v55, -v50, v54, v53
	v_fmac_f32_e32 v54, v55, v52
	v_fma_f32 v50, -v50, v54, v53
	v_div_fmas_f32 v50, v50, v52, v54
	v_div_fixup_f32 v44, v50, v44, 2.0
	v_pk_add_f32 v[44:45], v[44:45], 1.0 op_sel_hi:[1, 0] neg_lo:[1, 0] neg_hi:[1, 0]
	s_nop 0
	v_pk_add_f32 v[44:45], v[44:45], 1.0 op_sel_hi:[1, 0]
	s_nop 0
	v_pk_mul_f32 v[36:37], v[36:37], v[44:45]
	v_lshlrev_b32_e32 v44, 16, v51
	v_and_b32_e32 v45, 0xffff0000, v51
	v_pk_fma_f32 v[38:39], v[218:219], v[44:45], v[38:39]
	v_cvt_pk_bf16_f32 v36, v36, v37
	v_mul_f32_e32 v44, 0x3d372713, v38
	v_mul_f32_e32 v45, 0x3d372713, v39
	v_mul_f32_e32 v44, v38, v44
	v_mul_f32_e32 v45, v39, v45
	v_fma_f32 v44, v38, v44, v38
	v_fma_f32 v45, v39, v45, v39
	v_mul_f32_e32 v44, 0x3f4c422a, v44
	v_mul_f32_e32 v45, 0x3f4c422a, v45
	v_add_f32_e32 v44, v44, v44
	v_add_f32_e32 v45, v45, v45
	v_mul_f32_e32 v44, 0x3fb8aa3b, v44
	v_mul_f32_e32 v45, 0x3fb8aa3b, v45
	v_exp_f32_e32 v44, v44
	v_exp_f32_e32 v45, v45
	v_pk_mul_f32 v[38:39], v[38:39], 0.5 op_sel_hi:[1, 0]
	v_pk_add_f32 v[44:45], v[44:45], 1.0 op_sel_hi:[1, 0]
	s_nop 0
	v_div_scale_f32 v46, s[0:1], v45, v45, 2.0
	v_rcp_f32_e32 v47, v46
	s_nop 0
	v_fma_f32 v50, -v46, v47, 1.0
	v_fmac_f32_e32 v47, v50, v47
	v_div_scale_f32 v50, vcc, 2.0, v45, 2.0
	v_mul_f32_e32 v51, v50, v47
	v_fma_f32 v52, -v46, v51, v50
	v_fmac_f32_e32 v51, v52, v47
	v_fma_f32 v46, -v46, v51, v50
	v_div_fmas_f32 v46, v46, v47, v51
	v_div_fixup_f32 v45, v46, v45, 2.0
	v_div_scale_f32 v46, s[0:1], v44, v44, 2.0
	v_rcp_f32_e32 v47, v46
	s_nop 0
	v_fma_f32 v50, -v46, v47, 1.0
	v_fmac_f32_e32 v47, v50, v47
	v_div_scale_f32 v50, vcc, 2.0, v44, 2.0
	v_mul_f32_e32 v51, v50, v47
	v_fma_f32 v52, -v46, v51, v50
	v_fmac_f32_e32 v51, v52, v47
	v_fma_f32 v46, -v46, v51, v50
	v_div_fmas_f32 v46, v46, v47, v51
	v_div_fixup_f32 v44, v46, v44, 2.0
	v_pk_add_f32 v[44:45], v[44:45], 1.0 op_sel_hi:[1, 0] neg_lo:[1, 0] neg_hi:[1, 0]
	s_nop 0
	v_pk_add_f32 v[44:45], v[44:45], 1.0 op_sel_hi:[1, 0]
	s_nop 0
	v_pk_mul_f32 v[38:39], v[38:39], v[44:45]
	s_nop 0
	v_cvt_pk_bf16_f32 v37, v38, v39
	global_store_dwordx2 v[42:43], v[36:37], off
	v_lshl_add_u64 v[36:37], s[26:27], 0, v[224:225]
	v_lshl_add_u64 v[36:37], v[36:37], 0, s[8:9]
	v_lshl_add_u64 v[36:37], v[36:37], 0, v[128:129]
	s_waitcnt vmcnt(2)
	v_lshlrev_b32_e32 v46, 16, v236
	v_and_b32_e32 v47, 0xffff0000, v236
	s_waitcnt vmcnt(1)
	v_pk_fma_f32 v[32:33], v[244:245], v[46:47], v[32:33]
	s_nop 0
	v_mul_f32_e32 v38, 0x3d372713, v32
	v_mul_f32_e32 v38, v32, v38
	v_fma_f32 v38, v32, v38, v32
	v_mul_f32_e32 v38, 0x3f4c422a, v38
	v_add_f32_e32 v38, v38, v38
	v_mul_f32_e32 v38, 0x3fb8aa3b, v38
	v_exp_f32_e32 v42, v38
	v_mul_f32_e32 v38, 0x3d372713, v33
	v_mul_f32_e32 v38, v33, v38
	v_fma_f32 v38, v33, v38, v33
	v_mul_f32_e32 v38, 0x3f4c422a, v38
	v_add_f32_e32 v38, v38, v38
	v_mul_f32_e32 v38, 0x3fb8aa3b, v38
	v_exp_f32_e32 v43, v38
	v_pk_mul_f32 v[32:33], v[32:33], 0.5 op_sel_hi:[1, 0]
	v_pk_add_f32 v[42:43], v[42:43], 1.0 op_sel_hi:[1, 0]
	s_nop 0
	v_div_scale_f32 v38, s[0:1], v43, v43, 2.0
	v_rcp_f32_e32 v46, v38
	s_nop 0
	v_fma_f32 v47, -v38, v46, 1.0
	v_fmac_f32_e32 v46, v47, v46
	v_div_scale_f32 v47, vcc, 2.0, v43, 2.0
	v_mul_f32_e32 v50, v47, v46
	v_fma_f32 v51, -v38, v50, v47
	v_fmac_f32_e32 v50, v51, v46
	v_fma_f32 v38, -v38, v50, v47
	v_div_fmas_f32 v38, v38, v46, v50
	v_div_fixup_f32 v43, v38, v43, 2.0
	v_div_scale_f32 v38, s[0:1], v42, v42, 2.0
	v_rcp_f32_e32 v46, v38
	s_nop 0
	v_fma_f32 v47, -v38, v46, 1.0
	v_fmac_f32_e32 v46, v47, v46
	v_div_scale_f32 v47, vcc, 2.0, v42, 2.0
	v_mul_f32_e32 v50, v47, v46
	v_fma_f32 v51, -v38, v50, v47
	v_fmac_f32_e32 v50, v51, v46
	v_fma_f32 v38, -v38, v50, v47
	v_div_fmas_f32 v38, v38, v46, v50
	v_div_fixup_f32 v42, v38, v42, 2.0
	v_lshlrev_b32_e32 v38, 16, v237
	v_and_b32_e32 v39, 0xffff0000, v237
	v_pk_fma_f32 v[34:35], v[246:247], v[38:39], v[34:35]
	v_pk_add_f32 v[42:43], v[42:43], 1.0 op_sel_hi:[1, 0] neg_lo:[1, 0] neg_hi:[1, 0]
	v_mul_f32_e32 v38, 0x3d372713, v34
	v_mul_f32_e32 v39, 0x3d372713, v35
	v_mul_f32_e32 v38, v34, v38
	v_mul_f32_e32 v39, v35, v39
	v_fma_f32 v38, v34, v38, v34
	v_fma_f32 v39, v35, v39, v35
	v_mul_f32_e32 v38, 0x3f4c422a, v38
	v_mul_f32_e32 v39, 0x3f4c422a, v39
	v_add_f32_e32 v38, v38, v38
	v_add_f32_e32 v39, v39, v39
	v_mul_f32_e32 v38, 0x3fb8aa3b, v38
	v_mul_f32_e32 v39, 0x3fb8aa3b, v39
	v_exp_f32_e32 v38, v38
	v_exp_f32_e32 v39, v39
	v_pk_add_f32 v[42:43], v[42:43], 1.0 op_sel_hi:[1, 0]
; DI float bf_lo(unsigned u) { return __uint_as_float(u << 16); }
; DI float bf_hi(unsigned u) { return __uint_as_float(u & 0xffff0000u); }
; DI float fast_exp(float x) { return __builtin_amdgcn_exp2f(x * 1.44269504089f); }
; DI float gelu_tanh(float y) {
;   const float z = 0.7978845608028654f * (y + 0.044715f * y * y * y);
;   const float e = fast_exp(2.0f * z);
;   const float th = 1.0f - 2.0f / (e + 1.0f);
;   return 0.5f * y * (1.0f + th);
; }
; DI void phase_ssm_out(const Params& p, char* lds) {
;     ...
;     epi8_iter(acc, [&](int t, int n, float a, float b, float c, float d) {
;       const int nn = nt * 256 + n, tt = nn >> 4, pp = nn & 15;
;       const size_t tok = (size_t)(ct * 256 + t) * 32 + tt;
;       const uint2 uu = *(const uint2*)(u + tok * 512 + g * 16 + pp);
;       const float4 dd = *(const float4*)(p.ssm_d + g * 16 + pp);
;       store_bf4(yg + tok * 512 + g * 16 + pp, gelu_tanh(a + dd.x * bf_lo(uu.x)), gelu_tanh(b + dd.y * bf_hi(uu.x)),
;                 gelu_tanh(c + dd.z * bf_lo(uu.y)), gelu_tanh(d + dd.w * bf_hi(uu.y)));
	v_pk_mul_f32 v[34:35], v[34:35], 0.5 op_sel_hi:[1, 0]
	v_pk_mul_f32 v[32:33], v[32:33], v[42:43]
	v_pk_add_f32 v[38:39], v[38:39], 1.0 op_sel_hi:[1, 0]
	v_cvt_pk_bf16_f32 v32, v32, v33
	v_div_scale_f32 v42, s[0:1], v39, v39, 2.0
	v_rcp_f32_e32 v43, v42
	s_nop 0
	v_fma_f32 v44, -v42, v43, 1.0
	v_fmac_f32_e32 v43, v44, v43
	v_div_scale_f32 v44, vcc, 2.0, v39, 2.0
	v_mul_f32_e32 v45, v44, v43
	v_fma_f32 v46, -v42, v45, v44
	v_fmac_f32_e32 v45, v46, v43
	v_fma_f32 v42, -v42, v45, v44
	v_div_fmas_f32 v42, v42, v43, v45
	v_div_fixup_f32 v39, v42, v39, 2.0
	v_div_scale_f32 v42, s[0:1], v38, v38, 2.0
	v_rcp_f32_e32 v43, v42
	s_nop 0
	v_fma_f32 v44, -v42, v43, 1.0
	v_fmac_f32_e32 v43, v44, v43
	v_div_scale_f32 v44, vcc, 2.0, v38, 2.0
	v_mul_f32_e32 v45, v44, v43
	v_fma_f32 v46, -v42, v45, v44
	v_fmac_f32_e32 v45, v46, v43
	v_fma_f32 v42, -v42, v45, v44
	v_div_fmas_f32 v42, v42, v43, v45
	v_div_fixup_f32 v38, v42, v38, 2.0
	v_pk_add_f32 v[38:39], v[38:39], 1.0 op_sel_hi:[1, 0] neg_lo:[1, 0] neg_hi:[1, 0]
	s_nop 0
	v_pk_add_f32 v[38:39], v[38:39], 1.0 op_sel_hi:[1, 0]
	s_nop 0
	v_pk_mul_f32 v[34:35], v[34:35], v[38:39]
	s_nop 0
	v_cvt_pk_bf16_f32 v33, v34, v35
	global_store_dwordx2 v[36:37], v[32:33], off
	v_lshl_add_u64 v[32:33], v[64:65], 0, v[96:97]
	v_lshlrev_b64 v[32:33], 1, v[32:33]
	v_lshl_add_u64 v[34:35], s[36:37], 0, v[32:33]
	v_lshl_add_u64 v[34:35], v[34:35], 0, s[8:9]
	v_lshl_add_u64 v[34:35], v[34:35], 0, v[128:129]
	global_load_dwordx2 v[38:39], v[34:35], off
	global_load_dwordx4 v[184:187], v172, s[80:81]
	v_mov_b32_e32 v182, v177
	v_mov_b32_e32 v183, v178
	v_lshl_add_u64 v[188:189], v[64:65], 0, v[182:183]
	v_lshlrev_b64 v[190:191], 1, v[188:189]
	v_lshl_add_u64 v[192:193], s[36:37], 0, v[190:191]
	v_lshl_add_u64 v[194:195], v[192:193], 0, s[8:9]
	v_lshl_add_u64 v[196:197], v[194:195], 0, v[128:129]
	global_load_dwordx2 v[198:199], v[196:197], off
	global_load_dwordx4 v[200:203], v172, s[80:81]
	v_lshl_add_u64 v[32:33], s[26:27], 0, v[32:33]
	v_lshl_add_u64 v[32:33], v[32:33], 0, s[8:9]
	v_lshl_add_u64 v[32:33], v[32:33], 0, v[128:129]
	s_waitcnt vmcnt(3)
	v_lshlrev_b32_e32 v42, 16, v38
	v_and_b32_e32 v43, 0xffff0000, v38
	s_waitcnt vmcnt(2)
	v_pk_fma_f32 v[28:29], v[184:185], v[42:43], v[28:29]
	s_nop 0
	v_mul_f32_e32 v34, 0x3d372713, v28
	v_mul_f32_e32 v35, 0x3d372713, v29
	v_mul_f32_e32 v34, v28, v34
	v_mul_f32_e32 v35, v29, v35
	v_fma_f32 v34, v28, v34, v28
	v_fma_f32 v35, v29, v35, v29
	v_mul_f32_e32 v34, 0x3f4c422a, v34
	v_mul_f32_e32 v35, 0x3f4c422a, v35
	v_add_f32_e32 v34, v34, v34
	v_add_f32_e32 v35, v35, v35
	v_mul_f32_e32 v34, 0x3fb8aa3b, v34
	v_mul_f32_e32 v35, 0x3fb8aa3b, v35
	v_exp_f32_e32 v34, v34
	v_exp_f32_e32 v35, v35
	v_pk_mul_f32 v[28:29], v[28:29], 0.5 op_sel_hi:[1, 0]
	v_pk_add_f32 v[34:35], v[34:35], 1.0 op_sel_hi:[1, 0]
	s_nop 0
	v_div_scale_f32 v38, s[0:1], v35, v35, 2.0
	v_rcp_f32_e32 v42, v38
	s_nop 0
	v_fma_f32 v43, -v38, v42, 1.0
	v_fmac_f32_e32 v42, v43, v42
	v_div_scale_f32 v43, vcc, 2.0, v35, 2.0
	v_mul_f32_e32 v44, v43, v42
	v_fma_f32 v45, -v38, v44, v43
	v_fmac_f32_e32 v44, v45, v42
	v_fma_f32 v38, -v38, v44, v43
	v_div_fmas_f32 v38, v38, v42, v44
	v_div_fixup_f32 v35, v38, v35, 2.0
	v_div_scale_f32 v38, s[0:1], v34, v34, 2.0
	v_rcp_f32_e32 v42, v38
	s_nop 0
	v_fma_f32 v43, -v38, v42, 1.0
	v_fmac_f32_e32 v42, v43, v42
	v_div_scale_f32 v43, vcc, 2.0, v34, 2.0
	v_mul_f32_e32 v44, v43, v42
	v_fma_f32 v45, -v38, v44, v43
	v_fmac_f32_e32 v44, v45, v42
	v_fma_f32 v38, -v38, v44, v43
	v_div_fmas_f32 v38, v38, v42, v44
	v_div_fixup_f32 v34, v38, v34, 2.0
	v_pk_add_f32 v[34:35], v[34:35], 1.0 op_sel_hi:[1, 0] neg_lo:[1, 0] neg_hi:[1, 0]
	s_nop 0
	v_pk_add_f32 v[34:35], v[34:35], 1.0 op_sel_hi:[1, 0]
	s_nop 0
	v_pk_mul_f32 v[28:29], v[28:29], v[34:35]
	v_lshlrev_b32_e32 v34, 16, v39
	v_and_b32_e32 v35, 0xffff0000, v39
	v_pk_fma_f32 v[30:31], v[186:187], v[34:35], v[30:31]
	v_cvt_pk_bf16_f32 v28, v28, v29
	v_mul_f32_e32 v34, 0x3d372713, v30
	v_mul_f32_e32 v35, 0x3d372713, v31
	v_mul_f32_e32 v34, v30, v34
	v_mul_f32_e32 v35, v31, v35
	v_fma_f32 v34, v30, v34, v30
	v_fma_f32 v35, v31, v35, v31
	v_mul_f32_e32 v34, 0x3f4c422a, v34
	v_mul_f32_e32 v35, 0x3f4c422a, v35
	v_add_f32_e32 v34, v34, v34
	v_add_f32_e32 v35, v35, v35
	v_mul_f32_e32 v34, 0x3fb8aa3b, v34
	v_mul_f32_e32 v35, 0x3fb8aa3b, v35
	v_exp_f32_e32 v34, v34
	v_exp_f32_e32 v35, v35
	v_pk_mul_f32 v[30:31], v[30:31], 0.5 op_sel_hi:[1, 0]
	v_pk_add_f32 v[34:35], v[34:35], 1.0 op_sel_hi:[1, 0]
	s_nop 0
	v_div_scale_f32 v36, s[0:1], v35, v35, 2.0
	v_rcp_f32_e32 v37, v36
	s_nop 0
	v_fma_f32 v38, -v36, v37, 1.0
	v_fmac_f32_e32 v37, v38, v37
	v_div_scale_f32 v38, vcc, 2.0, v35, 2.0
	v_mul_f32_e32 v39, v38, v37
	v_fma_f32 v42, -v36, v39, v38
	v_fmac_f32_e32 v39, v42, v37
	v_fma_f32 v36, -v36, v39, v38
	v_div_fmas_f32 v36, v36, v37, v39
	v_div_fixup_f32 v35, v36, v35, 2.0
	v_div_scale_f32 v36, s[0:1], v34, v34, 2.0
	v_rcp_f32_e32 v37, v36
	s_nop 0
	v_fma_f32 v38, -v36, v37, 1.0
	v_fmac_f32_e32 v37, v38, v37
	v_div_scale_f32 v38, vcc, 2.0, v34, 2.0
	v_mul_f32_e32 v39, v38, v37
	v_fma_f32 v42, -v36, v39, v38
	v_fmac_f32_e32 v39, v42, v37
	v_fma_f32 v36, -v36, v39, v38
	v_div_fmas_f32 v36, v36, v37, v39
	v_div_fixup_f32 v34, v36, v34, 2.0
	v_pk_add_f32 v[34:35], v[34:35], 1.0 op_sel_hi:[1, 0] neg_lo:[1, 0] neg_hi:[1, 0]
	s_nop 0
	v_pk_add_f32 v[34:35], v[34:35], 1.0 op_sel_hi:[1, 0]
	s_nop 0
	v_pk_mul_f32 v[30:31], v[30:31], v[34:35]
	s_nop 0
	v_cvt_pk_bf16_f32 v29, v30, v31
	global_store_dwordx2 v[32:33], v[28:29], off
	v_lshl_add_u64 v[28:29], s[26:27], 0, v[190:191]
	v_lshl_add_u64 v[28:29], v[28:29], 0, s[8:9]
	v_lshl_add_u64 v[28:29], v[28:29], 0, v[128:129]
	s_waitcnt vmcnt(2)
; DI float bf_lo(unsigned u) { return __uint_as_float(u << 16); }
; DI float bf_hi(unsigned u) { return __uint_as_float(u & 0xffff0000u); }
; DI float fast_exp(float x) { return __builtin_amdgcn_exp2f(x * 1.44269504089f); }
; DI float gelu_tanh(float y) {
;   const float z = 0.7978845608028654f * (y + 0.044715f * y * y * y);
;   const float e = fast_exp(2.0f * z);
;   const float th = 1.0f - 2.0f / (e + 1.0f);
;   return 0.5f * y * (1.0f + th);
; }
; DI void phase_ssm_out(const Params& p, char* lds) {
;     ...
;     epi8_iter(acc, [&](int t, int n, float a, float b, float c, float d) {
;       const int nn = nt * 256 + n, tt = nn >> 4, pp = nn & 15;
;       const size_t tok = (size_t)(ct * 256 + t) * 32 + tt;
;       const uint2 uu = *(const uint2*)(u + tok * 512 + g * 16 + pp);
;       const float4 dd = *(const float4*)(p.ssm_d + g * 16 + pp);
;       store_bf4(yg + tok * 512 + g * 16 + pp, gelu_tanh(a + dd.x * bf_lo(uu.x)), gelu_tanh(b + dd.y * bf_hi(uu.x)),
;                 gelu_tanh(c + dd.z * bf_lo(uu.y)), gelu_tanh(d + dd.w * bf_hi(uu.y)));
	v_lshlrev_b32_e32 v36, 16, v198
	v_and_b32_e32 v37, 0xffff0000, v198
	s_waitcnt vmcnt(1)
	v_pk_fma_f32 v[24:25], v[200:201], v[36:37], v[24:25]
	s_nop 0
	v_mul_f32_e32 v30, 0x3d372713, v24
	v_mul_f32_e32 v31, 0x3d372713, v25
	v_mul_f32_e32 v30, v24, v30
	v_mul_f32_e32 v31, v25, v31
	v_fma_f32 v30, v24, v30, v24
	v_fma_f32 v31, v25, v31, v25
	v_mul_f32_e32 v30, 0x3f4c422a, v30
	v_mul_f32_e32 v31, 0x3f4c422a, v31
	v_add_f32_e32 v30, v30, v30
	v_add_f32_e32 v31, v31, v31
	v_mul_f32_e32 v30, 0x3fb8aa3b, v30
	v_mul_f32_e32 v31, 0x3fb8aa3b, v31
	v_exp_f32_e32 v30, v30
	v_exp_f32_e32 v31, v31
	v_pk_mul_f32 v[24:25], v[24:25], 0.5 op_sel_hi:[1, 0]
	v_pk_add_f32 v[30:31], v[30:31], 1.0 op_sel_hi:[1, 0]
	s_nop 0
	v_div_scale_f32 v34, s[0:1], v31, v31, 2.0
	v_rcp_f32_e32 v36, v34
	s_nop 0
	v_fma_f32 v37, -v34, v36, 1.0
	v_fmac_f32_e32 v36, v37, v36
	v_div_scale_f32 v37, vcc, 2.0, v31, 2.0
	v_mul_f32_e32 v38, v37, v36
	v_fma_f32 v39, -v34, v38, v37
	v_fmac_f32_e32 v38, v39, v36
	v_fma_f32 v34, -v34, v38, v37
	v_div_fmas_f32 v34, v34, v36, v38
	v_div_fixup_f32 v31, v34, v31, 2.0
	v_div_scale_f32 v34, s[0:1], v30, v30, 2.0
	v_rcp_f32_e32 v36, v34
	s_nop 0
	v_fma_f32 v37, -v34, v36, 1.0
	v_fmac_f32_e32 v36, v37, v36
	v_div_scale_f32 v37, vcc, 2.0, v30, 2.0
	v_mul_f32_e32 v38, v37, v36
	v_fma_f32 v39, -v34, v38, v37
	v_fmac_f32_e32 v38, v39, v36
	v_fma_f32 v34, -v34, v38, v37
	v_div_fmas_f32 v34, v34, v36, v38
	v_div_fixup_f32 v30, v34, v30, 2.0
	v_pk_add_f32 v[30:31], v[30:31], 1.0 op_sel_hi:[1, 0] neg_lo:[1, 0] neg_hi:[1, 0]
	s_nop 0
	v_pk_add_f32 v[30:31], v[30:31], 1.0 op_sel_hi:[1, 0]
	s_nop 0
	v_pk_mul_f32 v[24:25], v[24:25], v[30:31]
	v_lshlrev_b32_e32 v30, 16, v199
	v_and_b32_e32 v31, 0xffff0000, v199
	v_pk_fma_f32 v[26:27], v[202:203], v[30:31], v[26:27]
	v_cvt_pk_bf16_f32 v24, v24, v25
	v_mul_f32_e32 v30, 0x3d372713, v26
	v_mul_f32_e32 v31, 0x3d372713, v27
	v_mul_f32_e32 v30, v26, v30
	v_mul_f32_e32 v31, v27, v31
	v_fma_f32 v30, v26, v30, v26
	v_fma_f32 v31, v27, v31, v27
	v_mul_f32_e32 v30, 0x3f4c422a, v30
	v_mul_f32_e32 v31, 0x3f4c422a, v31
	v_add_f32_e32 v30, v30, v30
	v_add_f32_e32 v31, v31, v31
	v_mul_f32_e32 v30, 0x3fb8aa3b, v30
	v_mul_f32_e32 v31, 0x3fb8aa3b, v31
	v_exp_f32_e32 v30, v30
	v_exp_f32_e32 v31, v31
	v_pk_mul_f32 v[26:27], v[26:27], 0.5 op_sel_hi:[1, 0]
	v_pk_add_f32 v[30:31], v[30:31], 1.0 op_sel_hi:[1, 0]
	s_nop 0
	v_div_scale_f32 v32, s[0:1], v31, v31, 2.0
	v_rcp_f32_e32 v33, v32
	s_nop 0
	v_fma_f32 v34, -v32, v33, 1.0
	v_fmac_f32_e32 v33, v34, v33
	v_div_scale_f32 v34, vcc, 2.0, v31, 2.0
	v_mul_f32_e32 v35, v34, v33
	v_fma_f32 v36, -v32, v35, v34
	v_fmac_f32_e32 v35, v36, v33
	v_fma_f32 v32, -v32, v35, v34
	v_div_fmas_f32 v32, v32, v33, v35
	v_div_fixup_f32 v31, v32, v31, 2.0
	v_div_scale_f32 v32, s[0:1], v30, v30, 2.0
	v_rcp_f32_e32 v33, v32
	s_nop 0
	v_fma_f32 v34, -v32, v33, 1.0
	v_fmac_f32_e32 v33, v34, v33
	v_div_scale_f32 v34, vcc, 2.0, v30, 2.0
	v_mul_f32_e32 v35, v34, v33
	v_fma_f32 v36, -v32, v35, v34
	v_fmac_f32_e32 v35, v36, v33
	v_fma_f32 v32, -v32, v35, v34
	v_div_fmas_f32 v32, v32, v33, v35
	v_div_fixup_f32 v30, v32, v30, 2.0
	v_pk_add_f32 v[30:31], v[30:31], 1.0 op_sel_hi:[1, 0] neg_lo:[1, 0] neg_hi:[1, 0]
	s_nop 0
	v_pk_add_f32 v[30:31], v[30:31], 1.0 op_sel_hi:[1, 0]
	s_nop 0
	v_pk_mul_f32 v[26:27], v[26:27], v[30:31]
	s_nop 0
	v_cvt_pk_bf16_f32 v25, v26, v27
	global_store_dwordx2 v[28:29], v[24:25], off
	v_lshl_add_u64 v[24:25], v[56:57], 0, v[96:97]
	v_lshlrev_b64 v[24:25], 1, v[24:25]
	v_lshl_add_u64 v[26:27], s[36:37], 0, v[24:25]
	v_lshl_add_u64 v[26:27], v[26:27], 0, s[8:9]
	v_lshl_add_u64 v[26:27], v[26:27], 0, v[128:129]
	global_load_dwordx2 v[30:31], v[26:27], off
	global_load_dwordx4 v[216:219], v172, s[80:81]
	v_mov_b32_e32 v212, v177
	v_mov_b32_e32 v213, v178
	v_lshl_add_u64 v[220:221], v[56:57], 0, v[212:213]
	v_lshlrev_b64 v[224:225], 1, v[220:221]
	v_lshl_add_u64 v[226:227], s[36:37], 0, v[224:225]
	v_lshl_add_u64 v[228:229], v[226:227], 0, s[8:9]
	v_lshl_add_u64 v[230:231], v[228:229], 0, v[128:129]
	global_load_dwordx2 v[236:237], v[230:231], off
	global_load_dwordx4 v[244:247], v172, s[80:81]
	v_lshl_add_u64 v[24:25], s[26:27], 0, v[24:25]
	v_lshl_add_u64 v[24:25], v[24:25], 0, s[8:9]
	v_lshl_add_u64 v[24:25], v[24:25], 0, v[128:129]
	s_waitcnt vmcnt(3)
	v_lshlrev_b32_e32 v32, 16, v30
	v_and_b32_e32 v33, 0xffff0000, v30
	s_waitcnt vmcnt(2)
; DI float bf_lo(unsigned u) { return __uint_as_float(u << 16); }
; DI float bf_hi(unsigned u) { return __uint_as_float(u & 0xffff0000u); }
; DI float fast_exp(float x) { return __builtin_amdgcn_exp2f(x * 1.44269504089f); }
; DI float gelu_tanh(float y) {
;   const float z = 0.7978845608028654f * (y + 0.044715f * y * y * y);
;   const float e = fast_exp(2.0f * z);
;   const float th = 1.0f - 2.0f / (e + 1.0f);
;   return 0.5f * y * (1.0f + th);
; }
; DI void phase_ssm_out(const Params& p, char* lds) {
;     ...
;     epi8_iter(acc, [&](int t, int n, float a, float b, float c, float d) {
;       const int nn = nt * 256 + n, tt = nn >> 4, pp = nn & 15;
;       const size_t tok = (size_t)(ct * 256 + t) * 32 + tt;
;       const uint2 uu = *(const uint2*)(u + tok * 512 + g * 16 + pp);
;       const float4 dd = *(const float4*)(p.ssm_d + g * 16 + pp);
;       store_bf4(yg + tok * 512 + g * 16 + pp, gelu_tanh(a + dd.x * bf_lo(uu.x)), gelu_tanh(b + dd.y * bf_hi(uu.x)),
;                 gelu_tanh(c + dd.z * bf_lo(uu.y)), gelu_tanh(d + dd.w * bf_hi(uu.y)));
	v_pk_fma_f32 v[20:21], v[216:217], v[32:33], v[20:21]
	s_nop 0
	v_mul_f32_e32 v26, 0x3d372713, v20
	v_mul_f32_e32 v27, 0x3d372713, v21
	v_mul_f32_e32 v26, v20, v26
	v_mul_f32_e32 v27, v21, v27
	v_fma_f32 v26, v20, v26, v20
	v_fma_f32 v27, v21, v27, v21
	v_mul_f32_e32 v26, 0x3f4c422a, v26
	v_mul_f32_e32 v27, 0x3f4c422a, v27
	v_add_f32_e32 v26, v26, v26
	v_add_f32_e32 v27, v27, v27
	v_mul_f32_e32 v26, 0x3fb8aa3b, v26
	v_mul_f32_e32 v27, 0x3fb8aa3b, v27
	v_exp_f32_e32 v26, v26
	v_exp_f32_e32 v27, v27
	v_pk_mul_f32 v[20:21], v[20:21], 0.5 op_sel_hi:[1, 0]
	v_pk_add_f32 v[26:27], v[26:27], 1.0 op_sel_hi:[1, 0]
	s_nop 0
	v_div_scale_f32 v30, s[0:1], v27, v27, 2.0
	v_rcp_f32_e32 v32, v30
	s_nop 0
	v_fma_f32 v33, -v30, v32, 1.0
	v_fmac_f32_e32 v32, v33, v32
	v_div_scale_f32 v33, vcc, 2.0, v27, 2.0
	v_mul_f32_e32 v34, v33, v32
	v_fma_f32 v35, -v30, v34, v33
	v_fmac_f32_e32 v34, v35, v32
	v_fma_f32 v30, -v30, v34, v33
	v_div_fmas_f32 v30, v30, v32, v34
	v_div_fixup_f32 v27, v30, v27, 2.0
	v_div_scale_f32 v30, s[0:1], v26, v26, 2.0
	v_rcp_f32_e32 v32, v30
	s_nop 0
	v_fma_f32 v33, -v30, v32, 1.0
	v_fmac_f32_e32 v32, v33, v32
	v_div_scale_f32 v33, vcc, 2.0, v26, 2.0
	v_mul_f32_e32 v34, v33, v32
	v_fma_f32 v35, -v30, v34, v33
	v_fmac_f32_e32 v34, v35, v32
	v_fma_f32 v30, -v30, v34, v33
	v_div_fmas_f32 v30, v30, v32, v34
	v_div_fixup_f32 v26, v30, v26, 2.0
	v_pk_add_f32 v[26:27], v[26:27], 1.0 op_sel_hi:[1, 0] neg_lo:[1, 0] neg_hi:[1, 0]
	s_nop 0
	v_pk_add_f32 v[26:27], v[26:27], 1.0 op_sel_hi:[1, 0]
	s_nop 0
	v_pk_mul_f32 v[20:21], v[20:21], v[26:27]
	v_lshlrev_b32_e32 v26, 16, v31
	v_and_b32_e32 v27, 0xffff0000, v31
	v_pk_fma_f32 v[22:23], v[218:219], v[26:27], v[22:23]
	v_cvt_pk_bf16_f32 v20, v20, v21
	v_mul_f32_e32 v26, 0x3d372713, v22
	v_mul_f32_e32 v27, 0x3d372713, v23
	v_mul_f32_e32 v26, v22, v26
	v_mul_f32_e32 v27, v23, v27
	v_fma_f32 v26, v22, v26, v22
	v_fma_f32 v27, v23, v27, v23
	v_mul_f32_e32 v26, 0x3f4c422a, v26
	v_mul_f32_e32 v27, 0x3f4c422a, v27
	v_add_f32_e32 v26, v26, v26
	v_add_f32_e32 v27, v27, v27
	v_mul_f32_e32 v26, 0x3fb8aa3b, v26
	v_mul_f32_e32 v27, 0x3fb8aa3b, v27
	v_exp_f32_e32 v26, v26
	v_exp_f32_e32 v27, v27
	v_pk_mul_f32 v[22:23], v[22:23], 0.5 op_sel_hi:[1, 0]
	v_pk_add_f32 v[26:27], v[26:27], 1.0 op_sel_hi:[1, 0]
	s_nop 0
	v_div_scale_f32 v28, s[0:1], v27, v27, 2.0
	v_rcp_f32_e32 v29, v28
	s_nop 0
	v_fma_f32 v30, -v28, v29, 1.0
	v_fmac_f32_e32 v29, v30, v29
	v_div_scale_f32 v30, vcc, 2.0, v27, 2.0
	v_mul_f32_e32 v31, v30, v29
	v_fma_f32 v32, -v28, v31, v30
	v_fmac_f32_e32 v31, v32, v29
	v_fma_f32 v28, -v28, v31, v30
	v_div_fmas_f32 v28, v28, v29, v31
	v_div_fixup_f32 v27, v28, v27, 2.0
	v_div_scale_f32 v28, s[0:1], v26, v26, 2.0
	v_rcp_f32_e32 v29, v28
	s_nop 0
	v_fma_f32 v30, -v28, v29, 1.0
	v_fmac_f32_e32 v29, v30, v29
	v_div_scale_f32 v30, vcc, 2.0, v26, 2.0
	v_mul_f32_e32 v31, v30, v29
	v_fma_f32 v32, -v28, v31, v30
	v_fmac_f32_e32 v31, v32, v29
	v_fma_f32 v28, -v28, v31, v30
	v_div_fmas_f32 v28, v28, v29, v31
	v_div_fixup_f32 v26, v28, v26, 2.0
	v_pk_add_f32 v[26:27], v[26:27], 1.0 op_sel_hi:[1, 0] neg_lo:[1, 0] neg_hi:[1, 0]
	s_nop 0
	v_pk_add_f32 v[26:27], v[26:27], 1.0 op_sel_hi:[1, 0]
	s_nop 0
	v_pk_mul_f32 v[22:23], v[22:23], v[26:27]
	s_nop 0
	v_cvt_pk_bf16_f32 v21, v22, v23
	global_store_dwordx2 v[24:25], v[20:21], off
	v_lshl_add_u64 v[20:21], s[26:27], 0, v[224:225]
	v_lshl_add_u64 v[20:21], v[20:21], 0, s[8:9]
	v_lshl_add_u64 v[20:21], v[20:21], 0, v[128:129]
	s_waitcnt vmcnt(2)
	v_lshlrev_b32_e32 v28, 16, v236
	v_and_b32_e32 v29, 0xffff0000, v236
	s_waitcnt vmcnt(1)
	v_pk_fma_f32 v[16:17], v[244:245], v[28:29], v[16:17]
	s_nop 0
	v_mul_f32_e32 v22, 0x3d372713, v16
	v_mul_f32_e32 v23, 0x3d372713, v17
	v_mul_f32_e32 v22, v16, v22
	v_mul_f32_e32 v23, v17, v23
	v_fma_f32 v22, v16, v22, v16
	v_fma_f32 v23, v17, v23, v17
	v_mul_f32_e32 v22, 0x3f4c422a, v22
	v_mul_f32_e32 v23, 0x3f4c422a, v23
	v_add_f32_e32 v22, v22, v22
	v_add_f32_e32 v23, v23, v23
	v_mul_f32_e32 v22, 0x3fb8aa3b, v22
	v_mul_f32_e32 v23, 0x3fb8aa3b, v23
	v_exp_f32_e32 v22, v22
	v_exp_f32_e32 v23, v23
	v_pk_mul_f32 v[16:17], v[16:17], 0.5 op_sel_hi:[1, 0]
	v_pk_add_f32 v[22:23], v[22:23], 1.0 op_sel_hi:[1, 0]
	s_nop 0
	v_div_scale_f32 v26, s[0:1], v23, v23, 2.0
	v_rcp_f32_e32 v28, v26
	s_nop 0
	v_fma_f32 v29, -v26, v28, 1.0
	v_fmac_f32_e32 v28, v29, v28
	v_div_scale_f32 v29, vcc, 2.0, v23, 2.0
	v_mul_f32_e32 v30, v29, v28
	v_fma_f32 v31, -v26, v30, v29
	v_fmac_f32_e32 v30, v31, v28
	v_fma_f32 v26, -v26, v30, v29
	v_div_fmas_f32 v26, v26, v28, v30
	v_div_fixup_f32 v23, v26, v23, 2.0
	v_div_scale_f32 v26, s[0:1], v22, v22, 2.0
	v_rcp_f32_e32 v28, v26
	s_nop 0
	v_fma_f32 v29, -v26, v28, 1.0
	v_fmac_f32_e32 v28, v29, v28
	v_div_scale_f32 v29, vcc, 2.0, v22, 2.0
	v_mul_f32_e32 v30, v29, v28
	v_fma_f32 v31, -v26, v30, v29
	v_fmac_f32_e32 v30, v31, v28
	v_fma_f32 v26, -v26, v30, v29
	v_div_fmas_f32 v26, v26, v28, v30
	v_div_fixup_f32 v22, v26, v22, 2.0
	v_pk_add_f32 v[22:23], v[22:23], 1.0 op_sel_hi:[1, 0] neg_lo:[1, 0] neg_hi:[1, 0]
	s_nop 0
	v_pk_add_f32 v[22:23], v[22:23], 1.0 op_sel_hi:[1, 0]
	s_nop 0
	v_pk_mul_f32 v[16:17], v[16:17], v[22:23]
	v_lshlrev_b32_e32 v22, 16, v237
	v_and_b32_e32 v23, 0xffff0000, v237
	v_pk_fma_f32 v[18:19], v[246:247], v[22:23], v[18:19]
	v_cvt_pk_bf16_f32 v16, v16, v17
	v_mul_f32_e32 v22, 0x3d372713, v18
	v_mul_f32_e32 v23, 0x3d372713, v19
	v_mul_f32_e32 v22, v18, v22
	v_mul_f32_e32 v23, v19, v23
	v_fma_f32 v22, v18, v22, v18
	v_fma_f32 v23, v19, v23, v19
	v_mul_f32_e32 v22, 0x3f4c422a, v22
	v_mul_f32_e32 v23, 0x3f4c422a, v23
	v_add_f32_e32 v22, v22, v22
	v_add_f32_e32 v23, v23, v23
	v_mul_f32_e32 v22, 0x3fb8aa3b, v22
; DI float bf_lo(unsigned u) { return __uint_as_float(u << 16); }
; DI float bf_hi(unsigned u) { return __uint_as_float(u & 0xffff0000u); }
; DI float fast_exp(float x) { return __builtin_amdgcn_exp2f(x * 1.44269504089f); }
; DI float gelu_tanh(float y) {
;   const float z = 0.7978845608028654f * (y + 0.044715f * y * y * y);
;   const float e = fast_exp(2.0f * z);
;   const float th = 1.0f - 2.0f / (e + 1.0f);
;   return 0.5f * y * (1.0f + th);
; }
; DI void phase_ssm_out(const Params& p, char* lds) {
;     ...
;     epi8_iter(acc, [&](int t, int n, float a, float b, float c, float d) {
;       const int nn = nt * 256 + n, tt = nn >> 4, pp = nn & 15;
;       const size_t tok = (size_t)(ct * 256 + t) * 32 + tt;
;       const uint2 uu = *(const uint2*)(u + tok * 512 + g * 16 + pp);
;       const float4 dd = *(const float4*)(p.ssm_d + g * 16 + pp);
;       store_bf4(yg + tok * 512 + g * 16 + pp, gelu_tanh(a + dd.x * bf_lo(uu.x)), gelu_tanh(b + dd.y * bf_hi(uu.x)),
;                 gelu_tanh(c + dd.z * bf_lo(uu.y)), gelu_tanh(d + dd.w * bf_hi(uu.y)));
	v_mul_f32_e32 v23, 0x3fb8aa3b, v23
	v_exp_f32_e32 v22, v22
	v_exp_f32_e32 v23, v23
	v_pk_mul_f32 v[18:19], v[18:19], 0.5 op_sel_hi:[1, 0]
	v_pk_add_f32 v[22:23], v[22:23], 1.0 op_sel_hi:[1, 0]
	s_nop 0
	v_div_scale_f32 v24, s[0:1], v23, v23, 2.0
	v_rcp_f32_e32 v25, v24
	s_nop 0
	v_fma_f32 v26, -v24, v25, 1.0
	v_fmac_f32_e32 v25, v26, v25
	v_div_scale_f32 v26, vcc, 2.0, v23, 2.0
	v_mul_f32_e32 v27, v26, v25
	v_fma_f32 v28, -v24, v27, v26
	v_fmac_f32_e32 v27, v28, v25
	v_fma_f32 v24, -v24, v27, v26
	v_div_fmas_f32 v24, v24, v25, v27
	v_div_fixup_f32 v23, v24, v23, 2.0
	v_div_scale_f32 v24, s[0:1], v22, v22, 2.0
	v_rcp_f32_e32 v25, v24
	s_nop 0
	v_fma_f32 v26, -v24, v25, 1.0
	v_fmac_f32_e32 v25, v26, v25
	v_div_scale_f32 v26, vcc, 2.0, v22, 2.0
	v_mul_f32_e32 v27, v26, v25
	v_fma_f32 v28, -v24, v27, v26
	v_fmac_f32_e32 v27, v28, v25
	v_fma_f32 v24, -v24, v27, v26
	v_div_fmas_f32 v24, v24, v25, v27
	v_div_fixup_f32 v22, v24, v22, 2.0
	v_pk_add_f32 v[22:23], v[22:23], 1.0 op_sel_hi:[1, 0] neg_lo:[1, 0] neg_hi:[1, 0]
	s_nop 0
	v_pk_add_f32 v[22:23], v[22:23], 1.0 op_sel_hi:[1, 0]
	s_nop 0
	v_pk_mul_f32 v[18:19], v[18:19], v[22:23]
	s_nop 0
	v_cvt_pk_bf16_f32 v17, v18, v19
	global_store_dwordx2 v[20:21], v[16:17], off
	v_lshl_add_u64 v[16:17], v[48:49], 0, v[96:97]
	v_lshlrev_b64 v[16:17], 1, v[16:17]
	v_lshl_add_u64 v[18:19], s[36:37], 0, v[16:17]
	v_lshl_add_u64 v[18:19], v[18:19], 0, s[8:9]
	v_lshl_add_u64 v[18:19], v[18:19], 0, v[128:129]
	global_load_dwordx2 v[22:23], v[18:19], off
	global_load_dwordx4 v[184:187], v172, s[80:81]
	v_mov_b32_e32 v182, v177
	v_mov_b32_e32 v183, v178
	v_lshl_add_u64 v[188:189], v[48:49], 0, v[182:183]
	v_lshlrev_b64 v[190:191], 1, v[188:189]
	v_lshl_add_u64 v[192:193], s[36:37], 0, v[190:191]
	v_lshl_add_u64 v[194:195], v[192:193], 0, s[8:9]
	v_lshl_add_u64 v[196:197], v[194:195], 0, v[128:129]
	global_load_dwordx2 v[198:199], v[196:197], off
	global_load_dwordx4 v[200:203], v172, s[80:81]
	v_lshl_add_u64 v[16:17], s[26:27], 0, v[16:17]
	v_lshl_add_u64 v[16:17], v[16:17], 0, s[8:9]
	v_lshl_add_u64 v[16:17], v[16:17], 0, v[128:129]
	s_waitcnt vmcnt(3)
	v_lshlrev_b32_e32 v24, 16, v22
	v_and_b32_e32 v25, 0xffff0000, v22
	s_waitcnt vmcnt(2)
	v_pk_fma_f32 v[12:13], v[184:185], v[24:25], v[12:13]
	s_nop 0
	v_mul_f32_e32 v18, 0x3d372713, v12
	v_mul_f32_e32 v19, 0x3d372713, v13
	v_mul_f32_e32 v18, v12, v18
	v_mul_f32_e32 v19, v13, v19
	v_fma_f32 v18, v12, v18, v12
	v_fma_f32 v19, v13, v19, v13
	v_mul_f32_e32 v18, 0x3f4c422a, v18
	v_mul_f32_e32 v19, 0x3f4c422a, v19
	v_add_f32_e32 v18, v18, v18
	v_add_f32_e32 v19, v19, v19
	v_mul_f32_e32 v18, 0x3fb8aa3b, v18
	v_mul_f32_e32 v19, 0x3fb8aa3b, v19
	v_exp_f32_e32 v18, v18
	v_exp_f32_e32 v19, v19
	v_pk_mul_f32 v[12:13], v[12:13], 0.5 op_sel_hi:[1, 0]
	v_pk_add_f32 v[18:19], v[18:19], 1.0 op_sel_hi:[1, 0]
	s_nop 0
	v_div_scale_f32 v22, s[0:1], v19, v19, 2.0
	v_rcp_f32_e32 v24, v22
	s_nop 0
	v_fma_f32 v25, -v22, v24, 1.0
	v_fmac_f32_e32 v24, v25, v24
	v_div_scale_f32 v25, vcc, 2.0, v19, 2.0
	v_mul_f32_e32 v26, v25, v24
	v_fma_f32 v27, -v22, v26, v25
	v_fmac_f32_e32 v26, v27, v24
	v_fma_f32 v22, -v22, v26, v25
	v_div_fmas_f32 v22, v22, v24, v26
	v_div_fixup_f32 v19, v22, v19, 2.0
	v_div_scale_f32 v22, s[0:1], v18, v18, 2.0
	v_rcp_f32_e32 v24, v22
	s_nop 0
	v_fma_f32 v25, -v22, v24, 1.0
	v_fmac_f32_e32 v24, v25, v24
	v_div_scale_f32 v25, vcc, 2.0, v18, 2.0
	v_mul_f32_e32 v26, v25, v24
	v_fma_f32 v27, -v22, v26, v25
	v_fmac_f32_e32 v26, v27, v24
	v_fma_f32 v22, -v22, v26, v25
	v_div_fmas_f32 v22, v22, v24, v26
	v_div_fixup_f32 v18, v22, v18, 2.0
	v_pk_add_f32 v[18:19], v[18:19], 1.0 op_sel_hi:[1, 0] neg_lo:[1, 0] neg_hi:[1, 0]
	s_nop 0
	v_pk_add_f32 v[18:19], v[18:19], 1.0 op_sel_hi:[1, 0]
	s_nop 0
	v_pk_mul_f32 v[12:13], v[12:13], v[18:19]
	v_lshlrev_b32_e32 v18, 16, v23
	v_and_b32_e32 v19, 0xffff0000, v23
	v_pk_fma_f32 v[14:15], v[186:187], v[18:19], v[14:15]
	v_cvt_pk_bf16_f32 v12, v12, v13
	v_mul_f32_e32 v18, 0x3d372713, v14
	v_mul_f32_e32 v19, 0x3d372713, v15
	v_mul_f32_e32 v18, v14, v18
	v_mul_f32_e32 v19, v15, v19
	v_fma_f32 v18, v14, v18, v14
	v_fma_f32 v19, v15, v19, v15
	v_mul_f32_e32 v18, 0x3f4c422a, v18
	v_mul_f32_e32 v19, 0x3f4c422a, v19
	v_add_f32_e32 v18, v18, v18
	v_add_f32_e32 v19, v19, v19
	v_mul_f32_e32 v18, 0x3fb8aa3b, v18
	v_mul_f32_e32 v19, 0x3fb8aa3b, v19
	v_exp_f32_e32 v18, v18
	v_exp_f32_e32 v19, v19
	v_pk_mul_f32 v[14:15], v[14:15], 0.5 op_sel_hi:[1, 0]
	v_pk_add_f32 v[18:19], v[18:19], 1.0 op_sel_hi:[1, 0]
	s_nop 0
	v_div_scale_f32 v20, s[0:1], v19, v19, 2.0
	v_rcp_f32_e32 v21, v20
	s_nop 0
	v_fma_f32 v22, -v20, v21, 1.0
	v_fmac_f32_e32 v21, v22, v21
	v_div_scale_f32 v22, vcc, 2.0, v19, 2.0
	v_mul_f32_e32 v23, v22, v21
	v_fma_f32 v24, -v20, v23, v22
	v_fmac_f32_e32 v23, v24, v21
	v_fma_f32 v20, -v20, v23, v22
	v_div_fmas_f32 v20, v20, v21, v23
	v_div_fixup_f32 v19, v20, v19, 2.0
	v_div_scale_f32 v20, s[0:1], v18, v18, 2.0
	v_rcp_f32_e32 v21, v20
	s_nop 0
	v_fma_f32 v22, -v20, v21, 1.0
	v_fmac_f32_e32 v21, v22, v21
	v_div_scale_f32 v22, vcc, 2.0, v18, 2.0
	v_mul_f32_e32 v23, v22, v21
	v_fma_f32 v24, -v20, v23, v22
	v_fmac_f32_e32 v23, v24, v21
	v_fma_f32 v20, -v20, v23, v22
	v_div_fmas_f32 v20, v20, v21, v23
	v_div_fixup_f32 v18, v20, v18, 2.0
	v_pk_add_f32 v[18:19], v[18:19], 1.0 op_sel_hi:[1, 0] neg_lo:[1, 0] neg_hi:[1, 0]
	s_nop 0
	v_pk_add_f32 v[18:19], v[18:19], 1.0 op_sel_hi:[1, 0]
	s_nop 0
	v_pk_mul_f32 v[14:15], v[14:15], v[18:19]
	s_nop 0
	v_cvt_pk_bf16_f32 v13, v14, v15
	global_store_dwordx2 v[16:17], v[12:13], off
	v_lshl_add_u64 v[12:13], s[26:27], 0, v[190:191]
	v_lshl_add_u64 v[12:13], v[12:13], 0, s[8:9]
	v_lshl_add_u64 v[12:13], v[12:13], 0, v[128:129]
	s_waitcnt vmcnt(2)
; DI float bf_lo(unsigned u) { return __uint_as_float(u << 16); }
; DI float bf_hi(unsigned u) { return __uint_as_float(u & 0xffff0000u); }
; DI float fast_exp(float x) { return __builtin_amdgcn_exp2f(x * 1.44269504089f); }
; DI float gelu_tanh(float y) {
;   const float z = 0.7978845608028654f * (y + 0.044715f * y * y * y);
;   const float e = fast_exp(2.0f * z);
;   const float th = 1.0f - 2.0f / (e + 1.0f);
;   return 0.5f * y * (1.0f + th);
; }
; DI void phase_ssm_out(const Params& p, char* lds) {
;     ...
;     epi8_iter(acc, [&](int t, int n, float a, float b, float c, float d) {
;       const int nn = nt * 256 + n, tt = nn >> 4, pp = nn & 15;
;       const size_t tok = (size_t)(ct * 256 + t) * 32 + tt;
;       const uint2 uu = *(const uint2*)(u + tok * 512 + g * 16 + pp);
;       const float4 dd = *(const float4*)(p.ssm_d + g * 16 + pp);
;       store_bf4(yg + tok * 512 + g * 16 + pp, gelu_tanh(a + dd.x * bf_lo(uu.x)), gelu_tanh(b + dd.y * bf_hi(uu.x)),
;                 gelu_tanh(c + dd.z * bf_lo(uu.y)), gelu_tanh(d + dd.w * bf_hi(uu.y)));
	v_lshlrev_b32_e32 v20, 16, v198
	v_and_b32_e32 v21, 0xffff0000, v198
	s_waitcnt vmcnt(1)
	v_pk_fma_f32 v[8:9], v[200:201], v[20:21], v[8:9]
	s_nop 0
	v_mul_f32_e32 v14, 0x3d372713, v8
	v_mul_f32_e32 v15, 0x3d372713, v9
	v_mul_f32_e32 v14, v8, v14
	v_mul_f32_e32 v15, v9, v15
	v_fma_f32 v14, v8, v14, v8
	v_fma_f32 v15, v9, v15, v9
	v_mul_f32_e32 v14, 0x3f4c422a, v14
	v_mul_f32_e32 v15, 0x3f4c422a, v15
	v_add_f32_e32 v14, v14, v14
	v_add_f32_e32 v15, v15, v15
	v_mul_f32_e32 v14, 0x3fb8aa3b, v14
	v_mul_f32_e32 v15, 0x3fb8aa3b, v15
	v_exp_f32_e32 v14, v14
	v_exp_f32_e32 v15, v15
	v_pk_mul_f32 v[8:9], v[8:9], 0.5 op_sel_hi:[1, 0]
	v_pk_add_f32 v[14:15], v[14:15], 1.0 op_sel_hi:[1, 0]
	s_nop 0
	v_div_scale_f32 v18, s[0:1], v15, v15, 2.0
	v_rcp_f32_e32 v20, v18
	s_nop 0
	v_fma_f32 v21, -v18, v20, 1.0
	v_fmac_f32_e32 v20, v21, v20
	v_div_scale_f32 v21, vcc, 2.0, v15, 2.0
	v_mul_f32_e32 v22, v21, v20
	v_fma_f32 v23, -v18, v22, v21
	v_fmac_f32_e32 v22, v23, v20
	v_fma_f32 v18, -v18, v22, v21
	v_div_fmas_f32 v18, v18, v20, v22
	v_div_fixup_f32 v15, v18, v15, 2.0
	v_div_scale_f32 v18, s[0:1], v14, v14, 2.0
	v_rcp_f32_e32 v20, v18
	s_nop 0
	v_fma_f32 v21, -v18, v20, 1.0
	v_fmac_f32_e32 v20, v21, v20
	v_div_scale_f32 v21, vcc, 2.0, v14, 2.0
	v_mul_f32_e32 v22, v21, v20
	v_fma_f32 v23, -v18, v22, v21
	v_fmac_f32_e32 v22, v23, v20
	v_fma_f32 v18, -v18, v22, v21
	v_div_fmas_f32 v18, v18, v20, v22
	v_div_fixup_f32 v14, v18, v14, 2.0
	v_pk_add_f32 v[14:15], v[14:15], 1.0 op_sel_hi:[1, 0] neg_lo:[1, 0] neg_hi:[1, 0]
	s_nop 0
	v_pk_add_f32 v[14:15], v[14:15], 1.0 op_sel_hi:[1, 0]
	s_nop 0
	v_pk_mul_f32 v[8:9], v[8:9], v[14:15]
	v_lshlrev_b32_e32 v14, 16, v199
	v_and_b32_e32 v15, 0xffff0000, v199
	v_pk_fma_f32 v[10:11], v[202:203], v[14:15], v[10:11]
	v_cvt_pk_bf16_f32 v8, v8, v9
	v_mul_f32_e32 v14, 0x3d372713, v10
	v_mul_f32_e32 v15, 0x3d372713, v11
	v_mul_f32_e32 v14, v10, v14
	v_mul_f32_e32 v15, v11, v15
	v_fma_f32 v14, v10, v14, v10
	v_fma_f32 v15, v11, v15, v11
	v_mul_f32_e32 v14, 0x3f4c422a, v14
	v_mul_f32_e32 v15, 0x3f4c422a, v15
	v_add_f32_e32 v14, v14, v14
	v_add_f32_e32 v15, v15, v15
	v_mul_f32_e32 v14, 0x3fb8aa3b, v14
	v_mul_f32_e32 v15, 0x3fb8aa3b, v15
	v_exp_f32_e32 v14, v14
	v_exp_f32_e32 v15, v15
	v_pk_mul_f32 v[10:11], v[10:11], 0.5 op_sel_hi:[1, 0]
	v_pk_add_f32 v[14:15], v[14:15], 1.0 op_sel_hi:[1, 0]
	s_nop 0
	v_div_scale_f32 v16, s[0:1], v15, v15, 2.0
	v_rcp_f32_e32 v17, v16
	s_nop 0
	v_fma_f32 v18, -v16, v17, 1.0
	v_fmac_f32_e32 v17, v18, v17
	v_div_scale_f32 v18, vcc, 2.0, v15, 2.0
	v_mul_f32_e32 v19, v18, v17
	v_fma_f32 v20, -v16, v19, v18
	v_fmac_f32_e32 v19, v20, v17
	v_fma_f32 v16, -v16, v19, v18
	v_div_fmas_f32 v16, v16, v17, v19
	v_div_fixup_f32 v15, v16, v15, 2.0
	v_div_scale_f32 v16, s[0:1], v14, v14, 2.0
	v_rcp_f32_e32 v17, v16
	s_nop 0
	v_fma_f32 v18, -v16, v17, 1.0
	v_fmac_f32_e32 v17, v18, v17
	v_div_scale_f32 v18, vcc, 2.0, v14, 2.0
	v_mul_f32_e32 v19, v18, v17
	v_fma_f32 v20, -v16, v19, v18
	v_fmac_f32_e32 v19, v20, v17
	v_fma_f32 v16, -v16, v19, v18
	v_div_fmas_f32 v16, v16, v17, v19
	v_div_fixup_f32 v14, v16, v14, 2.0
	v_pk_add_f32 v[14:15], v[14:15], 1.0 op_sel_hi:[1, 0] neg_lo:[1, 0] neg_hi:[1, 0]
	s_nop 0
	v_pk_add_f32 v[14:15], v[14:15], 1.0 op_sel_hi:[1, 0]
	s_nop 0
	v_pk_mul_f32 v[10:11], v[10:11], v[14:15]
	s_nop 0
	v_cvt_pk_bf16_f32 v9, v10, v11
	global_store_dwordx2 v[12:13], v[8:9], off
	v_lshl_add_u64 v[8:9], v[40:41], 0, v[96:97]
	v_lshlrev_b64 v[8:9], 1, v[8:9]
	v_lshl_add_u64 v[10:11], s[36:37], 0, v[8:9]
	v_lshl_add_u64 v[10:11], v[10:11], 0, s[8:9]
	v_lshl_add_u64 v[10:11], v[10:11], 0, v[128:129]
	global_load_dwordx2 v[14:15], v[10:11], off
	global_load_dwordx4 v[216:219], v172, s[80:81]
	v_mov_b32_e32 v212, v177
	v_mov_b32_e32 v213, v178
	v_lshl_add_u64 v[220:221], v[40:41], 0, v[212:213]
	v_lshlrev_b64 v[224:225], 1, v[220:221]
	v_lshl_add_u64 v[226:227], s[36:37], 0, v[224:225]
	v_lshl_add_u64 v[228:229], v[226:227], 0, s[8:9]
	v_lshl_add_u64 v[230:231], v[228:229], 0, v[128:129]
	global_load_dwordx2 v[236:237], v[230:231], off
	global_load_dwordx4 v[244:247], v172, s[80:81]
	v_lshl_add_u64 v[8:9], s[26:27], 0, v[8:9]
	v_lshl_add_u64 v[8:9], v[8:9], 0, s[8:9]
	v_lshl_add_u64 v[8:9], v[8:9], 0, v[128:129]
	s_waitcnt vmcnt(3)
	v_lshlrev_b32_e32 v16, 16, v14
	v_and_b32_e32 v17, 0xffff0000, v14
	s_waitcnt vmcnt(2)
; DI int bidx() { int b = blockIdx.x; asm volatile("" : "+s"(b)); return b; }
; DI float bf_lo(unsigned u) { return __uint_as_float(u << 16); }
; DI float bf_hi(unsigned u) { return __uint_as_float(u & 0xffff0000u); }
; DI void phase_ssm_out(const Params& p, char* lds) {
;     ...
;   for (int it = bidx(); it < 32 * 4 * 2; it += gridDim.x) {
;     const int g = it >> 3, ct = (it >> 1) & 3, nt = it & 1;
;     ...
;     epi8_iter(acc, [&](int t, int n, float a, float b, float c, float d) {
;       const int nn = nt * 256 + n, tt = nn >> 4, pp = nn & 15;
;       const size_t tok = (size_t)(ct * 256 + t) * 32 + tt;
;       const uint2 uu = *(const uint2*)(u + tok * 512 + g * 16 + pp);
;       const float4 dd = *(const float4*)(p.ssm_d + g * 16 + pp);
;       store_bf4(yg + tok * 512 + g * 16 + pp, gelu_tanh(a + dd.x * bf_lo(uu.x)), gelu_tanh(b + dd.y * bf_hi(uu.x)),
;                 gelu_tanh(c + dd.z * bf_lo(uu.y)), gelu_tanh(d + dd.w * bf_hi(uu.y)));
	v_pk_fma_f32 v[4:5], v[216:217], v[16:17], v[4:5]
	s_nop 0
	v_mul_f32_e32 v10, 0x3d372713, v4
	v_mul_f32_e32 v11, 0x3d372713, v5
	v_mul_f32_e32 v10, v4, v10
	v_mul_f32_e32 v11, v5, v11
	v_fma_f32 v10, v4, v10, v4
	v_fma_f32 v11, v5, v11, v5
	v_mul_f32_e32 v10, 0x3f4c422a, v10
	v_mul_f32_e32 v11, 0x3f4c422a, v11
	v_add_f32_e32 v10, v10, v10
	v_add_f32_e32 v11, v11, v11
	v_mul_f32_e32 v10, 0x3fb8aa3b, v10
	v_mul_f32_e32 v11, 0x3fb8aa3b, v11
	v_exp_f32_e32 v10, v10
	v_exp_f32_e32 v11, v11
	v_pk_mul_f32 v[4:5], v[4:5], 0.5 op_sel_hi:[1, 0]
	v_pk_add_f32 v[10:11], v[10:11], 1.0 op_sel_hi:[1, 0]
	s_nop 0
	v_div_scale_f32 v14, s[0:1], v11, v11, 2.0
	v_rcp_f32_e32 v16, v14
	s_nop 0
	v_fma_f32 v17, -v14, v16, 1.0
	v_fmac_f32_e32 v16, v17, v16
	v_div_scale_f32 v17, vcc, 2.0, v11, 2.0
	v_mul_f32_e32 v18, v17, v16
	v_fma_f32 v19, -v14, v18, v17
	v_fmac_f32_e32 v18, v19, v16
	v_fma_f32 v14, -v14, v18, v17
	v_div_fmas_f32 v14, v14, v16, v18
	v_div_fixup_f32 v11, v14, v11, 2.0
	v_div_scale_f32 v14, s[0:1], v10, v10, 2.0
	v_rcp_f32_e32 v16, v14
	s_nop 0
	v_fma_f32 v17, -v14, v16, 1.0
	v_fmac_f32_e32 v16, v17, v16
	v_div_scale_f32 v17, vcc, 2.0, v10, 2.0
	v_mul_f32_e32 v18, v17, v16
	v_fma_f32 v19, -v14, v18, v17
	v_fmac_f32_e32 v18, v19, v16
	v_fma_f32 v14, -v14, v18, v17
	v_div_fmas_f32 v14, v14, v16, v18
	v_div_fixup_f32 v10, v14, v10, 2.0
	v_pk_add_f32 v[10:11], v[10:11], 1.0 op_sel_hi:[1, 0] neg_lo:[1, 0] neg_hi:[1, 0]
	s_nop 0
	v_pk_add_f32 v[10:11], v[10:11], 1.0 op_sel_hi:[1, 0]
	s_nop 0
	v_pk_mul_f32 v[4:5], v[4:5], v[10:11]
	v_lshlrev_b32_e32 v10, 16, v15
	v_and_b32_e32 v11, 0xffff0000, v15
	v_pk_fma_f32 v[6:7], v[218:219], v[10:11], v[6:7]
	v_cvt_pk_bf16_f32 v4, v4, v5
	v_mul_f32_e32 v10, 0x3d372713, v6
	v_mul_f32_e32 v11, 0x3d372713, v7
	v_mul_f32_e32 v10, v6, v10
	v_mul_f32_e32 v11, v7, v11
	v_fma_f32 v10, v6, v10, v6
	v_fma_f32 v11, v7, v11, v7
	v_mul_f32_e32 v10, 0x3f4c422a, v10
	v_mul_f32_e32 v11, 0x3f4c422a, v11
	v_add_f32_e32 v10, v10, v10
	v_add_f32_e32 v11, v11, v11
	v_mul_f32_e32 v10, 0x3fb8aa3b, v10
	v_mul_f32_e32 v11, 0x3fb8aa3b, v11
	v_exp_f32_e32 v10, v10
	v_exp_f32_e32 v11, v11
	v_pk_mul_f32 v[6:7], v[6:7], 0.5 op_sel_hi:[1, 0]
	v_pk_add_f32 v[10:11], v[10:11], 1.0 op_sel_hi:[1, 0]
	s_nop 0
	v_div_scale_f32 v12, s[0:1], v11, v11, 2.0
	v_rcp_f32_e32 v13, v12
	s_nop 0
	v_fma_f32 v14, -v12, v13, 1.0
	v_fmac_f32_e32 v13, v14, v13
	v_div_scale_f32 v14, vcc, 2.0, v11, 2.0
	v_mul_f32_e32 v15, v14, v13
	v_fma_f32 v16, -v12, v15, v14
	v_fmac_f32_e32 v15, v16, v13
	v_fma_f32 v12, -v12, v15, v14
	v_div_fmas_f32 v12, v12, v13, v15
	v_div_fixup_f32 v11, v12, v11, 2.0
	v_div_scale_f32 v12, s[0:1], v10, v10, 2.0
	v_rcp_f32_e32 v13, v12
	s_nop 0
	v_fma_f32 v14, -v12, v13, 1.0
	v_fmac_f32_e32 v13, v14, v13
	v_div_scale_f32 v14, vcc, 2.0, v10, 2.0
	v_mul_f32_e32 v15, v14, v13
	v_fma_f32 v16, -v12, v15, v14
	v_fmac_f32_e32 v15, v16, v13
	v_fma_f32 v12, -v12, v15, v14
	v_div_fmas_f32 v12, v12, v13, v15
	v_div_fixup_f32 v10, v12, v10, 2.0
	v_pk_add_f32 v[10:11], v[10:11], 1.0 op_sel_hi:[1, 0] neg_lo:[1, 0] neg_hi:[1, 0]
	s_nop 0
	v_pk_add_f32 v[10:11], v[10:11], 1.0 op_sel_hi:[1, 0]
	s_nop 0
	v_pk_mul_f32 v[6:7], v[6:7], v[10:11]
	s_nop 0
	v_cvt_pk_bf16_f32 v5, v6, v7
	global_store_dwordx2 v[8:9], v[4:5], off
	v_lshl_add_u64 v[4:5], s[26:27], 0, v[224:225]
	v_lshl_add_u64 v[4:5], v[4:5], 0, s[8:9]
	v_lshl_add_u64 v[4:5], v[4:5], 0, v[128:129]
	s_waitcnt vmcnt(2)
	v_lshlrev_b32_e32 v12, 16, v236
	v_and_b32_e32 v13, 0xffff0000, v236
	s_waitcnt vmcnt(1)
	v_pk_fma_f32 v[0:1], v[244:245], v[12:13], v[0:1]
	s_nop 0
	v_mul_f32_e32 v6, 0x3d372713, v0
	v_mul_f32_e32 v7, 0x3d372713, v1
	v_mul_f32_e32 v6, v0, v6
	v_mul_f32_e32 v7, v1, v7
	v_fma_f32 v6, v0, v6, v0
	v_fma_f32 v7, v1, v7, v1
	v_mul_f32_e32 v6, 0x3f4c422a, v6
	v_mul_f32_e32 v7, 0x3f4c422a, v7
	v_add_f32_e32 v6, v6, v6
	v_add_f32_e32 v7, v7, v7
	v_mul_f32_e32 v6, 0x3fb8aa3b, v6
	v_mul_f32_e32 v7, 0x3fb8aa3b, v7
	v_exp_f32_e32 v6, v6
	v_exp_f32_e32 v7, v7
	v_pk_mul_f32 v[0:1], v[0:1], 0.5 op_sel_hi:[1, 0]
	v_pk_add_f32 v[6:7], v[6:7], 1.0 op_sel_hi:[1, 0]
	s_nop 0
	v_div_scale_f32 v10, s[0:1], v7, v7, 2.0
	v_rcp_f32_e32 v12, v10
	s_nop 0
	v_fma_f32 v13, -v10, v12, 1.0
	v_fmac_f32_e32 v12, v13, v12
	v_div_scale_f32 v13, vcc, 2.0, v7, 2.0
	v_mul_f32_e32 v14, v13, v12
	v_fma_f32 v15, -v10, v14, v13
	v_fmac_f32_e32 v14, v15, v12
	v_fma_f32 v10, -v10, v14, v13
	v_div_fmas_f32 v10, v10, v12, v14
	v_div_fixup_f32 v7, v10, v7, 2.0
	v_div_scale_f32 v10, s[0:1], v6, v6, 2.0
	v_rcp_f32_e32 v12, v10
	s_nop 0
	v_fma_f32 v13, -v10, v12, 1.0
	v_fmac_f32_e32 v12, v13, v12
	v_div_scale_f32 v13, vcc, 2.0, v6, 2.0
	v_mul_f32_e32 v14, v13, v12
	v_fma_f32 v15, -v10, v14, v13
	v_fmac_f32_e32 v14, v15, v12
	v_fma_f32 v10, -v10, v14, v13
	v_div_fmas_f32 v10, v10, v12, v14
	v_div_fixup_f32 v6, v10, v6, 2.0
	v_pk_add_f32 v[6:7], v[6:7], 1.0 op_sel_hi:[1, 0] neg_lo:[1, 0] neg_hi:[1, 0]
	s_nop 0
	v_pk_add_f32 v[6:7], v[6:7], 1.0 op_sel_hi:[1, 0]
	s_nop 0
	v_pk_mul_f32 v[0:1], v[0:1], v[6:7]
	v_lshlrev_b32_e32 v6, 16, v237
	v_and_b32_e32 v7, 0xffff0000, v237
	v_pk_fma_f32 v[2:3], v[246:247], v[6:7], v[2:3]
	v_cvt_pk_bf16_f32 v0, v0, v1
	v_mul_f32_e32 v6, 0x3d372713, v2
	v_mul_f32_e32 v7, 0x3d372713, v3
	v_mul_f32_e32 v6, v2, v6
	v_mul_f32_e32 v7, v3, v7
	v_fma_f32 v6, v2, v6, v2
	v_fma_f32 v7, v3, v7, v3
	v_mul_f32_e32 v6, 0x3f4c422a, v6
	v_mul_f32_e32 v7, 0x3f4c422a, v7
	v_add_f32_e32 v6, v6, v6
	v_add_f32_e32 v7, v7, v7
	v_mul_f32_e32 v6, 0x3fb8aa3b, v6
	v_mul_f32_e32 v7, 0x3fb8aa3b, v7
	v_exp_f32_e32 v6, v6
	v_exp_f32_e32 v7, v7
	v_pk_mul_f32 v[2:3], v[2:3], 0.5 op_sel_hi:[1, 0]
	v_pk_add_f32 v[6:7], v[6:7], 1.0 op_sel_hi:[1, 0]
	s_nop 0
	v_div_scale_f32 v8, s[0:1], v7, v7, 2.0
	v_rcp_f32_e32 v9, v8
	s_nop 0
	v_fma_f32 v10, -v8, v9, 1.0
	v_fmac_f32_e32 v9, v10, v9
	v_div_scale_f32 v10, vcc, 2.0, v7, 2.0
	v_mul_f32_e32 v11, v10, v9
	v_fma_f32 v12, -v8, v11, v10
	v_fmac_f32_e32 v11, v12, v9
	v_fma_f32 v8, -v8, v11, v10
	v_div_fmas_f32 v8, v8, v9, v11
	v_div_fixup_f32 v7, v8, v7, 2.0
	v_div_scale_f32 v8, s[0:1], v6, v6, 2.0
	v_rcp_f32_e32 v9, v8
	v_readlane_b32 s0, v254, 24
	v_readlane_b32 s1, v254, 25
	s_xor_b64 s[4:5], s[4:5], s[0:1]
	v_fma_f32 v10, -v8, v9, 1.0
	v_fmac_f32_e32 v9, v10, v9
	v_div_scale_f32 v10, vcc, 2.0, v6, 2.0
	v_mul_f32_e32 v11, v10, v9
	v_fma_f32 v12, -v8, v11, v10
	v_fmac_f32_e32 v11, v12, v9
	v_fma_f32 v8, -v8, v11, v10
	v_div_fmas_f32 v8, v8, v9, v11
	v_div_fixup_f32 v6, v8, v6, 2.0
	v_pk_add_f32 v[6:7], v[6:7], 1.0 op_sel_hi:[1, 0] neg_lo:[1, 0] neg_hi:[1, 0]
	s_cmpk_lt_i32 s21, 0x100
	v_pk_add_f32 v[6:7], v[6:7], 1.0 op_sel_hi:[1, 0]
	s_nop 0
	v_pk_mul_f32 v[2:3], v[2:3], v[6:7]
	s_nop 0
	v_cvt_pk_bf16_f32 v1, v2, v3
	global_store_dwordx2 v[4:5], v[0:1], off
	s_cbranch_scc0 .LBB0_248

; DI int tidx() { int t = threadIdx.x; asm volatile("" : "+v"(t)); return t; }
; DI float bf_lo(unsigned u) { return __uint_as_float(u << 16); }
; DI float bf_hi(unsigned u) { return __uint_as_float(u & 0xffff0000u); }
; DI float sigmoidf_(float z) { return 1.0f / (1.0f + fast_exp(-z)); }
; template <class F>
; DI void epi8_iter(const acc8_t& acc, F f) {
;   const int lane = tidx() & 63, wid = tidx() >> 6, wr = wid >> 2, wc = wid & 3, fr = lane & 15, fq = lane >> 4;
; #pragma unroll
;   for (int ai = 0; ai < 2; ++ai)
; #pragma unroll
;     for (int bj = 0; bj < 2; ++bj)
; #pragma unroll
;       for (int m = 0; m < 4; ++m)
; #pragma unroll
;         for (int q = 0; q < 2; ++q)
;           f(bj * 128 + wc * 32 + q * 16 + fr, ai * 128 + wr * 64 + m * 16 + fq * 4, acc[ai][bj][m][q][0], acc[ai][bj][m][q][1],
;             acc[ai][bj][m][q][2], acc[ai][bj][m][q][3]);
; DI void phase_glu(const Params& p, char* lds) {
;     ...
;     epi8_iter(acc, [&](int t, int n, float a, float b, float c, float d) {
;       const size_t off = (size_t)(mt * 256 + t) * 512 + nt * 256 + n;
;       const uint2 yy = *(const uint2*)(yg + off);
;       const float4 bb = *(const float4*)(p.b_glu + nt * 256 + n);
;       store_bf4(so + off, bf_lo(yy.x) * sigmoidf_(a + bb.x), bf_hi(yy.x) * sigmoidf_(b + bb.y), bf_lo(yy.y) * sigmoidf_(c + bb.z),
;                 bf_hi(yy.y) * sigmoidf_(d + bb.w));
;     });
.LBB0_261:
	v_mov_b32_e32 v128, v162
	v_mov_b32_e32 v129, v162
	v_and_b32_e32 v132, 15, v128
	v_lshrrev_b32_e32 v128, 2, v128
	v_lshrrev_b32_e32 v130, 1, v129
	v_ashrrev_i32_e32 v129, 2, v129
	v_and_b32_e32 v128, 12, v128
	s_movk_i32 s1, 0xffc0
	v_and_b32_e32 v133, 0x60, v130
	v_and_or_b32 v130, v129, s1, v128
	s_lshl_b32 s1, s8, 8
	v_or3_b32 v134, v132, v133, s1
	v_ashrrev_i32_e32 v131, 31, v130
	v_ashrrev_i32_e32 v135, 31, v134
	s_lshl_b32 s96, s0, 8
	v_lshlrev_b64 v[132:133], 9, v[134:135]
	v_lshl_add_u64 v[136:137], v[130:131], 0, s[96:97]
	v_lshl_add_u64 v[128:129], v[132:133], 0, v[136:137]
	s_lshl_b32 s0, s0, 10
	v_readlane_b32 s8, v255, 1
	v_lshlrev_b64 v[142:143], 1, v[128:129]
	v_readlane_b32 s9, v255, 2
	s_add_u32 s0, s8, s0
	v_lshl_add_u64 v[128:129], s[26:27], 0, v[142:143]
	s_addc_u32 s1, s9, 0
	global_load_dwordx2 v[144:145], v[128:129], off
	v_lshl_add_u64 v[172:173], v[130:131], 2, s[0:1]
	global_load_dwordx4 v[176:179], v[172:173], off
	v_or_b32_e32 v182, 16, v134
	v_ashrrev_i32_e32 v183, 31, v182
	v_lshlrev_b64 v[184:185], 9, v[182:183]
	v_lshl_add_u64 v[186:187], v[184:185], 0, v[136:137]
	v_lshlrev_b64 v[188:189], 1, v[186:187]
	v_lshl_add_u64 v[190:191], s[26:27], 0, v[188:189]
	global_load_dwordx2 v[192:193], v[190:191], off
	global_load_dwordx4 v[196:199], v[172:173], off
	v_lshl_add_u64 v[142:143], s[36:37], 0, v[142:143]
	s_add_i32 s21, s21, s16
	v_readlane_b32 s58, v254, 26
	v_readlane_b32 s59, v254, 27
	s_waitcnt vmcnt(2)
	v_lshlrev_b32_e32 v146, 16, v144
	v_and_b32_e32 v147, 0xffff0000, v144
	v_add_f32_e32 v124, v124, v176
	v_add_f32_e32 v125, v125, v177
	v_mul_f32_e32 v124, 0xbfb8aa3b, v124
	v_mul_f32_e32 v125, 0xbfb8aa3b, v125
	v_exp_f32_e32 v124, v124
	v_exp_f32_e32 v125, v125
	v_add_f32_e32 v126, v126, v178
	v_add_f32_e32 v127, v127, v179
	v_mul_f32_e32 v126, 0xbfb8aa3b, v126
	v_pk_add_f32 v[124:125], v[124:125], 1.0 op_sel_hi:[1, 0]
	v_mul_f32_e32 v127, 0xbfb8aa3b, v127
	v_div_scale_f32 v131, s[0:1], v125, v125, 1.0
	v_rcp_f32_e32 v135, v131
	v_exp_f32_e32 v126, v126
	v_exp_f32_e32 v127, v127
	v_fma_f32 v138, -v131, v135, 1.0
	v_fmac_f32_e32 v135, v138, v135
	v_div_scale_f32 v138, vcc, 1.0, v125, 1.0
	v_mul_f32_e32 v139, v138, v135
	v_fma_f32 v144, -v131, v139, v138
	v_fmac_f32_e32 v139, v144, v135
	v_fma_f32 v131, -v131, v139, v138
	v_div_fmas_f32 v131, v131, v135, v139
	v_div_fixup_f32 v125, v131, v125, 1.0
	v_div_scale_f32 v131, s[0:1], v124, v124, 1.0
	v_rcp_f32_e32 v135, v131
	v_pk_add_f32 v[126:127], v[126:127], 1.0 op_sel_hi:[1, 0]
	v_fma_f32 v138, -v131, v135, 1.0
	v_fmac_f32_e32 v135, v138, v135
	v_div_scale_f32 v138, vcc, 1.0, v124, 1.0
	v_mul_f32_e32 v139, v138, v135
	v_fma_f32 v144, -v131, v139, v138
	v_fmac_f32_e32 v139, v144, v135
	v_fma_f32 v131, -v131, v139, v138
	v_div_fmas_f32 v131, v131, v135, v139
	v_div_fixup_f32 v124, v131, v124, 1.0
	v_div_scale_f32 v131, s[0:1], v127, v127, 1.0
	v_rcp_f32_e32 v135, v131
	v_lshlrev_b32_e32 v138, 16, v145
	v_and_b32_e32 v139, 0xffff0000, v145
	v_pk_mul_f32 v[124:125], v[124:125], v[146:147]
	v_fma_f32 v140, -v131, v135, 1.0
	v_fmac_f32_e32 v135, v140, v135
	v_div_scale_f32 v140, vcc, 1.0, v127, 1.0
	v_mul_f32_e32 v141, v140, v135
	v_fma_f32 v144, -v131, v141, v140
	v_fmac_f32_e32 v141, v144, v135
	v_fma_f32 v131, -v131, v141, v140
	v_div_fmas_f32 v131, v131, v135, v141
	v_div_fixup_f32 v127, v131, v127, 1.0
	v_div_scale_f32 v131, s[0:1], v126, v126, 1.0
	v_rcp_f32_e32 v135, v131
	v_cvt_pk_bf16_f32 v124, v124, v125
	v_fma_f32 v140, -v131, v135, 1.0
	v_fmac_f32_e32 v135, v140, v135
	v_div_scale_f32 v140, vcc, 1.0, v126, 1.0
	v_mul_f32_e32 v141, v140, v135
	v_fma_f32 v144, -v131, v141, v140
	v_fmac_f32_e32 v141, v144, v135
	v_fma_f32 v131, -v131, v141, v140
	v_div_fmas_f32 v131, v131, v135, v141
	v_div_fixup_f32 v126, v131, v126, 1.0
	v_pk_mul_f32 v[126:127], v[126:127], v[138:139]
	s_nop 0
	v_cvt_pk_bf16_f32 v125, v126, v127
	global_store_dwordx2 v[142:143], v[124:125], off
	s_nop 0
	v_lshl_add_u64 v[126:127], s[36:37], 0, v[188:189]
	s_waitcnt vmcnt(2)
	v_lshlrev_b32_e32 v144, 16, v192
	s_waitcnt vmcnt(1)
	v_add_f32_e32 v120, v120, v196
	v_add_f32_e32 v121, v121, v197
	v_mul_f32_e32 v120, 0xbfb8aa3b, v120
	v_mul_f32_e32 v121, 0xbfb8aa3b, v121
	v_exp_f32_e32 v120, v120
	v_exp_f32_e32 v121, v121
	v_and_b32_e32 v145, 0xffff0000, v192
	v_add_f32_e32 v122, v122, v198
	v_add_f32_e32 v123, v123, v199
	v_pk_add_f32 v[120:121], v[120:121], 1.0 op_sel_hi:[1, 0]
	v_mul_f32_e32 v122, 0xbfb8aa3b, v122
	v_div_scale_f32 v131, s[0:1], v121, v121, 1.0
	v_rcp_f32_e32 v135, v131
	v_mul_f32_e32 v123, 0xbfb8aa3b, v123
	v_exp_f32_e32 v122, v122
	v_exp_f32_e32 v123, v123
	v_fma_f32 v138, -v131, v135, 1.0
	v_fmac_f32_e32 v135, v138, v135
	v_div_scale_f32 v138, vcc, 1.0, v121, 1.0
	v_mul_f32_e32 v139, v138, v135
	v_fma_f32 v142, -v131, v139, v138
	v_fmac_f32_e32 v139, v142, v135
	v_fma_f32 v131, -v131, v139, v138
	v_div_fmas_f32 v131, v131, v135, v139
	v_div_fixup_f32 v121, v131, v121, 1.0
	v_div_scale_f32 v131, s[0:1], v120, v120, 1.0
	v_rcp_f32_e32 v135, v131
	v_pk_add_f32 v[122:123], v[122:123], 1.0 op_sel_hi:[1, 0]
	v_fma_f32 v138, -v131, v135, 1.0
	v_fmac_f32_e32 v135, v138, v135
	v_div_scale_f32 v138, vcc, 1.0, v120, 1.0
	v_mul_f32_e32 v139, v138, v135
	v_fma_f32 v142, -v131, v139, v138
	v_fmac_f32_e32 v139, v142, v135
	v_fma_f32 v131, -v131, v139, v138
	v_div_fmas_f32 v131, v131, v135, v139
	v_div_fixup_f32 v120, v131, v120, 1.0
	v_div_scale_f32 v131, s[0:1], v123, v123, 1.0
	v_rcp_f32_e32 v135, v131
	v_lshlrev_b32_e32 v138, 16, v193
	v_and_b32_e32 v139, 0xffff0000, v193
	v_pk_mul_f32 v[120:121], v[120:121], v[144:145]
	v_fma_f32 v140, -v131, v135, 1.0
; DI float bf_lo(unsigned u) { return __uint_as_float(u << 16); }
; DI float bf_hi(unsigned u) { return __uint_as_float(u & 0xffff0000u); }
; DI float fast_exp(float x) { return __builtin_amdgcn_exp2f(x * 1.44269504089f); }
; DI float sigmoidf_(float z) { return 1.0f / (1.0f + fast_exp(-z)); }
; DI void phase_glu(const Params& p, char* lds) {
;     ...
;     epi8_iter(acc, [&](int t, int n, float a, float b, float c, float d) {
;       const size_t off = (size_t)(mt * 256 + t) * 512 + nt * 256 + n;
;       const uint2 yy = *(const uint2*)(yg + off);
;       const float4 bb = *(const float4*)(p.b_glu + nt * 256 + n);
;       store_bf4(so + off, bf_lo(yy.x) * sigmoidf_(a + bb.x), bf_hi(yy.x) * sigmoidf_(b + bb.y), bf_lo(yy.y) * sigmoidf_(c + bb.z),
;                 bf_hi(yy.y) * sigmoidf_(d + bb.w));
;     });
	v_fmac_f32_e32 v135, v140, v135
	v_div_scale_f32 v140, vcc, 1.0, v123, 1.0
	v_mul_f32_e32 v141, v140, v135
	v_fma_f32 v142, -v131, v141, v140
	v_fmac_f32_e32 v141, v142, v135
	v_fma_f32 v131, -v131, v141, v140
	v_div_fmas_f32 v131, v131, v135, v141
	v_div_fixup_f32 v123, v131, v123, 1.0
	v_div_scale_f32 v131, s[0:1], v122, v122, 1.0
	v_rcp_f32_e32 v135, v131
	v_cvt_pk_bf16_f32 v120, v120, v121
	v_fma_f32 v140, -v131, v135, 1.0
	v_fmac_f32_e32 v135, v140, v135
	v_div_scale_f32 v140, vcc, 1.0, v122, 1.0
	v_mul_f32_e32 v141, v140, v135
	v_fma_f32 v142, -v131, v141, v140
	v_fmac_f32_e32 v141, v142, v135
	v_fma_f32 v131, -v131, v141, v140
	v_div_fmas_f32 v131, v131, v135, v141
	v_div_fixup_f32 v122, v131, v122, 1.0
	v_pk_mul_f32 v[122:123], v[122:123], v[138:139]
	s_nop 0
	v_cvt_pk_bf16_f32 v121, v122, v123
	global_store_dwordx2 v[126:127], v[120:121], off
	v_or_b32_e32 v120, 16, v130
	v_ashrrev_i32_e32 v121, 31, v120
	v_lshl_add_u64 v[120:121], v[120:121], 0, s[96:97]
	v_lshl_add_u64 v[122:123], v[120:121], 0, v[132:133]
	v_lshlrev_b64 v[122:123], 1, v[122:123]
	v_lshl_add_u64 v[126:127], s[26:27], 0, v[122:123]
	global_load_dwordx2 v[126:127], v[126:127], off
	global_load_dwordx4 v[212:215], v[172:173], off offset:64
	v_lshl_add_u64 v[216:217], v[184:185], 0, v[120:121]
	v_lshlrev_b64 v[218:219], 1, v[216:217]
	v_lshl_add_u64 v[220:221], s[26:27], 0, v[218:219]
	global_load_dwordx2 v[224:225], v[220:221], off
	global_load_dwordx4 v[228:231], v[172:173], off offset:64
	s_nop 0
	v_lshl_add_u64 v[122:123], s[36:37], 0, v[122:123]
	s_waitcnt vmcnt(3)
	v_lshlrev_b32_e32 v142, 16, v126
	s_waitcnt vmcnt(2)
	v_add_f32_e32 v116, v116, v212
	v_add_f32_e32 v117, v117, v213
	v_mul_f32_e32 v116, 0xbfb8aa3b, v116
	v_mul_f32_e32 v117, 0xbfb8aa3b, v117
	v_exp_f32_e32 v116, v116
	v_exp_f32_e32 v117, v117
	v_and_b32_e32 v143, 0xffff0000, v126
	v_add_f32_e32 v118, v118, v214
	v_add_f32_e32 v119, v119, v215
	v_pk_add_f32 v[116:117], v[116:117], 1.0 op_sel_hi:[1, 0]
	v_mul_f32_e32 v118, 0xbfb8aa3b, v118
	v_div_scale_f32 v126, s[0:1], v117, v117, 1.0
	v_rcp_f32_e32 v131, v126
	v_mul_f32_e32 v119, 0xbfb8aa3b, v119
	v_exp_f32_e32 v118, v118
	v_exp_f32_e32 v119, v119
	v_fma_f32 v135, -v126, v131, 1.0
	v_fmac_f32_e32 v131, v135, v131
	v_div_scale_f32 v135, vcc, 1.0, v117, 1.0
	v_mul_f32_e32 v138, v135, v131
	v_fma_f32 v139, -v126, v138, v135
	v_fmac_f32_e32 v138, v139, v131
	v_fma_f32 v126, -v126, v138, v135
	v_div_fmas_f32 v126, v126, v131, v138
	v_div_fixup_f32 v117, v126, v117, 1.0
	v_div_scale_f32 v126, s[0:1], v116, v116, 1.0
	v_rcp_f32_e32 v131, v126
	v_pk_add_f32 v[118:119], v[118:119], 1.0 op_sel_hi:[1, 0]
	v_fma_f32 v135, -v126, v131, 1.0
	v_fmac_f32_e32 v131, v135, v131
	v_div_scale_f32 v135, vcc, 1.0, v116, 1.0
	v_mul_f32_e32 v138, v135, v131
	v_fma_f32 v139, -v126, v138, v135
	v_fmac_f32_e32 v138, v139, v131
	v_fma_f32 v126, -v126, v138, v135
	v_div_fmas_f32 v126, v126, v131, v138
	v_div_scale_f32 v131, s[0:1], v119, v119, 1.0
	v_rcp_f32_e32 v135, v131
	v_div_fixup_f32 v116, v126, v116, 1.0
	v_lshlrev_b32_e32 v126, 16, v127
	v_and_b32_e32 v127, 0xffff0000, v127
	v_fma_f32 v138, -v131, v135, 1.0
	v_fmac_f32_e32 v135, v138, v135
	v_div_scale_f32 v138, vcc, 1.0, v119, 1.0
	v_mul_f32_e32 v139, v138, v135
	v_fma_f32 v140, -v131, v139, v138
	v_fmac_f32_e32 v139, v140, v135
	v_fma_f32 v131, -v131, v139, v138
	v_div_fmas_f32 v131, v131, v135, v139
	v_div_fixup_f32 v119, v131, v119, 1.0
	v_div_scale_f32 v131, s[0:1], v118, v118, 1.0
	v_rcp_f32_e32 v135, v131
	v_pk_mul_f32 v[116:117], v[116:117], v[142:143]
	v_fma_f32 v138, -v131, v135, 1.0
	v_fmac_f32_e32 v135, v138, v135
	v_div_scale_f32 v138, vcc, 1.0, v118, 1.0
	v_mul_f32_e32 v139, v138, v135
	v_fma_f32 v140, -v131, v139, v138
	v_fmac_f32_e32 v139, v140, v135
	v_fma_f32 v131, -v131, v139, v138
	v_div_fmas_f32 v131, v131, v135, v139
	v_div_fixup_f32 v118, v131, v118, 1.0
	v_pk_mul_f32 v[118:119], v[118:119], v[126:127]
	v_cvt_pk_bf16_f32 v116, v116, v117
	v_cvt_pk_bf16_f32 v117, v118, v119
	global_store_dwordx2 v[122:123], v[116:117], off
	s_nop 0
	v_lshl_add_u64 v[122:123], s[36:37], 0, v[218:219]
	s_waitcnt vmcnt(2)
	v_lshlrev_b32_e32 v138, 16, v224
	s_waitcnt vmcnt(1)
	v_add_f32_e32 v112, v112, v228
	v_add_f32_e32 v113, v113, v229
	v_mul_f32_e32 v112, 0xbfb8aa3b, v112
	v_mul_f32_e32 v113, 0xbfb8aa3b, v113
	v_exp_f32_e32 v112, v112
	v_exp_f32_e32 v113, v113
	v_and_b32_e32 v139, 0xffff0000, v224
	v_add_f32_e32 v114, v114, v230
	v_add_f32_e32 v115, v115, v231
	v_pk_add_f32 v[112:113], v[112:113], 1.0 op_sel_hi:[1, 0]
	v_mul_f32_e32 v114, 0xbfb8aa3b, v114
	v_div_scale_f32 v116, s[0:1], v113, v113, 1.0
	v_rcp_f32_e32 v117, v116
	v_mul_f32_e32 v115, 0xbfb8aa3b, v115
	v_exp_f32_e32 v114, v114
	v_exp_f32_e32 v115, v115
	v_fma_f32 v126, -v116, v117, 1.0
	v_fmac_f32_e32 v117, v126, v117
	v_div_scale_f32 v126, vcc, 1.0, v113, 1.0
	v_mul_f32_e32 v131, v126, v117
	v_fma_f32 v135, -v116, v131, v126
	v_fmac_f32_e32 v131, v135, v117
	v_fma_f32 v116, -v116, v131, v126
	v_div_fmas_f32 v116, v116, v117, v131
	v_div_fixup_f32 v113, v116, v113, 1.0
	v_div_scale_f32 v116, s[0:1], v112, v112, 1.0
	v_rcp_f32_e32 v117, v116
	v_pk_add_f32 v[114:115], v[114:115], 1.0 op_sel_hi:[1, 0]
	v_fma_f32 v126, -v116, v117, 1.0
	v_div_scale_f32 v118, s[0:1], v115, v115, 1.0
	v_fmac_f32_e32 v117, v126, v117
	v_div_scale_f32 v126, vcc, 1.0, v112, 1.0
	v_rcp_f32_e32 v119, v118
	v_mul_f32_e32 v131, v126, v117
	v_fma_f32 v135, -v116, v131, v126
	v_fmac_f32_e32 v131, v135, v117
	v_fma_f32 v116, -v116, v131, v126
	v_fma_f32 v126, -v118, v119, 1.0
	v_div_fmas_f32 v116, v116, v117, v131
	v_fmac_f32_e32 v119, v126, v119
	v_div_scale_f32 v126, vcc, 1.0, v115, 1.0
; DI float bf_lo(unsigned u) { return __uint_as_float(u << 16); }
; DI float bf_hi(unsigned u) { return __uint_as_float(u & 0xffff0000u); }
; DI float sigmoidf_(float z) { return 1.0f / (1.0f + fast_exp(-z)); }
; DI void phase_glu(const Params& p, char* lds) {
;     ...
;     epi8_iter(acc, [&](int t, int n, float a, float b, float c, float d) {
;       const size_t off = (size_t)(mt * 256 + t) * 512 + nt * 256 + n;
;       const uint2 yy = *(const uint2*)(yg + off);
;       const float4 bb = *(const float4*)(p.b_glu + nt * 256 + n);
;       store_bf4(so + off, bf_lo(yy.x) * sigmoidf_(a + bb.x), bf_hi(yy.x) * sigmoidf_(b + bb.y), bf_lo(yy.y) * sigmoidf_(c + bb.z),
;                 bf_hi(yy.y) * sigmoidf_(d + bb.w));
;     });
	v_div_fixup_f32 v112, v116, v112, 1.0
	v_lshlrev_b32_e32 v116, 16, v225
	v_and_b32_e32 v117, 0xffff0000, v225
	v_mul_f32_e32 v127, v126, v119
	v_fma_f32 v131, -v118, v127, v126
	v_fmac_f32_e32 v127, v131, v119
	v_fma_f32 v118, -v118, v127, v126
	v_div_fmas_f32 v118, v118, v119, v127
	v_div_fixup_f32 v115, v118, v115, 1.0
	v_div_scale_f32 v118, s[0:1], v114, v114, 1.0
	v_rcp_f32_e32 v119, v118
	v_pk_mul_f32 v[112:113], v[112:113], v[138:139]
	v_fma_f32 v126, -v118, v119, 1.0
	v_fmac_f32_e32 v119, v126, v119
	v_div_scale_f32 v126, vcc, 1.0, v114, 1.0
	v_mul_f32_e32 v127, v126, v119
	v_fma_f32 v131, -v118, v127, v126
	v_fmac_f32_e32 v127, v131, v119
	v_fma_f32 v118, -v118, v127, v126
	v_div_fmas_f32 v118, v118, v119, v127
	v_div_fixup_f32 v114, v118, v114, 1.0
	v_pk_mul_f32 v[114:115], v[114:115], v[116:117]
	v_cvt_pk_bf16_f32 v112, v112, v113
	v_cvt_pk_bf16_f32 v113, v114, v115
	global_store_dwordx2 v[122:123], v[112:113], off
	v_or_b32_e32 v112, 32, v130
	v_ashrrev_i32_e32 v113, 31, v112
	v_lshl_add_u64 v[112:113], v[112:113], 0, s[96:97]
	v_lshl_add_u64 v[114:115], v[112:113], 0, v[132:133]
	v_lshlrev_b64 v[118:119], 1, v[114:115]
	v_lshl_add_u64 v[114:115], s[26:27], 0, v[118:119]
	global_load_dwordx2 v[122:123], v[114:115], off
	global_load_dwordx4 v[176:179], v[172:173], off offset:128
	v_lshl_add_u64 v[182:183], v[184:185], 0, v[112:113]
	v_lshlrev_b64 v[186:187], 1, v[182:183]
	v_lshl_add_u64 v[188:189], s[26:27], 0, v[186:187]
	global_load_dwordx2 v[190:191], v[188:189], off
	global_load_dwordx4 v[192:195], v[172:173], off offset:128
	s_nop 0
	v_lshl_add_u64 v[118:119], s[36:37], 0, v[118:119]
	s_waitcnt vmcnt(3)
	v_lshlrev_b32_e32 v126, 16, v122
	s_waitcnt vmcnt(2)
	v_add_f32_e32 v108, v108, v176
	v_add_f32_e32 v109, v109, v177
	v_mul_f32_e32 v108, 0xbfb8aa3b, v108
	v_mul_f32_e32 v109, 0xbfb8aa3b, v109
	v_exp_f32_e32 v108, v108
	v_exp_f32_e32 v109, v109
	v_and_b32_e32 v127, 0xffff0000, v122
	v_add_f32_e32 v110, v110, v178
	v_add_f32_e32 v111, v111, v179
	v_pk_add_f32 v[108:109], v[108:109], 1.0 op_sel_hi:[1, 0]
	v_mul_f32_e32 v110, 0xbfb8aa3b, v110
	v_div_scale_f32 v114, s[0:1], v109, v109, 1.0
	v_rcp_f32_e32 v115, v114
	v_mul_f32_e32 v111, 0xbfb8aa3b, v111
	v_exp_f32_e32 v110, v110
	v_exp_f32_e32 v111, v111
	v_fma_f32 v122, -v114, v115, 1.0
	v_fmac_f32_e32 v115, v122, v115
	v_div_scale_f32 v122, vcc, 1.0, v109, 1.0
	v_mul_f32_e32 v131, v122, v115
	v_fma_f32 v135, -v114, v131, v122
	v_fmac_f32_e32 v131, v135, v115
	v_fma_f32 v114, -v114, v131, v122
	v_div_fmas_f32 v114, v114, v115, v131
	v_div_fixup_f32 v109, v114, v109, 1.0
	v_div_scale_f32 v114, s[0:1], v108, v108, 1.0
	v_rcp_f32_e32 v115, v114
	v_pk_add_f32 v[110:111], v[110:111], 1.0 op_sel_hi:[1, 0]
	v_fma_f32 v122, -v114, v115, 1.0
	v_div_scale_f32 v116, s[0:1], v111, v111, 1.0
	v_fmac_f32_e32 v115, v122, v115
	v_div_scale_f32 v122, vcc, 1.0, v108, 1.0
	v_rcp_f32_e32 v117, v116
	v_mul_f32_e32 v131, v122, v115
	v_fma_f32 v135, -v114, v131, v122
	v_fmac_f32_e32 v131, v135, v115
	v_fma_f32 v114, -v114, v131, v122
	v_fma_f32 v122, -v116, v117, 1.0
	v_div_fmas_f32 v114, v114, v115, v131
	v_fmac_f32_e32 v117, v122, v117
	v_div_scale_f32 v122, vcc, 1.0, v111, 1.0
	v_div_fixup_f32 v108, v114, v108, 1.0
	v_lshlrev_b32_e32 v114, 16, v123
	v_and_b32_e32 v115, 0xffff0000, v123
	v_mul_f32_e32 v123, v122, v117
	v_pk_mul_f32 v[108:109], v[108:109], v[126:127]
	v_fma_f32 v126, -v116, v123, v122
	v_fmac_f32_e32 v123, v126, v117
	v_fma_f32 v116, -v116, v123, v122
	v_div_fmas_f32 v116, v116, v117, v123
	v_div_fixup_f32 v111, v116, v111, 1.0
	v_div_scale_f32 v116, s[0:1], v110, v110, 1.0
	v_rcp_f32_e32 v117, v116
	v_cvt_pk_bf16_f32 v108, v108, v109
	v_fma_f32 v122, -v116, v117, 1.0
	v_fmac_f32_e32 v117, v122, v117
	v_div_scale_f32 v122, vcc, 1.0, v110, 1.0
	v_mul_f32_e32 v123, v122, v117
	v_fma_f32 v126, -v116, v123, v122
	v_fmac_f32_e32 v123, v126, v117
	v_fma_f32 v116, -v116, v123, v122
	v_div_fmas_f32 v116, v116, v117, v123
	v_div_fixup_f32 v110, v116, v110, 1.0
	v_pk_mul_f32 v[110:111], v[110:111], v[114:115]
	s_nop 0
	v_cvt_pk_bf16_f32 v109, v110, v111
	global_store_dwordx2 v[118:119], v[108:109], off
	s_nop 0
	v_lshl_add_u64 v[114:115], s[36:37], 0, v[186:187]
	s_waitcnt vmcnt(2)
	v_lshlrev_b32_e32 v118, 16, v190
	s_waitcnt vmcnt(1)
; DI float bf_lo(unsigned u) { return __uint_as_float(u << 16); }
; DI float bf_hi(unsigned u) { return __uint_as_float(u & 0xffff0000u); }
; DI float sigmoidf_(float z) { return 1.0f / (1.0f + fast_exp(-z)); }
; DI void phase_glu(const Params& p, char* lds) {
;     ...
;     epi8_iter(acc, [&](int t, int n, float a, float b, float c, float d) {
;       const size_t off = (size_t)(mt * 256 + t) * 512 + nt * 256 + n;
;       const uint2 yy = *(const uint2*)(yg + off);
;       const float4 bb = *(const float4*)(p.b_glu + nt * 256 + n);
;       store_bf4(so + off, bf_lo(yy.x) * sigmoidf_(a + bb.x), bf_hi(yy.x) * sigmoidf_(b + bb.y), bf_lo(yy.y) * sigmoidf_(c + bb.z),
;                 bf_hi(yy.y) * sigmoidf_(d + bb.w));
;     });
	v_add_f32_e32 v104, v104, v192
	v_add_f32_e32 v105, v105, v193
	v_mul_f32_e32 v104, 0xbfb8aa3b, v104
	v_mul_f32_e32 v105, 0xbfb8aa3b, v105
	v_exp_f32_e32 v104, v104
	v_exp_f32_e32 v105, v105
	v_and_b32_e32 v119, 0xffff0000, v190
	v_add_f32_e32 v106, v106, v194
	v_add_f32_e32 v107, v107, v195
	v_pk_add_f32 v[104:105], v[104:105], 1.0 op_sel_hi:[1, 0]
	v_mul_f32_e32 v106, 0xbfb8aa3b, v106
	v_div_scale_f32 v108, s[0:1], v105, v105, 1.0
	v_rcp_f32_e32 v109, v108
	v_mul_f32_e32 v107, 0xbfb8aa3b, v107
	v_exp_f32_e32 v106, v106
	v_exp_f32_e32 v107, v107
	v_fma_f32 v116, -v108, v109, 1.0
	v_fmac_f32_e32 v109, v116, v109
	v_div_scale_f32 v116, vcc, 1.0, v105, 1.0
	v_mul_f32_e32 v122, v116, v109
	v_fma_f32 v123, -v108, v122, v116
	v_fmac_f32_e32 v122, v123, v109
	v_fma_f32 v108, -v108, v122, v116
	v_div_fmas_f32 v108, v108, v109, v122
	v_div_fixup_f32 v105, v108, v105, 1.0
	v_div_scale_f32 v108, s[0:1], v104, v104, 1.0
	v_rcp_f32_e32 v109, v108
	v_pk_add_f32 v[106:107], v[106:107], 1.0 op_sel_hi:[1, 0]
	v_fma_f32 v116, -v108, v109, 1.0
	v_div_scale_f32 v110, s[0:1], v107, v107, 1.0
	v_fmac_f32_e32 v109, v116, v109
	v_div_scale_f32 v116, vcc, 1.0, v104, 1.0
	v_rcp_f32_e32 v111, v110
	v_mul_f32_e32 v122, v116, v109
	v_fma_f32 v123, -v108, v122, v116
	v_fmac_f32_e32 v122, v123, v109
	v_fma_f32 v108, -v108, v122, v116
	v_fma_f32 v116, -v110, v111, 1.0
	v_div_fmas_f32 v108, v108, v109, v122
	v_fmac_f32_e32 v111, v116, v111
	v_div_scale_f32 v116, vcc, 1.0, v107, 1.0
	v_div_fixup_f32 v104, v108, v104, 1.0
	v_lshlrev_b32_e32 v108, 16, v191
	v_and_b32_e32 v109, 0xffff0000, v191
	v_mul_f32_e32 v117, v116, v111
	v_pk_mul_f32 v[104:105], v[104:105], v[118:119]
	v_fma_f32 v118, -v110, v117, v116
	v_fmac_f32_e32 v117, v118, v111
	v_fma_f32 v110, -v110, v117, v116
	v_div_fmas_f32 v110, v110, v111, v117
	v_div_fixup_f32 v107, v110, v107, 1.0
	v_div_scale_f32 v110, s[0:1], v106, v106, 1.0
	v_rcp_f32_e32 v111, v110
	v_cvt_pk_bf16_f32 v104, v104, v105
	v_fma_f32 v116, -v110, v111, 1.0
	v_fmac_f32_e32 v111, v116, v111
	v_div_scale_f32 v116, vcc, 1.0, v106, 1.0
	v_mul_f32_e32 v117, v116, v111
	v_fma_f32 v118, -v110, v117, v116
	v_fmac_f32_e32 v117, v118, v111
	v_fma_f32 v110, -v110, v117, v116
	v_div_fmas_f32 v110, v110, v111, v117
	v_div_fixup_f32 v106, v110, v106, 1.0
	v_pk_mul_f32 v[106:107], v[106:107], v[108:109]
	s_nop 0
	v_cvt_pk_bf16_f32 v105, v106, v107
	global_store_dwordx2 v[114:115], v[104:105], off
	v_or_b32_e32 v104, 48, v130
	v_ashrrev_i32_e32 v105, 31, v104
	v_lshl_add_u64 v[104:105], v[104:105], 0, s[96:97]
	v_lshl_add_u64 v[106:107], v[104:105], 0, v[132:133]
	v_lshlrev_b64 v[110:111], 1, v[106:107]
	v_lshl_add_u64 v[106:107], s[26:27], 0, v[110:111]
	global_load_dwordx2 v[114:115], v[106:107], off
	global_load_dwordx4 v[216:219], v[172:173], off offset:192
	v_lshl_add_u64 v[212:213], v[184:185], 0, v[104:105]
	v_lshlrev_b64 v[220:221], 1, v[212:213]
	v_lshl_add_u64 v[224:225], s[26:27], 0, v[220:221]
	global_load_dwordx2 v[226:227], v[224:225], off
	global_load_dwordx4 v[228:231], v[172:173], off offset:192
	s_nop 0
	v_lshl_add_u64 v[110:111], s[36:37], 0, v[110:111]
	s_waitcnt vmcnt(3)
	v_lshlrev_b32_e32 v116, 16, v114
	s_waitcnt vmcnt(2)
	v_add_f32_e32 v100, v100, v216
	v_add_f32_e32 v101, v101, v217
	v_mul_f32_e32 v100, 0xbfb8aa3b, v100
	v_mul_f32_e32 v101, 0xbfb8aa3b, v101
	v_exp_f32_e32 v100, v100
	v_exp_f32_e32 v101, v101
	v_and_b32_e32 v117, 0xffff0000, v114
	v_add_f32_e32 v102, v102, v218
	v_add_f32_e32 v103, v103, v219
	v_pk_add_f32 v[100:101], v[100:101], 1.0 op_sel_hi:[1, 0]
	v_mul_f32_e32 v102, 0xbfb8aa3b, v102
	v_div_scale_f32 v106, s[0:1], v101, v101, 1.0
	v_rcp_f32_e32 v107, v106
	v_mul_f32_e32 v103, 0xbfb8aa3b, v103
	v_exp_f32_e32 v102, v102
	v_exp_f32_e32 v103, v103
	v_fma_f32 v114, -v106, v107, 1.0
	v_fmac_f32_e32 v107, v114, v107
	v_div_scale_f32 v114, vcc, 1.0, v101, 1.0
	v_mul_f32_e32 v118, v114, v107
	v_fma_f32 v119, -v106, v118, v114
	v_fmac_f32_e32 v118, v119, v107
	v_fma_f32 v106, -v106, v118, v114
	v_div_fmas_f32 v106, v106, v107, v118
	v_div_fixup_f32 v101, v106, v101, 1.0
	v_div_scale_f32 v106, s[0:1], v100, v100, 1.0
	v_rcp_f32_e32 v107, v106
	v_pk_add_f32 v[102:103], v[102:103], 1.0 op_sel_hi:[1, 0]
	v_fma_f32 v114, -v106, v107, 1.0
	v_div_scale_f32 v108, s[0:1], v103, v103, 1.0
	v_fmac_f32_e32 v107, v114, v107
	v_div_scale_f32 v114, vcc, 1.0, v100, 1.0
	v_rcp_f32_e32 v109, v108
	v_mul_f32_e32 v118, v114, v107
	v_fma_f32 v119, -v106, v118, v114
	v_fmac_f32_e32 v118, v119, v107
	v_fma_f32 v106, -v106, v118, v114
	v_fma_f32 v114, -v108, v109, 1.0
	v_div_fmas_f32 v106, v106, v107, v118
	v_fmac_f32_e32 v109, v114, v109
	v_div_scale_f32 v114, vcc, 1.0, v103, 1.0
	v_div_fixup_f32 v100, v106, v100, 1.0
	v_lshlrev_b32_e32 v106, 16, v115
	v_and_b32_e32 v107, 0xffff0000, v115
	v_mul_f32_e32 v115, v114, v109
	v_pk_mul_f32 v[100:101], v[100:101], v[116:117]
	v_fma_f32 v116, -v108, v115, v114
	v_fmac_f32_e32 v115, v116, v109
	v_fma_f32 v108, -v108, v115, v114
	v_div_fmas_f32 v108, v108, v109, v115
	v_div_fixup_f32 v103, v108, v103, 1.0
	v_div_scale_f32 v108, s[0:1], v102, v102, 1.0
	v_rcp_f32_e32 v109, v108
	v_cvt_pk_bf16_f32 v100, v100, v101
	v_fma_f32 v114, -v108, v109, 1.0
	v_fmac_f32_e32 v109, v114, v109
	v_div_scale_f32 v114, vcc, 1.0, v102, 1.0
	v_mul_f32_e32 v115, v114, v109
	v_fma_f32 v116, -v108, v115, v114
	v_fmac_f32_e32 v115, v116, v109
	v_fma_f32 v108, -v108, v115, v114
	v_div_fmas_f32 v108, v108, v109, v115
	v_div_fixup_f32 v102, v108, v102, 1.0
	v_pk_mul_f32 v[102:103], v[102:103], v[106:107]
	s_nop 0
	v_cvt_pk_bf16_f32 v101, v102, v103
	global_store_dwordx2 v[110:111], v[100:101], off
	s_nop 0
	v_lshl_add_u64 v[106:107], s[36:37], 0, v[220:221]
	s_waitcnt vmcnt(2)
; DI float bf_lo(unsigned u) { return __uint_as_float(u << 16); }
; DI float bf_hi(unsigned u) { return __uint_as_float(u & 0xffff0000u); }
; DI float sigmoidf_(float z) { return 1.0f / (1.0f + fast_exp(-z)); }
; DI void phase_glu(const Params& p, char* lds) {
;     ...
;     epi8_iter(acc, [&](int t, int n, float a, float b, float c, float d) {
;       const size_t off = (size_t)(mt * 256 + t) * 512 + nt * 256 + n;
;       const uint2 yy = *(const uint2*)(yg + off);
;       const float4 bb = *(const float4*)(p.b_glu + nt * 256 + n);
;       store_bf4(so + off, bf_lo(yy.x) * sigmoidf_(a + bb.x), bf_hi(yy.x) * sigmoidf_(b + bb.y), bf_lo(yy.y) * sigmoidf_(c + bb.z),
;                 bf_hi(yy.y) * sigmoidf_(d + bb.w));
;     });
	v_lshlrev_b32_e32 v110, 16, v226
	s_waitcnt vmcnt(1)
	v_add_f32_e32 v96, v96, v228
	v_add_f32_e32 v97, v97, v229
	v_mul_f32_e32 v96, 0xbfb8aa3b, v96
	v_mul_f32_e32 v97, 0xbfb8aa3b, v97
	v_exp_f32_e32 v96, v96
	v_exp_f32_e32 v97, v97
	v_and_b32_e32 v111, 0xffff0000, v226
	v_add_f32_e32 v98, v98, v230
	v_add_f32_e32 v99, v99, v231
	v_pk_add_f32 v[96:97], v[96:97], 1.0 op_sel_hi:[1, 0]
	v_mul_f32_e32 v98, 0xbfb8aa3b, v98
	v_div_scale_f32 v100, s[0:1], v97, v97, 1.0
	v_rcp_f32_e32 v101, v100
	v_mul_f32_e32 v99, 0xbfb8aa3b, v99
	v_exp_f32_e32 v98, v98
	v_exp_f32_e32 v99, v99
	v_fma_f32 v108, -v100, v101, 1.0
	v_fmac_f32_e32 v101, v108, v101
	v_div_scale_f32 v108, vcc, 1.0, v97, 1.0
	v_mul_f32_e32 v114, v108, v101
	v_fma_f32 v115, -v100, v114, v108
	v_fmac_f32_e32 v114, v115, v101
	v_fma_f32 v100, -v100, v114, v108
	v_div_fmas_f32 v100, v100, v101, v114
	v_div_fixup_f32 v97, v100, v97, 1.0
	v_div_scale_f32 v100, s[0:1], v96, v96, 1.0
	v_rcp_f32_e32 v101, v100
	v_pk_add_f32 v[98:99], v[98:99], 1.0 op_sel_hi:[1, 0]
	v_fma_f32 v108, -v100, v101, 1.0
	v_div_scale_f32 v102, s[0:1], v99, v99, 1.0
	v_fmac_f32_e32 v101, v108, v101
	v_div_scale_f32 v108, vcc, 1.0, v96, 1.0
	v_rcp_f32_e32 v103, v102
	v_mul_f32_e32 v114, v108, v101
	v_fma_f32 v115, -v100, v114, v108
	v_fmac_f32_e32 v114, v115, v101
	v_fma_f32 v100, -v100, v114, v108
	v_fma_f32 v108, -v102, v103, 1.0
	v_div_fmas_f32 v100, v100, v101, v114
	v_fmac_f32_e32 v103, v108, v103
	v_div_scale_f32 v108, vcc, 1.0, v99, 1.0
	v_div_fixup_f32 v96, v100, v96, 1.0
	v_lshlrev_b32_e32 v100, 16, v227
	v_and_b32_e32 v101, 0xffff0000, v227
	v_mul_f32_e32 v109, v108, v103
	v_pk_mul_f32 v[96:97], v[96:97], v[110:111]
	v_fma_f32 v110, -v102, v109, v108
	v_fmac_f32_e32 v109, v110, v103
	v_fma_f32 v102, -v102, v109, v108
	v_div_fmas_f32 v102, v102, v103, v109
	v_div_fixup_f32 v99, v102, v99, 1.0
	v_div_scale_f32 v102, s[0:1], v98, v98, 1.0
	v_rcp_f32_e32 v103, v102
	v_cvt_pk_bf16_f32 v96, v96, v97
	v_fma_f32 v108, -v102, v103, 1.0
	v_fmac_f32_e32 v103, v108, v103
	v_div_scale_f32 v108, vcc, 1.0, v98, 1.0
	v_mul_f32_e32 v109, v108, v103
	v_fma_f32 v110, -v102, v109, v108
	v_fmac_f32_e32 v109, v110, v103
	v_fma_f32 v102, -v102, v109, v108
	v_div_fmas_f32 v102, v102, v103, v109
	v_div_fixup_f32 v98, v102, v98, 1.0
	v_pk_mul_f32 v[98:99], v[98:99], v[100:101]
	s_nop 0
	v_cvt_pk_bf16_f32 v97, v98, v99
	global_store_dwordx2 v[106:107], v[96:97], off
	v_or_b32_e32 v96, 0x80, v134
	v_ashrrev_i32_e32 v97, 31, v96
	v_lshlrev_b64 v[96:97], 9, v[96:97]
	v_lshl_add_u64 v[98:99], v[96:97], 0, v[136:137]
	v_lshlrev_b64 v[102:103], 1, v[98:99]
	v_lshl_add_u64 v[98:99], s[26:27], 0, v[102:103]
	global_load_dwordx2 v[106:107], v[98:99], off
	global_load_dwordx4 v[176:179], v[172:173], off
	v_or_b32_e32 v182, 0x90, v134
	v_ashrrev_i32_e32 v183, 31, v182
	v_lshlrev_b64 v[186:187], 9, v[182:183]
	v_lshl_add_u64 v[188:189], v[186:187], 0, v[136:137]
	v_lshlrev_b64 v[190:191], 1, v[188:189]
	v_lshl_add_u64 v[192:193], s[26:27], 0, v[190:191]
	global_load_dwordx2 v[194:195], v[192:193], off
	global_load_dwordx4 v[196:199], v[172:173], off
	s_nop 0
	v_lshl_add_u64 v[102:103], s[36:37], 0, v[102:103]
	s_waitcnt vmcnt(3)
	v_lshlrev_b32_e32 v108, 16, v106
	s_waitcnt vmcnt(2)
	v_add_f32_e32 v92, v92, v176
	v_add_f32_e32 v93, v93, v177
	v_mul_f32_e32 v92, 0xbfb8aa3b, v92
	v_mul_f32_e32 v93, 0xbfb8aa3b, v93
	v_exp_f32_e32 v92, v92
	v_exp_f32_e32 v93, v93
	v_and_b32_e32 v109, 0xffff0000, v106
	v_add_f32_e32 v94, v94, v178
	v_add_f32_e32 v95, v95, v179
	v_pk_add_f32 v[92:93], v[92:93], 1.0 op_sel_hi:[1, 0]
	v_mul_f32_e32 v94, 0xbfb8aa3b, v94
	v_div_scale_f32 v98, s[0:1], v93, v93, 1.0
	v_rcp_f32_e32 v99, v98
	v_mul_f32_e32 v95, 0xbfb8aa3b, v95
	v_exp_f32_e32 v94, v94
	v_exp_f32_e32 v95, v95
	v_fma_f32 v106, -v98, v99, 1.0
	v_fmac_f32_e32 v99, v106, v99
	v_div_scale_f32 v106, vcc, 1.0, v93, 1.0
	v_mul_f32_e32 v110, v106, v99
	v_fma_f32 v111, -v98, v110, v106
	v_fmac_f32_e32 v110, v111, v99
	v_fma_f32 v98, -v98, v110, v106
	v_div_fmas_f32 v98, v98, v99, v110
	v_div_fixup_f32 v93, v98, v93, 1.0
	v_div_scale_f32 v98, s[0:1], v92, v92, 1.0
	v_rcp_f32_e32 v99, v98
	v_pk_add_f32 v[94:95], v[94:95], 1.0 op_sel_hi:[1, 0]
	v_fma_f32 v106, -v98, v99, 1.0
	v_div_scale_f32 v100, s[0:1], v95, v95, 1.0
	v_fmac_f32_e32 v99, v106, v99
	v_div_scale_f32 v106, vcc, 1.0, v92, 1.0
	v_rcp_f32_e32 v101, v100
	v_mul_f32_e32 v110, v106, v99
	v_fma_f32 v111, -v98, v110, v106
	v_fmac_f32_e32 v110, v111, v99
	v_fma_f32 v98, -v98, v110, v106
	v_fma_f32 v106, -v100, v101, 1.0
	v_div_fmas_f32 v98, v98, v99, v110
	v_fmac_f32_e32 v101, v106, v101
	v_div_scale_f32 v106, vcc, 1.0, v95, 1.0
	v_div_fixup_f32 v92, v98, v92, 1.0
	v_lshlrev_b32_e32 v98, 16, v107
	v_and_b32_e32 v99, 0xffff0000, v107
	v_mul_f32_e32 v107, v106, v101
	v_pk_mul_f32 v[92:93], v[92:93], v[108:109]
	v_fma_f32 v108, -v100, v107, v106
	v_fmac_f32_e32 v107, v108, v101
	v_fma_f32 v100, -v100, v107, v106
	v_div_fmas_f32 v100, v100, v101, v107
	v_div_fixup_f32 v95, v100, v95, 1.0
	v_div_scale_f32 v100, s[0:1], v94, v94, 1.0
	v_rcp_f32_e32 v101, v100
	v_cvt_pk_bf16_f32 v92, v92, v93
	v_fma_f32 v106, -v100, v101, 1.0
	v_fmac_f32_e32 v101, v106, v101
	v_div_scale_f32 v106, vcc, 1.0, v94, 1.0
	v_mul_f32_e32 v107, v106, v101
	v_fma_f32 v108, -v100, v107, v106
	v_fmac_f32_e32 v107, v108, v101
	v_fma_f32 v100, -v100, v107, v106
	v_div_fmas_f32 v100, v100, v101, v107
	v_div_fixup_f32 v94, v100, v94, 1.0
	v_pk_mul_f32 v[94:95], v[94:95], v[98:99]
	s_nop 0
	v_cvt_pk_bf16_f32 v93, v94, v95
	global_store_dwordx2 v[102:103], v[92:93], off
	s_nop 0
	v_lshl_add_u64 v[94:95], s[36:37], 0, v[190:191]
	s_waitcnt vmcnt(2)
; DI float bf_lo(unsigned u) { return __uint_as_float(u << 16); }
; DI float bf_hi(unsigned u) { return __uint_as_float(u & 0xffff0000u); }
; DI float sigmoidf_(float z) { return 1.0f / (1.0f + fast_exp(-z)); }
; DI void phase_glu(const Params& p, char* lds) {
;     ...
;     epi8_iter(acc, [&](int t, int n, float a, float b, float c, float d) {
;       const size_t off = (size_t)(mt * 256 + t) * 512 + nt * 256 + n;
;       const uint2 yy = *(const uint2*)(yg + off);
;       const float4 bb = *(const float4*)(p.b_glu + nt * 256 + n);
;       store_bf4(so + off, bf_lo(yy.x) * sigmoidf_(a + bb.x), bf_hi(yy.x) * sigmoidf_(b + bb.y), bf_lo(yy.y) * sigmoidf_(c + bb.z),
;                 bf_hi(yy.y) * sigmoidf_(d + bb.w));
;     });
	v_lshlrev_b32_e32 v106, 16, v194
	s_waitcnt vmcnt(1)
	v_add_f32_e32 v88, v88, v196
	v_add_f32_e32 v89, v89, v197
	v_mul_f32_e32 v88, 0xbfb8aa3b, v88
	v_mul_f32_e32 v89, 0xbfb8aa3b, v89
	v_exp_f32_e32 v88, v88
	v_exp_f32_e32 v89, v89
	v_and_b32_e32 v107, 0xffff0000, v194
	v_add_f32_e32 v90, v90, v198
	v_add_f32_e32 v91, v91, v199
	v_pk_add_f32 v[88:89], v[88:89], 1.0 op_sel_hi:[1, 0]
	v_mul_f32_e32 v90, 0xbfb8aa3b, v90
	v_div_scale_f32 v98, s[0:1], v89, v89, 1.0
	v_rcp_f32_e32 v99, v98
	v_mul_f32_e32 v91, 0xbfb8aa3b, v91
	v_exp_f32_e32 v90, v90
	v_exp_f32_e32 v91, v91
	v_fma_f32 v102, -v98, v99, 1.0
	v_fmac_f32_e32 v99, v102, v99
	v_div_scale_f32 v102, vcc, 1.0, v89, 1.0
	v_mul_f32_e32 v108, v102, v99
	v_fma_f32 v109, -v98, v108, v102
	v_fmac_f32_e32 v108, v109, v99
	v_fma_f32 v98, -v98, v108, v102
	v_div_fmas_f32 v98, v98, v99, v108
	v_div_fixup_f32 v89, v98, v89, 1.0
	v_div_scale_f32 v98, s[0:1], v88, v88, 1.0
	v_rcp_f32_e32 v99, v98
	v_pk_add_f32 v[90:91], v[90:91], 1.0 op_sel_hi:[1, 0]
	v_fma_f32 v102, -v98, v99, 1.0
	v_div_scale_f32 v100, s[0:1], v91, v91, 1.0
	v_fmac_f32_e32 v99, v102, v99
	v_div_scale_f32 v102, vcc, 1.0, v88, 1.0
	v_rcp_f32_e32 v101, v100
	v_mul_f32_e32 v108, v102, v99
	v_fma_f32 v109, -v98, v108, v102
	v_fmac_f32_e32 v108, v109, v99
	v_fma_f32 v98, -v98, v108, v102
	v_fma_f32 v102, -v100, v101, 1.0
	v_div_fmas_f32 v98, v98, v99, v108
	v_fmac_f32_e32 v101, v102, v101
	v_div_scale_f32 v102, vcc, 1.0, v91, 1.0
	v_div_fixup_f32 v88, v98, v88, 1.0
	v_lshlrev_b32_e32 v98, 16, v195
	v_and_b32_e32 v99, 0xffff0000, v195
	v_mul_f32_e32 v103, v102, v101
	v_pk_mul_f32 v[88:89], v[88:89], v[106:107]
	v_fma_f32 v106, -v100, v103, v102
	v_fmac_f32_e32 v103, v106, v101
	v_fma_f32 v100, -v100, v103, v102
	v_div_fmas_f32 v100, v100, v101, v103
	v_div_fixup_f32 v91, v100, v91, 1.0
	v_div_scale_f32 v100, s[0:1], v90, v90, 1.0
	v_rcp_f32_e32 v101, v100
	v_cvt_pk_bf16_f32 v88, v88, v89
	v_fma_f32 v102, -v100, v101, 1.0
	v_fmac_f32_e32 v101, v102, v101
	v_div_scale_f32 v102, vcc, 1.0, v90, 1.0
	v_mul_f32_e32 v103, v102, v101
	v_fma_f32 v106, -v100, v103, v102
	v_fmac_f32_e32 v103, v106, v101
	v_fma_f32 v100, -v100, v103, v102
	v_div_fmas_f32 v100, v100, v101, v103
	v_div_fixup_f32 v90, v100, v90, 1.0
	v_pk_mul_f32 v[90:91], v[90:91], v[98:99]
	s_nop 0
	v_cvt_pk_bf16_f32 v89, v90, v91
	global_store_dwordx2 v[94:95], v[88:89], off
	v_lshl_add_u64 v[88:89], v[96:97], 0, v[120:121]
	v_lshlrev_b64 v[94:95], 1, v[88:89]
	v_lshl_add_u64 v[88:89], s[26:27], 0, v[94:95]
	global_load_dwordx2 v[98:99], v[88:89], off
	global_load_dwordx4 v[216:219], v[172:173], off offset:64
	v_lshl_add_u64 v[212:213], v[186:187], 0, v[120:121]
	v_lshlrev_b64 v[220:221], 1, v[212:213]
	v_lshl_add_u64 v[224:225], s[26:27], 0, v[220:221]
	global_load_dwordx2 v[226:227], v[224:225], off
	global_load_dwordx4 v[228:231], v[172:173], off offset:64
	s_nop 0
	v_lshl_add_u64 v[94:95], s[36:37], 0, v[94:95]
	s_waitcnt vmcnt(3)
	v_lshlrev_b32_e32 v100, 16, v98
	s_waitcnt vmcnt(2)
	v_add_f32_e32 v84, v84, v216
	v_add_f32_e32 v85, v85, v217
	v_mul_f32_e32 v84, 0xbfb8aa3b, v84
	v_mul_f32_e32 v85, 0xbfb8aa3b, v85
	v_exp_f32_e32 v84, v84
	v_exp_f32_e32 v85, v85
	v_and_b32_e32 v101, 0xffff0000, v98
	v_add_f32_e32 v86, v86, v218
	v_add_f32_e32 v87, v87, v219
	v_pk_add_f32 v[84:85], v[84:85], 1.0 op_sel_hi:[1, 0]
	v_mul_f32_e32 v86, 0xbfb8aa3b, v86
	v_div_scale_f32 v88, s[0:1], v85, v85, 1.0
	v_rcp_f32_e32 v89, v88
	v_mul_f32_e32 v87, 0xbfb8aa3b, v87
	v_exp_f32_e32 v86, v86
	v_exp_f32_e32 v87, v87
	v_fma_f32 v98, -v88, v89, 1.0
	v_fmac_f32_e32 v89, v98, v89
	v_div_scale_f32 v98, vcc, 1.0, v85, 1.0
	v_mul_f32_e32 v102, v98, v89
	v_fma_f32 v103, -v88, v102, v98
	v_fmac_f32_e32 v102, v103, v89
	v_fma_f32 v88, -v88, v102, v98
	v_div_fmas_f32 v88, v88, v89, v102
	v_div_fixup_f32 v85, v88, v85, 1.0
	v_div_scale_f32 v88, s[0:1], v84, v84, 1.0
	v_rcp_f32_e32 v89, v88
	v_pk_add_f32 v[86:87], v[86:87], 1.0 op_sel_hi:[1, 0]
	v_fma_f32 v98, -v88, v89, 1.0
	v_div_scale_f32 v90, s[0:1], v87, v87, 1.0
	v_fmac_f32_e32 v89, v98, v89
	v_div_scale_f32 v98, vcc, 1.0, v84, 1.0
	v_rcp_f32_e32 v91, v90
	v_mul_f32_e32 v102, v98, v89
	v_fma_f32 v103, -v88, v102, v98
	v_fmac_f32_e32 v102, v103, v89
	v_fma_f32 v88, -v88, v102, v98
	v_fma_f32 v98, -v90, v91, 1.0
	v_div_fmas_f32 v88, v88, v89, v102
	v_fmac_f32_e32 v91, v98, v91
	v_div_scale_f32 v98, vcc, 1.0, v87, 1.0
	v_div_fixup_f32 v84, v88, v84, 1.0
	v_lshlrev_b32_e32 v88, 16, v99
	v_and_b32_e32 v89, 0xffff0000, v99
	v_mul_f32_e32 v99, v98, v91
	v_pk_mul_f32 v[84:85], v[84:85], v[100:101]
	v_fma_f32 v100, -v90, v99, v98
	v_fmac_f32_e32 v99, v100, v91
	v_fma_f32 v90, -v90, v99, v98
	v_div_fmas_f32 v90, v90, v91, v99
	v_div_fixup_f32 v87, v90, v87, 1.0
	v_div_scale_f32 v90, s[0:1], v86, v86, 1.0
	v_rcp_f32_e32 v91, v90
	v_cvt_pk_bf16_f32 v84, v84, v85
	v_fma_f32 v98, -v90, v91, 1.0
	v_fmac_f32_e32 v91, v98, v91
	v_div_scale_f32 v98, vcc, 1.0, v86, 1.0
	v_mul_f32_e32 v99, v98, v91
	v_fma_f32 v100, -v90, v99, v98
	v_fmac_f32_e32 v99, v100, v91
	v_fma_f32 v90, -v90, v99, v98
	v_div_fmas_f32 v90, v90, v91, v99
	v_div_fixup_f32 v86, v90, v86, 1.0
	v_pk_mul_f32 v[86:87], v[86:87], v[88:89]
	s_nop 0
	v_cvt_pk_bf16_f32 v85, v86, v87
	global_store_dwordx2 v[94:95], v[84:85], off
	s_nop 0
	v_lshl_add_u64 v[88:89], s[36:37], 0, v[220:221]
	s_waitcnt vmcnt(2)
	v_lshlrev_b32_e32 v94, 16, v226
	s_waitcnt vmcnt(1)
; DI float bf_lo(unsigned u) { return __uint_as_float(u << 16); }
; DI float bf_hi(unsigned u) { return __uint_as_float(u & 0xffff0000u); }
; DI float sigmoidf_(float z) { return 1.0f / (1.0f + fast_exp(-z)); }
; DI void phase_glu(const Params& p, char* lds) {
;     ...
;     epi8_iter(acc, [&](int t, int n, float a, float b, float c, float d) {
;       const size_t off = (size_t)(mt * 256 + t) * 512 + nt * 256 + n;
;       const uint2 yy = *(const uint2*)(yg + off);
;       const float4 bb = *(const float4*)(p.b_glu + nt * 256 + n);
;       store_bf4(so + off, bf_lo(yy.x) * sigmoidf_(a + bb.x), bf_hi(yy.x) * sigmoidf_(b + bb.y), bf_lo(yy.y) * sigmoidf_(c + bb.z),
;                 bf_hi(yy.y) * sigmoidf_(d + bb.w));
;     });
	v_add_f32_e32 v80, v80, v228
	v_add_f32_e32 v81, v81, v229
	v_mul_f32_e32 v80, 0xbfb8aa3b, v80
	v_mul_f32_e32 v81, 0xbfb8aa3b, v81
	v_exp_f32_e32 v80, v80
	v_exp_f32_e32 v81, v81
	v_and_b32_e32 v95, 0xffff0000, v226
	v_add_f32_e32 v82, v82, v230
	v_add_f32_e32 v83, v83, v231
	v_pk_add_f32 v[80:81], v[80:81], 1.0 op_sel_hi:[1, 0]
	v_mul_f32_e32 v82, 0xbfb8aa3b, v82
	v_div_scale_f32 v84, s[0:1], v81, v81, 1.0
	v_rcp_f32_e32 v85, v84
	v_mul_f32_e32 v83, 0xbfb8aa3b, v83
	v_exp_f32_e32 v82, v82
	v_exp_f32_e32 v83, v83
	v_fma_f32 v90, -v84, v85, 1.0
	v_fmac_f32_e32 v85, v90, v85
	v_div_scale_f32 v90, vcc, 1.0, v81, 1.0
	v_mul_f32_e32 v98, v90, v85
	v_fma_f32 v99, -v84, v98, v90
	v_fmac_f32_e32 v98, v99, v85
	v_fma_f32 v84, -v84, v98, v90
	v_div_fmas_f32 v84, v84, v85, v98
	v_div_fixup_f32 v81, v84, v81, 1.0
	v_div_scale_f32 v84, s[0:1], v80, v80, 1.0
	v_rcp_f32_e32 v85, v84
	v_pk_add_f32 v[82:83], v[82:83], 1.0 op_sel_hi:[1, 0]
	v_fma_f32 v90, -v84, v85, 1.0
	v_div_scale_f32 v86, s[0:1], v83, v83, 1.0
	v_fmac_f32_e32 v85, v90, v85
	v_div_scale_f32 v90, vcc, 1.0, v80, 1.0
	v_rcp_f32_e32 v87, v86
	v_mul_f32_e32 v98, v90, v85
	v_fma_f32 v99, -v84, v98, v90
	v_fmac_f32_e32 v98, v99, v85
	v_fma_f32 v84, -v84, v98, v90
	v_fma_f32 v90, -v86, v87, 1.0
	v_div_fmas_f32 v84, v84, v85, v98
	v_fmac_f32_e32 v87, v90, v87
	v_div_scale_f32 v90, vcc, 1.0, v83, 1.0
	v_div_fixup_f32 v80, v84, v80, 1.0
	v_lshlrev_b32_e32 v84, 16, v227
	v_and_b32_e32 v85, 0xffff0000, v227
	v_mul_f32_e32 v91, v90, v87
	v_pk_mul_f32 v[80:81], v[80:81], v[94:95]
	v_fma_f32 v94, -v86, v91, v90
	v_fmac_f32_e32 v91, v94, v87
	v_fma_f32 v86, -v86, v91, v90
	v_div_fmas_f32 v86, v86, v87, v91
	v_div_fixup_f32 v83, v86, v83, 1.0
	v_div_scale_f32 v86, s[0:1], v82, v82, 1.0
	v_rcp_f32_e32 v87, v86
	v_cvt_pk_bf16_f32 v80, v80, v81
	v_fma_f32 v90, -v86, v87, 1.0
	v_fmac_f32_e32 v87, v90, v87
	v_div_scale_f32 v90, vcc, 1.0, v82, 1.0
	v_mul_f32_e32 v91, v90, v87
	v_fma_f32 v94, -v86, v91, v90
	v_fmac_f32_e32 v91, v94, v87
	v_fma_f32 v86, -v86, v91, v90
	v_div_fmas_f32 v86, v86, v87, v91
	v_div_fixup_f32 v82, v86, v82, 1.0
	v_pk_mul_f32 v[82:83], v[82:83], v[84:85]
	s_nop 0
	v_cvt_pk_bf16_f32 v81, v82, v83
	global_store_dwordx2 v[88:89], v[80:81], off
	v_lshl_add_u64 v[80:81], v[96:97], 0, v[112:113]
	v_lshlrev_b64 v[84:85], 1, v[80:81]
	v_lshl_add_u64 v[80:81], s[26:27], 0, v[84:85]
	global_load_dwordx2 v[86:87], v[80:81], off
	global_load_dwordx4 v[176:179], v[172:173], off offset:128
	v_lshl_add_u64 v[182:183], v[186:187], 0, v[112:113]
	v_lshlrev_b64 v[188:189], 1, v[182:183]
	v_lshl_add_u64 v[190:191], s[26:27], 0, v[188:189]
	global_load_dwordx2 v[192:193], v[190:191], off
	global_load_dwordx4 v[196:199], v[172:173], off offset:128
	s_nop 0
	v_lshl_add_u64 v[84:85], s[36:37], 0, v[84:85]
	s_waitcnt vmcnt(3)
	v_lshlrev_b32_e32 v88, 16, v86
	s_waitcnt vmcnt(2)
	v_add_f32_e32 v76, v76, v176
	v_add_f32_e32 v77, v77, v177
	v_mul_f32_e32 v76, 0xbfb8aa3b, v76
	v_mul_f32_e32 v77, 0xbfb8aa3b, v77
	v_exp_f32_e32 v76, v76
	v_exp_f32_e32 v77, v77
	v_and_b32_e32 v89, 0xffff0000, v86
	v_add_f32_e32 v78, v78, v178
	v_add_f32_e32 v79, v79, v179
	v_pk_add_f32 v[76:77], v[76:77], 1.0 op_sel_hi:[1, 0]
	v_mul_f32_e32 v78, 0xbfb8aa3b, v78
	v_div_scale_f32 v80, s[0:1], v77, v77, 1.0
	v_rcp_f32_e32 v81, v80
	v_mul_f32_e32 v79, 0xbfb8aa3b, v79
	v_exp_f32_e32 v78, v78
	v_exp_f32_e32 v79, v79
	v_fma_f32 v86, -v80, v81, 1.0
	v_fmac_f32_e32 v81, v86, v81
	v_div_scale_f32 v86, vcc, 1.0, v77, 1.0
	v_mul_f32_e32 v90, v86, v81
	v_fma_f32 v91, -v80, v90, v86
	v_fmac_f32_e32 v90, v91, v81
	v_fma_f32 v80, -v80, v90, v86
	v_div_fmas_f32 v80, v80, v81, v90
	v_div_fixup_f32 v77, v80, v77, 1.0
	v_div_scale_f32 v80, s[0:1], v76, v76, 1.0
	v_rcp_f32_e32 v81, v80
	v_pk_add_f32 v[78:79], v[78:79], 1.0 op_sel_hi:[1, 0]
	v_fma_f32 v86, -v80, v81, 1.0
	v_div_scale_f32 v82, s[0:1], v79, v79, 1.0
	v_fmac_f32_e32 v81, v86, v81
	v_div_scale_f32 v86, vcc, 1.0, v76, 1.0
	v_rcp_f32_e32 v83, v82
	v_mul_f32_e32 v90, v86, v81
	v_fma_f32 v91, -v80, v90, v86
	v_fmac_f32_e32 v90, v91, v81
	v_fma_f32 v80, -v80, v90, v86
	v_fma_f32 v86, -v82, v83, 1.0
	v_div_fmas_f32 v80, v80, v81, v90
	v_fmac_f32_e32 v83, v86, v83
	v_div_scale_f32 v86, vcc, 1.0, v79, 1.0
	v_div_fixup_f32 v76, v80, v76, 1.0
	v_lshlrev_b32_e32 v80, 16, v87
	v_and_b32_e32 v81, 0xffff0000, v87
	v_mul_f32_e32 v87, v86, v83
	v_pk_mul_f32 v[76:77], v[76:77], v[88:89]
	v_fma_f32 v88, -v82, v87, v86
	v_fmac_f32_e32 v87, v88, v83
	v_fma_f32 v82, -v82, v87, v86
	v_div_fmas_f32 v82, v82, v83, v87
	v_div_fixup_f32 v79, v82, v79, 1.0
	v_div_scale_f32 v82, s[0:1], v78, v78, 1.0
	v_rcp_f32_e32 v83, v82
	v_cvt_pk_bf16_f32 v76, v76, v77
	v_fma_f32 v86, -v82, v83, 1.0
	v_fmac_f32_e32 v83, v86, v83
	v_div_scale_f32 v86, vcc, 1.0, v78, 1.0
	v_mul_f32_e32 v87, v86, v83
	v_fma_f32 v88, -v82, v87, v86
	v_fmac_f32_e32 v87, v88, v83
	v_fma_f32 v82, -v82, v87, v86
	v_div_fmas_f32 v82, v82, v83, v87
	v_div_fixup_f32 v78, v82, v78, 1.0
	v_pk_mul_f32 v[78:79], v[78:79], v[80:81]
	s_nop 0
	v_cvt_pk_bf16_f32 v77, v78, v79
	global_store_dwordx2 v[84:85], v[76:77], off
	s_nop 0
	v_lshl_add_u64 v[80:81], s[36:37], 0, v[188:189]
	s_waitcnt vmcnt(2)
	v_lshlrev_b32_e32 v84, 16, v192
	s_waitcnt vmcnt(1)
; DI float bf_lo(unsigned u) { return __uint_as_float(u << 16); }
; DI float bf_hi(unsigned u) { return __uint_as_float(u & 0xffff0000u); }
; DI float sigmoidf_(float z) { return 1.0f / (1.0f + fast_exp(-z)); }
; DI void phase_glu(const Params& p, char* lds) {
;     ...
;     epi8_iter(acc, [&](int t, int n, float a, float b, float c, float d) {
;       const size_t off = (size_t)(mt * 256 + t) * 512 + nt * 256 + n;
;       const uint2 yy = *(const uint2*)(yg + off);
;       const float4 bb = *(const float4*)(p.b_glu + nt * 256 + n);
;       store_bf4(so + off, bf_lo(yy.x) * sigmoidf_(a + bb.x), bf_hi(yy.x) * sigmoidf_(b + bb.y), bf_lo(yy.y) * sigmoidf_(c + bb.z),
;                 bf_hi(yy.y) * sigmoidf_(d + bb.w));
;     });
	v_add_f32_e32 v72, v72, v196
	v_add_f32_e32 v73, v73, v197
	v_mul_f32_e32 v72, 0xbfb8aa3b, v72
	v_mul_f32_e32 v73, 0xbfb8aa3b, v73
	v_exp_f32_e32 v72, v72
	v_exp_f32_e32 v73, v73
	v_and_b32_e32 v85, 0xffff0000, v192
	v_add_f32_e32 v74, v74, v198
	v_add_f32_e32 v75, v75, v199
	v_pk_add_f32 v[72:73], v[72:73], 1.0 op_sel_hi:[1, 0]
	v_mul_f32_e32 v74, 0xbfb8aa3b, v74
	v_div_scale_f32 v76, s[0:1], v73, v73, 1.0
	v_rcp_f32_e32 v77, v76
	v_mul_f32_e32 v75, 0xbfb8aa3b, v75
	v_exp_f32_e32 v74, v74
	v_exp_f32_e32 v75, v75
	v_fma_f32 v82, -v76, v77, 1.0
	v_fmac_f32_e32 v77, v82, v77
	v_div_scale_f32 v82, vcc, 1.0, v73, 1.0
	v_mul_f32_e32 v86, v82, v77
	v_fma_f32 v87, -v76, v86, v82
	v_fmac_f32_e32 v86, v87, v77
	v_fma_f32 v76, -v76, v86, v82
	v_div_fmas_f32 v76, v76, v77, v86
	v_div_fixup_f32 v73, v76, v73, 1.0
	v_div_scale_f32 v76, s[0:1], v72, v72, 1.0
	v_rcp_f32_e32 v77, v76
	v_pk_add_f32 v[74:75], v[74:75], 1.0 op_sel_hi:[1, 0]
	v_fma_f32 v82, -v76, v77, 1.0
	v_div_scale_f32 v78, s[0:1], v75, v75, 1.0
	v_fmac_f32_e32 v77, v82, v77
	v_div_scale_f32 v82, vcc, 1.0, v72, 1.0
	v_rcp_f32_e32 v79, v78
	v_mul_f32_e32 v86, v82, v77
	v_fma_f32 v87, -v76, v86, v82
	v_fmac_f32_e32 v86, v87, v77
	v_fma_f32 v76, -v76, v86, v82
	v_fma_f32 v82, -v78, v79, 1.0
	v_div_fmas_f32 v76, v76, v77, v86
	v_fmac_f32_e32 v79, v82, v79
	v_div_scale_f32 v82, vcc, 1.0, v75, 1.0
	v_div_fixup_f32 v72, v76, v72, 1.0
	v_lshlrev_b32_e32 v76, 16, v193
	v_and_b32_e32 v77, 0xffff0000, v193
	v_mul_f32_e32 v83, v82, v79
	v_pk_mul_f32 v[72:73], v[72:73], v[84:85]
	v_fma_f32 v84, -v78, v83, v82
	v_fmac_f32_e32 v83, v84, v79
	v_fma_f32 v78, -v78, v83, v82
	v_div_fmas_f32 v78, v78, v79, v83
	v_div_fixup_f32 v75, v78, v75, 1.0
	v_div_scale_f32 v78, s[0:1], v74, v74, 1.0
	v_rcp_f32_e32 v79, v78
	v_cvt_pk_bf16_f32 v72, v72, v73
	v_fma_f32 v82, -v78, v79, 1.0
	v_fmac_f32_e32 v79, v82, v79
	v_div_scale_f32 v82, vcc, 1.0, v74, 1.0
	v_mul_f32_e32 v83, v82, v79
	v_fma_f32 v84, -v78, v83, v82
	v_fmac_f32_e32 v83, v84, v79
	v_fma_f32 v78, -v78, v83, v82
	v_div_fmas_f32 v78, v78, v79, v83
	v_div_fixup_f32 v74, v78, v74, 1.0
	v_pk_mul_f32 v[74:75], v[74:75], v[76:77]
	s_nop 0
	v_cvt_pk_bf16_f32 v73, v74, v75
	global_store_dwordx2 v[80:81], v[72:73], off
	v_lshl_add_u64 v[72:73], v[96:97], 0, v[104:105]
	v_lshlrev_b64 v[76:77], 1, v[72:73]
	v_lshl_add_u64 v[72:73], s[26:27], 0, v[76:77]
	global_load_dwordx2 v[78:79], v[72:73], off
	global_load_dwordx4 v[216:219], v[172:173], off offset:192
	v_lshl_add_u64 v[212:213], v[186:187], 0, v[104:105]
	v_lshlrev_b64 v[220:221], 1, v[212:213]
	v_lshl_add_u64 v[224:225], s[26:27], 0, v[220:221]
	global_load_dwordx2 v[226:227], v[224:225], off
	global_load_dwordx4 v[228:231], v[172:173], off offset:192
	s_nop 0
	v_lshl_add_u64 v[76:77], s[36:37], 0, v[76:77]
	s_waitcnt vmcnt(3)
	v_lshlrev_b32_e32 v80, 16, v78
	s_waitcnt vmcnt(2)
	v_add_f32_e32 v68, v68, v216
	v_add_f32_e32 v69, v69, v217
	v_mul_f32_e32 v68, 0xbfb8aa3b, v68
	v_mul_f32_e32 v69, 0xbfb8aa3b, v69
	v_exp_f32_e32 v68, v68
	v_exp_f32_e32 v69, v69
	v_and_b32_e32 v81, 0xffff0000, v78
	v_add_f32_e32 v70, v70, v218
	v_add_f32_e32 v71, v71, v219
	v_pk_add_f32 v[68:69], v[68:69], 1.0 op_sel_hi:[1, 0]
	v_mul_f32_e32 v70, 0xbfb8aa3b, v70
	v_div_scale_f32 v72, s[0:1], v69, v69, 1.0
	v_rcp_f32_e32 v73, v72
	v_mul_f32_e32 v71, 0xbfb8aa3b, v71
	v_exp_f32_e32 v70, v70
	v_exp_f32_e32 v71, v71
	v_fma_f32 v78, -v72, v73, 1.0
	v_fmac_f32_e32 v73, v78, v73
	v_div_scale_f32 v78, vcc, 1.0, v69, 1.0
	v_mul_f32_e32 v82, v78, v73
	v_fma_f32 v83, -v72, v82, v78
	v_fmac_f32_e32 v82, v83, v73
	v_fma_f32 v72, -v72, v82, v78
	v_div_fmas_f32 v72, v72, v73, v82
	v_div_fixup_f32 v69, v72, v69, 1.0
	v_div_scale_f32 v72, s[0:1], v68, v68, 1.0
	v_rcp_f32_e32 v73, v72
	v_pk_add_f32 v[70:71], v[70:71], 1.0 op_sel_hi:[1, 0]
	v_fma_f32 v78, -v72, v73, 1.0
	v_div_scale_f32 v74, s[0:1], v71, v71, 1.0
	v_fmac_f32_e32 v73, v78, v73
	v_div_scale_f32 v78, vcc, 1.0, v68, 1.0
	v_rcp_f32_e32 v75, v74
	v_mul_f32_e32 v82, v78, v73
	v_fma_f32 v83, -v72, v82, v78
	v_fmac_f32_e32 v82, v83, v73
	v_fma_f32 v72, -v72, v82, v78
	v_fma_f32 v78, -v74, v75, 1.0
	v_div_fmas_f32 v72, v72, v73, v82
	v_fmac_f32_e32 v75, v78, v75
	v_div_scale_f32 v78, vcc, 1.0, v71, 1.0
	v_div_fixup_f32 v68, v72, v68, 1.0
	v_lshlrev_b32_e32 v72, 16, v79
	v_and_b32_e32 v73, 0xffff0000, v79
	v_mul_f32_e32 v79, v78, v75
	v_pk_mul_f32 v[68:69], v[68:69], v[80:81]
	v_fma_f32 v80, -v74, v79, v78
	v_fmac_f32_e32 v79, v80, v75
	v_fma_f32 v74, -v74, v79, v78
	v_div_fmas_f32 v74, v74, v75, v79
	v_div_fixup_f32 v71, v74, v71, 1.0
	v_div_scale_f32 v74, s[0:1], v70, v70, 1.0
	v_rcp_f32_e32 v75, v74
	v_cvt_pk_bf16_f32 v68, v68, v69
	v_fma_f32 v78, -v74, v75, 1.0
	v_fmac_f32_e32 v75, v78, v75
	v_div_scale_f32 v78, vcc, 1.0, v70, 1.0
	v_mul_f32_e32 v79, v78, v75
	v_fma_f32 v80, -v74, v79, v78
	v_fmac_f32_e32 v79, v80, v75
	v_fma_f32 v74, -v74, v79, v78
	v_div_fmas_f32 v74, v74, v75, v79
	v_div_fixup_f32 v70, v74, v70, 1.0
	v_pk_mul_f32 v[70:71], v[70:71], v[72:73]
	s_nop 0
	v_cvt_pk_bf16_f32 v69, v70, v71
	global_store_dwordx2 v[76:77], v[68:69], off
	s_nop 0
	v_lshl_add_u64 v[72:73], s[36:37], 0, v[220:221]
	s_waitcnt vmcnt(2)
	v_lshlrev_b32_e32 v76, 16, v226
	s_waitcnt vmcnt(1)
; DI float bf_lo(unsigned u) { return __uint_as_float(u << 16); }
; DI float bf_hi(unsigned u) { return __uint_as_float(u & 0xffff0000u); }
; DI float sigmoidf_(float z) { return 1.0f / (1.0f + fast_exp(-z)); }
; DI void phase_glu(const Params& p, char* lds) {
;     ...
;     epi8_iter(acc, [&](int t, int n, float a, float b, float c, float d) {
;       const size_t off = (size_t)(mt * 256 + t) * 512 + nt * 256 + n;
;       const uint2 yy = *(const uint2*)(yg + off);
;       const float4 bb = *(const float4*)(p.b_glu + nt * 256 + n);
;       store_bf4(so + off, bf_lo(yy.x) * sigmoidf_(a + bb.x), bf_hi(yy.x) * sigmoidf_(b + bb.y), bf_lo(yy.y) * sigmoidf_(c + bb.z),
;                 bf_hi(yy.y) * sigmoidf_(d + bb.w));
;     });
	v_add_f32_e32 v64, v64, v228
	v_add_f32_e32 v65, v65, v229
	v_mul_f32_e32 v64, 0xbfb8aa3b, v64
	v_mul_f32_e32 v65, 0xbfb8aa3b, v65
	v_exp_f32_e32 v64, v64
	v_exp_f32_e32 v65, v65
	v_and_b32_e32 v77, 0xffff0000, v226
	v_add_f32_e32 v66, v66, v230
	v_add_f32_e32 v67, v67, v231
	v_pk_add_f32 v[64:65], v[64:65], 1.0 op_sel_hi:[1, 0]
	v_mul_f32_e32 v66, 0xbfb8aa3b, v66
	v_div_scale_f32 v68, s[0:1], v65, v65, 1.0
	v_rcp_f32_e32 v69, v68
	v_mul_f32_e32 v67, 0xbfb8aa3b, v67
	v_exp_f32_e32 v66, v66
	v_exp_f32_e32 v67, v67
	v_fma_f32 v74, -v68, v69, 1.0
	v_fmac_f32_e32 v69, v74, v69
	v_div_scale_f32 v74, vcc, 1.0, v65, 1.0
	v_mul_f32_e32 v78, v74, v69
	v_fma_f32 v79, -v68, v78, v74
	v_fmac_f32_e32 v78, v79, v69
	v_fma_f32 v68, -v68, v78, v74
	v_div_fmas_f32 v68, v68, v69, v78
	v_div_fixup_f32 v65, v68, v65, 1.0
	v_div_scale_f32 v68, s[0:1], v64, v64, 1.0
	v_rcp_f32_e32 v69, v68
	v_pk_add_f32 v[66:67], v[66:67], 1.0 op_sel_hi:[1, 0]
	v_fma_f32 v74, -v68, v69, 1.0
	v_div_scale_f32 v70, s[0:1], v67, v67, 1.0
	v_fmac_f32_e32 v69, v74, v69
	v_div_scale_f32 v74, vcc, 1.0, v64, 1.0
	v_rcp_f32_e32 v71, v70
	v_mul_f32_e32 v78, v74, v69
	v_fma_f32 v79, -v68, v78, v74
	v_fmac_f32_e32 v78, v79, v69
	v_fma_f32 v68, -v68, v78, v74
	v_fma_f32 v74, -v70, v71, 1.0
	v_div_fmas_f32 v68, v68, v69, v78
	v_fmac_f32_e32 v71, v74, v71
	v_div_scale_f32 v74, vcc, 1.0, v67, 1.0
	v_div_fixup_f32 v64, v68, v64, 1.0
	v_lshlrev_b32_e32 v68, 16, v227
	v_and_b32_e32 v69, 0xffff0000, v227
	v_mul_f32_e32 v75, v74, v71
	v_pk_mul_f32 v[64:65], v[64:65], v[76:77]
	v_fma_f32 v76, -v70, v75, v74
	v_fmac_f32_e32 v75, v76, v71
	v_fma_f32 v70, -v70, v75, v74
	v_div_fmas_f32 v70, v70, v71, v75
	v_div_fixup_f32 v67, v70, v67, 1.0
	v_div_scale_f32 v70, s[0:1], v66, v66, 1.0
	v_rcp_f32_e32 v71, v70
	v_cvt_pk_bf16_f32 v64, v64, v65
	v_fma_f32 v74, -v70, v71, 1.0
	v_fmac_f32_e32 v71, v74, v71
	v_div_scale_f32 v74, vcc, 1.0, v66, 1.0
	v_mul_f32_e32 v75, v74, v71
	v_fma_f32 v76, -v70, v75, v74
	v_fmac_f32_e32 v75, v76, v71
	v_fma_f32 v70, -v70, v75, v74
	v_div_fmas_f32 v70, v70, v71, v75
	v_div_fixup_f32 v66, v70, v66, 1.0
	v_pk_mul_f32 v[66:67], v[66:67], v[68:69]
	s_nop 0
	v_cvt_pk_bf16_f32 v65, v66, v67
	global_store_dwordx2 v[72:73], v[64:65], off
	v_add_u32_e32 v64, 0x80, v130
	v_ashrrev_i32_e32 v65, 31, v64
	v_lshl_add_u64 v[64:65], v[64:65], 0, s[96:97]
	v_lshl_add_u64 v[66:67], v[64:65], 0, v[132:133]
	v_lshlrev_b64 v[70:71], 1, v[66:67]
	v_lshl_add_u64 v[66:67], s[26:27], 0, v[70:71]
	global_load_dwordx2 v[72:73], v[66:67], off
	global_load_dwordx4 v[176:179], v[172:173], off offset:512
	v_lshl_add_u64 v[182:183], v[184:185], 0, v[64:65]
	v_lshlrev_b64 v[188:189], 1, v[182:183]
	v_lshl_add_u64 v[190:191], s[26:27], 0, v[188:189]
	global_load_dwordx2 v[192:193], v[190:191], off
	global_load_dwordx4 v[196:199], v[172:173], off offset:512
	s_nop 0
	v_lshl_add_u64 v[70:71], s[36:37], 0, v[70:71]
	s_waitcnt vmcnt(3)
	v_lshlrev_b32_e32 v74, 16, v72
	s_waitcnt vmcnt(2)
	v_add_f32_e32 v60, v60, v176
	v_add_f32_e32 v61, v61, v177
	v_mul_f32_e32 v60, 0xbfb8aa3b, v60
	v_mul_f32_e32 v61, 0xbfb8aa3b, v61
	v_exp_f32_e32 v60, v60
	v_exp_f32_e32 v61, v61
	v_and_b32_e32 v75, 0xffff0000, v72
	v_add_f32_e32 v62, v62, v178
	v_add_f32_e32 v63, v63, v179
	v_pk_add_f32 v[60:61], v[60:61], 1.0 op_sel_hi:[1, 0]
	v_mul_f32_e32 v62, 0xbfb8aa3b, v62
	v_div_scale_f32 v66, s[0:1], v61, v61, 1.0
	v_rcp_f32_e32 v67, v66
	v_mul_f32_e32 v63, 0xbfb8aa3b, v63
	v_exp_f32_e32 v62, v62
	v_exp_f32_e32 v63, v63
	v_fma_f32 v72, -v66, v67, 1.0
	v_fmac_f32_e32 v67, v72, v67
	v_div_scale_f32 v72, vcc, 1.0, v61, 1.0
	v_mul_f32_e32 v76, v72, v67
	v_fma_f32 v77, -v66, v76, v72
	v_fmac_f32_e32 v76, v77, v67
	v_fma_f32 v66, -v66, v76, v72
	v_div_fmas_f32 v66, v66, v67, v76
	v_div_fixup_f32 v61, v66, v61, 1.0
	v_div_scale_f32 v66, s[0:1], v60, v60, 1.0
	v_rcp_f32_e32 v67, v66
	v_pk_add_f32 v[62:63], v[62:63], 1.0 op_sel_hi:[1, 0]
	v_fma_f32 v72, -v66, v67, 1.0
	v_div_scale_f32 v68, s[0:1], v63, v63, 1.0
	v_fmac_f32_e32 v67, v72, v67
	v_div_scale_f32 v72, vcc, 1.0, v60, 1.0
	v_rcp_f32_e32 v69, v68
	v_mul_f32_e32 v76, v72, v67
	v_fma_f32 v77, -v66, v76, v72
	v_fmac_f32_e32 v76, v77, v67
	v_fma_f32 v66, -v66, v76, v72
	v_fma_f32 v72, -v68, v69, 1.0
	v_div_fmas_f32 v66, v66, v67, v76
	v_fmac_f32_e32 v69, v72, v69
	v_div_scale_f32 v72, vcc, 1.0, v63, 1.0
	v_div_fixup_f32 v60, v66, v60, 1.0
	v_lshlrev_b32_e32 v66, 16, v73
	v_and_b32_e32 v67, 0xffff0000, v73
	v_mul_f32_e32 v73, v72, v69
	v_pk_mul_f32 v[60:61], v[60:61], v[74:75]
	v_fma_f32 v74, -v68, v73, v72
	v_fmac_f32_e32 v73, v74, v69
	v_fma_f32 v68, -v68, v73, v72
	v_div_fmas_f32 v68, v68, v69, v73
	v_div_fixup_f32 v63, v68, v63, 1.0
	v_div_scale_f32 v68, s[0:1], v62, v62, 1.0
	v_rcp_f32_e32 v69, v68
	v_cvt_pk_bf16_f32 v60, v60, v61
	v_fma_f32 v72, -v68, v69, 1.0
	v_fmac_f32_e32 v69, v72, v69
	v_div_scale_f32 v72, vcc, 1.0, v62, 1.0
	v_mul_f32_e32 v73, v72, v69
	v_fma_f32 v74, -v68, v73, v72
	v_fmac_f32_e32 v73, v74, v69
	v_fma_f32 v68, -v68, v73, v72
	v_div_fmas_f32 v68, v68, v69, v73
	v_div_fixup_f32 v62, v68, v62, 1.0
	v_pk_mul_f32 v[62:63], v[62:63], v[66:67]
	s_nop 0
	v_cvt_pk_bf16_f32 v61, v62, v63
	global_store_dwordx2 v[70:71], v[60:61], off
	s_nop 0
	v_lshl_add_u64 v[66:67], s[36:37], 0, v[188:189]
	s_waitcnt vmcnt(2)
	v_lshlrev_b32_e32 v70, 16, v192
	s_waitcnt vmcnt(1)
; DI float bf_lo(unsigned u) { return __uint_as_float(u << 16); }
; DI float bf_hi(unsigned u) { return __uint_as_float(u & 0xffff0000u); }
; DI float sigmoidf_(float z) { return 1.0f / (1.0f + fast_exp(-z)); }
; DI void phase_glu(const Params& p, char* lds) {
;     ...
;     epi8_iter(acc, [&](int t, int n, float a, float b, float c, float d) {
;       const size_t off = (size_t)(mt * 256 + t) * 512 + nt * 256 + n;
;       const uint2 yy = *(const uint2*)(yg + off);
;       const float4 bb = *(const float4*)(p.b_glu + nt * 256 + n);
;       store_bf4(so + off, bf_lo(yy.x) * sigmoidf_(a + bb.x), bf_hi(yy.x) * sigmoidf_(b + bb.y), bf_lo(yy.y) * sigmoidf_(c + bb.z),
;                 bf_hi(yy.y) * sigmoidf_(d + bb.w));
;     });
	v_add_f32_e32 v56, v56, v196
	v_add_f32_e32 v57, v57, v197
	v_mul_f32_e32 v56, 0xbfb8aa3b, v56
	v_mul_f32_e32 v57, 0xbfb8aa3b, v57
	v_exp_f32_e32 v56, v56
	v_exp_f32_e32 v57, v57
	v_and_b32_e32 v71, 0xffff0000, v192
	v_add_f32_e32 v58, v58, v198
	v_add_f32_e32 v59, v59, v199
	v_pk_add_f32 v[56:57], v[56:57], 1.0 op_sel_hi:[1, 0]
	v_mul_f32_e32 v58, 0xbfb8aa3b, v58
	v_div_scale_f32 v60, s[0:1], v57, v57, 1.0
	v_rcp_f32_e32 v61, v60
	v_mul_f32_e32 v59, 0xbfb8aa3b, v59
	v_exp_f32_e32 v58, v58
	v_exp_f32_e32 v59, v59
	v_fma_f32 v68, -v60, v61, 1.0
	v_fmac_f32_e32 v61, v68, v61
	v_div_scale_f32 v68, vcc, 1.0, v57, 1.0
	v_mul_f32_e32 v72, v68, v61
	v_fma_f32 v73, -v60, v72, v68
	v_fmac_f32_e32 v72, v73, v61
	v_fma_f32 v60, -v60, v72, v68
	v_div_fmas_f32 v60, v60, v61, v72
	v_div_fixup_f32 v57, v60, v57, 1.0
	v_div_scale_f32 v60, s[0:1], v56, v56, 1.0
	v_rcp_f32_e32 v61, v60
	v_pk_add_f32 v[58:59], v[58:59], 1.0 op_sel_hi:[1, 0]
	v_fma_f32 v68, -v60, v61, 1.0
	v_div_scale_f32 v62, s[0:1], v59, v59, 1.0
	v_fmac_f32_e32 v61, v68, v61
	v_div_scale_f32 v68, vcc, 1.0, v56, 1.0
	v_rcp_f32_e32 v63, v62
	v_mul_f32_e32 v72, v68, v61
	v_fma_f32 v73, -v60, v72, v68
	v_fmac_f32_e32 v72, v73, v61
	v_fma_f32 v60, -v60, v72, v68
	v_fma_f32 v68, -v62, v63, 1.0
	v_div_fmas_f32 v60, v60, v61, v72
	v_fmac_f32_e32 v63, v68, v63
	v_div_scale_f32 v68, vcc, 1.0, v59, 1.0
	v_div_fixup_f32 v56, v60, v56, 1.0
	v_lshlrev_b32_e32 v60, 16, v193
	v_and_b32_e32 v61, 0xffff0000, v193
	v_mul_f32_e32 v69, v68, v63
	v_pk_mul_f32 v[56:57], v[56:57], v[70:71]
	v_fma_f32 v70, -v62, v69, v68
	v_fmac_f32_e32 v69, v70, v63
	v_fma_f32 v62, -v62, v69, v68
	v_div_fmas_f32 v62, v62, v63, v69
	v_div_fixup_f32 v59, v62, v59, 1.0
	v_div_scale_f32 v62, s[0:1], v58, v58, 1.0
	v_rcp_f32_e32 v63, v62
	v_cvt_pk_bf16_f32 v56, v56, v57
	v_fma_f32 v68, -v62, v63, 1.0
	v_fmac_f32_e32 v63, v68, v63
	v_div_scale_f32 v68, vcc, 1.0, v58, 1.0
	v_mul_f32_e32 v69, v68, v63
	v_fma_f32 v70, -v62, v69, v68
	v_fmac_f32_e32 v69, v70, v63
	v_fma_f32 v62, -v62, v69, v68
	v_div_fmas_f32 v62, v62, v63, v69
	v_div_fixup_f32 v58, v62, v58, 1.0
	v_pk_mul_f32 v[58:59], v[58:59], v[60:61]
	s_nop 0
	v_cvt_pk_bf16_f32 v57, v58, v59
	global_store_dwordx2 v[66:67], v[56:57], off
	v_add_u32_e32 v56, 0x90, v130
	v_ashrrev_i32_e32 v57, 31, v56
	v_lshl_add_u64 v[56:57], v[56:57], 0, s[96:97]
	v_lshl_add_u64 v[58:59], v[56:57], 0, v[132:133]
	v_lshlrev_b64 v[62:63], 1, v[58:59]
	v_lshl_add_u64 v[58:59], s[26:27], 0, v[62:63]
	global_load_dwordx2 v[66:67], v[58:59], off
	global_load_dwordx4 v[216:219], v[172:173], off offset:576
	v_lshl_add_u64 v[212:213], v[184:185], 0, v[56:57]
	v_lshlrev_b64 v[220:221], 1, v[212:213]
	v_lshl_add_u64 v[224:225], s[26:27], 0, v[220:221]
	global_load_dwordx2 v[226:227], v[224:225], off
	global_load_dwordx4 v[228:231], v[172:173], off offset:576
	s_nop 0
	v_lshl_add_u64 v[62:63], s[36:37], 0, v[62:63]
	s_waitcnt vmcnt(3)
	v_lshlrev_b32_e32 v68, 16, v66
	s_waitcnt vmcnt(2)
	v_add_f32_e32 v52, v52, v216
	v_add_f32_e32 v53, v53, v217
	v_mul_f32_e32 v52, 0xbfb8aa3b, v52
	v_mul_f32_e32 v53, 0xbfb8aa3b, v53
	v_exp_f32_e32 v52, v52
	v_exp_f32_e32 v53, v53
	v_and_b32_e32 v69, 0xffff0000, v66
	v_add_f32_e32 v54, v54, v218
	v_add_f32_e32 v55, v55, v219
	v_pk_add_f32 v[52:53], v[52:53], 1.0 op_sel_hi:[1, 0]
	v_mul_f32_e32 v54, 0xbfb8aa3b, v54
	v_div_scale_f32 v58, s[0:1], v53, v53, 1.0
	v_rcp_f32_e32 v59, v58
	v_mul_f32_e32 v55, 0xbfb8aa3b, v55
	v_exp_f32_e32 v54, v54
	v_exp_f32_e32 v55, v55
	v_fma_f32 v66, -v58, v59, 1.0
	v_fmac_f32_e32 v59, v66, v59
	v_div_scale_f32 v66, vcc, 1.0, v53, 1.0
	v_mul_f32_e32 v70, v66, v59
	v_fma_f32 v71, -v58, v70, v66
	v_fmac_f32_e32 v70, v71, v59
	v_fma_f32 v58, -v58, v70, v66
	v_div_fmas_f32 v58, v58, v59, v70
	v_div_fixup_f32 v53, v58, v53, 1.0
	v_div_scale_f32 v58, s[0:1], v52, v52, 1.0
	v_rcp_f32_e32 v59, v58
	v_pk_add_f32 v[54:55], v[54:55], 1.0 op_sel_hi:[1, 0]
	v_fma_f32 v66, -v58, v59, 1.0
	v_div_scale_f32 v60, s[0:1], v55, v55, 1.0
	v_fmac_f32_e32 v59, v66, v59
	v_div_scale_f32 v66, vcc, 1.0, v52, 1.0
	v_rcp_f32_e32 v61, v60
	v_mul_f32_e32 v70, v66, v59
	v_fma_f32 v71, -v58, v70, v66
	v_fmac_f32_e32 v70, v71, v59
	v_fma_f32 v58, -v58, v70, v66
	v_fma_f32 v66, -v60, v61, 1.0
	v_div_fmas_f32 v58, v58, v59, v70
	v_fmac_f32_e32 v61, v66, v61
	v_div_scale_f32 v66, vcc, 1.0, v55, 1.0
	v_div_fixup_f32 v52, v58, v52, 1.0
	v_lshlrev_b32_e32 v58, 16, v67
	v_and_b32_e32 v59, 0xffff0000, v67
	v_mul_f32_e32 v67, v66, v61
	v_pk_mul_f32 v[52:53], v[52:53], v[68:69]
	v_fma_f32 v68, -v60, v67, v66
	v_fmac_f32_e32 v67, v68, v61
	v_fma_f32 v60, -v60, v67, v66
	v_div_fmas_f32 v60, v60, v61, v67
	v_div_fixup_f32 v55, v60, v55, 1.0
	v_div_scale_f32 v60, s[0:1], v54, v54, 1.0
	v_rcp_f32_e32 v61, v60
	v_cvt_pk_bf16_f32 v52, v52, v53
	v_fma_f32 v66, -v60, v61, 1.0
	v_fmac_f32_e32 v61, v66, v61
	v_div_scale_f32 v66, vcc, 1.0, v54, 1.0
	v_mul_f32_e32 v67, v66, v61
	v_fma_f32 v68, -v60, v67, v66
	v_fmac_f32_e32 v67, v68, v61
	v_fma_f32 v60, -v60, v67, v66
	v_div_fmas_f32 v60, v60, v61, v67
	v_div_fixup_f32 v54, v60, v54, 1.0
	v_pk_mul_f32 v[54:55], v[54:55], v[58:59]
	s_nop 0
	v_cvt_pk_bf16_f32 v53, v54, v55
	global_store_dwordx2 v[62:63], v[52:53], off
	s_nop 0
	v_lshl_add_u64 v[58:59], s[36:37], 0, v[220:221]
	s_waitcnt vmcnt(2)
	v_lshlrev_b32_e32 v62, 16, v226
	s_waitcnt vmcnt(1)
; DI float bf_lo(unsigned u) { return __uint_as_float(u << 16); }
; DI float bf_hi(unsigned u) { return __uint_as_float(u & 0xffff0000u); }
; DI float sigmoidf_(float z) { return 1.0f / (1.0f + fast_exp(-z)); }
; DI void phase_glu(const Params& p, char* lds) {
;     ...
;     epi8_iter(acc, [&](int t, int n, float a, float b, float c, float d) {
;       const size_t off = (size_t)(mt * 256 + t) * 512 + nt * 256 + n;
;       const uint2 yy = *(const uint2*)(yg + off);
;       const float4 bb = *(const float4*)(p.b_glu + nt * 256 + n);
;       store_bf4(so + off, bf_lo(yy.x) * sigmoidf_(a + bb.x), bf_hi(yy.x) * sigmoidf_(b + bb.y), bf_lo(yy.y) * sigmoidf_(c + bb.z),
;                 bf_hi(yy.y) * sigmoidf_(d + bb.w));
;     });
	v_add_f32_e32 v48, v48, v228
	v_add_f32_e32 v49, v49, v229
	v_mul_f32_e32 v48, 0xbfb8aa3b, v48
	v_mul_f32_e32 v49, 0xbfb8aa3b, v49
	v_exp_f32_e32 v48, v48
	v_exp_f32_e32 v49, v49
	v_and_b32_e32 v63, 0xffff0000, v226
	v_add_f32_e32 v50, v50, v230
	v_add_f32_e32 v51, v51, v231
	v_pk_add_f32 v[48:49], v[48:49], 1.0 op_sel_hi:[1, 0]
	v_mul_f32_e32 v50, 0xbfb8aa3b, v50
	v_div_scale_f32 v52, s[0:1], v49, v49, 1.0
	v_rcp_f32_e32 v53, v52
	v_mul_f32_e32 v51, 0xbfb8aa3b, v51
	v_exp_f32_e32 v50, v50
	v_exp_f32_e32 v51, v51
	v_fma_f32 v60, -v52, v53, 1.0
	v_fmac_f32_e32 v53, v60, v53
	v_div_scale_f32 v60, vcc, 1.0, v49, 1.0
	v_mul_f32_e32 v66, v60, v53
	v_fma_f32 v67, -v52, v66, v60
	v_fmac_f32_e32 v66, v67, v53
	v_fma_f32 v52, -v52, v66, v60
	v_div_fmas_f32 v52, v52, v53, v66
	v_div_fixup_f32 v49, v52, v49, 1.0
	v_div_scale_f32 v52, s[0:1], v48, v48, 1.0
	v_rcp_f32_e32 v53, v52
	v_pk_add_f32 v[50:51], v[50:51], 1.0 op_sel_hi:[1, 0]
	v_fma_f32 v60, -v52, v53, 1.0
	v_div_scale_f32 v54, s[0:1], v51, v51, 1.0
	v_fmac_f32_e32 v53, v60, v53
	v_div_scale_f32 v60, vcc, 1.0, v48, 1.0
	v_rcp_f32_e32 v55, v54
	v_mul_f32_e32 v66, v60, v53
	v_fma_f32 v67, -v52, v66, v60
	v_fmac_f32_e32 v66, v67, v53
	v_fma_f32 v52, -v52, v66, v60
	v_fma_f32 v60, -v54, v55, 1.0
	v_div_fmas_f32 v52, v52, v53, v66
	v_fmac_f32_e32 v55, v60, v55
	v_div_scale_f32 v60, vcc, 1.0, v51, 1.0
	v_div_fixup_f32 v48, v52, v48, 1.0
	v_lshlrev_b32_e32 v52, 16, v227
	v_and_b32_e32 v53, 0xffff0000, v227
	v_mul_f32_e32 v61, v60, v55
	v_pk_mul_f32 v[48:49], v[48:49], v[62:63]
	v_fma_f32 v62, -v54, v61, v60
	v_fmac_f32_e32 v61, v62, v55
	v_fma_f32 v54, -v54, v61, v60
	v_div_fmas_f32 v54, v54, v55, v61
	v_div_fixup_f32 v51, v54, v51, 1.0
	v_div_scale_f32 v54, s[0:1], v50, v50, 1.0
	v_rcp_f32_e32 v55, v54
	v_cvt_pk_bf16_f32 v48, v48, v49
	v_fma_f32 v60, -v54, v55, 1.0
	v_fmac_f32_e32 v55, v60, v55
	v_div_scale_f32 v60, vcc, 1.0, v50, 1.0
	v_mul_f32_e32 v61, v60, v55
	v_fma_f32 v62, -v54, v61, v60
	v_fmac_f32_e32 v61, v62, v55
	v_fma_f32 v54, -v54, v61, v60
	v_div_fmas_f32 v54, v54, v55, v61
	v_div_fixup_f32 v50, v54, v50, 1.0
	v_pk_mul_f32 v[50:51], v[50:51], v[52:53]
	s_nop 0
	v_cvt_pk_bf16_f32 v49, v50, v51
	global_store_dwordx2 v[58:59], v[48:49], off
	v_add_u32_e32 v48, 0xa0, v130
	v_ashrrev_i32_e32 v49, 31, v48
	v_lshl_add_u64 v[48:49], v[48:49], 0, s[96:97]
	v_lshl_add_u64 v[50:51], v[48:49], 0, v[132:133]
	v_lshlrev_b64 v[54:55], 1, v[50:51]
	v_lshl_add_u64 v[50:51], s[26:27], 0, v[54:55]
	global_load_dwordx2 v[58:59], v[50:51], off
	global_load_dwordx4 v[176:179], v[172:173], off offset:640
	v_lshl_add_u64 v[182:183], v[184:185], 0, v[48:49]
	v_lshlrev_b64 v[188:189], 1, v[182:183]
	v_lshl_add_u64 v[190:191], s[26:27], 0, v[188:189]
	global_load_dwordx2 v[192:193], v[190:191], off
	global_load_dwordx4 v[196:199], v[172:173], off offset:640
	s_nop 0
	v_lshl_add_u64 v[54:55], s[36:37], 0, v[54:55]
	s_waitcnt vmcnt(3)
	v_lshlrev_b32_e32 v60, 16, v58
	s_waitcnt vmcnt(2)
	v_add_f32_e32 v44, v44, v176
	v_add_f32_e32 v45, v45, v177
	v_mul_f32_e32 v44, 0xbfb8aa3b, v44
	v_mul_f32_e32 v45, 0xbfb8aa3b, v45
	v_exp_f32_e32 v44, v44
	v_exp_f32_e32 v45, v45
	v_and_b32_e32 v61, 0xffff0000, v58
	v_add_f32_e32 v46, v46, v178
	v_add_f32_e32 v47, v47, v179
	v_pk_add_f32 v[44:45], v[44:45], 1.0 op_sel_hi:[1, 0]
	v_mul_f32_e32 v46, 0xbfb8aa3b, v46
	v_div_scale_f32 v50, s[0:1], v45, v45, 1.0
	v_rcp_f32_e32 v51, v50
	v_mul_f32_e32 v47, 0xbfb8aa3b, v47
	v_exp_f32_e32 v46, v46
	v_exp_f32_e32 v47, v47
	v_fma_f32 v58, -v50, v51, 1.0
	v_fmac_f32_e32 v51, v58, v51
	v_div_scale_f32 v58, vcc, 1.0, v45, 1.0
	v_mul_f32_e32 v62, v58, v51
	v_fma_f32 v63, -v50, v62, v58
	v_fmac_f32_e32 v62, v63, v51
	v_fma_f32 v50, -v50, v62, v58
	v_div_fmas_f32 v50, v50, v51, v62
	v_div_fixup_f32 v45, v50, v45, 1.0
	v_div_scale_f32 v50, s[0:1], v44, v44, 1.0
	v_rcp_f32_e32 v51, v50
	v_pk_add_f32 v[46:47], v[46:47], 1.0 op_sel_hi:[1, 0]
	v_fma_f32 v58, -v50, v51, 1.0
	v_div_scale_f32 v52, s[0:1], v47, v47, 1.0
	v_fmac_f32_e32 v51, v58, v51
	v_div_scale_f32 v58, vcc, 1.0, v44, 1.0
	v_rcp_f32_e32 v53, v52
	v_mul_f32_e32 v62, v58, v51
	v_fma_f32 v63, -v50, v62, v58
	v_fmac_f32_e32 v62, v63, v51
	v_fma_f32 v50, -v50, v62, v58
	v_fma_f32 v58, -v52, v53, 1.0
	v_div_fmas_f32 v50, v50, v51, v62
	v_fmac_f32_e32 v53, v58, v53
	v_div_scale_f32 v58, vcc, 1.0, v47, 1.0
	v_div_fixup_f32 v44, v50, v44, 1.0
	v_lshlrev_b32_e32 v50, 16, v59
	v_and_b32_e32 v51, 0xffff0000, v59
	v_mul_f32_e32 v59, v58, v53
	v_pk_mul_f32 v[44:45], v[44:45], v[60:61]
	v_fma_f32 v60, -v52, v59, v58
	v_fmac_f32_e32 v59, v60, v53
	v_fma_f32 v52, -v52, v59, v58
	v_div_fmas_f32 v52, v52, v53, v59
	v_div_fixup_f32 v47, v52, v47, 1.0
	v_div_scale_f32 v52, s[0:1], v46, v46, 1.0
	v_rcp_f32_e32 v53, v52
	v_cvt_pk_bf16_f32 v44, v44, v45
	v_fma_f32 v58, -v52, v53, 1.0
	v_fmac_f32_e32 v53, v58, v53
	v_div_scale_f32 v58, vcc, 1.0, v46, 1.0
	v_mul_f32_e32 v59, v58, v53
	v_fma_f32 v60, -v52, v59, v58
	v_fmac_f32_e32 v59, v60, v53
	v_fma_f32 v52, -v52, v59, v58
	v_div_fmas_f32 v52, v52, v53, v59
	v_div_fixup_f32 v46, v52, v46, 1.0
	v_pk_mul_f32 v[46:47], v[46:47], v[50:51]
	s_nop 0
	v_cvt_pk_bf16_f32 v45, v46, v47
	global_store_dwordx2 v[54:55], v[44:45], off
	s_nop 0
	v_lshl_add_u64 v[50:51], s[36:37], 0, v[188:189]
	s_waitcnt vmcnt(2)
	v_lshlrev_b32_e32 v54, 16, v192
	s_waitcnt vmcnt(1)
; DI float bf_lo(unsigned u) { return __uint_as_float(u << 16); }
; DI float bf_hi(unsigned u) { return __uint_as_float(u & 0xffff0000u); }
; DI float sigmoidf_(float z) { return 1.0f / (1.0f + fast_exp(-z)); }
; DI void phase_glu(const Params& p, char* lds) {
;     ...
;     epi8_iter(acc, [&](int t, int n, float a, float b, float c, float d) {
;       const size_t off = (size_t)(mt * 256 + t) * 512 + nt * 256 + n;
;       const uint2 yy = *(const uint2*)(yg + off);
;       const float4 bb = *(const float4*)(p.b_glu + nt * 256 + n);
;       store_bf4(so + off, bf_lo(yy.x) * sigmoidf_(a + bb.x), bf_hi(yy.x) * sigmoidf_(b + bb.y), bf_lo(yy.y) * sigmoidf_(c + bb.z),
;                 bf_hi(yy.y) * sigmoidf_(d + bb.w));
;     });
	v_add_f32_e32 v40, v40, v196
	v_add_f32_e32 v41, v41, v197
	v_mul_f32_e32 v40, 0xbfb8aa3b, v40
	v_mul_f32_e32 v41, 0xbfb8aa3b, v41
	v_exp_f32_e32 v40, v40
	v_exp_f32_e32 v41, v41
	v_and_b32_e32 v55, 0xffff0000, v192
	v_add_f32_e32 v42, v42, v198
	v_add_f32_e32 v43, v43, v199
	v_pk_add_f32 v[40:41], v[40:41], 1.0 op_sel_hi:[1, 0]
	v_mul_f32_e32 v42, 0xbfb8aa3b, v42
	v_div_scale_f32 v44, s[0:1], v41, v41, 1.0
	v_rcp_f32_e32 v45, v44
	v_mul_f32_e32 v43, 0xbfb8aa3b, v43
	v_exp_f32_e32 v42, v42
	v_exp_f32_e32 v43, v43
	v_fma_f32 v52, -v44, v45, 1.0
	v_fmac_f32_e32 v45, v52, v45
	v_div_scale_f32 v52, vcc, 1.0, v41, 1.0
	v_mul_f32_e32 v58, v52, v45
	v_fma_f32 v59, -v44, v58, v52
	v_fmac_f32_e32 v58, v59, v45
	v_fma_f32 v44, -v44, v58, v52
	v_div_fmas_f32 v44, v44, v45, v58
	v_div_fixup_f32 v41, v44, v41, 1.0
	v_div_scale_f32 v44, s[0:1], v40, v40, 1.0
	v_rcp_f32_e32 v45, v44
	v_pk_add_f32 v[42:43], v[42:43], 1.0 op_sel_hi:[1, 0]
	v_fma_f32 v52, -v44, v45, 1.0
	v_div_scale_f32 v46, s[0:1], v43, v43, 1.0
	v_fmac_f32_e32 v45, v52, v45
	v_div_scale_f32 v52, vcc, 1.0, v40, 1.0
	v_rcp_f32_e32 v47, v46
	v_mul_f32_e32 v58, v52, v45
	v_fma_f32 v59, -v44, v58, v52
	v_fmac_f32_e32 v58, v59, v45
	v_fma_f32 v44, -v44, v58, v52
	v_fma_f32 v52, -v46, v47, 1.0
	v_div_fmas_f32 v44, v44, v45, v58
	v_fmac_f32_e32 v47, v52, v47
	v_div_scale_f32 v52, vcc, 1.0, v43, 1.0
	v_div_fixup_f32 v40, v44, v40, 1.0
	v_lshlrev_b32_e32 v44, 16, v193
	v_and_b32_e32 v45, 0xffff0000, v193
	v_mul_f32_e32 v53, v52, v47
	v_pk_mul_f32 v[40:41], v[40:41], v[54:55]
	v_fma_f32 v54, -v46, v53, v52
	v_fmac_f32_e32 v53, v54, v47
	v_fma_f32 v46, -v46, v53, v52
	v_div_fmas_f32 v46, v46, v47, v53
	v_div_fixup_f32 v43, v46, v43, 1.0
	v_div_scale_f32 v46, s[0:1], v42, v42, 1.0
	v_rcp_f32_e32 v47, v46
	v_cvt_pk_bf16_f32 v40, v40, v41
	v_fma_f32 v52, -v46, v47, 1.0
	v_fmac_f32_e32 v47, v52, v47
	v_div_scale_f32 v52, vcc, 1.0, v42, 1.0
	v_mul_f32_e32 v53, v52, v47
	v_fma_f32 v54, -v46, v53, v52
	v_fmac_f32_e32 v53, v54, v47
	v_fma_f32 v46, -v46, v53, v52
	v_div_fmas_f32 v46, v46, v47, v53
	v_div_fixup_f32 v42, v46, v42, 1.0
	v_pk_mul_f32 v[42:43], v[42:43], v[44:45]
	s_nop 0
	v_cvt_pk_bf16_f32 v41, v42, v43
	global_store_dwordx2 v[50:51], v[40:41], off
	v_add_u32_e32 v40, 0xb0, v130
	v_ashrrev_i32_e32 v41, 31, v40
	v_lshl_add_u64 v[40:41], v[40:41], 0, s[96:97]
	v_lshl_add_u64 v[42:43], v[40:41], 0, v[132:133]
	v_lshlrev_b64 v[46:47], 1, v[42:43]
	v_lshl_add_u64 v[42:43], s[26:27], 0, v[46:47]
	global_load_dwordx2 v[50:51], v[42:43], off
	global_load_dwordx4 v[216:219], v[172:173], off offset:704
	v_lshl_add_u64 v[212:213], v[184:185], 0, v[40:41]
	v_lshlrev_b64 v[220:221], 1, v[212:213]
	v_lshl_add_u64 v[224:225], s[26:27], 0, v[220:221]
	global_load_dwordx2 v[226:227], v[224:225], off
	global_load_dwordx4 v[228:231], v[172:173], off offset:704
	s_nop 0
	v_lshl_add_u64 v[46:47], s[36:37], 0, v[46:47]
	s_movk_i32 s96, 0x7fff
	s_waitcnt vmcnt(3)
	v_lshlrev_b32_e32 v52, 16, v50
	s_waitcnt vmcnt(2)
	v_add_f32_e32 v36, v36, v216
	v_add_f32_e32 v37, v37, v217
	v_mul_f32_e32 v36, 0xbfb8aa3b, v36
	v_mul_f32_e32 v37, 0xbfb8aa3b, v37
	v_exp_f32_e32 v36, v36
	v_exp_f32_e32 v37, v37
	v_and_b32_e32 v53, 0xffff0000, v50
	v_add_f32_e32 v38, v38, v218
	v_add_f32_e32 v39, v39, v219
	v_pk_add_f32 v[36:37], v[36:37], 1.0 op_sel_hi:[1, 0]
	v_mul_f32_e32 v38, 0xbfb8aa3b, v38
	v_div_scale_f32 v42, s[0:1], v37, v37, 1.0
	v_rcp_f32_e32 v43, v42
	v_mul_f32_e32 v39, 0xbfb8aa3b, v39
	v_exp_f32_e32 v38, v38
	v_exp_f32_e32 v39, v39
	v_fma_f32 v50, -v42, v43, 1.0
	v_fmac_f32_e32 v43, v50, v43
	v_div_scale_f32 v50, vcc, 1.0, v37, 1.0
	v_mul_f32_e32 v54, v50, v43
	v_fma_f32 v55, -v42, v54, v50
	v_fmac_f32_e32 v54, v55, v43
	v_fma_f32 v42, -v42, v54, v50
	v_div_fmas_f32 v42, v42, v43, v54
	v_div_fixup_f32 v37, v42, v37, 1.0
	v_div_scale_f32 v42, s[0:1], v36, v36, 1.0
	v_rcp_f32_e32 v43, v42
	v_pk_add_f32 v[38:39], v[38:39], 1.0 op_sel_hi:[1, 0]
	v_fma_f32 v50, -v42, v43, 1.0
	v_div_scale_f32 v44, s[0:1], v39, v39, 1.0
	v_fmac_f32_e32 v43, v50, v43
	v_div_scale_f32 v50, vcc, 1.0, v36, 1.0
	v_rcp_f32_e32 v45, v44
	v_mul_f32_e32 v54, v50, v43
	v_fma_f32 v55, -v42, v54, v50
	v_fmac_f32_e32 v54, v55, v43
	v_fma_f32 v42, -v42, v54, v50
	v_fma_f32 v50, -v44, v45, 1.0
	v_div_fmas_f32 v42, v42, v43, v54
	v_fmac_f32_e32 v45, v50, v45
	v_div_scale_f32 v50, vcc, 1.0, v39, 1.0
	v_div_fixup_f32 v36, v42, v36, 1.0
	v_lshlrev_b32_e32 v42, 16, v51
	v_and_b32_e32 v43, 0xffff0000, v51
	v_mul_f32_e32 v51, v50, v45
	v_pk_mul_f32 v[36:37], v[36:37], v[52:53]
	v_fma_f32 v52, -v44, v51, v50
	v_fmac_f32_e32 v51, v52, v45
	v_fma_f32 v44, -v44, v51, v50
	v_div_fmas_f32 v44, v44, v45, v51
	v_div_fixup_f32 v39, v44, v39, 1.0
	v_div_scale_f32 v44, s[0:1], v38, v38, 1.0
	v_rcp_f32_e32 v45, v44
	v_cvt_pk_bf16_f32 v36, v36, v37
	v_fma_f32 v50, -v44, v45, 1.0
	v_fmac_f32_e32 v45, v50, v45
	v_div_scale_f32 v50, vcc, 1.0, v38, 1.0
	v_mul_f32_e32 v51, v50, v45
	v_fma_f32 v52, -v44, v51, v50
	v_fmac_f32_e32 v51, v52, v45
	v_fma_f32 v44, -v44, v51, v50
	v_div_fmas_f32 v44, v44, v45, v51
	v_div_fixup_f32 v38, v44, v38, 1.0
	v_pk_mul_f32 v[38:39], v[38:39], v[42:43]
	s_nop 0
	v_cvt_pk_bf16_f32 v37, v38, v39
	global_store_dwordx2 v[46:47], v[36:37], off
	s_nop 0
	v_lshl_add_u64 v[42:43], s[36:37], 0, v[220:221]
	s_waitcnt vmcnt(2)
	v_lshlrev_b32_e32 v46, 16, v226
	s_waitcnt vmcnt(1)
; DI float bf_lo(unsigned u) { return __uint_as_float(u << 16); }
; DI float bf_hi(unsigned u) { return __uint_as_float(u & 0xffff0000u); }
; DI float sigmoidf_(float z) { return 1.0f / (1.0f + fast_exp(-z)); }
; DI void phase_glu(const Params& p, char* lds) {
;     ...
;     epi8_iter(acc, [&](int t, int n, float a, float b, float c, float d) {
;       const size_t off = (size_t)(mt * 256 + t) * 512 + nt * 256 + n;
;       const uint2 yy = *(const uint2*)(yg + off);
;       const float4 bb = *(const float4*)(p.b_glu + nt * 256 + n);
;       store_bf4(so + off, bf_lo(yy.x) * sigmoidf_(a + bb.x), bf_hi(yy.x) * sigmoidf_(b + bb.y), bf_lo(yy.y) * sigmoidf_(c + bb.z),
;                 bf_hi(yy.y) * sigmoidf_(d + bb.w));
;     });
	v_add_f32_e32 v32, v32, v228
	v_add_f32_e32 v33, v33, v229
	v_mul_f32_e32 v32, 0xbfb8aa3b, v32
	v_mul_f32_e32 v33, 0xbfb8aa3b, v33
	v_exp_f32_e32 v32, v32
	v_exp_f32_e32 v33, v33
	v_and_b32_e32 v47, 0xffff0000, v226
	v_add_f32_e32 v34, v34, v230
	v_add_f32_e32 v35, v35, v231
	v_pk_add_f32 v[32:33], v[32:33], 1.0 op_sel_hi:[1, 0]
	v_mul_f32_e32 v34, 0xbfb8aa3b, v34
	v_div_scale_f32 v36, s[0:1], v33, v33, 1.0
	v_rcp_f32_e32 v37, v36
	v_mul_f32_e32 v35, 0xbfb8aa3b, v35
	v_exp_f32_e32 v34, v34
	v_exp_f32_e32 v35, v35
	v_fma_f32 v44, -v36, v37, 1.0
	v_fmac_f32_e32 v37, v44, v37
	v_div_scale_f32 v44, vcc, 1.0, v33, 1.0
	v_mul_f32_e32 v50, v44, v37
	v_fma_f32 v51, -v36, v50, v44
	v_fmac_f32_e32 v50, v51, v37
	v_fma_f32 v36, -v36, v50, v44
	v_div_fmas_f32 v36, v36, v37, v50
	v_div_fixup_f32 v33, v36, v33, 1.0
	v_div_scale_f32 v36, s[0:1], v32, v32, 1.0
	v_rcp_f32_e32 v37, v36
	v_pk_add_f32 v[34:35], v[34:35], 1.0 op_sel_hi:[1, 0]
	v_fma_f32 v44, -v36, v37, 1.0
	v_div_scale_f32 v38, s[0:1], v35, v35, 1.0
	v_fmac_f32_e32 v37, v44, v37
	v_div_scale_f32 v44, vcc, 1.0, v32, 1.0
	v_rcp_f32_e32 v39, v38
	v_mul_f32_e32 v50, v44, v37
	v_fma_f32 v51, -v36, v50, v44
	v_fmac_f32_e32 v50, v51, v37
	v_fma_f32 v36, -v36, v50, v44
	v_fma_f32 v44, -v38, v39, 1.0
	v_div_fmas_f32 v36, v36, v37, v50
	v_fmac_f32_e32 v39, v44, v39
	v_div_scale_f32 v44, vcc, 1.0, v35, 1.0
	v_div_fixup_f32 v32, v36, v32, 1.0
	v_lshlrev_b32_e32 v36, 16, v227
	v_and_b32_e32 v37, 0xffff0000, v227
	v_mul_f32_e32 v45, v44, v39
	v_pk_mul_f32 v[32:33], v[32:33], v[46:47]
	v_fma_f32 v46, -v38, v45, v44
	v_fmac_f32_e32 v45, v46, v39
	v_fma_f32 v38, -v38, v45, v44
	v_div_fmas_f32 v38, v38, v39, v45
	v_div_fixup_f32 v35, v38, v35, 1.0
	v_div_scale_f32 v38, s[0:1], v34, v34, 1.0
	v_rcp_f32_e32 v39, v38
	v_cvt_pk_bf16_f32 v32, v32, v33
	v_fma_f32 v44, -v38, v39, 1.0
	v_fmac_f32_e32 v39, v44, v39
	v_div_scale_f32 v44, vcc, 1.0, v34, 1.0
	v_mul_f32_e32 v45, v44, v39
	v_fma_f32 v46, -v38, v45, v44
	v_fmac_f32_e32 v45, v46, v39
	v_fma_f32 v38, -v38, v45, v44
	v_div_fmas_f32 v38, v38, v39, v45
	v_div_fixup_f32 v34, v38, v34, 1.0
	v_pk_mul_f32 v[34:35], v[34:35], v[36:37]
	s_nop 0
	v_cvt_pk_bf16_f32 v33, v34, v35
	global_store_dwordx2 v[42:43], v[32:33], off
	v_lshl_add_u64 v[32:33], v[96:97], 0, v[64:65]
	v_lshlrev_b64 v[36:37], 1, v[32:33]
	v_lshl_add_u64 v[32:33], s[26:27], 0, v[36:37]
	global_load_dwordx2 v[38:39], v[32:33], off
	global_load_dwordx4 v[176:179], v[172:173], off offset:512
	v_lshl_add_u64 v[182:183], v[186:187], 0, v[64:65]
	v_lshlrev_b64 v[188:189], 1, v[182:183]
	v_lshl_add_u64 v[190:191], s[26:27], 0, v[188:189]
	global_load_dwordx2 v[192:193], v[190:191], off
	global_load_dwordx4 v[196:199], v[172:173], off offset:512
	s_nop 0
	v_lshl_add_u64 v[36:37], s[36:37], 0, v[36:37]
	s_waitcnt vmcnt(3)
	v_lshlrev_b32_e32 v42, 16, v38
	s_waitcnt vmcnt(2)
	v_add_f32_e32 v28, v28, v176
	v_add_f32_e32 v29, v29, v177
	v_mul_f32_e32 v28, 0xbfb8aa3b, v28
	v_mul_f32_e32 v29, 0xbfb8aa3b, v29
	v_exp_f32_e32 v28, v28
	v_exp_f32_e32 v29, v29
	v_and_b32_e32 v43, 0xffff0000, v38
	v_add_f32_e32 v30, v30, v178
	v_add_f32_e32 v31, v31, v179
	v_pk_add_f32 v[28:29], v[28:29], 1.0 op_sel_hi:[1, 0]
	v_mul_f32_e32 v30, 0xbfb8aa3b, v30
	v_div_scale_f32 v32, s[0:1], v29, v29, 1.0
	v_rcp_f32_e32 v33, v32
	v_mul_f32_e32 v31, 0xbfb8aa3b, v31
	v_exp_f32_e32 v30, v30
	v_exp_f32_e32 v31, v31
	v_fma_f32 v38, -v32, v33, 1.0
	v_fmac_f32_e32 v33, v38, v33
	v_div_scale_f32 v38, vcc, 1.0, v29, 1.0
	v_mul_f32_e32 v44, v38, v33
	v_fma_f32 v45, -v32, v44, v38
	v_fmac_f32_e32 v44, v45, v33
	v_fma_f32 v32, -v32, v44, v38
	v_div_fmas_f32 v32, v32, v33, v44
	v_div_fixup_f32 v29, v32, v29, 1.0
	v_div_scale_f32 v32, s[0:1], v28, v28, 1.0
	v_rcp_f32_e32 v33, v32
	v_pk_add_f32 v[30:31], v[30:31], 1.0 op_sel_hi:[1, 0]
	v_fma_f32 v38, -v32, v33, 1.0
	v_div_scale_f32 v34, s[0:1], v31, v31, 1.0
	v_fmac_f32_e32 v33, v38, v33
	v_div_scale_f32 v38, vcc, 1.0, v28, 1.0
	v_rcp_f32_e32 v35, v34
	v_mul_f32_e32 v44, v38, v33
	v_fma_f32 v45, -v32, v44, v38
	v_fmac_f32_e32 v44, v45, v33
	v_fma_f32 v32, -v32, v44, v38
	v_fma_f32 v38, -v34, v35, 1.0
	v_div_fmas_f32 v32, v32, v33, v44
	v_fmac_f32_e32 v35, v38, v35
	v_div_scale_f32 v38, vcc, 1.0, v31, 1.0
	v_div_fixup_f32 v28, v32, v28, 1.0
	v_lshlrev_b32_e32 v32, 16, v39
	v_and_b32_e32 v33, 0xffff0000, v39
	v_mul_f32_e32 v39, v38, v35
	v_pk_mul_f32 v[28:29], v[28:29], v[42:43]
	v_fma_f32 v42, -v34, v39, v38
	v_fmac_f32_e32 v39, v42, v35
	v_fma_f32 v34, -v34, v39, v38
	v_div_fmas_f32 v34, v34, v35, v39
	v_div_fixup_f32 v31, v34, v31, 1.0
	v_div_scale_f32 v34, s[0:1], v30, v30, 1.0
	v_rcp_f32_e32 v35, v34
	v_cvt_pk_bf16_f32 v28, v28, v29
	v_fma_f32 v38, -v34, v35, 1.0
	v_fmac_f32_e32 v35, v38, v35
	v_div_scale_f32 v38, vcc, 1.0, v30, 1.0
	v_mul_f32_e32 v39, v38, v35
	v_fma_f32 v42, -v34, v39, v38
	v_fmac_f32_e32 v39, v42, v35
	v_fma_f32 v34, -v34, v39, v38
	v_div_fmas_f32 v34, v34, v35, v39
	v_div_fixup_f32 v30, v34, v30, 1.0
	v_pk_mul_f32 v[30:31], v[30:31], v[32:33]
	s_nop 0
	v_cvt_pk_bf16_f32 v29, v30, v31
	global_store_dwordx2 v[36:37], v[28:29], off
	s_nop 0
	v_lshl_add_u64 v[32:33], s[36:37], 0, v[188:189]
	s_waitcnt vmcnt(2)
	v_lshlrev_b32_e32 v36, 16, v192
	s_waitcnt vmcnt(1)
; DI float bf_lo(unsigned u) { return __uint_as_float(u << 16); }
; DI float bf_hi(unsigned u) { return __uint_as_float(u & 0xffff0000u); }
; DI float sigmoidf_(float z) { return 1.0f / (1.0f + fast_exp(-z)); }
; DI void phase_glu(const Params& p, char* lds) {
;     ...
;     epi8_iter(acc, [&](int t, int n, float a, float b, float c, float d) {
;       const size_t off = (size_t)(mt * 256 + t) * 512 + nt * 256 + n;
;       const uint2 yy = *(const uint2*)(yg + off);
;       const float4 bb = *(const float4*)(p.b_glu + nt * 256 + n);
;       store_bf4(so + off, bf_lo(yy.x) * sigmoidf_(a + bb.x), bf_hi(yy.x) * sigmoidf_(b + bb.y), bf_lo(yy.y) * sigmoidf_(c + bb.z),
;                 bf_hi(yy.y) * sigmoidf_(d + bb.w));
;     });
	v_add_f32_e32 v24, v24, v196
	v_add_f32_e32 v25, v25, v197
	v_mul_f32_e32 v24, 0xbfb8aa3b, v24
	v_mul_f32_e32 v25, 0xbfb8aa3b, v25
	v_exp_f32_e32 v24, v24
	v_exp_f32_e32 v25, v25
	v_and_b32_e32 v37, 0xffff0000, v192
	v_add_f32_e32 v26, v26, v198
	v_add_f32_e32 v27, v27, v199
	v_pk_add_f32 v[24:25], v[24:25], 1.0 op_sel_hi:[1, 0]
	v_mul_f32_e32 v26, 0xbfb8aa3b, v26
	v_div_scale_f32 v28, s[0:1], v25, v25, 1.0
	v_rcp_f32_e32 v29, v28
	v_mul_f32_e32 v27, 0xbfb8aa3b, v27
	v_exp_f32_e32 v26, v26
	v_exp_f32_e32 v27, v27
	v_fma_f32 v34, -v28, v29, 1.0
	v_fmac_f32_e32 v29, v34, v29
	v_div_scale_f32 v34, vcc, 1.0, v25, 1.0
	v_mul_f32_e32 v38, v34, v29
	v_fma_f32 v39, -v28, v38, v34
	v_fmac_f32_e32 v38, v39, v29
	v_fma_f32 v28, -v28, v38, v34
	v_div_fmas_f32 v28, v28, v29, v38
	v_div_fixup_f32 v25, v28, v25, 1.0
	v_div_scale_f32 v28, s[0:1], v24, v24, 1.0
	v_rcp_f32_e32 v29, v28
	v_pk_add_f32 v[26:27], v[26:27], 1.0 op_sel_hi:[1, 0]
	v_fma_f32 v34, -v28, v29, 1.0
	v_div_scale_f32 v30, s[0:1], v27, v27, 1.0
	v_fmac_f32_e32 v29, v34, v29
	v_div_scale_f32 v34, vcc, 1.0, v24, 1.0
	v_rcp_f32_e32 v31, v30
	v_mul_f32_e32 v38, v34, v29
	v_fma_f32 v39, -v28, v38, v34
	v_fmac_f32_e32 v38, v39, v29
	v_fma_f32 v28, -v28, v38, v34
	v_fma_f32 v34, -v30, v31, 1.0
	v_div_fmas_f32 v28, v28, v29, v38
	v_fmac_f32_e32 v31, v34, v31
	v_div_scale_f32 v34, vcc, 1.0, v27, 1.0
	v_div_fixup_f32 v24, v28, v24, 1.0
	v_lshlrev_b32_e32 v28, 16, v193
	v_and_b32_e32 v29, 0xffff0000, v193
	v_mul_f32_e32 v35, v34, v31
	v_pk_mul_f32 v[24:25], v[24:25], v[36:37]
	v_fma_f32 v36, -v30, v35, v34
	v_fmac_f32_e32 v35, v36, v31
	v_fma_f32 v30, -v30, v35, v34
	v_div_fmas_f32 v30, v30, v31, v35
	v_div_fixup_f32 v27, v30, v27, 1.0
	v_div_scale_f32 v30, s[0:1], v26, v26, 1.0
	v_rcp_f32_e32 v31, v30
	v_cvt_pk_bf16_f32 v24, v24, v25
	v_fma_f32 v34, -v30, v31, 1.0
	v_fmac_f32_e32 v31, v34, v31
	v_div_scale_f32 v34, vcc, 1.0, v26, 1.0
	v_mul_f32_e32 v35, v34, v31
	v_fma_f32 v36, -v30, v35, v34
	v_fmac_f32_e32 v35, v36, v31
	v_fma_f32 v30, -v30, v35, v34
	v_div_fmas_f32 v30, v30, v31, v35
	v_div_fixup_f32 v26, v30, v26, 1.0
	v_pk_mul_f32 v[26:27], v[26:27], v[28:29]
	s_nop 0
	v_cvt_pk_bf16_f32 v25, v26, v27
	global_store_dwordx2 v[32:33], v[24:25], off
	v_lshl_add_u64 v[24:25], v[96:97], 0, v[56:57]
	v_lshlrev_b64 v[28:29], 1, v[24:25]
	v_lshl_add_u64 v[24:25], s[26:27], 0, v[28:29]
	global_load_dwordx2 v[30:31], v[24:25], off
	global_load_dwordx4 v[216:219], v[172:173], off offset:576
	v_lshl_add_u64 v[212:213], v[186:187], 0, v[56:57]
	v_lshlrev_b64 v[220:221], 1, v[212:213]
	v_lshl_add_u64 v[224:225], s[26:27], 0, v[220:221]
	global_load_dwordx2 v[226:227], v[224:225], off
	global_load_dwordx4 v[228:231], v[172:173], off offset:576
	s_nop 0
	v_lshl_add_u64 v[28:29], s[36:37], 0, v[28:29]
	s_waitcnt vmcnt(3)
	v_lshlrev_b32_e32 v32, 16, v30
	s_waitcnt vmcnt(2)
	v_add_f32_e32 v20, v20, v216
	v_add_f32_e32 v21, v21, v217
	v_mul_f32_e32 v20, 0xbfb8aa3b, v20
	v_mul_f32_e32 v21, 0xbfb8aa3b, v21
	v_exp_f32_e32 v20, v20
	v_exp_f32_e32 v21, v21
	v_and_b32_e32 v33, 0xffff0000, v30
	v_add_f32_e32 v22, v22, v218
	v_add_f32_e32 v23, v23, v219
	v_pk_add_f32 v[20:21], v[20:21], 1.0 op_sel_hi:[1, 0]
	v_mul_f32_e32 v22, 0xbfb8aa3b, v22
	v_div_scale_f32 v24, s[0:1], v21, v21, 1.0
	v_rcp_f32_e32 v25, v24
	v_mul_f32_e32 v23, 0xbfb8aa3b, v23
	v_exp_f32_e32 v22, v22
	v_exp_f32_e32 v23, v23
	v_fma_f32 v30, -v24, v25, 1.0
	v_fmac_f32_e32 v25, v30, v25
	v_div_scale_f32 v30, vcc, 1.0, v21, 1.0
	v_mul_f32_e32 v34, v30, v25
	v_fma_f32 v35, -v24, v34, v30
	v_fmac_f32_e32 v34, v35, v25
	v_fma_f32 v24, -v24, v34, v30
	v_div_fmas_f32 v24, v24, v25, v34
	v_div_fixup_f32 v21, v24, v21, 1.0
	v_div_scale_f32 v24, s[0:1], v20, v20, 1.0
	v_rcp_f32_e32 v25, v24
	v_pk_add_f32 v[22:23], v[22:23], 1.0 op_sel_hi:[1, 0]
	v_fma_f32 v30, -v24, v25, 1.0
	v_div_scale_f32 v26, s[0:1], v23, v23, 1.0
	v_fmac_f32_e32 v25, v30, v25
	v_div_scale_f32 v30, vcc, 1.0, v20, 1.0
	v_rcp_f32_e32 v27, v26
	v_mul_f32_e32 v34, v30, v25
	v_fma_f32 v35, -v24, v34, v30
	v_fmac_f32_e32 v34, v35, v25
	v_fma_f32 v24, -v24, v34, v30
	v_fma_f32 v30, -v26, v27, 1.0
	v_div_fmas_f32 v24, v24, v25, v34
	v_fmac_f32_e32 v27, v30, v27
	v_div_scale_f32 v30, vcc, 1.0, v23, 1.0
	v_div_fixup_f32 v20, v24, v20, 1.0
	v_lshlrev_b32_e32 v24, 16, v31
	v_and_b32_e32 v25, 0xffff0000, v31
	v_mul_f32_e32 v31, v30, v27
	v_pk_mul_f32 v[20:21], v[20:21], v[32:33]
	v_fma_f32 v32, -v26, v31, v30
	v_fmac_f32_e32 v31, v32, v27
	v_fma_f32 v26, -v26, v31, v30
	v_div_fmas_f32 v26, v26, v27, v31
	v_div_fixup_f32 v23, v26, v23, 1.0
	v_div_scale_f32 v26, s[0:1], v22, v22, 1.0
	v_rcp_f32_e32 v27, v26
	v_cvt_pk_bf16_f32 v20, v20, v21
	v_fma_f32 v30, -v26, v27, 1.0
	v_fmac_f32_e32 v27, v30, v27
	v_div_scale_f32 v30, vcc, 1.0, v22, 1.0
	v_mul_f32_e32 v31, v30, v27
	v_fma_f32 v32, -v26, v31, v30
	v_fmac_f32_e32 v31, v32, v27
	v_fma_f32 v26, -v26, v31, v30
	v_div_fmas_f32 v26, v26, v27, v31
	v_div_fixup_f32 v22, v26, v22, 1.0
	v_pk_mul_f32 v[22:23], v[22:23], v[24:25]
	s_nop 0
	v_cvt_pk_bf16_f32 v21, v22, v23
	global_store_dwordx2 v[28:29], v[20:21], off
	s_nop 0
	v_lshl_add_u64 v[24:25], s[36:37], 0, v[220:221]
	s_waitcnt vmcnt(2)
	v_lshlrev_b32_e32 v28, 16, v226
	s_waitcnt vmcnt(1)
; DI float bf_lo(unsigned u) { return __uint_as_float(u << 16); }
; DI float bf_hi(unsigned u) { return __uint_as_float(u & 0xffff0000u); }
; DI float sigmoidf_(float z) { return 1.0f / (1.0f + fast_exp(-z)); }
; DI void phase_glu(const Params& p, char* lds) {
;     ...
;     epi8_iter(acc, [&](int t, int n, float a, float b, float c, float d) {
;       const size_t off = (size_t)(mt * 256 + t) * 512 + nt * 256 + n;
;       const uint2 yy = *(const uint2*)(yg + off);
;       const float4 bb = *(const float4*)(p.b_glu + nt * 256 + n);
;       store_bf4(so + off, bf_lo(yy.x) * sigmoidf_(a + bb.x), bf_hi(yy.x) * sigmoidf_(b + bb.y), bf_lo(yy.y) * sigmoidf_(c + bb.z),
;                 bf_hi(yy.y) * sigmoidf_(d + bb.w));
;     });
	v_add_f32_e32 v16, v16, v228
	v_add_f32_e32 v17, v17, v229
	v_mul_f32_e32 v16, 0xbfb8aa3b, v16
	v_mul_f32_e32 v17, 0xbfb8aa3b, v17
	v_exp_f32_e32 v16, v16
	v_exp_f32_e32 v17, v17
	v_and_b32_e32 v29, 0xffff0000, v226
	v_add_f32_e32 v18, v18, v230
	v_add_f32_e32 v19, v19, v231
	v_pk_add_f32 v[16:17], v[16:17], 1.0 op_sel_hi:[1, 0]
	v_mul_f32_e32 v18, 0xbfb8aa3b, v18
	v_div_scale_f32 v20, s[0:1], v17, v17, 1.0
	v_rcp_f32_e32 v21, v20
	v_mul_f32_e32 v19, 0xbfb8aa3b, v19
	v_exp_f32_e32 v18, v18
	v_exp_f32_e32 v19, v19
	v_fma_f32 v26, -v20, v21, 1.0
	v_fmac_f32_e32 v21, v26, v21
	v_div_scale_f32 v26, vcc, 1.0, v17, 1.0
	v_mul_f32_e32 v30, v26, v21
	v_fma_f32 v31, -v20, v30, v26
	v_fmac_f32_e32 v30, v31, v21
	v_fma_f32 v20, -v20, v30, v26
	v_div_fmas_f32 v20, v20, v21, v30
	v_div_fixup_f32 v17, v20, v17, 1.0
	v_div_scale_f32 v20, s[0:1], v16, v16, 1.0
	v_rcp_f32_e32 v21, v20
	v_pk_add_f32 v[18:19], v[18:19], 1.0 op_sel_hi:[1, 0]
	v_fma_f32 v26, -v20, v21, 1.0
	v_div_scale_f32 v22, s[0:1], v19, v19, 1.0
	v_fmac_f32_e32 v21, v26, v21
	v_div_scale_f32 v26, vcc, 1.0, v16, 1.0
	v_rcp_f32_e32 v23, v22
	v_mul_f32_e32 v30, v26, v21
	v_fma_f32 v31, -v20, v30, v26
	v_fmac_f32_e32 v30, v31, v21
	v_fma_f32 v20, -v20, v30, v26
	v_fma_f32 v26, -v22, v23, 1.0
	v_div_fmas_f32 v20, v20, v21, v30
	v_fmac_f32_e32 v23, v26, v23
	v_div_scale_f32 v26, vcc, 1.0, v19, 1.0
	v_div_fixup_f32 v16, v20, v16, 1.0
	v_lshlrev_b32_e32 v20, 16, v227
	v_and_b32_e32 v21, 0xffff0000, v227
	v_mul_f32_e32 v27, v26, v23
	v_pk_mul_f32 v[16:17], v[16:17], v[28:29]
	v_fma_f32 v28, -v22, v27, v26
	v_fmac_f32_e32 v27, v28, v23
	v_fma_f32 v22, -v22, v27, v26
	v_div_fmas_f32 v22, v22, v23, v27
	v_div_fixup_f32 v19, v22, v19, 1.0
	v_div_scale_f32 v22, s[0:1], v18, v18, 1.0
	v_rcp_f32_e32 v23, v22
	v_cvt_pk_bf16_f32 v16, v16, v17
	v_fma_f32 v26, -v22, v23, 1.0
	v_fmac_f32_e32 v23, v26, v23
	v_div_scale_f32 v26, vcc, 1.0, v18, 1.0
	v_mul_f32_e32 v27, v26, v23
	v_fma_f32 v28, -v22, v27, v26
	v_fmac_f32_e32 v27, v28, v23
	v_fma_f32 v22, -v22, v27, v26
	v_div_fmas_f32 v22, v22, v23, v27
	v_div_fixup_f32 v18, v22, v18, 1.0
	v_pk_mul_f32 v[18:19], v[18:19], v[20:21]
	s_nop 0
	v_cvt_pk_bf16_f32 v17, v18, v19
	global_store_dwordx2 v[24:25], v[16:17], off
	v_lshl_add_u64 v[16:17], v[96:97], 0, v[48:49]
	v_lshlrev_b64 v[20:21], 1, v[16:17]
	v_lshl_add_u64 v[16:17], s[26:27], 0, v[20:21]
	global_load_dwordx2 v[22:23], v[16:17], off
	global_load_dwordx4 v[176:179], v[172:173], off offset:640
	v_lshl_add_u64 v[182:183], v[186:187], 0, v[48:49]
	v_lshlrev_b64 v[188:189], 1, v[182:183]
	v_lshl_add_u64 v[190:191], s[26:27], 0, v[188:189]
	global_load_dwordx2 v[192:193], v[190:191], off
	global_load_dwordx4 v[196:199], v[172:173], off offset:640
	s_nop 0
	v_lshl_add_u64 v[20:21], s[36:37], 0, v[20:21]
	s_waitcnt vmcnt(3)
	v_lshlrev_b32_e32 v24, 16, v22
	s_waitcnt vmcnt(2)
	v_add_f32_e32 v12, v12, v176
	v_add_f32_e32 v13, v13, v177
	v_mul_f32_e32 v12, 0xbfb8aa3b, v12
	v_mul_f32_e32 v13, 0xbfb8aa3b, v13
	v_exp_f32_e32 v12, v12
	v_exp_f32_e32 v13, v13
	v_and_b32_e32 v25, 0xffff0000, v22
	v_add_f32_e32 v14, v14, v178
	v_add_f32_e32 v15, v15, v179
	v_pk_add_f32 v[12:13], v[12:13], 1.0 op_sel_hi:[1, 0]
	v_mul_f32_e32 v14, 0xbfb8aa3b, v14
	v_div_scale_f32 v16, s[0:1], v13, v13, 1.0
	v_rcp_f32_e32 v17, v16
	v_mul_f32_e32 v15, 0xbfb8aa3b, v15
	v_exp_f32_e32 v14, v14
	v_exp_f32_e32 v15, v15
	v_fma_f32 v22, -v16, v17, 1.0
	v_fmac_f32_e32 v17, v22, v17
	v_div_scale_f32 v22, vcc, 1.0, v13, 1.0
	v_mul_f32_e32 v26, v22, v17
	v_fma_f32 v27, -v16, v26, v22
	v_fmac_f32_e32 v26, v27, v17
	v_fma_f32 v16, -v16, v26, v22
	v_div_fmas_f32 v16, v16, v17, v26
	v_div_fixup_f32 v13, v16, v13, 1.0
	v_div_scale_f32 v16, s[0:1], v12, v12, 1.0
	v_rcp_f32_e32 v17, v16
	v_pk_add_f32 v[14:15], v[14:15], 1.0 op_sel_hi:[1, 0]
	v_fma_f32 v22, -v16, v17, 1.0
	v_div_scale_f32 v18, s[0:1], v15, v15, 1.0
	v_fmac_f32_e32 v17, v22, v17
	v_div_scale_f32 v22, vcc, 1.0, v12, 1.0
	v_rcp_f32_e32 v19, v18
	v_mul_f32_e32 v26, v22, v17
	v_fma_f32 v27, -v16, v26, v22
	v_fmac_f32_e32 v26, v27, v17
	v_fma_f32 v16, -v16, v26, v22
	v_fma_f32 v22, -v18, v19, 1.0
	v_div_fmas_f32 v16, v16, v17, v26
	v_fmac_f32_e32 v19, v22, v19
	v_div_scale_f32 v22, vcc, 1.0, v15, 1.0
	v_div_fixup_f32 v12, v16, v12, 1.0
	v_lshlrev_b32_e32 v16, 16, v23
	v_and_b32_e32 v17, 0xffff0000, v23
	v_mul_f32_e32 v23, v22, v19
	v_pk_mul_f32 v[12:13], v[12:13], v[24:25]
	v_fma_f32 v24, -v18, v23, v22
	v_fmac_f32_e32 v23, v24, v19
	v_fma_f32 v18, -v18, v23, v22
	v_div_fmas_f32 v18, v18, v19, v23
	v_div_fixup_f32 v15, v18, v15, 1.0
	v_div_scale_f32 v18, s[0:1], v14, v14, 1.0
	v_rcp_f32_e32 v19, v18
	v_cvt_pk_bf16_f32 v12, v12, v13
	v_fma_f32 v22, -v18, v19, 1.0
	v_fmac_f32_e32 v19, v22, v19
	v_div_scale_f32 v22, vcc, 1.0, v14, 1.0
	v_mul_f32_e32 v23, v22, v19
	v_fma_f32 v24, -v18, v23, v22
	v_fmac_f32_e32 v23, v24, v19
	v_fma_f32 v18, -v18, v23, v22
	v_div_fmas_f32 v18, v18, v19, v23
	v_div_fixup_f32 v14, v18, v14, 1.0
	v_pk_mul_f32 v[14:15], v[14:15], v[16:17]
	s_nop 0
	v_cvt_pk_bf16_f32 v13, v14, v15
	global_store_dwordx2 v[20:21], v[12:13], off
	s_nop 0
	v_lshl_add_u64 v[16:17], s[36:37], 0, v[188:189]
	s_waitcnt vmcnt(2)
	v_lshlrev_b32_e32 v20, 16, v192
	s_waitcnt vmcnt(1)
; DI float bf_lo(unsigned u) { return __uint_as_float(u << 16); }
; DI float bf_hi(unsigned u) { return __uint_as_float(u & 0xffff0000u); }
; DI float sigmoidf_(float z) { return 1.0f / (1.0f + fast_exp(-z)); }
; DI void phase_glu(const Params& p, char* lds) {
;     ...
;     epi8_iter(acc, [&](int t, int n, float a, float b, float c, float d) {
;       const size_t off = (size_t)(mt * 256 + t) * 512 + nt * 256 + n;
;       const uint2 yy = *(const uint2*)(yg + off);
;       const float4 bb = *(const float4*)(p.b_glu + nt * 256 + n);
;       store_bf4(so + off, bf_lo(yy.x) * sigmoidf_(a + bb.x), bf_hi(yy.x) * sigmoidf_(b + bb.y), bf_lo(yy.y) * sigmoidf_(c + bb.z),
;                 bf_hi(yy.y) * sigmoidf_(d + bb.w));
;     });
	v_add_f32_e32 v8, v8, v196
	v_add_f32_e32 v9, v9, v197
	v_mul_f32_e32 v8, 0xbfb8aa3b, v8
	v_mul_f32_e32 v9, 0xbfb8aa3b, v9
	v_exp_f32_e32 v8, v8
	v_exp_f32_e32 v9, v9
	v_and_b32_e32 v21, 0xffff0000, v192
	v_add_f32_e32 v10, v10, v198
	v_add_f32_e32 v11, v11, v199
	v_pk_add_f32 v[8:9], v[8:9], 1.0 op_sel_hi:[1, 0]
	v_mul_f32_e32 v10, 0xbfb8aa3b, v10
	v_div_scale_f32 v12, s[0:1], v9, v9, 1.0
	v_rcp_f32_e32 v13, v12
	v_mul_f32_e32 v11, 0xbfb8aa3b, v11
	v_exp_f32_e32 v10, v10
	v_exp_f32_e32 v11, v11
	v_fma_f32 v18, -v12, v13, 1.0
	v_fmac_f32_e32 v13, v18, v13
	v_div_scale_f32 v18, vcc, 1.0, v9, 1.0
	v_mul_f32_e32 v22, v18, v13
	v_fma_f32 v23, -v12, v22, v18
	v_fmac_f32_e32 v22, v23, v13
	v_fma_f32 v12, -v12, v22, v18
	v_div_fmas_f32 v12, v12, v13, v22
	v_div_fixup_f32 v9, v12, v9, 1.0
	v_div_scale_f32 v12, s[0:1], v8, v8, 1.0
	v_rcp_f32_e32 v13, v12
	v_pk_add_f32 v[10:11], v[10:11], 1.0 op_sel_hi:[1, 0]
	v_fma_f32 v18, -v12, v13, 1.0
	v_div_scale_f32 v14, s[0:1], v11, v11, 1.0
	v_fmac_f32_e32 v13, v18, v13
	v_div_scale_f32 v18, vcc, 1.0, v8, 1.0
	v_rcp_f32_e32 v15, v14
	v_mul_f32_e32 v22, v18, v13
	v_fma_f32 v23, -v12, v22, v18
	v_fmac_f32_e32 v22, v23, v13
	v_fma_f32 v12, -v12, v22, v18
	v_fma_f32 v18, -v14, v15, 1.0
	v_div_fmas_f32 v12, v12, v13, v22
	v_fmac_f32_e32 v15, v18, v15
	v_div_scale_f32 v18, vcc, 1.0, v11, 1.0
	v_div_fixup_f32 v8, v12, v8, 1.0
	v_lshlrev_b32_e32 v12, 16, v193
	v_and_b32_e32 v13, 0xffff0000, v193
	v_mul_f32_e32 v19, v18, v15
	v_pk_mul_f32 v[8:9], v[8:9], v[20:21]
	v_fma_f32 v20, -v14, v19, v18
	v_fmac_f32_e32 v19, v20, v15
	v_fma_f32 v14, -v14, v19, v18
	v_div_fmas_f32 v14, v14, v15, v19
	v_div_fixup_f32 v11, v14, v11, 1.0
	v_div_scale_f32 v14, s[0:1], v10, v10, 1.0
	v_rcp_f32_e32 v15, v14
	v_cvt_pk_bf16_f32 v8, v8, v9
	v_fma_f32 v18, -v14, v15, 1.0
	v_fmac_f32_e32 v15, v18, v15
	v_div_scale_f32 v18, vcc, 1.0, v10, 1.0
	v_mul_f32_e32 v19, v18, v15
	v_fma_f32 v20, -v14, v19, v18
	v_fmac_f32_e32 v19, v20, v15
	v_fma_f32 v14, -v14, v19, v18
	v_div_fmas_f32 v14, v14, v15, v19
	v_div_fixup_f32 v10, v14, v10, 1.0
	v_pk_mul_f32 v[10:11], v[10:11], v[12:13]
	s_nop 0
	v_cvt_pk_bf16_f32 v9, v10, v11
	global_store_dwordx2 v[16:17], v[8:9], off
	v_lshl_add_u64 v[8:9], v[96:97], 0, v[40:41]
	v_lshlrev_b64 v[12:13], 1, v[8:9]
	v_lshl_add_u64 v[8:9], s[26:27], 0, v[12:13]
	global_load_dwordx2 v[14:15], v[8:9], off
	global_load_dwordx4 v[216:219], v[172:173], off offset:704
	v_lshl_add_u64 v[212:213], v[186:187], 0, v[40:41]
	v_lshlrev_b64 v[220:221], 1, v[212:213]
	v_lshl_add_u64 v[224:225], s[26:27], 0, v[220:221]
	global_load_dwordx2 v[226:227], v[224:225], off
	global_load_dwordx4 v[228:231], v[172:173], off offset:704
	s_nop 0
	v_lshl_add_u64 v[12:13], s[36:37], 0, v[12:13]
	s_waitcnt vmcnt(3)
	v_lshlrev_b32_e32 v16, 16, v14
	s_waitcnt vmcnt(2)
; DI int bidx() { int b = blockIdx.x; asm volatile("" : "+s"(b)); return b; }
; DI float bf_lo(unsigned u) { return __uint_as_float(u << 16); }
; DI float bf_hi(unsigned u) { return __uint_as_float(u & 0xffff0000u); }
; DI float sigmoidf_(float z) { return 1.0f / (1.0f + fast_exp(-z)); }
; DI void phase_glu(const Params& p, char* lds) {
;     ...
;   for (int it = bidx(); it < 128 * 2; it += gridDim.x) {
;     const int mt = it >> 1, nt = it & 1;
;     acc8_t acc; zero_acc8(acc);
;     asm volatile("s_waitcnt vmcnt(0)" ::: "memory");
;     gemm_main8(acc, (const bf16_t*)(p.ws + OFF_WGLU) + (size_t)nt * 256 * 512, 512, yg + (size_t)mt * 256 * 512, 512, 8, lds);
;     epi8_iter(acc, [&](int t, int n, float a, float b, float c, float d) {
;       const size_t off = (size_t)(mt * 256 + t) * 512 + nt * 256 + n;
;       const uint2 yy = *(const uint2*)(yg + off);
;       const float4 bb = *(const float4*)(p.b_glu + nt * 256 + n);
;       store_bf4(so + off, bf_lo(yy.x) * sigmoidf_(a + bb.x), bf_hi(yy.x) * sigmoidf_(b + bb.y), bf_lo(yy.y) * sigmoidf_(c + bb.z),
;                 bf_hi(yy.y) * sigmoidf_(d + bb.w));
;     });
	v_add_f32_e32 v4, v4, v216
	v_add_f32_e32 v5, v5, v217
	v_mul_f32_e32 v4, 0xbfb8aa3b, v4
	v_mul_f32_e32 v5, 0xbfb8aa3b, v5
	v_exp_f32_e32 v4, v4
	v_exp_f32_e32 v5, v5
	v_and_b32_e32 v17, 0xffff0000, v14
	v_add_f32_e32 v6, v6, v218
	v_add_f32_e32 v7, v7, v219
	v_pk_add_f32 v[4:5], v[4:5], 1.0 op_sel_hi:[1, 0]
	v_mul_f32_e32 v6, 0xbfb8aa3b, v6
	v_div_scale_f32 v8, s[0:1], v5, v5, 1.0
	v_rcp_f32_e32 v9, v8
	v_mul_f32_e32 v7, 0xbfb8aa3b, v7
	v_exp_f32_e32 v6, v6
	v_exp_f32_e32 v7, v7
	v_fma_f32 v14, -v8, v9, 1.0
	v_fmac_f32_e32 v9, v14, v9
	v_div_scale_f32 v14, vcc, 1.0, v5, 1.0
	v_mul_f32_e32 v18, v14, v9
	v_fma_f32 v19, -v8, v18, v14
	v_fmac_f32_e32 v18, v19, v9
	v_fma_f32 v8, -v8, v18, v14
	v_div_fmas_f32 v8, v8, v9, v18
	v_div_fixup_f32 v5, v8, v5, 1.0
	v_div_scale_f32 v8, s[0:1], v4, v4, 1.0
	v_rcp_f32_e32 v9, v8
	v_pk_add_f32 v[6:7], v[6:7], 1.0 op_sel_hi:[1, 0]
	v_fma_f32 v14, -v8, v9, 1.0
	v_div_scale_f32 v10, s[0:1], v7, v7, 1.0
	v_fmac_f32_e32 v9, v14, v9
	v_div_scale_f32 v14, vcc, 1.0, v4, 1.0
	v_rcp_f32_e32 v11, v10
	v_mul_f32_e32 v18, v14, v9
	v_fma_f32 v19, -v8, v18, v14
	v_fmac_f32_e32 v18, v19, v9
	v_fma_f32 v8, -v8, v18, v14
	v_fma_f32 v14, -v10, v11, 1.0
	v_div_fmas_f32 v8, v8, v9, v18
	v_fmac_f32_e32 v11, v14, v11
	v_div_scale_f32 v14, vcc, 1.0, v7, 1.0
	v_div_fixup_f32 v4, v8, v4, 1.0
	v_lshlrev_b32_e32 v8, 16, v15
	v_and_b32_e32 v9, 0xffff0000, v15
	v_mul_f32_e32 v15, v14, v11
	v_pk_mul_f32 v[4:5], v[4:5], v[16:17]
	v_fma_f32 v16, -v10, v15, v14
	v_fmac_f32_e32 v15, v16, v11
	v_fma_f32 v10, -v10, v15, v14
	v_div_fmas_f32 v10, v10, v11, v15
	v_div_fixup_f32 v7, v10, v7, 1.0
	v_div_scale_f32 v10, s[0:1], v6, v6, 1.0
	v_rcp_f32_e32 v11, v10
	v_cvt_pk_bf16_f32 v4, v4, v5
	v_fma_f32 v14, -v10, v11, 1.0
	v_fmac_f32_e32 v11, v14, v11
	v_div_scale_f32 v14, vcc, 1.0, v6, 1.0
	v_mul_f32_e32 v15, v14, v11
	v_fma_f32 v16, -v10, v15, v14
	v_fmac_f32_e32 v15, v16, v11
	v_fma_f32 v10, -v10, v15, v14
	v_div_fmas_f32 v10, v10, v11, v15
	v_div_fixup_f32 v6, v10, v6, 1.0
	v_pk_mul_f32 v[6:7], v[6:7], v[8:9]
	s_nop 0
	v_cvt_pk_bf16_f32 v5, v6, v7
	global_store_dwordx2 v[12:13], v[4:5], off
	s_nop 0
	v_lshl_add_u64 v[8:9], s[36:37], 0, v[220:221]
	s_waitcnt vmcnt(2)
	v_lshlrev_b32_e32 v12, 16, v226
	s_waitcnt vmcnt(1)
	v_add_f32_e32 v0, v0, v228
	v_add_f32_e32 v1, v1, v229
	v_mul_f32_e32 v0, 0xbfb8aa3b, v0
	v_mul_f32_e32 v1, 0xbfb8aa3b, v1
	v_exp_f32_e32 v0, v0
	v_exp_f32_e32 v1, v1
	v_and_b32_e32 v13, 0xffff0000, v226
	v_add_f32_e32 v2, v2, v230
	v_add_f32_e32 v3, v3, v231
	v_pk_add_f32 v[0:1], v[0:1], 1.0 op_sel_hi:[1, 0]
	v_mul_f32_e32 v2, 0xbfb8aa3b, v2
	v_div_scale_f32 v4, s[0:1], v1, v1, 1.0
	v_rcp_f32_e32 v5, v4
	v_mul_f32_e32 v3, 0xbfb8aa3b, v3
	v_exp_f32_e32 v2, v2
	v_exp_f32_e32 v3, v3
	v_fma_f32 v10, -v4, v5, 1.0
	v_fmac_f32_e32 v5, v10, v5
	v_div_scale_f32 v10, vcc, 1.0, v1, 1.0
	v_mul_f32_e32 v14, v10, v5
	v_fma_f32 v15, -v4, v14, v10
	v_fmac_f32_e32 v14, v15, v5
	v_fma_f32 v4, -v4, v14, v10
	v_div_fmas_f32 v4, v4, v5, v14
	v_div_fixup_f32 v1, v4, v1, 1.0
	v_div_scale_f32 v4, s[0:1], v0, v0, 1.0
	v_rcp_f32_e32 v5, v4
	v_pk_add_f32 v[2:3], v[2:3], 1.0 op_sel_hi:[1, 0]
	v_fma_f32 v10, -v4, v5, 1.0
	v_div_scale_f32 v6, s[0:1], v3, v3, 1.0
	v_fmac_f32_e32 v5, v10, v5
	v_div_scale_f32 v10, vcc, 1.0, v0, 1.0
	v_rcp_f32_e32 v7, v6
	v_mul_f32_e32 v14, v10, v5
	v_fma_f32 v15, -v4, v14, v10
	v_fmac_f32_e32 v14, v15, v5
	v_fma_f32 v4, -v4, v14, v10
	v_fma_f32 v10, -v6, v7, 1.0
	v_div_fmas_f32 v4, v4, v5, v14
	v_fmac_f32_e32 v7, v10, v7
	v_div_scale_f32 v10, vcc, 1.0, v3, 1.0
	v_div_fixup_f32 v0, v4, v0, 1.0
	v_lshlrev_b32_e32 v4, 16, v227
	v_and_b32_e32 v5, 0xffff0000, v227
	v_mul_f32_e32 v11, v10, v7
	v_pk_mul_f32 v[0:1], v[0:1], v[12:13]
	v_fma_f32 v12, -v6, v11, v10
	v_fmac_f32_e32 v11, v12, v7
	v_fma_f32 v6, -v6, v11, v10
	v_div_fmas_f32 v6, v6, v7, v11
	v_div_fixup_f32 v3, v6, v3, 1.0
	v_div_scale_f32 v6, s[0:1], v2, v2, 1.0
	v_rcp_f32_e32 v7, v6
	v_readlane_b32 s0, v254, 24
	v_readlane_b32 s1, v254, 25
	s_xor_b64 s[4:5], s[4:5], s[0:1]
	v_fma_f32 v10, -v6, v7, 1.0
	v_fmac_f32_e32 v7, v10, v7
	v_div_scale_f32 v10, vcc, 1.0, v2, 1.0
	v_mul_f32_e32 v11, v10, v7
	v_fma_f32 v12, -v6, v11, v10
	v_fmac_f32_e32 v11, v12, v7
	v_fma_f32 v6, -v6, v11, v10
	v_div_fmas_f32 v6, v6, v7, v11
	v_div_fixup_f32 v2, v6, v2, 1.0
	v_pk_mul_f32 v[2:3], v[2:3], v[4:5]
	v_cvt_pk_bf16_f32 v0, v0, v1
	v_cvt_pk_bf16_f32 v1, v2, v3
	s_cmpk_lt_i32 s21, 0x100
	global_store_dwordx2 v[8:9], v[0:1], off
	s_cbranch_scc0 .LBB0_268
